# second f32->bf16 conversion pass (131 more sites) and sample-task gated o_c LDS read-mul-write chain batched 8 deep
# speedup vs baseline: 1.0139x; 1.0086x over previous
; __device__ __forceinline__ unsigned pk2(float lo, float hi) { return f2bf(lo) | (f2bf(hi) << 16); }
; __device__ __forceinline__ void phase_prologue(const Prm& P, Ctx& C) {
;     ...
; #pragma unroll
;         for (int u = 0; u < 4; ++u) { const int m = m0 + u * NGW;
;             if (m < MA) {
; #pragma unroll
;                 for (int j = 0; j < 4; ++j) { u32x2 o; o.x = pk2(v[u][j][0], v[u][j][1]); o.y = pk2(v[u][j][2], v[u][j][3]); *(u32x2*)(XA + (size_t)m * DM + 4 * C.lane + 256 * j) = o; } } }
.LBB0_135:
	s_waitcnt vmcnt(0)
	v_cvt_pk_bf16_f32 v4, v4, v5
	v_cvt_pk_bf16_f32 v5, v6, v7
	global_store_dwordx2 v[68:69], v[4:5], off
	v_cvt_pk_bf16_f32 v0, v0, v1
	v_cvt_pk_bf16_f32 v1, v2, v3
	global_store_dwordx2 v[68:69], v[0:1], off offset:512
	v_cvt_pk_bf16_f32 v0, v12, v13
	v_cvt_pk_bf16_f32 v1, v14, v15
	global_store_dwordx2 v[68:69], v[0:1], off offset:1024
	v_cvt_pk_bf16_f32 v0, v8, v9
	v_cvt_pk_bf16_f32 v1, v10, v11
	s_cmp_gt_i32 s28, 0x80ff
	global_store_dwordx2 v[68:69], v[0:1], off offset:1536
	s_cbranch_scc1 .LBB0_138
	v_cvt_pk_bf16_f32 v0, v24, v25
	s_ashr_i32 s29, s28, 31
	s_lshl_b64 s[0:1], s[28:29], 11
	v_cvt_pk_bf16_f32 v1, v26, v27
	v_lshl_add_u64 v[2:3], v[66:67], 0, s[0:1]
	global_store_dwordx2 v[2:3], v[0:1], off
	v_cvt_pk_bf16_f32 v0, v16, v17
	v_cvt_pk_bf16_f32 v1, v18, v19
	global_store_dwordx2 v[2:3], v[0:1], off offset:512
	v_cvt_pk_bf16_f32 v0, v28, v29
	v_cvt_pk_bf16_f32 v1, v30, v31
	global_store_dwordx2 v[2:3], v[0:1], off offset:1024
	v_cvt_pk_bf16_f32 v0, v20, v21
	v_cvt_pk_bf16_f32 v1, v22, v23
	global_store_dwordx2 v[2:3], v[0:1], off offset:1536
	s_cmp_gt_i32 s30, 0x80ff
	s_cbranch_scc0 .LBB0_139

; __device__ __forceinline__ unsigned pk2(float lo, float hi) { return f2bf(lo) | (f2bf(hi) << 16); }
; __device__ __forceinline__ float sigmoidf_(float x) { return __builtin_amdgcn_rcpf(1.0f + __expf(-x)); }
; __device__ __forceinline__ void st8bf(bf16_t* p, f32x4 a, f32x4 b) { u32x4 w; w.x = pk2(a[0], a[1]); w.y = pk2(a[2], a[3]); w.z = pk2(b[0], b[1]); w.w = pk2(b[2], b[3]); st16(p, w); }
; __device__ __forceinline__ void stnt8(float* o, f32x4 a, f32x4 b) { __builtin_nontemporal_store(a, (f32x4*)o); __builtin_nontemporal_store(b, (f32x4*)(o + 4)); }
; __device__ __forceinline__ f32x4 sig4(f32x4 v) { f32x4 r; r[0] = sigmoidf_(v[0]); r[1] = sigmoidf_(v[1]); r[2] = sigmoidf_(v[2]); r[3] = sigmoidf_(v[3]); return r; }
;     __device__ __forceinline__ void st(int pn, int row, int c, f32x4 v0, f32x4 v1) const {
;     ...
;         if (pn < 6 || pn == 11 || pn == 12) st8bf((pn < 6 ? AG : BG) + (size_t)row * 512 + (pn < 6 ? pn - 4 : pn - 11) * 256 + c, v0 * sig4(v0), v1 * sig4(v1));
.LBB0_335:
	s_and_b64 s[10:11], s[66:67], exec
	s_cselect_b32 s11, s51, s79
	s_cselect_b32 s10, s33, s78
	v_lshl_add_u64 v[144:145], s[10:11], 0, v[2:3]
	v_mul_f32_e32 v146, 0xbfb8aa3b, v120
	v_lshl_add_u64 v[144:145], s[64:65], 1, v[144:145]
	v_exp_f32_e32 v150, v146
	v_lshlrev_b32_e32 v146, 1, v206
	v_mov_b32_e32 v147, v1
	v_lshl_add_u64 v[148:149], v[144:145], 0, v[146:147]
	v_mul_f32_e32 v145, 0xbfb8aa3b, v121
	v_exp_f32_e32 v145, v145
	v_mul_f32_e32 v146, 0xbfb8aa3b, v122
	v_mul_f32_e32 v147, 0xbfb8aa3b, v123
	v_exp_f32_e32 v146, v146
	v_exp_f32_e32 v147, v147
	v_add_f32_e32 v144, 1.0, v150
	v_add_f32_e32 v145, 1.0, v145
	v_rcp_f32_e32 v144, v144
	v_rcp_f32_e32 v145, v145
	v_mul_f32_e32 v150, 0xbfb8aa3b, v116
	v_mul_f32_e32 v151, 0xbfb8aa3b, v117
	v_exp_f32_e32 v150, v150
	v_exp_f32_e32 v151, v151
	v_add_f32_e32 v146, 1.0, v146
	v_add_f32_e32 v147, 1.0, v147
	v_rcp_f32_e32 v146, v146
	v_rcp_f32_e32 v147, v147
	v_mul_f32_e32 v152, 0xbfb8aa3b, v118
	v_mul_f32_e32 v153, 0xbfb8aa3b, v119
	v_exp_f32_e32 v152, v152
	v_exp_f32_e32 v153, v153
	v_pk_mul_f32 v[144:145], v[120:121], v[144:145]
	v_add_f32_e32 v150, 1.0, v150
	v_add_f32_e32 v151, 1.0, v151
	v_rcp_f32_e32 v150, v150
	v_rcp_f32_e32 v151, v151
	v_pk_mul_f32 v[146:147], v[122:123], v[146:147]
	v_add_f32_e32 v152, 1.0, v152
	v_add_f32_e32 v153, 1.0, v153
	v_cvt_pk_bf16_f32 v144, v144, v145
	v_rcp_f32_e32 v152, v152
	v_rcp_f32_e32 v153, v153
	v_pk_mul_f32 v[150:151], v[116:117], v[150:151]
	v_cvt_pk_bf16_f32 v145, v146, v147
	v_pk_mul_f32 v[152:153], v[118:119], v[152:153]
	v_cvt_pk_bf16_f32 v146, v150, v151
	v_bfe_u32 v147, v152, 16, 1
	v_add3_u32 v147, v152, v147, s81
	v_bfe_u32 v150, v153, 16, 1
	v_lshrrev_b32_e32 v147, 16, v147
	v_add3_u32 v150, v153, v150, s81
	v_and_or_b32 v147, v150, s25, v147
	global_store_dwordx4 v[148:149], v[144:147], off
	s_andn2_b64 vcc, exec, s[68:69]
	s_mov_b64 s[10:11], -1
	s_cbranch_vccz .LBB0_313

; __device__ __forceinline__ unsigned pk2(float lo, float hi) { return f2bf(lo) | (f2bf(hi) << 16); }
; __device__ __forceinline__ float sigmoidf_(float x) { return __builtin_amdgcn_rcpf(1.0f + __expf(-x)); }
; __device__ __forceinline__ void st8bf(bf16_t* p, f32x4 a, f32x4 b) { u32x4 w; w.x = pk2(a[0], a[1]); w.y = pk2(a[2], a[3]); w.z = pk2(b[0], b[1]); w.w = pk2(b[2], b[3]); st16(p, w); }
; __device__ __forceinline__ void stnt8(float* o, f32x4 a, f32x4 b) { __builtin_nontemporal_store(a, (f32x4*)o); __builtin_nontemporal_store(b, (f32x4*)(o + 4)); }
; __device__ __forceinline__ f32x4 sig4(f32x4 v) { f32x4 r; r[0] = sigmoidf_(v[0]); r[1] = sigmoidf_(v[1]); r[2] = sigmoidf_(v[2]); r[3] = sigmoidf_(v[3]); return r; }
;     __device__ __forceinline__ void st(int pn, int row, int c, f32x4 v0, f32x4 v1) const {
;     ...
;         if (pn < 6 || pn == 11 || pn == 12) st8bf((pn < 6 ? AG : BG) + (size_t)row * 512 + (pn < 6 ? pn - 4 : pn - 11) * 256 + c, v0 * sig4(v0), v1 * sig4(v1));
.LBB0_455:
	s_and_b64 s[76:77], s[66:67], exec
	s_cselect_b32 s77, s51, s79
	s_cselect_b32 s76, s33, s78
	v_lshl_add_u64 v[114:115], s[76:77], 0, v[102:103]
	v_mul_f32_e32 v116, 0xbfb8aa3b, v88
	v_lshl_add_u64 v[114:115], s[64:65], 1, v[114:115]
	v_exp_f32_e32 v120, v116
	v_lshlrev_b32_e32 v116, 1, v206
	v_mov_b32_e32 v117, v1
	v_lshl_add_u64 v[118:119], v[114:115], 0, v[116:117]
	v_mul_f32_e32 v115, 0xbfb8aa3b, v89
	v_exp_f32_e32 v115, v115
	v_mul_f32_e32 v116, 0xbfb8aa3b, v90
	v_mul_f32_e32 v117, 0xbfb8aa3b, v91
	v_exp_f32_e32 v116, v116
	v_exp_f32_e32 v117, v117
	v_add_f32_e32 v114, 1.0, v120
	v_add_f32_e32 v115, 1.0, v115
	v_rcp_f32_e32 v114, v114
	v_rcp_f32_e32 v115, v115
	v_mul_f32_e32 v120, 0xbfb8aa3b, v84
	v_mul_f32_e32 v121, 0xbfb8aa3b, v85
	v_exp_f32_e32 v120, v120
	v_exp_f32_e32 v121, v121
	v_add_f32_e32 v116, 1.0, v116
	v_add_f32_e32 v117, 1.0, v117
	v_rcp_f32_e32 v116, v116
	v_rcp_f32_e32 v117, v117
	v_mul_f32_e32 v122, 0xbfb8aa3b, v86
	v_mul_f32_e32 v123, 0xbfb8aa3b, v87
	v_exp_f32_e32 v122, v122
	v_exp_f32_e32 v123, v123
	v_pk_mul_f32 v[114:115], v[88:89], v[114:115]
	v_add_f32_e32 v120, 1.0, v120
	v_add_f32_e32 v121, 1.0, v121
	v_rcp_f32_e32 v120, v120
	v_rcp_f32_e32 v121, v121
	v_pk_mul_f32 v[116:117], v[90:91], v[116:117]
	v_add_f32_e32 v122, 1.0, v122
	v_add_f32_e32 v123, 1.0, v123
	v_cvt_pk_bf16_f32 v114, v114, v115
	v_rcp_f32_e32 v122, v122
	v_rcp_f32_e32 v123, v123
	v_pk_mul_f32 v[120:121], v[84:85], v[120:121]
	v_cvt_pk_bf16_f32 v115, v116, v117
	v_pk_mul_f32 v[122:123], v[86:87], v[122:123]
	v_cvt_pk_bf16_f32 v116, v120, v121
	v_bfe_u32 v117, v122, 16, 1
	v_add3_u32 v117, v122, v117, s81
	v_bfe_u32 v120, v123, 16, 1
	v_lshrrev_b32_e32 v117, 16, v117
	v_add3_u32 v120, v123, v120, s81
	v_and_or_b32 v117, v120, s25, v117
	global_store_dwordx4 v[118:119], v[114:117], off
	s_and_b64 vcc, exec, s[12:13]
	s_mov_b64 s[12:13], -1
	s_cbranch_vccz .LBB0_433

; __device__ __forceinline__ unsigned pk2(float lo, float hi) { return f2bf(lo) | (f2bf(hi) << 16); }
; __device__ __forceinline__ float sigmoidf_(float x) { return __builtin_amdgcn_rcpf(1.0f + __expf(-x)); }
; __device__ __forceinline__ void st8bf(bf16_t* p, f32x4 a, f32x4 b) { u32x4 w; w.x = pk2(a[0], a[1]); w.y = pk2(a[2], a[3]); w.z = pk2(b[0], b[1]); w.w = pk2(b[2], b[3]); st16(p, w); }
; __device__ __forceinline__ void stnt8(float* o, f32x4 a, f32x4 b) { __builtin_nontemporal_store(a, (f32x4*)o); __builtin_nontemporal_store(b, (f32x4*)(o + 4)); }
; __device__ __forceinline__ f32x4 sig4(f32x4 v) { f32x4 r; r[0] = sigmoidf_(v[0]); r[1] = sigmoidf_(v[1]); r[2] = sigmoidf_(v[2]); r[3] = sigmoidf_(v[3]); return r; }
;     __device__ __forceinline__ void st(int pn, int row, int c, f32x4 v0, f32x4 v1) const {
;     ...
;         if (pn < 6 || pn == 11 || pn == 12) st8bf((pn < 6 ? AG : BG) + (size_t)row * 512 + (pn < 6 ? pn - 4 : pn - 11) * 256 + c, v0 * sig4(v0), v1 * sig4(v1));
.LBB0_517:
	s_and_b64 s[76:77], s[66:67], exec
	s_cselect_b32 s77, s51, s79
	s_cselect_b32 s76, s33, s78
	v_lshl_add_u64 v[98:99], s[76:77], 0, v[86:87]
	v_mul_f32_e32 v100, 0xbfb8aa3b, v72
	v_lshl_add_u64 v[98:99], s[64:65], 1, v[98:99]
	v_exp_f32_e32 v104, v100
	v_lshlrev_b32_e32 v100, 1, v206
	v_mov_b32_e32 v101, v1
	v_lshl_add_u64 v[102:103], v[98:99], 0, v[100:101]
	v_mul_f32_e32 v99, 0xbfb8aa3b, v73
	v_exp_f32_e32 v99, v99
	v_mul_f32_e32 v100, 0xbfb8aa3b, v74
	v_mul_f32_e32 v101, 0xbfb8aa3b, v75
	v_exp_f32_e32 v100, v100
	v_exp_f32_e32 v101, v101
	v_add_f32_e32 v98, 1.0, v104
	v_add_f32_e32 v99, 1.0, v99
	v_rcp_f32_e32 v98, v98
	v_rcp_f32_e32 v99, v99
	v_mul_f32_e32 v104, 0xbfb8aa3b, v68
	v_mul_f32_e32 v105, 0xbfb8aa3b, v69
	v_exp_f32_e32 v104, v104
	v_exp_f32_e32 v105, v105
	v_add_f32_e32 v100, 1.0, v100
	v_add_f32_e32 v101, 1.0, v101
	v_rcp_f32_e32 v100, v100
	v_rcp_f32_e32 v101, v101
	v_mul_f32_e32 v106, 0xbfb8aa3b, v70
	v_mul_f32_e32 v107, 0xbfb8aa3b, v71
	v_exp_f32_e32 v106, v106
	v_exp_f32_e32 v107, v107
	v_pk_mul_f32 v[98:99], v[72:73], v[98:99]
	v_add_f32_e32 v104, 1.0, v104
	v_add_f32_e32 v105, 1.0, v105
	v_rcp_f32_e32 v104, v104
	v_rcp_f32_e32 v105, v105
	v_pk_mul_f32 v[100:101], v[74:75], v[100:101]
	v_add_f32_e32 v106, 1.0, v106
	v_add_f32_e32 v107, 1.0, v107
	v_cvt_pk_bf16_f32 v98, v98, v99
	v_rcp_f32_e32 v106, v106
	v_rcp_f32_e32 v107, v107
	v_pk_mul_f32 v[104:105], v[68:69], v[104:105]
	v_cvt_pk_bf16_f32 v99, v100, v101
	v_pk_mul_f32 v[106:107], v[70:71], v[106:107]
	v_cvt_pk_bf16_f32 v100, v104, v105
	v_bfe_u32 v101, v106, 16, 1
	v_add3_u32 v101, v106, v101, s81
	v_bfe_u32 v104, v107, 16, 1
	v_lshrrev_b32_e32 v101, 16, v101
	v_add3_u32 v104, v107, v104, s81
	v_and_or_b32 v101, v104, s25, v101
	global_store_dwordx4 v[102:103], v[98:101], off
	s_and_b64 vcc, exec, s[12:13]
	s_mov_b64 s[12:13], -1
	s_cbranch_vccz .LBB0_493

; __device__ __forceinline__ unsigned pk2(float lo, float hi) { return f2bf(lo) | (f2bf(hi) << 16); }
; __device__ __forceinline__ float sigmoidf_(float x) { return __builtin_amdgcn_rcpf(1.0f + __expf(-x)); }
; __device__ __forceinline__ void st8bf(bf16_t* p, f32x4 a, f32x4 b) { u32x4 w; w.x = pk2(a[0], a[1]); w.y = pk2(a[2], a[3]); w.z = pk2(b[0], b[1]); w.w = pk2(b[2], b[3]); st16(p, w); }
; __device__ __forceinline__ void stnt8(float* o, f32x4 a, f32x4 b) { __builtin_nontemporal_store(a, (f32x4*)o); __builtin_nontemporal_store(b, (f32x4*)(o + 4)); }
; __device__ __forceinline__ f32x4 sig4(f32x4 v) { f32x4 r; r[0] = sigmoidf_(v[0]); r[1] = sigmoidf_(v[1]); r[2] = sigmoidf_(v[2]); r[3] = sigmoidf_(v[3]); return r; }
;     __device__ __forceinline__ void st(int pn, int row, int c, f32x4 v0, f32x4 v1) const {
;     ...
;         if (pn < 6 || pn == 11 || pn == 12) st8bf((pn < 6 ? AG : BG) + (size_t)row * 512 + (pn < 6 ? pn - 4 : pn - 11) * 256 + c, v0 * sig4(v0), v1 * sig4(v1));
.LBB0_579:
	s_and_b64 s[76:77], s[66:67], exec
	s_cselect_b32 s77, s51, s79
	s_cselect_b32 s76, s33, s78
	v_lshl_add_u64 v[82:83], s[76:77], 0, v[70:71]
	v_mul_f32_e32 v84, 0xbfb8aa3b, v56
	v_lshl_add_u64 v[82:83], s[64:65], 1, v[82:83]
	v_exp_f32_e32 v88, v84
	v_lshlrev_b32_e32 v84, 1, v206
	v_mov_b32_e32 v85, v1
	v_lshl_add_u64 v[86:87], v[82:83], 0, v[84:85]
	v_mul_f32_e32 v83, 0xbfb8aa3b, v57
	v_exp_f32_e32 v83, v83
	v_mul_f32_e32 v84, 0xbfb8aa3b, v58
	v_mul_f32_e32 v85, 0xbfb8aa3b, v59
	v_exp_f32_e32 v84, v84
	v_exp_f32_e32 v85, v85
	v_add_f32_e32 v82, 1.0, v88
	v_add_f32_e32 v83, 1.0, v83
	v_rcp_f32_e32 v82, v82
	v_rcp_f32_e32 v83, v83
	v_mul_f32_e32 v88, 0xbfb8aa3b, v52
	v_mul_f32_e32 v89, 0xbfb8aa3b, v53
	v_exp_f32_e32 v88, v88
	v_exp_f32_e32 v89, v89
	v_add_f32_e32 v84, 1.0, v84
	v_add_f32_e32 v85, 1.0, v85
	v_rcp_f32_e32 v84, v84
	v_rcp_f32_e32 v85, v85
	v_mul_f32_e32 v90, 0xbfb8aa3b, v54
	v_mul_f32_e32 v91, 0xbfb8aa3b, v55
	v_exp_f32_e32 v90, v90
	v_exp_f32_e32 v91, v91
	v_pk_mul_f32 v[82:83], v[56:57], v[82:83]
	v_add_f32_e32 v88, 1.0, v88
	v_add_f32_e32 v89, 1.0, v89
	v_rcp_f32_e32 v88, v88
	v_rcp_f32_e32 v89, v89
	v_pk_mul_f32 v[84:85], v[58:59], v[84:85]
	v_add_f32_e32 v90, 1.0, v90
	v_add_f32_e32 v91, 1.0, v91
	v_cvt_pk_bf16_f32 v82, v82, v83
	v_rcp_f32_e32 v90, v90
	v_rcp_f32_e32 v91, v91
	v_pk_mul_f32 v[88:89], v[52:53], v[88:89]
	v_cvt_pk_bf16_f32 v83, v84, v85
	v_pk_mul_f32 v[90:91], v[54:55], v[90:91]
	v_cvt_pk_bf16_f32 v84, v88, v89
	v_bfe_u32 v85, v90, 16, 1
	v_add3_u32 v85, v90, v85, s81
	v_bfe_u32 v88, v91, 16, 1
	v_lshrrev_b32_e32 v85, 16, v85
	v_add3_u32 v88, v91, v88, s81
	v_and_or_b32 v85, v88, s25, v85
	global_store_dwordx4 v[86:87], v[82:85], off
	s_and_b64 vcc, exec, s[12:13]
	s_mov_b64 s[12:13], -1
	s_cbranch_vccz .LBB0_555

; __device__ __forceinline__ unsigned pk2(float lo, float hi) { return f2bf(lo) | (f2bf(hi) << 16); }
; __device__ __forceinline__ float sigmoidf_(float x) { return __builtin_amdgcn_rcpf(1.0f + __expf(-x)); }
; __device__ __forceinline__ void st8bf(bf16_t* p, f32x4 a, f32x4 b) { u32x4 w; w.x = pk2(a[0], a[1]); w.y = pk2(a[2], a[3]); w.z = pk2(b[0], b[1]); w.w = pk2(b[2], b[3]); st16(p, w); }
; __device__ __forceinline__ void stnt8(float* o, f32x4 a, f32x4 b) { __builtin_nontemporal_store(a, (f32x4*)o); __builtin_nontemporal_store(b, (f32x4*)(o + 4)); }
; __device__ __forceinline__ f32x4 sig4(f32x4 v) { f32x4 r; r[0] = sigmoidf_(v[0]); r[1] = sigmoidf_(v[1]); r[2] = sigmoidf_(v[2]); r[3] = sigmoidf_(v[3]); return r; }
;     __device__ __forceinline__ void st(int pn, int row, int c, f32x4 v0, f32x4 v1) const {
;     ...
;         if (pn < 6 || pn == 11 || pn == 12) st8bf((pn < 6 ? AG : BG) + (size_t)row * 512 + (pn < 6 ? pn - 4 : pn - 11) * 256 + c, v0 * sig4(v0), v1 * sig4(v1));
.LBB0_699:
	s_and_b64 s[76:77], s[66:67], exec
	s_cselect_b32 s77, s51, s79
	s_cselect_b32 s76, s33, s78
	v_lshl_add_u64 v[50:51], s[76:77], 0, v[38:39]
	v_mul_f32_e32 v52, 0xbfb8aa3b, v24
	v_lshl_add_u64 v[50:51], s[64:65], 1, v[50:51]
	v_exp_f32_e32 v56, v52
	v_lshlrev_b32_e32 v52, 1, v206
	v_mov_b32_e32 v53, v1
	v_lshl_add_u64 v[54:55], v[50:51], 0, v[52:53]
	v_mul_f32_e32 v51, 0xbfb8aa3b, v25
	v_exp_f32_e32 v51, v51
	v_mul_f32_e32 v52, 0xbfb8aa3b, v26
	v_mul_f32_e32 v53, 0xbfb8aa3b, v27
	v_exp_f32_e32 v52, v52
	v_exp_f32_e32 v53, v53
	v_add_f32_e32 v50, 1.0, v56
	v_add_f32_e32 v51, 1.0, v51
	v_rcp_f32_e32 v50, v50
	v_rcp_f32_e32 v51, v51
	v_mul_f32_e32 v56, 0xbfb8aa3b, v20
	v_mul_f32_e32 v57, 0xbfb8aa3b, v21
	v_exp_f32_e32 v56, v56
	v_exp_f32_e32 v57, v57
	v_add_f32_e32 v52, 1.0, v52
	v_add_f32_e32 v53, 1.0, v53
	v_rcp_f32_e32 v52, v52
	v_rcp_f32_e32 v53, v53
	v_mul_f32_e32 v58, 0xbfb8aa3b, v22
	v_mul_f32_e32 v59, 0xbfb8aa3b, v23
	v_exp_f32_e32 v58, v58
	v_exp_f32_e32 v59, v59
	v_pk_mul_f32 v[50:51], v[24:25], v[50:51]
	v_add_f32_e32 v56, 1.0, v56
	v_add_f32_e32 v57, 1.0, v57
	v_rcp_f32_e32 v56, v56
	v_rcp_f32_e32 v57, v57
	v_pk_mul_f32 v[52:53], v[26:27], v[52:53]
	v_add_f32_e32 v58, 1.0, v58
	v_add_f32_e32 v59, 1.0, v59
	v_cvt_pk_bf16_f32 v50, v50, v51
	v_rcp_f32_e32 v58, v58
	v_rcp_f32_e32 v59, v59
	v_pk_mul_f32 v[56:57], v[20:21], v[56:57]
	v_cvt_pk_bf16_f32 v51, v52, v53
	v_pk_mul_f32 v[58:59], v[22:23], v[58:59]
	v_cvt_pk_bf16_f32 v52, v56, v57
	v_bfe_u32 v53, v58, 16, 1
	v_add3_u32 v53, v58, v53, s81
	v_bfe_u32 v56, v59, 16, 1
	v_lshrrev_b32_e32 v53, 16, v53
	v_add3_u32 v56, v59, v56, s81
	v_and_or_b32 v53, v56, s25, v53
	global_store_dwordx4 v[54:55], v[50:53], off
	s_and_b64 vcc, exec, s[12:13]
	s_mov_b64 s[12:13], -1
	s_cbranch_vccz .LBB0_677

; #define LAS __attribute__((address_space(3)))
; __device__ __forceinline__ unsigned pk2(float lo, float hi) { return f2bf(lo) | (f2bf(hi) << 16); }
; __device__ __forceinline__ float siluf_(float x) { return x * sigmoidf_(x); }
; __device__ __forceinline__ void conv_unit_piped(const Prm& P, Ctx& C, int b, int t0, unsigned (&ur)[62], const float (&w)[31], const float bias, bool has_next, int nb, int nt0) {
;     ...
;     for (int rq = 0; rq < NRW; ++rq) {
;         const int i = C.wave + rq * NWAVES;
;         if (i < NT) {
;             const size_t row = (size_t)(row0 + i);
;             f32x4 v0 = *(const LAS f32x4*)(y + i * 512 + c8), v1 = *(const LAS f32x4*)(y + i * 512 + c8 + 4);
;             const float s = ((v0[0] + v0[1]) + (v0[2] + v0[3])) + ((v1[0] + v1[1]) + (v1[2] + v1[3]));
;             const float mean = wave_sum(s) * (1.f / 512.f);
;             v0 = v0 - mean; v1 = v1 - mean;
;             const float q2 = ((v0[0] * v0[0] + v0[1] * v0[1]) + (v0[2] * v0[2] + v0[3] * v0[3])) + ((v1[0] * v1[0] + v1[1] * v1[1]) + (v1[2] * v1[2] + v1[3] * v1[3]));
;             const float rstd = 1.f / sqrtf(wave_sum(q2) * (1.f / 512.f) + LN_EPS);
;             const u32x4 ag = agv[rq];
;             f32x4 z0 = v0 * rstd * g0 + b0, z1 = v1 * rstd * g1 + b1;
;             z0[0] = siluf_(z0[0]) * bflo(ag.x); z0[1] = siluf_(z0[1]) * bfhi(ag.x); z0[2] = siluf_(z0[2]) * bflo(ag.y); z0[3] = siluf_(z0[3]) * bfhi(ag.y);
;             z1[0] = siluf_(z1[0]) * bflo(ag.z); z1[1] = siluf_(z1[1]) * bfhi(ag.z); z1[2] = siluf_(z1[2]) * bflo(ag.w); z1[3] = siluf_(z1[3]) * bfhi(ag.w);
;             u32x4 o; o.x = pk2(z0[0], z0[1]); o.y = pk2(z0[2], z0[3]); o.z = pk2(z1[0], z1[1]); o.w = pk2(z1[2], z1[3]);
;             *(u32x4*)(H2 + row * 1024 + c8) = o;
.LBB0_989:
	v_add_u32_e32 v163, s57, v162
	s_waitcnt vmcnt(32)
	ds_read_b128 v[28:31], v163
	ds_read_b128 v[164:167], v163 offset:16
	s_waitcnt lgkmcnt(1)
	v_mov_b32_e32 v168, v28
	s_waitcnt lgkmcnt(0)
	v_mov_b32_e32 v169, v164
	v_mov_b32_e32 v170, v29
	v_mov_b32_e32 v171, v165
	v_pk_add_f32 v[168:169], v[168:169], v[170:171]
	v_mov_b32_e32 v170, v30
	v_mov_b32_e32 v171, v166
	v_mov_b32_e32 v172, v31
	v_mov_b32_e32 v173, v167
	v_pk_add_f32 v[170:171], v[170:171], v[172:173]
	s_nop 0
	v_pk_add_f32 v[168:169], v[168:169], v[170:171]
	s_nop 0
	v_add_f32_e32 v163, v168, v169
	v_mov_b32_e32 v168, 0
	s_nop 0
	v_add_f32_dpp v163, v163, v163 row_shr:1 row_mask:0xf bank_mask:0xf bound_ctrl:1
	s_nop 1
	v_add_f32_dpp v163, v163, v163 row_shr:2 row_mask:0xf bank_mask:0xf bound_ctrl:1
	s_nop 1
	v_add_f32_dpp v163, v163, v163 row_shr:4 row_mask:0xf bank_mask:0xf bound_ctrl:1
	s_nop 1
	v_add_f32_dpp v163, v163, v163 row_shr:8 row_mask:0xf bank_mask:0xf bound_ctrl:1
	s_nop 1
	v_mov_b32_dpp v168, v163 row_bcast:15 row_mask:0xa bank_mask:0xf
	v_add_f32_e32 v163, v163, v168
	v_mov_b32_e32 v168, 0
	s_nop 1
	v_mov_b32_dpp v168, v163 row_bcast:31 row_mask:0xc bank_mask:0xf
	v_add_f32_e32 v163, v163, v168
	s_nop 0
	v_readlane_b32 s4, v163, 63
	s_nop 1
	v_fma_f32 v31, s4, v187, v31
	v_fmac_f32_e32 v29, s4, v187
	v_fma_f32 v30, s4, v187, v30
	v_fma_f32 v28, s4, v187, v28
	v_mul_f32_e32 v163, v29, v29
	v_mul_f32_e32 v168, v31, v31
	v_fma_f32 v167, s4, v187, v167
	v_fmac_f32_e32 v165, s4, v187
	v_fmac_f32_e32 v163, v28, v28
	v_fmac_f32_e32 v168, v30, v30
	v_fma_f32 v166, s4, v187, v166
	v_fma_f32 v164, s4, v187, v164
	v_add_f32_e32 v163, v163, v168
	v_mul_f32_e32 v168, v165, v165
	v_mul_f32_e32 v169, v167, v167
	v_fmac_f32_e32 v168, v164, v164
	v_fmac_f32_e32 v169, v166, v166
	v_add_f32_e32 v168, v168, v169
	v_add_f32_e32 v163, v163, v168
	v_mov_b32_e32 v168, 0
	s_nop 0
	v_add_f32_dpp v163, v163, v163 row_shr:1 row_mask:0xf bank_mask:0xf bound_ctrl:1
	s_nop 1
	v_add_f32_dpp v163, v163, v163 row_shr:2 row_mask:0xf bank_mask:0xf bound_ctrl:1
	s_nop 1
	v_add_f32_dpp v163, v163, v163 row_shr:4 row_mask:0xf bank_mask:0xf bound_ctrl:1
	s_nop 1
	v_add_f32_dpp v163, v163, v163 row_shr:8 row_mask:0xf bank_mask:0xf bound_ctrl:1
	s_nop 1
	v_mov_b32_dpp v168, v163 row_bcast:15 row_mask:0xa bank_mask:0xf
	v_add_f32_e32 v163, v163, v168
	v_mov_b32_e32 v168, 0
	s_nop 1
	v_mov_b32_dpp v168, v163 row_bcast:31 row_mask:0xc bank_mask:0xf
	v_add_f32_e32 v163, v163, v168
	s_nop 0
	v_readlane_b32 s4, v163, 63
	s_nop 1
	v_fma_f32 v163, s4, v188, v185
	v_mul_f32_e32 v168, 0x4f800000, v163
	v_cmp_gt_f32_e32 vcc, s63, v163
	s_nop 1
	v_cndmask_b32_e32 v163, v163, v168, vcc
	v_sqrt_f32_e32 v168, v163
	s_nop 0
	v_add_u32_e32 v169, -1, v168
	v_fma_f32 v170, -v169, v168, v163
	v_cmp_ge_f32_e64 s[4:5], 0, v170
	v_add_u32_e32 v170, 1, v168
	s_nop 0
	v_cndmask_b32_e64 v169, v168, v169, s[4:5]
	v_fma_f32 v168, -v170, v168, v163
	v_cmp_lt_f32_e64 s[4:5], 0, v168
	s_nop 1
	v_cndmask_b32_e64 v168, v169, v170, s[4:5]
	v_mul_f32_e32 v169, 0x37800000, v168
	v_cndmask_b32_e32 v168, v168, v169, vcc
	v_cmp_class_f32_e32 vcc, v163, v186
	s_nop 1
	v_cndmask_b32_e32 v163, v168, v163, vcc
	v_div_scale_f32 v168, s[4:5], v163, v163, 1.0
	v_rcp_f32_e32 v169, v168
	s_add_i32 s4, s66, s54
	s_ashr_i32 s5, s4, 31
	s_lshl_b64 s[4:5], s[4:5], 11
	v_fma_f32 v170, -v168, v169, 1.0
	v_fmac_f32_e32 v169, v170, v169
	v_div_scale_f32 v170, vcc, 1.0, v163, 1.0
	v_mul_f32_e32 v171, v170, v169
	v_fma_f32 v172, -v168, v171, v170
	v_fmac_f32_e32 v171, v172, v169
	v_fma_f32 v168, -v168, v171, v170
	v_div_fmas_f32 v168, v168, v169, v171
	v_div_fixup_f32 v168, v168, v163, 1.0
	v_pk_mul_f32 v[28:29], v[28:29], v[168:169] op_sel_hi:[1,0]
	v_pk_mul_f32 v[30:31], v[30:31], v[168:169] op_sel_hi:[1,0]
	v_pk_fma_f32 v[28:29], v[8:9], v[28:29], v[12:13]
	v_pk_mul_f32 v[164:165], v[164:165], v[168:169] op_sel_hi:[1,0]
	v_mul_f32_e32 v163, 0xbfb8aa3b, v28
	v_pk_mul_f32 v[166:167], v[166:167], v[168:169] op_sel_hi:[1,0]
	v_exp_f32_e32 v163, v163
	v_mul_f32_e32 v168, 0xbfb8aa3b, v29
	v_exp_f32_e32 v169, v168
	v_pk_fma_f32 v[30:31], v[10:11], v[30:31], v[14:15]
	v_add_f32_e32 v163, 1.0, v163
	v_rcp_f32_e32 v168, v163
	v_add_f32_e32 v163, 1.0, v169
	v_mul_f32_e32 v169, 0xbfb8aa3b, v30
	v_exp_f32_e32 v169, v169
	v_mul_f32_e32 v170, 0xbfb8aa3b, v31
	v_exp_f32_e32 v171, v170
	v_pk_fma_f32 v[164:165], v[0:1], v[164:165], v[4:5]
	v_rcp_f32_e32 v170, v163
	v_add_f32_e32 v163, 1.0, v169
	v_rcp_f32_e32 v169, v163
	v_add_f32_e32 v163, 1.0, v171
	v_mul_f32_e32 v171, 0xbfb8aa3b, v164
	v_exp_f32_e32 v172, v171
	v_mul_f32_e32 v171, 0xbfb8aa3b, v165
	v_exp_f32_e32 v173, v171
	v_pk_fma_f32 v[166:167], v[2:3], v[166:167], v[6:7]
	v_rcp_f32_e32 v171, v163
	v_add_f32_e32 v163, 1.0, v172
	v_rcp_f32_e32 v172, v163
	v_add_f32_e32 v163, 1.0, v173
	v_mul_f32_e32 v173, 0xbfb8aa3b, v166
	v_exp_f32_e32 v173, v173
	v_mul_f32_e32 v174, 0xbfb8aa3b, v167
	v_exp_f32_e32 v175, v174
	v_rcp_f32_e32 v174, v163
	v_add_f32_e32 v163, 1.0, v173
	v_rcp_f32_e32 v173, v163
	v_add_f32_e32 v163, 1.0, v175
	v_rcp_f32_e32 v175, v163
	v_mov_b32_e32 v176, v28
	v_mov_b32_e32 v177, v30
	v_mov_b32_e32 v30, v29
	v_pk_mul_f32 v[168:169], v[176:177], v[168:169]
	v_lshlrev_b32_e32 v177, 16, v25
	v_lshlrev_b32_e32 v176, 16, v24
	v_pk_mul_f32 v[28:29], v[30:31], v[170:171]
	v_and_b32_e32 v25, 0xffff0000, v25
	v_and_b32_e32 v24, 0xffff0000, v24
	v_pk_mul_f32 v[24:25], v[28:29], v[24:25]
	v_mov_b32_e32 v28, v164
	v_mov_b32_e32 v29, v166
	v_pk_mul_f32 v[28:29], v[28:29], v[172:173]
	v_lshlrev_b32_e32 v31, 16, v27
	v_lshlrev_b32_e32 v30, 16, v26
	v_mov_b32_e32 v166, v165
	v_pk_mul_f32 v[28:29], v[28:29], v[30:31]
	v_pk_mul_f32 v[30:31], v[166:167], v[174:175]
	v_and_b32_e32 v27, 0xffff0000, v27
	v_and_b32_e32 v26, 0xffff0000, v26
	v_pk_mul_f32 v[26:27], v[30:31], v[26:27]
	v_pk_mul_f32 v[168:169], v[168:169], v[176:177]
	v_cvt_pk_bf16_f32 v27, v29, v27
	v_cvt_pk_bf16_f32 v26, v28, v26
	v_cvt_pk_bf16_f32 v25, v169, v25
	v_cvt_pk_bf16_f32 v24, v168, v24
	v_lshl_add_u64 v[28:29], v[98:99], 0, s[4:5]
	global_store_dwordx4 v[28:29], v[24:27], off
	s_and_b64 vcc, exec, s[2:3]
	s_cbranch_vccz .LBB0_987

; __device__ __forceinline__ float ex2(float x) { return __builtin_amdgcn_exp2f(x); }
; __device__ __forceinline__ int crow(int r, int hi) { return (r & 3) + 8 * (r >> 2) + 4 * hi; }
; #define MFMA32(a, b, c) __builtin_amdgcn_mfma_f32_32x32x16_bf16((a), (b), (c), 0, 0, 0)
; __device__ __forceinline__ float quad_sum(float v) { v += __int_as_float(dpp_x1(__float_as_int(v))); v += __int_as_float(dpp_x2(__float_as_int(v))); return v; }
; __device__ __forceinline__ void cmp_task_lds(const Prm& P, Ctx& C, int b, int kvh, int tg, CStream& CS, const LAS bf16_t* wlb, const int NGW, bf16x8 (&qnx)[4], int& qnx_tg, const int tg_next) {
;     ...
;                     for (int r = 0; r < 16; ++r) { const bool valid = (32 * tile + crow(r, hi)) < nvq; S[r] = valid ? ex2(S[r] - ml) : 0.f; }
;                 }
; #pragma unroll
;                 for (int i = 0; i < 4; ++i) { const float v = quad_sum(S[4 * i] + S[4 * i + 1] + S[4 * i + 2]); if (g == tt) cur4[i] = v; }
;                 bf16x8 pf[2]; pf[0] = pack8(S, 0); pf[1] = pack8(S, 8);
; #pragma unroll
;                 for (int dk = 0; dk < 4; ++dk)
;                     o[dk >> 1] = MFMA32(((bf16x8){vlo[dk][0], vlo[dk][1], vlo[dk][2], vlo[dk][3], vhh[dk][0], vhh[dk][1], vhh[dk][2], vhh[dk][3]}), pf[dk & 1], o[dk >> 1]);
.LBB0_1090:
	v_mov_b32_e32 v2, v52
	v_mov_b32_e32 v3, v48
	v_mov_b32_e32 v4, v53
	v_mov_b32_e32 v5, v49
	v_pk_add_f32 v[2:3], v[2:3], v[4:5]
	v_mov_b32_e32 v4, v54
	v_mov_b32_e32 v5, v50
	v_pk_add_f32 v[2:3], v[4:5], v[2:3]
	s_nop 1
	v_mov_b32_dpp v5, v3 quad_perm:[1,0,3,2] row_mask:0xf bank_mask:0xf bound_ctrl:1
	s_nop 0
	v_mov_b32_dpp v4, v2 quad_perm:[1,0,3,2] row_mask:0xf bank_mask:0xf bound_ctrl:1
	v_pk_add_f32 v[2:3], v[2:3], v[4:5]
	s_nop 0
	s_nop 0
	v_mov_b32_dpp v5, v3 quad_perm:[2,3,0,1] row_mask:0xf bank_mask:0xf bound_ctrl:1
	v_mov_b32_dpp v4, v2 quad_perm:[2,3,0,1] row_mask:0xf bank_mask:0xf bound_ctrl:1
	v_pk_add_f32 v[2:3], v[2:3], v[4:5]
	v_cndmask_b32_e64 v152, v152, v2, s[6:7]
	v_cvt_pk_bf16_f32 v2, v48, v49
	v_cndmask_b32_e64 v153, v153, v3, s[6:7]
	v_cvt_pk_bf16_f32 v3, v50, v51
	v_cvt_pk_bf16_f32 v4, v52, v53
	v_cvt_pk_bf16_f32 v5, v54, v55
	v_cvt_pk_bf16_f32 v48, v56, v57
	s_waitcnt lgkmcnt(6)
	v_mfma_f32_32x32x16_bf16 v[32:47], v[116:119], v[2:5], v[32:47]
	v_cvt_pk_bf16_f32 v49, v58, v59
	v_cvt_pk_bf16_f32 v50, v60, v61
	s_waitcnt lgkmcnt(2)
	v_mfma_f32_32x32x16_bf16 v[16:31], v[104:107], v[2:5], v[16:31]
	v_cvt_pk_bf16_f32 v51, v62, v63
	v_mov_b32_e32 v214, v60
	v_mov_b32_e32 v215, v56
	v_mfma_f32_32x32x16_bf16 v[32:47], v[112:115], v[48:51], v[32:47]
	v_mov_b32_e32 v52, v61
	v_mov_b32_e32 v53, v57
	v_add_f32_e64 v52, v214, v52
	v_add_f32_e64 v53, v215, v53
	v_mov_b32_e32 v54, v62
	v_mov_b32_e32 v55, v58
	v_pk_add_f32 v[52:53], v[54:55], v[52:53]
	s_waitcnt lgkmcnt(0)
	v_mfma_f32_32x32x16_bf16 v[16:31], v[10:13], v[48:51], v[16:31]
	v_mov_b32_dpp v55, v53 quad_perm:[1,0,3,2] row_mask:0xf bank_mask:0xf bound_ctrl:1
	v_mov_b32_dpp v54, v52 quad_perm:[1,0,3,2] row_mask:0xf bank_mask:0xf bound_ctrl:1
	v_add_f32_e64 v2, v52, v54
	v_add_f32_e64 v3, v53, v55
	s_nop 1
	v_mov_b32_dpp v5, v3 quad_perm:[2,3,0,1] row_mask:0xf bank_mask:0xf bound_ctrl:1
	v_mov_b32_dpp v4, v2 quad_perm:[2,3,0,1] row_mask:0xf bank_mask:0xf bound_ctrl:1
	v_pk_add_f32 v[2:3], v[2:3], v[4:5]
	s_nop 0
	v_cndmask_b32_e64 v155, v155, v3, s[6:7]
	v_cndmask_b32_e64 v154, v154, v2, s[6:7]
	s_add_i32 s18, s16, 2
	s_cmp_ge_i32 s18, s14
	s_cbranch_scc1 .LBB0_1083

; __device__ __forceinline__ float ex2(float x) { return __builtin_amdgcn_exp2f(x); }
; __device__ __forceinline__ int crow(int r, int hi) { return (r & 3) + 8 * (r >> 2) + 4 * hi; }
; #define MFMA32(a, b, c) __builtin_amdgcn_mfma_f32_32x32x16_bf16((a), (b), (c), 0, 0, 0)
; __device__ __forceinline__ float quad_sum(float v) { v += __int_as_float(dpp_x1(__float_as_int(v))); v += __int_as_float(dpp_x2(__float_as_int(v))); return v; }
; __device__ __forceinline__ void cmp_task_lds(const Prm& P, Ctx& C, int b, int kvh, int tg, CStream& CS, const LAS bf16_t* wlb, const int NGW, bf16x8 (&qnx)[4], int& qnx_tg, const int tg_next) {
;     ...
;                     for (int r = 0; r < 16; ++r) { const bool valid = (32 * tile + crow(r, hi)) < nvq; S[r] = valid ? ex2(S[r] - ml) : 0.f; }
;                 }
; #pragma unroll
;                 for (int i = 0; i < 4; ++i) { const float v = quad_sum(S[4 * i] + S[4 * i + 1] + S[4 * i + 2]); if (g == tt) cur4[i] = v; }
;                 bf16x8 pf[2]; pf[0] = pack8(S, 0); pf[1] = pack8(S, 8);
; #pragma unroll
;                 for (int dk = 0; dk < 4; ++dk)
;                     o[dk >> 1] = MFMA32(((bf16x8){vlo[dk][0], vlo[dk][1], vlo[dk][2], vlo[dk][3], vhh[dk][0], vhh[dk][1], vhh[dk][2], vhh[dk][3]}), pf[dk & 1], o[dk >> 1]);
.LBB0_1095:
	v_mov_b32_e32 v6, v52
	v_mov_b32_e32 v7, v48
	v_mov_b32_e32 v8, v53
	v_mov_b32_e32 v9, v49
	v_pk_add_f32 v[6:7], v[6:7], v[8:9]
	v_mov_b32_e32 v8, v54
	v_mov_b32_e32 v9, v50
	v_pk_add_f32 v[6:7], v[8:9], v[6:7]
	s_nop 1
	v_mov_b32_dpp v9, v7 quad_perm:[1,0,3,2] row_mask:0xf bank_mask:0xf bound_ctrl:1
	s_nop 0
	v_mov_b32_dpp v8, v6 quad_perm:[1,0,3,2] row_mask:0xf bank_mask:0xf bound_ctrl:1
	v_pk_add_f32 v[6:7], v[6:7], v[8:9]
	s_nop 0
	s_nop 0
	v_mov_b32_dpp v9, v7 quad_perm:[2,3,0,1] row_mask:0xf bank_mask:0xf bound_ctrl:1
	v_mov_b32_dpp v8, v6 quad_perm:[2,3,0,1] row_mask:0xf bank_mask:0xf bound_ctrl:1
	v_pk_add_f32 v[6:7], v[6:7], v[8:9]
	v_cndmask_b32_e64 v152, v152, v6, s[8:9]
	v_cvt_pk_bf16_f32 v6, v48, v49
	v_cndmask_b32_e64 v153, v153, v7, s[8:9]
	v_cvt_pk_bf16_f32 v7, v50, v51
	v_cvt_pk_bf16_f32 v8, v52, v53
	v_cvt_pk_bf16_f32 v9, v54, v55
	v_cvt_pk_bf16_f32 v48, v56, v57
	s_waitcnt lgkmcnt(6)
	v_mfma_f32_32x32x16_bf16 v[32:47], v[116:119], v[6:9], v[32:47]
	v_cvt_pk_bf16_f32 v49, v58, v59
	v_cvt_pk_bf16_f32 v50, v60, v61
	s_waitcnt lgkmcnt(2)
	v_mfma_f32_32x32x16_bf16 v[16:31], v[100:103], v[6:9], v[16:31]
	v_cvt_pk_bf16_f32 v51, v62, v63
	v_mov_b32_e32 v214, v60
	v_mov_b32_e32 v215, v56
	v_mfma_f32_32x32x16_bf16 v[32:47], v[104:107], v[48:51], v[32:47]
	v_mov_b32_e32 v52, v61
	v_mov_b32_e32 v53, v57
	v_add_f32_e64 v52, v214, v52
	v_add_f32_e64 v53, v215, v53
	v_mov_b32_e32 v54, v62
	v_mov_b32_e32 v55, v58
	v_pk_add_f32 v[52:53], v[54:55], v[52:53]
	s_waitcnt lgkmcnt(0)
	v_mfma_f32_32x32x16_bf16 v[16:31], v[96:99], v[48:51], v[16:31]
	v_mov_b32_dpp v55, v53 quad_perm:[1,0,3,2] row_mask:0xf bank_mask:0xf bound_ctrl:1
	v_mov_b32_dpp v54, v52 quad_perm:[1,0,3,2] row_mask:0xf bank_mask:0xf bound_ctrl:1
	v_add_f32_e64 v6, v52, v54
	v_add_f32_e64 v7, v53, v55
	s_nop 1
	v_mov_b32_dpp v9, v7 quad_perm:[2,3,0,1] row_mask:0xf bank_mask:0xf bound_ctrl:1
	v_mov_b32_dpp v8, v6 quad_perm:[2,3,0,1] row_mask:0xf bank_mask:0xf bound_ctrl:1
	v_pk_add_f32 v[6:7], v[6:7], v[8:9]
	s_nop 0
	v_cndmask_b32_e64 v155, v155, v7, s[8:9]
	v_cndmask_b32_e64 v154, v154, v6, s[8:9]
	s_add_i32 s18, s16, 3
	s_cmp_ge_i32 s18, s14
	s_cbranch_scc1 .LBB0_1084

; __device__ __forceinline__ float ex2(float x) { return __builtin_amdgcn_exp2f(x); }
; __device__ __forceinline__ int crow(int r, int hi) { return (r & 3) + 8 * (r >> 2) + 4 * hi; }
; #define MFMA32(a, b, c) __builtin_amdgcn_mfma_f32_32x32x16_bf16((a), (b), (c), 0, 0, 0)
; __device__ __forceinline__ float quad_sum(float v) { v += __int_as_float(dpp_x1(__float_as_int(v))); v += __int_as_float(dpp_x2(__float_as_int(v))); return v; }
; __device__ __forceinline__ void cmp_task_lds(const Prm& P, Ctx& C, int b, int kvh, int tg, CStream& CS, const LAS bf16_t* wlb, const int NGW, bf16x8 (&qnx)[4], int& qnx_tg, const int tg_next) {
;     ...
;                     for (int r = 0; r < 16; ++r) { const bool valid = (32 * tile + crow(r, hi)) < nvq; S[r] = valid ? ex2(S[r] - ml) : 0.f; }
;                 }
; #pragma unroll
;                 for (int i = 0; i < 4; ++i) { const float v = quad_sum(S[4 * i] + S[4 * i + 1] + S[4 * i + 2]); if (g == tt) cur4[i] = v; }
;                 bf16x8 pf[2]; pf[0] = pack8(S, 0); pf[1] = pack8(S, 8);
; #pragma unroll
;                 for (int dk = 0; dk < 4; ++dk)
;                     o[dk >> 1] = MFMA32(((bf16x8){vlo[dk][0], vlo[dk][1], vlo[dk][2], vlo[dk][3], vhh[dk][0], vhh[dk][1], vhh[dk][2], vhh[dk][3]}), pf[dk & 1], o[dk >> 1]);
.LBB0_1100:
	v_mov_b32_e32 v2, v52
	v_mov_b32_e32 v3, v48
	v_mov_b32_e32 v4, v53
	v_mov_b32_e32 v5, v49
	v_pk_add_f32 v[2:3], v[2:3], v[4:5]
	v_mov_b32_e32 v4, v54
	v_mov_b32_e32 v5, v50
	v_pk_add_f32 v[2:3], v[4:5], v[2:3]
	s_nop 1
	v_mov_b32_dpp v5, v3 quad_perm:[1,0,3,2] row_mask:0xf bank_mask:0xf bound_ctrl:1
	s_nop 0
	v_mov_b32_dpp v4, v2 quad_perm:[1,0,3,2] row_mask:0xf bank_mask:0xf bound_ctrl:1
	v_pk_add_f32 v[2:3], v[2:3], v[4:5]
	s_nop 0
	s_nop 0
	v_mov_b32_dpp v5, v3 quad_perm:[2,3,0,1] row_mask:0xf bank_mask:0xf bound_ctrl:1
	v_mov_b32_dpp v4, v2 quad_perm:[2,3,0,1] row_mask:0xf bank_mask:0xf bound_ctrl:1
	v_pk_add_f32 v[2:3], v[2:3], v[4:5]
	v_cndmask_b32_e64 v152, v152, v2, s[10:11]
	v_cvt_pk_bf16_f32 v2, v48, v49
	v_cndmask_b32_e64 v153, v153, v3, s[10:11]
	v_cvt_pk_bf16_f32 v3, v50, v51
	v_cvt_pk_bf16_f32 v4, v52, v53
	v_cvt_pk_bf16_f32 v5, v54, v55
	v_cvt_pk_bf16_f32 v48, v56, v57
	s_waitcnt lgkmcnt(6)
	v_mfma_f32_32x32x16_bf16 v[32:47], v[116:119], v[2:5], v[32:47]
	v_cvt_pk_bf16_f32 v49, v58, v59
	v_cvt_pk_bf16_f32 v50, v60, v61
	s_waitcnt lgkmcnt(2)
	v_mfma_f32_32x32x16_bf16 v[16:31], v[10:13], v[2:5], v[16:31]
	v_bfe_u32 v1, v62, 16, 1
	v_add3_u32 v1, v62, v1, s71
	v_bfe_u32 v51, v63, 16, 1
	v_lshrrev_b32_e32 v1, 16, v1
	v_add3_u32 v51, v63, v51, s71
	v_and_or_b32 v51, v51, s72, v1
	v_mov_b32_e32 v212, v60
	v_mov_b32_e32 v213, v56
	v_mfma_f32_32x32x16_bf16 v[32:47], v[112:115], v[48:51], v[32:47]
	v_mov_b32_e32 v52, v61
	v_mov_b32_e32 v53, v57
	v_add_f32_e64 v52, v212, v52
	v_add_f32_e64 v53, v213, v53
	v_mov_b32_e32 v54, v62
	v_mov_b32_e32 v55, v58
	v_pk_add_f32 v[52:53], v[54:55], v[52:53]
	s_waitcnt lgkmcnt(0)
	v_mfma_f32_32x32x16_bf16 v[16:31], v[6:9], v[48:51], v[16:31]
	v_mov_b32_dpp v55, v53 quad_perm:[1,0,3,2] row_mask:0xf bank_mask:0xf bound_ctrl:1
	v_mov_b32_dpp v54, v52 quad_perm:[1,0,3,2] row_mask:0xf bank_mask:0xf bound_ctrl:1
	v_add_f32_e64 v2, v52, v54
	v_add_f32_e64 v3, v53, v55
	s_nop 1
	v_mov_b32_dpp v5, v3 quad_perm:[2,3,0,1] row_mask:0xf bank_mask:0xf bound_ctrl:1
	v_mov_b32_dpp v4, v2 quad_perm:[2,3,0,1] row_mask:0xf bank_mask:0xf bound_ctrl:1
	v_pk_add_f32 v[2:3], v[2:3], v[4:5]
	s_nop 0
	v_cndmask_b32_e64 v155, v155, v3, s[10:11]
	v_cndmask_b32_e64 v154, v154, v2, s[10:11]

; #define LAS __attribute__((address_space(3)))
; __device__ __forceinline__ void cmp_fill_lds(const Prm& P, Ctx& C, int b, int kvh) {
;     const bf16_t* src = (const bf16_t*)(P.ws + WS_KC) + (size_t)b * 512 * 256 + kvh * 64;
; #pragma unroll
;     for (int it = 0; it < 8; ++it) {
;         const int idx = it * NTHR + C.tid, k = idx >> 3, c = idx & 7;
;         *(LAS u32x4*)(C.lds + CK_K + c * 8192 + k * 16) = *(const u32x4*)(src + (size_t)k * 256 + 8 * c);
;     }
; #pragma unroll
;     for (int it = 0; it < 8; ++it) {
;         const int idx = it * NTHR + C.tid, k = idx >> 3, c = idx & 7;
;         const u32x4 v = *(const u32x4*)(src + 128 + (size_t)k * 256 + 8 * c);
;         LAS bf16_t* d = (LAS bf16_t*)(C.lds + CK_V + (8 * c) * CK_VS) + k;
;         const unsigned w[4] = {v.x, v.y, v.z, v.w};
; #pragma unroll
;         for (int e = 0; e < 4; ++e) { d[(2 * e) * (CK_VS / 2)] = (bf16_t)(w[e] & 0xffffu); d[(2 * e + 1) * (CK_VS / 2)] = (bf16_t)(w[e] >> 16); }
;     }
.LBB0_1204:
	s_cbranch_execz .LBB0_1429
	s_cmp_lt_u32 s96, 4
	s_cbranch_scc1 .Lp2_prio_done
	s_setprio 1
.Lp2_prio_done:
	s_and_b32 s4, s77, 1
	s_lshl_b32 s0, s90, 18
	v_readlane_b32 s1, v251, 0
	s_add_u32 s0, s1, s0
	v_readlane_b32 s1, v250, 58
	v_add_u32_e32 v2, 0x200, v120
	s_addc_u32 s1, s1, 0
	s_lshl_b32 s2, s4, 7
	v_ashrrev_i32_e32 v60, 3, v120
	v_ashrrev_i32_e32 v62, 3, v2
	s_add_u32 s2, s0, s2
	v_ashrrev_i32_e32 v61, 31, v60
	v_ashrrev_i32_e32 v63, 31, v62
	s_addc_u32 s3, s1, 0
	v_and_b32_e32 v80, 7, v145
	v_lshlrev_b64 v[32:33], 9, v[60:61]
	v_lshlrev_b64 v[36:37], 9, v[62:63]
	v_lshl_add_u64 v[0:1], s[2:3], 0, v[32:33]
	v_lshlrev_b32_e32 v34, 4, v80
	v_mov_b32_e32 v35, 0
	v_lshl_add_u64 v[2:3], s[2:3], 0, v[36:37]
	v_lshl_add_u64 v[0:1], v[0:1], 0, v[34:35]
	v_lshl_add_u64 v[4:5], v[2:3], 0, v[34:35]
	global_load_dwordx4 v[0:3], v[0:1], off
	s_nop 0
	global_load_dwordx4 v[4:7], v[4:5], off
	v_add_u32_e32 v8, 0x400, v120
	v_add_u32_e32 v10, 0x600, v120
	v_ashrrev_i32_e32 v64, 3, v8
	v_ashrrev_i32_e32 v66, 3, v10
	v_ashrrev_i32_e32 v65, 31, v64
	v_ashrrev_i32_e32 v67, 31, v66
	v_add_u32_e32 v16, 0x800, v120
	v_add_u32_e32 v18, 0xa00, v120
	v_lshlrev_b64 v[40:41], 9, v[64:65]
	v_lshlrev_b64 v[44:45], 9, v[66:67]
	v_ashrrev_i32_e32 v68, 3, v16
	v_ashrrev_i32_e32 v70, 3, v18
	v_add_u32_e32 v24, 0xc00, v120
	v_add_u32_e32 v28, 0xe00, v120
	v_lshl_add_u64 v[8:9], s[2:3], 0, v[40:41]
	v_lshl_add_u64 v[10:11], s[2:3], 0, v[44:45]
	v_ashrrev_i32_e32 v69, 31, v68
	v_ashrrev_i32_e32 v71, 31, v70
	v_ashrrev_i32_e32 v72, 3, v24
	v_ashrrev_i32_e32 v74, 3, v28
	v_lshl_add_u64 v[8:9], v[8:9], 0, v[34:35]
	v_lshl_add_u64 v[12:13], v[10:11], 0, v[34:35]
	v_lshlrev_b64 v[48:49], 9, v[68:69]
	v_lshlrev_b64 v[52:53], 9, v[70:71]
	v_ashrrev_i32_e32 v73, 31, v72
	v_ashrrev_i32_e32 v75, 31, v74
	global_load_dwordx4 v[8:11], v[8:9], off
	s_nop 0
	global_load_dwordx4 v[12:15], v[12:13], off
	v_lshl_add_u64 v[16:17], s[2:3], 0, v[48:49]
	v_lshl_add_u64 v[18:19], s[2:3], 0, v[52:53]
	v_lshlrev_b64 v[56:57], 9, v[72:73]
	v_lshlrev_b64 v[76:77], 9, v[74:75]
	v_lshl_add_u64 v[16:17], v[16:17], 0, v[34:35]
	v_lshl_add_u64 v[20:21], v[18:19], 0, v[34:35]
	v_lshl_add_u64 v[24:25], s[2:3], 0, v[56:57]
	v_lshl_add_u64 v[28:29], s[2:3], 0, v[76:77]
	global_load_dwordx4 v[16:19], v[16:17], off
	s_nop 0
	global_load_dwordx4 v[20:23], v[20:21], off
	v_lshl_add_u64 v[24:25], v[24:25], 0, v[34:35]
	v_lshl_add_u64 v[28:29], v[28:29], 0, v[34:35]
	v_lshlrev_b32_e32 v34, 3, v145
	global_load_dwordx4 v[24:27], v[24:25], off
	v_and_b32_e32 v61, 56, v34
	global_load_dwordx4 v[28:31], v[28:29], off
	v_lshlrev_b32_e32 v34, 1, v61
	v_lshl_add_u64 v[78:79], s[2:3], 0, v[34:35]
	v_lshl_add_u64 v[32:33], v[78:79], 0, v[32:33]
	global_load_dwordx4 v[32:35], v[32:33], off offset:256
	v_lshl_add_u64 v[36:37], v[78:79], 0, v[36:37]
	global_load_dwordx4 v[36:39], v[36:37], off offset:256
	v_lshl_add_u64 v[40:41], v[78:79], 0, v[40:41]
	global_load_dwordx4 v[40:43], v[40:41], off offset:256
	v_lshl_add_u64 v[44:45], v[78:79], 0, v[44:45]
	global_load_dwordx4 v[44:47], v[44:45], off offset:256
	v_lshl_add_u64 v[48:49], v[78:79], 0, v[48:49]
	v_lshl_add_u32 v63, v80, 13, 0
	global_load_dwordx4 v[48:51], v[48:49], off offset:256
	v_lshl_add_u64 v[52:53], v[78:79], 0, v[52:53]
	v_lshl_add_u64 v[56:57], v[78:79], 0, v[56:57]
	v_lshl_add_u32 v65, v60, 4, v63
	global_load_dwordx4 v[52:55], v[52:53], off offset:256
	v_lshl_add_u32 v67, v62, 4, v63
	global_load_dwordx4 v[56:59], v[56:57], off offset:256
	s_add_i32 s0, 0, 0x10000
	s_movk_i32 s1, 0x408
	s_waitcnt vmcnt(14)
	ds_write_b128 v65, v[0:3]
	s_waitcnt vmcnt(13)
	ds_write_b128 v67, v[4:7]
	v_lshl_add_u64 v[0:1], v[78:79], 0, v[76:77]
	global_load_dwordx4 v[0:3], v[0:1], off offset:256
	v_lshl_add_u32 v4, v64, 4, v63
	s_mov_b32 s38, 0
	s_and_b64 vcc, exec, s[6:7]
	s_waitcnt vmcnt(13)
	ds_write_b128 v4, v[8:11]
	v_lshl_add_u32 v4, v66, 4, v63
	s_waitcnt vmcnt(12)
	ds_write_b128 v4, v[12:15]
	v_lshl_add_u32 v4, v68, 4, v63
	s_waitcnt vmcnt(11)
	ds_write_b128 v4, v[16:19]
	v_lshl_add_u32 v4, v70, 4, v63
	s_waitcnt vmcnt(10)
	ds_write_b128 v4, v[20:23]
	v_lshl_add_u32 v4, v72, 4, v63
	s_waitcnt vmcnt(9)
	ds_write_b128 v4, v[24:27]
	v_lshl_add_u32 v4, v74, 4, v63
	s_waitcnt vmcnt(8)
	ds_write_b128 v4, v[28:31]
	v_mov_b32_e32 v4, s0
	v_mad_u32_u24 v4, v61, s1, v4
	v_lshl_add_u32 v5, v60, 1, v4
	s_waitcnt vmcnt(7)
	ds_write_b16 v5, v32
	ds_write_b16_d16_hi v5, v32 offset:1032
	ds_write_b16 v5, v33 offset:2064
	ds_write_b16_d16_hi v5, v33 offset:3096
	ds_write_b16 v5, v34 offset:4128
	ds_write_b16_d16_hi v5, v34 offset:5160
	ds_write_b16 v5, v35 offset:6192
	ds_write_b16_d16_hi v5, v35 offset:7224
	v_lshl_add_u32 v5, v62, 1, v4
	s_waitcnt vmcnt(6)
; #define LAS __attribute__((address_space(3)))
; __device__ __forceinline__ void cs_issue(const Prm& P, CStream& S) {
;     if (S.tk < DB * NPAGES && !S.pend) {
;         int lane; asm volatile("v_mbcnt_lo_u32_b32 %0, -1, 0\n\tv_mbcnt_hi_u32_b32 %0, -1, %0" : "=v"(lane));
;         const int b = S.tk >> 7, p = S.tk & 127, r0 = 128 * p + 16 * S.i;
;         if (S.i == 0) { const int* pt = P.page_table + b * NPAGES + p; const int e0 = pt[0], e1 = pt[p < NPAGES - 1 ? 1 : 0];
;             S.pg0 = P.cache_c + (size_t)e0 * PAGE * 256; S.pg1 = P.cache_c + (size_t)e1 * PAGE * 256; }
;         if (r0 < PAST) {
;             const f32x4* c0 = (const f32x4*)((S.i < 8 ? S.pg0 + (size_t)(16 * S.i) * 256 : S.pg1)) + lane;
; #pragma unroll
;             for (int j = 0; j < 16; ++j) S.v[j] = __builtin_nontemporal_load(c0 + 64 * j);
;             S.pend = 1;
; __device__ __forceinline__ void cmp_fill_lds(const Prm& P, Ctx& C, int b, int kvh) {
;     ...
;     for (int it = 0; it < 8; ++it) {
;         const int idx = it * NTHR + C.tid, k = idx >> 3, c = idx & 7;
;         const u32x4 v = *(const u32x4*)(src + 128 + (size_t)k * 256 + 8 * c);
;         LAS bf16_t* d = (LAS bf16_t*)(C.lds + CK_V + (8 * c) * CK_VS) + k;
;         const unsigned w[4] = {v.x, v.y, v.z, v.w};
; #pragma unroll
;         for (int e = 0; e < 4; ++e) { d[(2 * e) * (CK_VS / 2)] = (bf16_t)(w[e] & 0xffffu); d[(2 * e + 1) * (CK_VS / 2)] = (bf16_t)(w[e] >> 16); }
;     }
	ds_write_b16 v5, v36
	ds_write_b16_d16_hi v5, v36 offset:1032
	ds_write_b16 v5, v37 offset:2064
	ds_write_b16_d16_hi v5, v37 offset:3096
	ds_write_b16 v5, v38 offset:4128
	ds_write_b16_d16_hi v5, v38 offset:5160
	ds_write_b16 v5, v39 offset:6192
	ds_write_b16_d16_hi v5, v39 offset:7224
	v_lshl_add_u32 v5, v64, 1, v4
	s_waitcnt vmcnt(5)
	ds_write_b16 v5, v40
	ds_write_b16_d16_hi v5, v40 offset:1032
	ds_write_b16 v5, v41 offset:2064
	ds_write_b16_d16_hi v5, v41 offset:3096
	ds_write_b16 v5, v42 offset:4128
	ds_write_b16_d16_hi v5, v42 offset:5160
	ds_write_b16 v5, v43 offset:6192
	ds_write_b16_d16_hi v5, v43 offset:7224
	v_lshl_add_u32 v5, v66, 1, v4
	s_waitcnt vmcnt(4)
	ds_write_b16 v5, v44
	ds_write_b16_d16_hi v5, v44 offset:1032
	ds_write_b16 v5, v45 offset:2064
	ds_write_b16_d16_hi v5, v45 offset:3096
	ds_write_b16 v5, v46 offset:4128
	ds_write_b16_d16_hi v5, v46 offset:5160
	ds_write_b16 v5, v47 offset:6192
	ds_write_b16_d16_hi v5, v47 offset:7224
	v_lshl_add_u32 v5, v68, 1, v4
	s_waitcnt vmcnt(3)
	ds_write_b16 v5, v48
	ds_write_b16_d16_hi v5, v48 offset:1032
	ds_write_b16 v5, v49 offset:2064
	ds_write_b16_d16_hi v5, v49 offset:3096
	ds_write_b16 v5, v50 offset:4128
	ds_write_b16_d16_hi v5, v50 offset:5160
	ds_write_b16 v5, v51 offset:6192
	ds_write_b16_d16_hi v5, v51 offset:7224
	v_lshl_add_u32 v5, v70, 1, v4
	s_waitcnt vmcnt(2)
	ds_write_b16 v5, v52
	ds_write_b16_d16_hi v5, v52 offset:1032
	ds_write_b16 v5, v53 offset:2064
	ds_write_b16_d16_hi v5, v53 offset:3096
	ds_write_b16 v5, v54 offset:4128
	ds_write_b16_d16_hi v5, v54 offset:5160
	ds_write_b16 v5, v55 offset:6192
	ds_write_b16_d16_hi v5, v55 offset:7224
	v_lshl_add_u32 v5, v72, 1, v4
	v_lshl_add_u32 v4, v74, 1, v4
	s_waitcnt vmcnt(1)
	ds_write_b16 v5, v56
	ds_write_b16_d16_hi v5, v56 offset:1032
	ds_write_b16 v5, v57 offset:2064
	ds_write_b16_d16_hi v5, v57 offset:3096
	ds_write_b16 v5, v58 offset:4128
	ds_write_b16_d16_hi v5, v58 offset:5160
	ds_write_b16 v5, v59 offset:6192
	ds_write_b16_d16_hi v5, v59 offset:7224
	s_waitcnt vmcnt(0)
	ds_write_b16 v4, v0
	ds_write_b16_d16_hi v4, v0 offset:1032
	ds_write_b16 v4, v1 offset:2064
	ds_write_b16_d16_hi v4, v1 offset:3096
	ds_write_b16 v4, v2 offset:4128
	ds_write_b16_d16_hi v4, v2 offset:5160
	ds_write_b16 v4, v3 offset:6192
	ds_write_b16_d16_hi v4, v3 offset:7224
	s_waitcnt lgkmcnt(0)
	s_barrier
	s_cbranch_vccnz .LBB0_1207
	v_readlane_b32 s8, v250, 12
	v_readlane_b32 s9, v250, 13
	v_readlane_b32 s10, v250, 14
	v_readlane_b32 s11, v250, 15
	v_readlane_b32 s12, v250, 16
	v_readlane_b32 s13, v250, 17
	s_and_b32 s0, s62, 0xffffff80
	v_readlane_b32 s14, v250, 18
	v_readlane_b32 s15, v250, 19
	v_readlane_b32 s16, v250, 20
	v_readlane_b32 s17, v250, 21
	v_readlane_b32 s18, v250, 22
	v_readlane_b32 s19, v250, 23
	v_readlane_b32 s20, v250, 24
	v_readlane_b32 s21, v250, 25
	s_mov_b64 s[8:9], s[12:13]
	s_ashr_i32 s1, s0, 31
	v_readlane_b32 s22, v250, 26
	v_readlane_b32 s23, v250, 27
	s_mov_b64 s[10:11], s[14:15]
	s_mov_b64 s[12:13], s[16:17]
	s_mov_b64 s[16:17], s[20:21]
	s_and_b32 s2, s62, 0x7f
	s_lshl_b64 s[0:1], s[0:1], 2
	s_mov_b64 s[18:19], s[22:23]
	s_add_u32 s0, s18, s0
	s_addc_u32 s1, s19, s1
	s_lshl_b32 s3, s2, 2
	v_mov_b32_e32 v1, s3
	v_mbcnt_lo_u32_b32 v0, -1, 0
	v_mbcnt_hi_u32_b32 v0, -1, v0
	global_load_dword v2, v1, s[0:1]
	s_add_u32 s0, s0, s3
	s_addc_u32 s1, s1, 0
	s_cmpk_lg_i32 s2, 0x7f
	s_cselect_b64 s[2:3], -1, 0
	v_cndmask_b32_e64 v3, 0, 1, s[2:3]
	v_lshlrev_b32_e32 v3, 2, v3
	global_load_dword v4, v3, s[0:1]
	v_ashrrev_i32_e32 v1, 31, v0
	s_movk_i32 s5, 0x1000
	s_movk_i32 s6, 0x2000
	s_mov_b32 s38, 1
	s_waitcnt vmcnt(1)
	v_ashrrev_i32_e32 v3, 31, v2
	v_lshlrev_b64 v[2:3], 17, v[2:3]
	v_lshl_add_u64 v[188:189], s[8:9], 0, v[2:3]
	v_lshl_add_u64 v[0:1], v[0:1], 4, v[188:189]
	v_add_co_u32_e32 v2, vcc, s5, v0
	global_load_dwordx4 v[64:67], v[0:1], off nt
	global_load_dwordx4 v[68:71], v[0:1], off offset:1024 nt
	global_load_dwordx4 v[72:75], v[0:1], off offset:2048 nt
	global_load_dwordx4 v[76:79], v[0:1], off offset:3072 nt
	v_addc_co_u32_e32 v3, vcc, 0, v1, vcc
	v_add_co_u32_e32 v6, vcc, s6, v0
	global_load_dwordx4 v[80:83], v[2:3], off offset:1024 nt
	global_load_dwordx4 v[84:87], v[2:3], off offset:2048 nt
	v_addc_co_u32_e32 v7, vcc, 0, v1, vcc
	v_add_co_u32_e32 v0, vcc, 0x3000, v0
	global_load_dwordx4 v[96:99], v[6:7], off nt
	global_load_dwordx4 v[100:103], v[6:7], off offset:1024 nt
	global_load_dwordx4 v[104:107], v[6:7], off offset:2048 nt
	global_load_dwordx4 v[108:111], v[6:7], off offset:3072 nt
	v_addc_co_u32_e32 v1, vcc, 0, v1, vcc
	global_load_dwordx4 v[92:95], v[2:3], off offset:3072 nt
	global_load_dwordx4 v[112:115], v[0:1], off nt
	global_load_dwordx4 v[116:119], v[0:1], off offset:1024 nt
	global_load_dwordx4 v[120:123], v[0:1], off offset:2048 nt
	global_load_dwordx4 v[88:91], v[6:7], off offset:-4096 nt
	global_load_dwordx4 v[124:127], v[0:1], off offset:3072 nt
	s_waitcnt vmcnt(16)
	v_ashrrev_i32_e32 v5, 31, v4
	v_lshlrev_b64 v[0:1], 17, v[4:5]
	v_lshl_add_u64 v[190:191], s[8:9], 0, v[0:1]
	s_branch .LBB0_1208

; __device__ __forceinline__ float ex2(float x) { return __builtin_amdgcn_exp2f(x); }
; __device__ __forceinline__ int crow(int r, int hi) { return (r & 3) + 8 * (r >> 2) + 4 * hi; }
; #define MFMA32(a, b, c) __builtin_amdgcn_mfma_f32_32x32x16_bf16((a), (b), (c), 0, 0, 0)
; __device__ __forceinline__ float quad_sum(float v) { v += __int_as_float(dpp_x1(__float_as_int(v))); v += __int_as_float(dpp_x2(__float_as_int(v))); return v; }
; __device__ __forceinline__ void cmp_task_lds(const Prm& P, Ctx& C, int b, int kvh, int tg, CStream& CS, const LAS bf16_t* wlb, const int NGW, bf16x8 (&qnx)[4], int& qnx_tg, const int tg_next) {
;     ...
;                     for (int r = 0; r < 16; ++r) { const bool valid = (32 * tile + crow(r, hi)) < nvq; S[r] = valid ? ex2(S[r] - ml) : 0.f; }
;                 }
; #pragma unroll
;                 for (int i = 0; i < 4; ++i) { const float v = quad_sum(S[4 * i] + S[4 * i + 1] + S[4 * i + 2]); if (g == tt) cur4[i] = v; }
;                 bf16x8 pf[2]; pf[0] = pack8(S, 0); pf[1] = pack8(S, 8);
; #pragma unroll
;                 for (int dk = 0; dk < 4; ++dk)
;                     o[dk >> 1] = MFMA32(((bf16x8){vlo[dk][0], vlo[dk][1], vlo[dk][2], vlo[dk][3], vhh[dk][0], vhh[dk][1], vhh[dk][2], vhh[dk][3]}), pf[dk & 1], o[dk >> 1]);
.LBB0_1304:
	v_mov_b32_e32 v2, v52
	v_mov_b32_e32 v3, v48
	v_mov_b32_e32 v4, v53
	v_mov_b32_e32 v5, v49
	v_pk_add_f32 v[2:3], v[2:3], v[4:5]
	v_mov_b32_e32 v4, v54
	v_mov_b32_e32 v5, v50
	v_pk_add_f32 v[2:3], v[4:5], v[2:3]
	s_nop 1
	v_mov_b32_dpp v5, v3 quad_perm:[1,0,3,2] row_mask:0xf bank_mask:0xf bound_ctrl:1
	s_nop 0
	v_mov_b32_dpp v4, v2 quad_perm:[1,0,3,2] row_mask:0xf bank_mask:0xf bound_ctrl:1
	v_pk_add_f32 v[2:3], v[2:3], v[4:5]
	s_nop 0
	s_nop 0
	v_mov_b32_dpp v5, v3 quad_perm:[2,3,0,1] row_mask:0xf bank_mask:0xf bound_ctrl:1
	v_mov_b32_dpp v4, v2 quad_perm:[2,3,0,1] row_mask:0xf bank_mask:0xf bound_ctrl:1
	v_pk_add_f32 v[2:3], v[2:3], v[4:5]
	v_cndmask_b32_e64 v204, v204, v2, s[6:7]
	v_cvt_pk_bf16_f32 v2, v48, v49
	v_cndmask_b32_e64 v205, v205, v3, s[6:7]
	v_cvt_pk_bf16_f32 v3, v50, v51
	v_cvt_pk_bf16_f32 v4, v52, v53
	v_cvt_pk_bf16_f32 v5, v54, v55
	v_cvt_pk_bf16_f32 v48, v56, v57
	s_waitcnt lgkmcnt(6)
	v_mfma_f32_32x32x16_bf16 v[32:47], v[184:187], v[2:5], v[32:47]
	v_cvt_pk_bf16_f32 v49, v58, v59
	v_cvt_pk_bf16_f32 v50, v60, v61
	s_waitcnt lgkmcnt(2)
	v_mfma_f32_32x32x16_bf16 v[16:31], v[10:13], v[2:5], v[16:31]
	v_bfe_u32 v1, v62, 16, 1
	v_add3_u32 v1, v62, v1, s70
	v_bfe_u32 v51, v63, 16, 1
	v_lshrrev_b32_e32 v1, 16, v1
	v_add3_u32 v51, v63, v51, s70
	v_and_or_b32 v51, v51, s69, v1
	v_mov_b32_e32 v208, v60
	v_mov_b32_e32 v209, v56
	v_mfma_f32_32x32x16_bf16 v[32:47], v[180:183], v[48:51], v[32:47]
	v_mov_b32_e32 v52, v61
	v_mov_b32_e32 v53, v57
	v_add_f32_e64 v52, v208, v52
	v_add_f32_e64 v53, v209, v53
	v_mov_b32_e32 v54, v62
	v_mov_b32_e32 v55, v58
	v_pk_add_f32 v[52:53], v[54:55], v[52:53]
	s_waitcnt lgkmcnt(0)
	v_mfma_f32_32x32x16_bf16 v[16:31], v[6:9], v[48:51], v[16:31]
	v_mov_b32_dpp v55, v53 quad_perm:[1,0,3,2] row_mask:0xf bank_mask:0xf bound_ctrl:1
	v_mov_b32_dpp v54, v52 quad_perm:[1,0,3,2] row_mask:0xf bank_mask:0xf bound_ctrl:1
	v_add_f32_e64 v2, v52, v54
	v_add_f32_e64 v3, v53, v55
	s_nop 1
	v_mov_b32_dpp v5, v3 quad_perm:[2,3,0,1] row_mask:0xf bank_mask:0xf bound_ctrl:1
	v_mov_b32_dpp v4, v2 quad_perm:[2,3,0,1] row_mask:0xf bank_mask:0xf bound_ctrl:1
	v_pk_add_f32 v[2:3], v[2:3], v[4:5]
	s_nop 0
	v_cndmask_b32_e64 v207, v207, v3, s[6:7]
	v_cndmask_b32_e64 v206, v206, v2, s[6:7]

; __device__ __forceinline__ unsigned xb_ld(unsigned* p)              { return __hip_atomic_load(p, __ATOMIC_RELAXED, __HIP_MEMORY_SCOPE_AGENT); }
; __device__ __forceinline__ void xcd_barrier_complete(unsigned* bar, unsigned x, unsigned& nloc, unsigned& nx) {
;     const unsigned G = gridDim.x * gridDim.y * gridDim.z;
;     unsigned sum, cnt, mine, sp = 0u;
;     for (;;) {
;         sum = 0u; cnt = 0u; mine = 0u;
; #pragma unroll
;         for (unsigned j = 0; j < 16; ++j) { const unsigned c = xb_ld(&bar[XB_XCNT(j)]); sum += c; cnt += (c > 0u) ? 1u : 0u; mine = (j == x) ? c : mine; }
; __device__ __forceinline__ void xcd_barrier(const XcdBarrier& b, const bool thread0) {
;     asm volatile("s_waitcnt vmcnt(0)" ::: "memory");
;     __syncthreads();
;     if (thread0) {
;         unsigned* bar = b.bar;
;         __builtin_amdgcn_s_waitcnt(0);
;         unsigned nloc = b.st[0], nx = b.st[1];
;         if (nloc == 0u) { xcd_barrier_complete(bar, b.x, nloc, nx); b.st[0] = nloc; b.st[1] = nx; }
.LBB0_1429:
	s_setprio 0
	v_readlane_b32 s0, v250, 49
	v_readlane_b32 s7, v250, 56
	v_readlane_b32 s1, v250, 50
	s_cmp_gt_i32 s7, 3
	v_readlane_b32 s2, v250, 51
	v_readlane_b32 s3, v250, 52
	s_cselect_b64 s[0:1], -1, 0
	s_and_b64 s[2:3], s[68:69], s[0:1]
	s_andn2_b64 vcc, exec, s[2:3]
	v_readlane_b32 s4, v250, 53
	v_readlane_b32 s5, v250, 54
	v_readlane_b32 s6, v250, 55
	s_cbranch_vccnz .LBB0_1479
	v_mbcnt_lo_u32_b32 v0, -1, 0
	v_mbcnt_hi_u32_b32 v0, -1, v0
	v_readlane_b32 s2, v250, 9
	s_waitcnt vmcnt(0)
	s_andn2_b32 s2, s2, 63
	v_sub_u32_e32 v0, 0, v0
	v_cmp_eq_u32_e32 vcc, s2, v0
	s_waitcnt vmcnt(0) lgkmcnt(0)
	s_barrier
	s_and_saveexec_b64 s[2:3], vcc
	s_cbranch_execz .LBB0_1478
	v_readlane_b32 s4, v250, 31
	s_waitcnt vmcnt(0) expcnt(0) lgkmcnt(0)
	s_nop 0
	v_mov_b32_e32 v0, s4
	ds_read_b32 v2, v0
	ds_read_b32 v0, v0 offset:4
	s_waitcnt lgkmcnt(1)
	v_cmp_ne_u32_e32 vcc, 0, v2
	s_cbranch_vccnz .LBB0_1446
	v_readlane_b32 s4, v250, 10
	v_readlane_b32 s5, v250, 11
	v_readlane_b32 s36, v250, 49
	s_load_dwordx2 s[8:9], s[4:5], 0x4
	v_readlane_b32 s40, v250, 53
	v_readlane_b32 s41, v250, 54
	s_add_u32 s4, s40, 0x4200
	s_addc_u32 s5, s41, 0
	s_add_u32 s6, s40, 0x4400
	s_addc_u32 s7, s41, 0
	v_readlane_b32 s10, v250, 8
	s_waitcnt lgkmcnt(0)
	s_mul_i32 s33, s8, s10
	s_add_u32 s8, s40, 0x4500
	s_mul_i32 s33, s33, s9
	s_addc_u32 s9, s41, 0
	s_add_u32 s10, s40, 0x4600
	s_addc_u32 s11, s41, 0
	s_add_u32 s12, s40, 0x4700
	s_addc_u32 s13, s41, 0
	s_add_u32 s14, s40, 0x4800
	s_addc_u32 s15, s41, 0
	s_add_u32 s16, s40, 0x4900
	s_addc_u32 s17, s41, 0
	s_add_u32 s18, s40, 0x4a00
	s_addc_u32 s19, s41, 0
	s_add_u32 s20, s40, 0x4b00
	s_addc_u32 s21, s41, 0
	s_add_u32 s22, s40, 0x4c00
	s_addc_u32 s23, s41, 0
	s_add_u32 s24, s40, 0x4d00
	s_addc_u32 s25, s41, 0
	s_add_u32 s26, s40, 0x4e00
	s_addc_u32 s27, s41, 0
	s_add_u32 s28, s40, 0x4f00
	s_addc_u32 s29, s41, 0
	s_add_u32 s30, s40, 0x5000
	s_addc_u32 s31, s41, 0
	s_add_u32 s34, s40, 0x5100
	s_addc_u32 s35, s41, 0
	v_readlane_b32 s37, v250, 50
	s_add_u32 s36, s40, 0x5200
	v_readlane_b32 s38, v250, 51
	s_addc_u32 s37, s41, 0
	v_readlane_b32 s39, v250, 52
	s_add_u32 s38, s40, 0x5300
	s_addc_u32 s39, s41, 0
	s_mov_b32 s46, 1
	v_mov_b32_e32 v16, 0
	v_readlane_b32 s42, v250, 55
	v_readlane_b32 s43, v250, 56
	s_branch .LBB0_1434

; #define LAS __attribute__((address_space(3)))
; __device__ __forceinline__ unsigned f2bf(float f) { unsigned u = __builtin_bit_cast(unsigned, f); return (u + 0x7fffu + ((u >> 16) & 1u)) >> 16; }
; __device__ __forceinline__ unsigned pk2(float lo, float hi) { return f2bf(lo) | (f2bf(hi) << 16); }
; __device__ __forceinline__ int crow(int r, int hi) { return (r & 3) + 8 * (r >> 2) + 4 * hi; }
; template <int MODE, int THRL>
; __device__ __forceinline__ void attn_unit(const Prm& P, int b, int h, int qb, LAS char* shm, int wid) {
;     ...
;   float rli[16];
; #pragma unroll
;   for (int r = 0; r < 16; ++r) rli[r] = wsf[32 + crow(r, hi)];
;   { LAS bf16_t* stg = (LAS bf16_t*)(shm + (MODE == 0 ? LDS_OS2 : LDS_OST)) + wid * 2048;
; #pragma unroll
;     for (int r = 0; r < 16; ++r) { const int orow = crow(r, hi);
; #pragma unroll
;       for (int d0 = 0; d0 < 2; ++d0) stg[orow * 64 + d0 * 32 + r32] = (bf16_t)f2bf(o[d0][r] * rli[r]); }
;     asm volatile("s_waitcnt lgkmcnt(0)" ::: "memory");
;     if (MODE == 1) {
;       const LAS bf16_t* stg2 = (const LAS bf16_t*)(shm + LDS_OS2) + wid * 2048;
;       bf16_t* hp = (bf16_t*)(P.ws + WS_H2) + row0 * 1024 + 512 + h * 64;
; #pragma unroll
;       for (int i = 0; i < 4; ++i) { const int row = i * 8 + (lane_e >> 3), ch = lane_e & 7;
;         const u32x4 a = *(const LAS u32x4*)(stg + row * 64 + ch * 8), s2 = *(const LAS u32x4*)(stg2 + row * 64 + ch * 8);
;         const u32x4 oc = ocv[i], bg = bgv[i];
;         u32x4 w;
;         w.x = pk2((bflo(a.x) + bflo(s2.x) + bflo(oc.x)) * bflo(bg.x), (bfhi(a.x) + bfhi(s2.x) + bfhi(oc.x)) * bfhi(bg.x));
;         w.y = pk2((bflo(a.y) + bflo(s2.y) + bflo(oc.y)) * bflo(bg.y), (bfhi(a.y) + bfhi(s2.y) + bfhi(oc.y)) * bfhi(bg.y));
.LBB0_1481:
	s_or_b64 exec, exec, s[0:1]
	s_waitcnt lgkmcnt(0)
	ds_read_b128 v[74:77], v80 offset:49280
	ds_read_b128 v[82:85], v80 offset:49312
	ds_read_b128 v[86:89], v80 offset:49344
	ds_read_b128 v[78:81], v80 offset:49376
	v_lshlrev_b32_e32 v90, 1, v204
	v_lshlrev_b32_e32 v91, 9, v206
	v_readlane_b32 s2, v251, 47
	s_waitcnt lgkmcnt(3)
	v_mul_f32_e32 v32, v32, v74
	s_movk_i32 s3, 0x7fff
	v_add3_u32 v90, s2, v90, v91
	v_bfe_u32 v91, v32, 16, 1
	v_add3_u32 v32, v32, v91, s3
	v_mul_f32_e32 v16, v16, v74
	ds_write_b16_d16_hi v90, v32 offset:55296
	v_bfe_u32 v32, v16, 16, 1
	v_add3_u32 v16, v16, v32, s3
	ds_write_b16_d16_hi v90, v16 offset:55360
	v_mul_f32_e32 v16, v33, v75
	v_bfe_u32 v32, v16, 16, 1
	v_add3_u32 v16, v16, v32, s3
	ds_write_b16_d16_hi v90, v16 offset:55424
	v_mul_f32_e32 v16, v17, v75
	v_bfe_u32 v17, v16, 16, 1
	v_add3_u32 v16, v16, v17, s3
	ds_write_b16_d16_hi v90, v16 offset:55488
	v_mul_f32_e32 v16, v34, v76
	v_bfe_u32 v17, v16, 16, 1
	v_add3_u32 v16, v16, v17, s3
	ds_write_b16_d16_hi v90, v16 offset:55552
	v_mul_f32_e32 v16, v18, v76
	v_bfe_u32 v17, v16, 16, 1
	v_add3_u32 v16, v16, v17, s3
	ds_write_b16_d16_hi v90, v16 offset:55616
	v_mul_f32_e32 v16, v35, v77
	v_bfe_u32 v17, v16, 16, 1
	v_add3_u32 v16, v16, v17, s3
	ds_write_b16_d16_hi v90, v16 offset:55680
	v_mul_f32_e32 v16, v19, v77
	v_bfe_u32 v17, v16, 16, 1
	v_add3_u32 v16, v16, v17, s3
	ds_write_b16_d16_hi v90, v16 offset:55744
	s_waitcnt lgkmcnt(10)
	v_mul_f32_e32 v16, v36, v82
	v_bfe_u32 v17, v16, 16, 1
	v_add3_u32 v16, v16, v17, s3
	ds_write_b16_d16_hi v90, v16 offset:56320
	v_mul_f32_e32 v16, v20, v82
	v_bfe_u32 v17, v16, 16, 1
	v_add3_u32 v16, v16, v17, s3
	ds_write_b16_d16_hi v90, v16 offset:56384
	v_mul_f32_e32 v16, v37, v83
	v_bfe_u32 v17, v16, 16, 1
	v_add3_u32 v16, v16, v17, s3
	ds_write_b16_d16_hi v90, v16 offset:56448
	v_mul_f32_e32 v16, v21, v83
	v_bfe_u32 v17, v16, 16, 1
	v_add3_u32 v16, v16, v17, s3
	ds_write_b16_d16_hi v90, v16 offset:56512
	v_mul_f32_e32 v16, v38, v84
	v_bfe_u32 v17, v16, 16, 1
	v_add3_u32 v16, v16, v17, s3
	ds_write_b16_d16_hi v90, v16 offset:56576
	v_mul_f32_e32 v16, v22, v84
	v_bfe_u32 v17, v16, 16, 1
	v_add3_u32 v16, v16, v17, s3
	ds_write_b16_d16_hi v90, v16 offset:56640
	v_mul_f32_e32 v16, v39, v85
	v_bfe_u32 v17, v16, 16, 1
	v_add3_u32 v16, v16, v17, s3
	ds_write_b16_d16_hi v90, v16 offset:56704
	v_mul_f32_e32 v16, v23, v85
	v_bfe_u32 v17, v16, 16, 1
	v_add3_u32 v16, v16, v17, s3
	ds_write_b16_d16_hi v90, v16 offset:56768
	s_waitcnt lgkmcnt(14)
	v_mul_f32_e32 v16, v40, v86
	v_bfe_u32 v17, v16, 16, 1
	v_add3_u32 v16, v16, v17, s3
	ds_write_b16_d16_hi v90, v16 offset:57344
	v_mul_f32_e32 v16, v24, v86
	v_bfe_u32 v17, v16, 16, 1
	v_add3_u32 v16, v16, v17, s3
	ds_write_b16_d16_hi v90, v16 offset:57408
	v_mul_f32_e32 v16, v41, v87
	v_bfe_u32 v17, v16, 16, 1
	v_add3_u32 v16, v16, v17, s3
	ds_write_b16_d16_hi v90, v16 offset:57472
	v_mul_f32_e32 v16, v25, v87
	v_bfe_u32 v17, v16, 16, 1
	v_add3_u32 v16, v16, v17, s3
	ds_write_b16_d16_hi v90, v16 offset:57536
	v_mul_f32_e32 v16, v42, v88
	v_bfe_u32 v17, v16, 16, 1
	v_add3_u32 v16, v16, v17, s3
	ds_write_b16_d16_hi v90, v16 offset:57600
	v_mul_f32_e32 v16, v26, v88
	v_bfe_u32 v17, v16, 16, 1
	v_add3_u32 v16, v16, v17, s3
	ds_write_b16_d16_hi v90, v16 offset:57664
	v_mul_f32_e32 v16, v43, v89
	v_bfe_u32 v17, v16, 16, 1
	v_add3_u32 v16, v16, v17, s3
	ds_write_b16_d16_hi v90, v16 offset:57728
	v_mul_f32_e32 v16, v27, v89
	v_bfe_u32 v17, v16, 16, 1
	v_add3_u32 v16, v16, v17, s3
	ds_write_b16_d16_hi v90, v16 offset:57792
	v_mul_f32_e32 v16, v44, v78
	v_bfe_u32 v17, v16, 16, 1
	v_add3_u32 v16, v16, v17, s3
	ds_write_b16_d16_hi v90, v16 offset:58368
	v_mul_f32_e32 v16, v28, v78
	v_bfe_u32 v17, v16, 16, 1
	v_add3_u32 v16, v16, v17, s3
	ds_write_b16_d16_hi v90, v16 offset:58432
	v_mul_f32_e32 v16, v45, v79
	v_bfe_u32 v17, v16, 16, 1
	v_add3_u32 v16, v16, v17, s3
	ds_write_b16_d16_hi v90, v16 offset:58496
	v_mul_f32_e32 v16, v29, v79
	v_bfe_u32 v17, v16, 16, 1
	v_add3_u32 v16, v16, v17, s3
	ds_write_b16_d16_hi v90, v16 offset:58560
	v_mul_f32_e32 v16, v46, v80
	v_bfe_u32 v17, v16, 16, 1
	v_add3_u32 v16, v16, v17, s3
	ds_write_b16_d16_hi v90, v16 offset:58624
	v_mul_f32_e32 v16, v30, v80
	v_bfe_u32 v17, v16, 16, 1
	v_add3_u32 v16, v16, v17, s3
	ds_write_b16_d16_hi v90, v16 offset:58688
	v_mul_f32_e32 v16, v47, v81
	v_bfe_u32 v17, v16, 16, 1
	v_add3_u32 v16, v16, v17, s3
	ds_write_b16_d16_hi v90, v16 offset:58752
	v_mul_f32_e32 v16, v31, v81
	v_bfe_u32 v17, v16, 16, 1
	v_add3_u32 v16, v16, v17, s3
	ds_write_b16_d16_hi v90, v16 offset:58816
	v_add_u32_e32 v32, s2, v0
	v_add_u32_e32 v33, s46, v0
	v_lshlrev_b32_e32 v16, 7, v72
	s_waitcnt lgkmcnt(0)
	v_add_u32_e32 v17, v32, v16
	v_add_u32_e32 v16, v33, v16
	ds_read_b128 v[18:21], v17 offset:55296
	ds_read_b128 v[22:25], v16
	s_lshl_b64 s[0:1], s[4:5], 11
	v_readlane_b32 s4, v250, 49
	v_readlane_b32 s8, v250, 53
	s_waitcnt lgkmcnt(1)
	v_lshlrev_b32_e32 v27, 16, v19
	v_lshlrev_b32_e32 v26, 16, v18
	s_waitcnt lgkmcnt(0)
	v_lshlrev_b32_e32 v29, 16, v23
	v_lshlrev_b32_e32 v28, 16, v22
	v_and_b32_e32 v19, 0xffff0000, v19
	v_and_b32_e32 v18, 0xffff0000, v18
	v_and_b32_e32 v23, 0xffff0000, v23
	v_and_b32_e32 v22, 0xffff0000, v22
	v_pk_add_f32 v[26:27], v[26:27], v[28:29]
	s_waitcnt vmcnt(7)
	v_lshlrev_b32_e32 v29, 16, v61
	v_lshlrev_b32_e32 v28, 16, v60
	v_pk_add_f32 v[18:19], v[18:19], v[22:23]
	v_and_b32_e32 v23, 0xffff0000, v61
	v_and_b32_e32 v22, 0xffff0000, v60
	v_pk_add_f32 v[26:27], v[26:27], v[28:29]
	s_waitcnt vmcnt(6)
; #define LAS __attribute__((address_space(3)))
; __device__ __forceinline__ unsigned pk2(float lo, float hi) { return f2bf(lo) | (f2bf(hi) << 16); }
; template <int MODE, int THRL>
; __device__ __forceinline__ void attn_unit(const Prm& P, int b, int h, int qb, LAS char* shm, int wid) {
;     ...
;     if (MODE == 1) {
;       const LAS bf16_t* stg2 = (const LAS bf16_t*)(shm + LDS_OS2) + wid * 2048;
;       bf16_t* hp = (bf16_t*)(P.ws + WS_H2) + row0 * 1024 + 512 + h * 64;
; #pragma unroll
;       for (int i = 0; i < 4; ++i) { const int row = i * 8 + (lane_e >> 3), ch = lane_e & 7;
;         const u32x4 a = *(const LAS u32x4*)(stg + row * 64 + ch * 8), s2 = *(const LAS u32x4*)(stg2 + row * 64 + ch * 8);
;         const u32x4 oc = ocv[i], bg = bgv[i];
;         u32x4 w;
;         w.x = pk2((bflo(a.x) + bflo(s2.x) + bflo(oc.x)) * bflo(bg.x), (bfhi(a.x) + bfhi(s2.x) + bfhi(oc.x)) * bfhi(bg.x));
;         w.y = pk2((bflo(a.y) + bflo(s2.y) + bflo(oc.y)) * bflo(bg.y), (bfhi(a.y) + bfhi(s2.y) + bfhi(oc.y)) * bfhi(bg.y));
;         w.z = pk2((bflo(a.z) + bflo(s2.z) + bflo(oc.z)) * bflo(bg.z), (bfhi(a.z) + bfhi(s2.z) + bfhi(oc.z)) * bfhi(bg.z));
;         w.w = pk2((bflo(a.w) + bflo(s2.w) + bflo(oc.w)) * bflo(bg.w), (bfhi(a.w) + bfhi(s2.w) + bfhi(oc.w)) * bfhi(bg.w));
;         *(u32x4*)(hp + (long)row * 1024 + ch * 8) = w; }
;     }
	v_lshlrev_b32_e32 v29, 16, v65
	v_lshlrev_b32_e32 v28, 16, v64
	v_pk_add_f32 v[18:19], v[18:19], v[22:23]
	v_and_b32_e32 v23, 0xffff0000, v65
	v_and_b32_e32 v22, 0xffff0000, v64
	v_readlane_b32 s9, v250, 54
	s_add_u32 s0, s8, s0
	v_pk_mul_f32 v[26:27], v[26:27], v[28:29]
	v_pk_mul_f32 v[18:19], v[18:19], v[22:23]
	v_lshlrev_b32_e32 v23, 16, v21
	v_lshlrev_b32_e32 v22, 16, v20
	v_lshlrev_b32_e32 v29, 16, v25
	v_lshlrev_b32_e32 v28, 16, v24
	v_and_b32_e32 v21, 0xffff0000, v21
	v_and_b32_e32 v20, 0xffff0000, v20
	v_and_b32_e32 v25, 0xffff0000, v25
	v_and_b32_e32 v24, 0xffff0000, v24
	s_addc_u32 s1, s9, s1
	v_pk_add_f32 v[20:21], v[20:21], v[24:25]
	v_and_b32_e32 v25, 0xffff0000, v63
	v_and_b32_e32 v24, 0xffff0000, v62
	s_add_u32 s0, s0, s24
	v_pk_add_f32 v[22:23], v[22:23], v[28:29]
	v_lshlrev_b32_e32 v29, 16, v63
	v_lshlrev_b32_e32 v28, 16, v62
	v_pk_add_f32 v[20:21], v[20:21], v[24:25]
	v_and_b32_e32 v25, 0xffff0000, v67
	v_and_b32_e32 v24, 0xffff0000, v66
	s_addc_u32 s1, s1, 0
	v_pk_add_f32 v[22:23], v[22:23], v[28:29]
	v_lshlrev_b32_e32 v29, 16, v67
	v_lshlrev_b32_e32 v28, 16, v66
	v_pk_mul_f32 v[20:21], v[20:21], v[24:25]
	v_lshl_add_u64 v[16:17], s[0:1], 0, v[0:1]
	v_pk_mul_f32 v[22:23], v[22:23], v[28:29]
	s_mov_b64 s[0:1], 0x13400400
	v_lshl_add_u64 v[16:17], v[16:17], 0, s[0:1]
	s_mov_b32 s0, 0xffff0000
	v_cvt_pk_bf16_f32 v21, v23, v21
	v_lshlrev_b32_e32 v0, 7, v70
	v_cvt_pk_bf16_f32 v20, v22, v20
	v_add_u32_e32 v22, v32, v0
	v_add_u32_e32 v0, v33, v0
	v_cvt_pk_bf16_f32 v19, v27, v19
	v_cvt_pk_bf16_f32 v18, v26, v18
	ds_read_b128 v[22:25], v22 offset:55296
	ds_read_b128 v[26:29], v0
	v_lshlrev_b64 v[30:31], 11, v[72:73]
	v_lshl_add_u64 v[30:31], v[16:17], 0, v[30:31]
	global_store_dwordx4 v[30:31], v[18:21], off
	v_lshlrev_b64 v[30:31], 11, v[70:71]
	v_lshl_add_u64 v[30:31], v[16:17], 0, v[30:31]
	s_waitcnt lgkmcnt(1)
	v_lshlrev_b32_e32 v19, 16, v23
	v_lshlrev_b32_e32 v18, 16, v22
	s_waitcnt lgkmcnt(0)
	v_lshlrev_b32_e32 v21, 16, v27
	v_lshlrev_b32_e32 v20, 16, v26
	v_pk_add_f32 v[18:19], v[18:19], v[20:21]
	s_waitcnt vmcnt(6)
	v_lshlrev_b32_e32 v21, 16, v53
	v_lshlrev_b32_e32 v20, 16, v52
	v_pk_add_f32 v[18:19], v[18:19], v[20:21]
	s_waitcnt vmcnt(5)
	v_lshlrev_b32_e32 v21, 16, v57
	v_lshlrev_b32_e32 v20, 16, v56
	v_pk_mul_f32 v[18:19], v[18:19], v[20:21]
	v_and_b32_e32 v21, 0xffff0000, v23
	v_and_b32_e32 v20, 0xffff0000, v22
	v_and_b32_e32 v23, 0xffff0000, v27
	v_and_b32_e32 v22, 0xffff0000, v26
	v_pk_add_f32 v[20:21], v[20:21], v[22:23]
	v_and_b32_e32 v23, 0xffff0000, v53
	v_and_b32_e32 v22, 0xffff0000, v52
	v_pk_add_f32 v[20:21], v[20:21], v[22:23]
	v_and_b32_e32 v23, 0xffff0000, v57
	v_and_b32_e32 v22, 0xffff0000, v56
	v_pk_mul_f32 v[20:21], v[20:21], v[22:23]
	v_lshlrev_b32_e32 v23, 16, v25
	v_lshlrev_b32_e32 v22, 16, v24
	v_lshlrev_b32_e32 v27, 16, v29
	v_lshlrev_b32_e32 v26, 16, v28
	v_pk_add_f32 v[22:23], v[22:23], v[26:27]
	v_lshlrev_b32_e32 v27, 16, v55
	v_lshlrev_b32_e32 v26, 16, v54
	v_pk_add_f32 v[22:23], v[22:23], v[26:27]
	v_lshlrev_b32_e32 v27, 16, v59
	v_lshlrev_b32_e32 v26, 16, v58
	v_pk_mul_f32 v[22:23], v[22:23], v[26:27]
	v_and_b32_e32 v25, 0xffff0000, v25
	v_and_b32_e32 v24, 0xffff0000, v24
	v_and_b32_e32 v27, 0xffff0000, v29
	v_and_b32_e32 v26, 0xffff0000, v28
	v_pk_add_f32 v[24:25], v[24:25], v[26:27]
	v_and_b32_e32 v27, 0xffff0000, v55
	v_and_b32_e32 v26, 0xffff0000, v54
	v_pk_add_f32 v[24:25], v[24:25], v[26:27]
	v_and_b32_e32 v27, 0xffff0000, v59
	v_and_b32_e32 v26, 0xffff0000, v58
	v_pk_mul_f32 v[24:25], v[24:25], v[26:27]
	v_bfe_u32 v28, v20, 16, 1
	v_bfe_u32 v26, v24, 16, 1
	v_bfe_u32 v0, v25, 16, 1
	v_bfe_u32 v27, v21, 16, 1
	v_add3_u32 v28, v20, v28, s3
	v_add3_u32 v20, v24, v26, s3
	v_bfe_u32 v26, v23, 16, 1
	v_add3_u32 v27, v21, v27, s3
	v_add3_u32 v0, v25, v0, s3
	v_bfe_u32 v21, v18, 16, 1
	v_bfe_u32 v25, v22, 16, 1
	v_add3_u32 v23, v23, v26, s3
	v_bfe_u32 v24, v19, 16, 1
	v_add3_u32 v22, v22, v25, s3
	v_add3_u32 v18, v18, v21, s3
	v_lshrrev_b32_e32 v21, 16, v23
	v_add3_u32 v19, v19, v24, s3
	v_lshrrev_b32_e32 v22, 16, v22
	v_and_or_b32 v21, v0, s0, v21
	v_lshlrev_b32_e32 v0, 7, v68
	v_lshrrev_b32_e32 v18, 16, v18
	v_lshrrev_b32_e32 v19, 16, v19
	v_and_or_b32 v20, v20, s0, v22
	v_add_u32_e32 v22, v32, v0
	v_add_u32_e32 v0, v33, v0
	v_and_or_b32 v19, v27, s0, v19
	v_and_or_b32 v18, v28, s0, v18
	ds_read_b128 v[22:25], v22 offset:55296
	ds_read_b128 v[26:29], v0
	global_store_dwordx4 v[30:31], v[18:21], off
	v_readlane_b32 s5, v250, 50
	v_readlane_b32 s6, v250, 51
	s_waitcnt lgkmcnt(1)
; #define LAS __attribute__((address_space(3)))
; __device__ __forceinline__ unsigned pk2(float lo, float hi) { return f2bf(lo) | (f2bf(hi) << 16); }
; template <int MODE, int THRL>
; __device__ __forceinline__ void attn_unit(const Prm& P, int b, int h, int qb, LAS char* shm, int wid) {
;     ...
;     if (MODE == 1) {
;       const LAS bf16_t* stg2 = (const LAS bf16_t*)(shm + LDS_OS2) + wid * 2048;
;       bf16_t* hp = (bf16_t*)(P.ws + WS_H2) + row0 * 1024 + 512 + h * 64;
; #pragma unroll
;       for (int i = 0; i < 4; ++i) { const int row = i * 8 + (lane_e >> 3), ch = lane_e & 7;
;         const u32x4 a = *(const LAS u32x4*)(stg + row * 64 + ch * 8), s2 = *(const LAS u32x4*)(stg2 + row * 64 + ch * 8);
;         const u32x4 oc = ocv[i], bg = bgv[i];
;         u32x4 w;
;         w.x = pk2((bflo(a.x) + bflo(s2.x) + bflo(oc.x)) * bflo(bg.x), (bfhi(a.x) + bfhi(s2.x) + bfhi(oc.x)) * bfhi(bg.x));
;         w.y = pk2((bflo(a.y) + bflo(s2.y) + bflo(oc.y)) * bflo(bg.y), (bfhi(a.y) + bfhi(s2.y) + bfhi(oc.y)) * bfhi(bg.y));
;         w.z = pk2((bflo(a.z) + bflo(s2.z) + bflo(oc.z)) * bflo(bg.z), (bfhi(a.z) + bfhi(s2.z) + bfhi(oc.z)) * bfhi(bg.z));
;         w.w = pk2((bflo(a.w) + bflo(s2.w) + bflo(oc.w)) * bflo(bg.w), (bfhi(a.w) + bfhi(s2.w) + bfhi(oc.w)) * bfhi(bg.w));
;         *(u32x4*)(hp + (long)row * 1024 + ch * 8) = w; }
;     }
;   }
;   asm volatile("s_waitcnt vmcnt(0) lgkmcnt(0)\n\ts_barrier" ::: "memory");
	v_lshlrev_b32_e32 v19, 16, v23
	v_lshlrev_b32_e32 v18, 16, v22
	s_waitcnt lgkmcnt(0)
	v_lshlrev_b32_e32 v21, 16, v27
	v_lshlrev_b32_e32 v20, 16, v26
	v_pk_add_f32 v[18:19], v[18:19], v[20:21]
	s_waitcnt vmcnt(5)
	v_lshlrev_b32_e32 v21, 16, v11
	v_lshlrev_b32_e32 v20, 16, v10
	v_pk_add_f32 v[18:19], v[18:19], v[20:21]
	s_waitcnt vmcnt(4)
	v_lshlrev_b32_e32 v21, 16, v49
	v_lshlrev_b32_e32 v20, 16, v48
	v_pk_mul_f32 v[18:19], v[18:19], v[20:21]
	v_and_b32_e32 v21, 0xffff0000, v23
	v_and_b32_e32 v20, 0xffff0000, v22
	v_and_b32_e32 v23, 0xffff0000, v27
	v_and_b32_e32 v22, 0xffff0000, v26
	v_pk_add_f32 v[20:21], v[20:21], v[22:23]
	v_and_b32_e32 v11, 0xffff0000, v11
	v_and_b32_e32 v10, 0xffff0000, v10
	v_pk_add_f32 v[10:11], v[20:21], v[10:11]
	v_and_b32_e32 v21, 0xffff0000, v49
	v_and_b32_e32 v20, 0xffff0000, v48
	v_pk_mul_f32 v[10:11], v[10:11], v[20:21]
	v_lshlrev_b32_e32 v21, 16, v25
	v_lshlrev_b32_e32 v20, 16, v24
	v_lshlrev_b32_e32 v23, 16, v29
	v_lshlrev_b32_e32 v22, 16, v28
	v_pk_add_f32 v[20:21], v[20:21], v[22:23]
	v_lshlrev_b32_e32 v23, 16, v13
	v_lshlrev_b32_e32 v22, 16, v12
	v_pk_add_f32 v[20:21], v[20:21], v[22:23]
	v_lshlrev_b32_e32 v23, 16, v51
	v_lshlrev_b32_e32 v22, 16, v50
	v_pk_mul_f32 v[20:21], v[20:21], v[22:23]
	v_and_b32_e32 v23, 0xffff0000, v25
	v_and_b32_e32 v22, 0xffff0000, v24
	v_and_b32_e32 v25, 0xffff0000, v29
	v_and_b32_e32 v24, 0xffff0000, v28
	v_pk_add_f32 v[22:23], v[22:23], v[24:25]
	v_and_b32_e32 v13, 0xffff0000, v13
	v_and_b32_e32 v12, 0xffff0000, v12
	v_pk_add_f32 v[12:13], v[22:23], v[12:13]
	v_and_b32_e32 v23, 0xffff0000, v51
	v_and_b32_e32 v22, 0xffff0000, v50
	v_pk_mul_f32 v[12:13], v[12:13], v[22:23]
	v_cvt_pk_bf16_f32 v13, v21, v13
	v_lshlrev_b32_e32 v0, 7, v14
	v_cvt_pk_bf16_f32 v10, v18, v10
	v_add_u32_e32 v18, v32, v0
	v_add_u32_e32 v0, v33, v0
	v_cvt_pk_bf16_f32 v12, v20, v12
	v_cvt_pk_bf16_f32 v11, v19, v11
	ds_read_b128 v[18:21], v18 offset:55296
	ds_read_b128 v[22:25], v0
	v_lshlrev_b64 v[26:27], 11, v[68:69]
	v_lshl_add_u64 v[26:27], v[16:17], 0, v[26:27]
	global_store_dwordx4 v[26:27], v[10:13], off
	v_readlane_b32 s7, v250, 52
	v_readlane_b32 s10, v250, 55
	s_waitcnt lgkmcnt(1)
	v_lshlrev_b32_e32 v11, 16, v19
	v_lshlrev_b32_e32 v10, 16, v18
	s_waitcnt lgkmcnt(0)
	v_lshlrev_b32_e32 v13, 16, v23
	v_lshlrev_b32_e32 v12, 16, v22
	v_pk_add_f32 v[10:11], v[10:11], v[12:13]
	s_waitcnt vmcnt(4)
	v_lshlrev_b32_e32 v13, 16, v3
	v_lshlrev_b32_e32 v12, 16, v2
	v_pk_add_f32 v[10:11], v[10:11], v[12:13]
	s_waitcnt vmcnt(3)
	v_lshlrev_b32_e32 v13, 16, v7
	v_lshlrev_b32_e32 v12, 16, v6
	v_pk_mul_f32 v[10:11], v[10:11], v[12:13]
	v_and_b32_e32 v13, 0xffff0000, v19
	v_and_b32_e32 v12, 0xffff0000, v18
	v_and_b32_e32 v19, 0xffff0000, v23
	v_and_b32_e32 v18, 0xffff0000, v22
	v_pk_add_f32 v[12:13], v[12:13], v[18:19]
	v_and_b32_e32 v3, 0xffff0000, v3
	v_and_b32_e32 v2, 0xffff0000, v2
	v_pk_add_f32 v[2:3], v[12:13], v[2:3]
	v_and_b32_e32 v7, 0xffff0000, v7
	v_and_b32_e32 v6, 0xffff0000, v6
	v_pk_mul_f32 v[2:3], v[2:3], v[6:7]
	v_lshlrev_b32_e32 v7, 16, v21
	v_lshlrev_b32_e32 v6, 16, v20
	v_lshlrev_b32_e32 v13, 16, v25
	v_lshlrev_b32_e32 v12, 16, v24
	v_pk_add_f32 v[6:7], v[6:7], v[12:13]
	v_lshlrev_b32_e32 v13, 16, v5
	v_lshlrev_b32_e32 v12, 16, v4
	v_pk_add_f32 v[6:7], v[6:7], v[12:13]
	v_lshlrev_b32_e32 v13, 16, v9
	v_lshlrev_b32_e32 v12, 16, v8
	v_pk_mul_f32 v[6:7], v[6:7], v[12:13]
	v_and_b32_e32 v13, 0xffff0000, v21
	v_and_b32_e32 v12, 0xffff0000, v20
	v_and_b32_e32 v19, 0xffff0000, v25
	v_and_b32_e32 v18, 0xffff0000, v24
	v_pk_add_f32 v[12:13], v[12:13], v[18:19]
	v_and_b32_e32 v5, 0xffff0000, v5
	v_and_b32_e32 v4, 0xffff0000, v4
	v_pk_add_f32 v[4:5], v[12:13], v[4:5]
	v_and_b32_e32 v9, 0xffff0000, v9
	v_and_b32_e32 v8, 0xffff0000, v8
	v_pk_mul_f32 v[4:5], v[4:5], v[8:9]
	v_bfe_u32 v0, v5, 16, 1
	v_add3_u32 v0, v5, v0, s3
	v_bfe_u32 v12, v7, 16, 1
	v_add3_u32 v7, v7, v12, s3
	v_lshrrev_b32_e32 v5, 16, v7
	v_cvt_pk_bf16_f32 v4, v6, v4
	v_lshlrev_b64 v[6:7], 11, v[14:15]
	v_and_or_b32 v5, v0, s0, v5
	v_cvt_pk_bf16_f32 v3, v11, v3
	v_cvt_pk_bf16_f32 v2, v10, v2
	v_lshl_add_u64 v[6:7], v[16:17], 0, v[6:7]
	global_store_dwordx4 v[6:7], v[2:5], off
	s_waitcnt lgkmcnt(0)
	s_barrier
	v_readlane_b32 s0, v251, 63
	s_add_i32 s0, s0, 1
	s_mov_b64 s[2:3], 0
	v_writelane_b32 v251, s0, 63
	v_readlane_b32 s11, v250, 56

; __device__ __forceinline__ float ex2(float x) { return __builtin_amdgcn_exp2f(x); }
; __device__ __forceinline__ float quad_sum(float v) { v += __int_as_float(dpp_x1(__float_as_int(v))); v += __int_as_float(dpp_x2(__float_as_int(v))); return v; }
; __device__ __forceinline__ void sample_task(const Prm& P, Ctx& C, int task) {
;     ...
;         float M = NEGB;
; #pragma unroll
;         for (int w = 0; w < 8; ++w) M = fmaxf(M, ml[(w * 32 + q) * 2]);
;         float L = 0.f;
; #pragma unroll
;         for (int w = 0; w < 8; ++w) L += ml[(w * 32 + q) * 2 + 1] * ex2(ml[(w * 32 + q) * 2] - M);
;         const float invl = L > 0.f ? 1.f / L : 0.f;
;         f32x16 o[2]; o[0] = f32x16{}; o[1] = f32x16{};
; #pragma unroll
;         for (int tt = 0; tt < 4; ++tt) { const int tile = C.wave + 8 * tt;
; #pragma unroll
;             for (int r = 0; r < 16; ++r) S[tt][r] = (S[tt][r] > -1e29f) ? ex2(S[tt][r] - M) * invl : 0.f;
; #pragma unroll
;             for (int i = 0; i < 4; ++i) { const float v = quad_sum(S[tt][4 * i] + S[tt][4 * i + 1] + S[tt][4 * i + 2]); if (g == 0) sc[slot * 256 + 8 * tile + 2 * i + hi] = v; }
.LBB0_1494:
	s_or_b64 exec, exec, vcc
	v_add_u32_e32 v0, 0x4000, v197
	s_waitcnt lgkmcnt(0)
	s_barrier
	ds_read2_b64 v[66:69], v0 offset1:32
	ds_read2_b64 v[70:73], v0 offset0:64 offset1:96
	ds_read2_b64 v[74:77], v0 offset0:128 offset1:160
	ds_read2_b64 v[78:81], v0 offset0:192 offset1:224
	s_mov_b32 s78, 0xf149f2ca
	s_waitcnt lgkmcnt(3)
	v_max3_f32 v0, v66, s78, v68
	s_waitcnt lgkmcnt(2)
	v_max3_f32 v0, v0, v70, v72
	s_waitcnt lgkmcnt(1)
	v_max3_f32 v0, v0, v74, v76
	s_waitcnt lgkmcnt(0)
	v_max3_f32 v0, v0, v78, v80
	v_sub_f32_e32 v66, v66, v0
	v_exp_f32_e32 v171, v66
	v_sub_f32_e32 v66, v68, v0
	v_exp_f32_e32 v170, v66
	v_sub_f32_e32 v68, v70, v0
	v_mov_b32_e32 v66, v69
	v_exp_f32_e32 v69, v68
	v_sub_f32_e32 v68, v72, v0
	v_exp_f32_e32 v68, v68
	v_pk_mul_f32 v[66:67], v[66:67], v[170:171]
	v_mov_b32_e32 v70, v73
	v_add_f32_e32 v67, 0, v67
	v_add_f32_e32 v72, v66, v67
	v_pk_mul_f32 v[66:67], v[68:69], v[70:71]
	v_sub_f32_e32 v68, v74, v0
	v_exp_f32_e32 v69, v68
	v_sub_f32_e32 v68, v76, v0
	v_exp_f32_e32 v68, v68
	v_add_f32_e32 v67, v67, v72
	v_mov_b32_e32 v74, v77
	v_add_f32_e32 v70, v66, v67
	v_pk_mul_f32 v[66:67], v[68:69], v[74:75]
	v_sub_f32_e32 v68, v78, v0
	v_exp_f32_e32 v69, v68
	v_sub_f32_e32 v68, v80, v0
	v_exp_f32_e32 v68, v68
	v_add_f32_e32 v67, v67, v70
	v_mov_b32_e32 v78, v81
	v_add_f32_e32 v70, v66, v67
	v_pk_mul_f32 v[66:67], v[68:69], v[78:79]
	v_sub_f32_e32 v50, v50, v0
	v_add_f32_e32 v67, v67, v70
	v_add_f32_e32 v66, v66, v67
	v_div_scale_f32 v67, s[82:83], v66, v66, 1.0
	v_rcp_f32_e32 v68, v67
	v_exp_f32_e32 v50, v50
	v_sub_f32_e32 v53, v53, v0
	v_exp_f32_e32 v53, v53
	v_fma_f32 v69, -v67, v68, 1.0
	v_fmac_f32_e32 v68, v69, v68
	v_div_scale_f32 v69, vcc, 1.0, v66, 1.0
	v_mul_f32_e32 v70, v69, v68
	v_fma_f32 v71, -v67, v70, v69
	v_fmac_f32_e32 v70, v71, v68
	v_fma_f32 v67, -v67, v70, v69
	v_div_fmas_f32 v67, v67, v68, v70
	v_div_fixup_f32 v67, v67, v66, 1.0
	v_cmp_lt_f32_e32 vcc, 0, v66
	v_sub_f32_e32 v66, v51, v0
	v_sub_f32_e32 v51, v52, v0
	v_exp_f32_e32 v51, v51
	v_exp_f32_e32 v52, v66
	v_cndmask_b32_e32 v170, 0, v67, vcc
	v_pk_mul_f32 v[50:51], v[50:51], v[170:171] op_sel_hi:[1,0]
	s_nop 0
	v_cndmask_b32_e64 v66, 0, v51, s[76:77]
	v_cndmask_b32_e64 v67, 0, v50, s[74:75]
	v_pk_mul_f32 v[50:51], v[52:53], v[170:171] op_sel_hi:[1,0]
	s_nop 0
	v_cndmask_b32_e64 v50, 0, v50, s[72:73]
	v_add_f32_e32 v52, v67, v50
	v_add_f32_e32 v52, v66, v52
	s_nop 1
	v_add_f32_dpp v52, v52, v52 quad_perm:[1,0,3,2] row_mask:0xf bank_mask:0xf bound_ctrl:1
	s_nop 1
	v_mov_b32_dpp v53, v52 quad_perm:[2,3,0,1] row_mask:0xf bank_mask:0xf bound_ctrl:1
	s_mov_b64 s[72:73], exec
	v_readlane_b32 s74, v251, 0
	v_readlane_b32 s75, v251, 1
	s_and_b64 s[74:75], s[72:73], s[74:75]
	s_mov_b64 exec, s[74:75]
	v_add_f32_e32 v52, v52, v53
	ds_write_b32 v179, v52
	s_or_b64 exec, exec, s[72:73]
	v_sub_f32_e32 v53, v55, v0
	v_sub_f32_e32 v52, v54, v0
	v_exp_f32_e32 v54, v53
	v_sub_f32_e32 v53, v56, v0
	v_sub_f32_e32 v55, v57, v0
	v_exp_f32_e32 v52, v52
	v_exp_f32_e32 v53, v53
	v_exp_f32_e32 v55, v55
	v_mov_b32_e32 v171, v170
	v_pk_mul_f32 v[56:57], v[52:53], v[170:171]
	v_pk_mul_f32 v[52:53], v[54:55], v[170:171]
	v_cndmask_b32_e64 v68, 0, v56, s[64:65]
	v_cndmask_b32_e64 v69, 0, v52, s[66:67]
	v_cndmask_b32_e64 v57, 0, v57, s[70:71]
	v_add_f32_e32 v52, v68, v69
	v_add_f32_e32 v52, v57, v52
	s_nop 1
	v_add_f32_dpp v52, v52, v52 quad_perm:[1,0,3,2] row_mask:0xf bank_mask:0xf bound_ctrl:1
	s_nop 1
	v_mov_b32_dpp v54, v52 quad_perm:[2,3,0,1] row_mask:0xf bank_mask:0xf bound_ctrl:1
	s_mov_b64 s[64:65], exec
	v_readlane_b32 s66, v251, 0
	v_readlane_b32 s67, v251, 1
	s_and_b64 s[66:67], s[64:65], s[66:67]
	s_mov_b64 exec, s[66:67]
	v_add_f32_e32 v52, v52, v54
	ds_write_b32 v179, v52 offset:8
	s_or_b64 exec, exec, s[64:65]
	v_sub_f32_e32 v52, v58, v0
	v_exp_f32_e32 v54, v52
	v_sub_f32_e32 v52, v59, v0
	v_exp_f32_e32 v58, v52
	v_sub_f32_e32 v52, v60, v0
	v_exp_f32_e32 v55, v52
	v_sub_f32_e32 v52, v61, v0
	v_exp_f32_e32 v59, v52
	v_pk_mul_f32 v[60:61], v[54:55], v[170:171]
	s_nop 0
	v_cndmask_b32_e64 v52, 0, v60, s[60:61]
	v_pk_mul_f32 v[54:55], v[58:59], v[170:171]
	v_cndmask_b32_e64 v56, 0, v61, s[68:69]
	v_cndmask_b32_e64 v54, 0, v54, s[62:63]
	v_add_f32_e32 v58, v52, v54
	v_add_f32_e32 v58, v56, v58
	s_nop 1
	v_add_f32_dpp v58, v58, v58 quad_perm:[1,0,3,2] row_mask:0xf bank_mask:0xf bound_ctrl:1
	s_nop 1
	v_mov_b32_dpp v59, v58 quad_perm:[2,3,0,1] row_mask:0xf bank_mask:0xf bound_ctrl:1
	s_mov_b64 s[60:61], exec
	v_readlane_b32 s62, v251, 0
	v_readlane_b32 s63, v251, 1
	s_and_b64 s[62:63], s[60:61], s[62:63]
	s_mov_b64 exec, s[62:63]
	v_add_f32_e32 v58, v58, v59
	ds_write_b32 v179, v58 offset:16
	s_or_b64 exec, exec, s[60:61]
	v_cndmask_b32_e64 v58, 0, v53, s[48:49]
	v_sub_f32_e32 v53, v62, v0
	v_exp_f32_e32 v60, v53
	v_sub_f32_e32 v53, v63, v0
	v_exp_f32_e32 v62, v53
	v_sub_f32_e32 v53, v64, v0
	v_exp_f32_e32 v61, v53
	v_sub_f32_e32 v53, v65, v0
	v_exp_f32_e32 v63, v53
	v_cndmask_b32_e64 v59, 0, v51, s[46:47]
	v_pk_mul_f32 v[60:61], v[60:61], v[170:171]
	v_cndmask_b32_e64 v51, 0, v55, s[58:59]
	v_pk_mul_f32 v[62:63], v[62:63], v[170:171]
	v_cndmask_b32_e64 v53, 0, v61, s[54:55]
	v_cndmask_b32_e64 v55, 0, v60, s[50:51]
	v_cndmask_b32_e64 v61, 0, v62, s[52:53]
	v_add_f32_e32 v62, v55, v61
	v_add_f32_e32 v62, v53, v62
	v_cndmask_b32_e64 v60, 0, v63, s[56:57]
	s_nop 0
	v_add_f32_dpp v62, v62, v62 quad_perm:[1,0,3,2] row_mask:0xf bank_mask:0xf bound_ctrl:1
	s_nop 1
	v_mov_b32_dpp v63, v62 quad_perm:[2,3,0,1] row_mask:0xf bank_mask:0xf bound_ctrl:1
	s_mov_b64 s[46:47], exec
	v_readlane_b32 s48, v251, 0
	v_readlane_b32 s49, v251, 1
	s_and_b64 s[48:49], s[46:47], s[48:49]
	s_mov_b64 exec, s[48:49]
	v_add_f32_e32 v62, v62, v63
	ds_write_b32 v179, v62 offset:24
	s_or_b64 exec, exec, s[46:47]
	v_bfe_u32 v63, v69, 16, 1
	s_movk_i32 s46, 0x7fff
	v_add3_u32 v63, v69, v63, s46
	v_bfe_u32 v62, v67, 16, 1
	v_bfe_u32 v65, v50, 16, 1
	v_add3_u32 v62, v67, v62, s46
	s_waitcnt vmcnt(15)
; #define LAS __attribute__((address_space(3)))
; __device__ __forceinline__ float ex2(float x) { return __builtin_amdgcn_exp2f(x); }
; #define LDS_WAIT() asm volatile("s_waitcnt lgkmcnt(0)" ::: "memory")
; #define MFMA32(a, b, c) __builtin_amdgcn_mfma_f32_32x32x16_bf16((a), (b), (c), 0, 0, 0)
; __device__ __forceinline__ float quad_sum(float v) { v += __int_as_float(dpp_x1(__float_as_int(v))); v += __int_as_float(dpp_x2(__float_as_int(v))); return v; }
; __device__ __forceinline__ void sample_task(const Prm& P, Ctx& C, int task) {
;     ...
;         for (int tt = 0; tt < 4; ++tt) { const int tile = C.wave + 8 * tt;
; #pragma unroll
;             for (int r = 0; r < 16; ++r) S[tt][r] = (S[tt][r] > -1e29f) ? ex2(S[tt][r] - M) * invl : 0.f;
; #pragma unroll
;             for (int i = 0; i < 4; ++i) { const float v = quad_sum(S[tt][4 * i] + S[tt][4 * i + 1] + S[tt][4 * i + 2]); if (g == 0) sc[slot * 256 + 8 * tile + 2 * i + hi] = v; }
;             {
;                 const int key = lane >> 1, d0 = 32 * (lane & 1);
; #pragma unroll
;                 for (int c = 0; c < 4; ++c) { const unsigned w[4] = {vld[tt][c].x, vld[tt][c].y, vld[tt][c].z, vld[tt][c].w};
; #pragma unroll
;                     for (int e = 0; e < 4; ++e) { vts[(d0 + 8 * c + 2 * e) * 36 + key] = (bf16_t)(w[e] & 0xffffu); vts[(d0 + 8 * c + 2 * e + 1) * 36 + key] = (bf16_t)(w[e] >> 16); } }
;             }
;             LDS_WAIT();
;             bf16x8 pf[2]; pf[0] = pack8(S[tt], 0); pf[1] = pack8(S[tt], 8);
; #pragma unroll
;             for (int dblk = 0; dblk < 2; ++dblk)
; #pragma unroll
;                 for (int ks = 0; ks < 2; ++ks) { const LAS bf16_t* vp = vts + (32 * dblk + q) * 36 + 16 * ks + 4 * hi;
;                     const s16x4 lo = *(const LAS s16x4*)vp, hh = *(const LAS s16x4*)(vp + 8);
;                     o[dblk] = MFMA32(((bf16x8){lo[0], lo[1], lo[2], lo[3], hh[0], hh[1], hh[2], hh[3]}), pf[ks], o[dblk]); }
;             LDS_WAIT();
	ds_write_b16 v181, v142 offset:18432
	ds_write_b16_d16_hi v181, v142 offset:18504
	ds_write_b16 v181, v143 offset:18576
	ds_write_b16_d16_hi v181, v143 offset:18648
	ds_write_b16 v181, v144 offset:18720
	ds_write_b16_d16_hi v181, v144 offset:18792
	ds_write_b16 v181, v145 offset:18864
	ds_write_b16_d16_hi v181, v145 offset:18936
	s_waitcnt vmcnt(14)
	ds_write_b16 v181, v138 offset:19008
	ds_write_b16_d16_hi v181, v138 offset:19080
	ds_write_b16 v181, v139 offset:19152
	ds_write_b16_d16_hi v181, v139 offset:19224
	ds_write_b16 v181, v140 offset:19296
	ds_write_b16_d16_hi v181, v140 offset:19368
	ds_write_b16 v181, v141 offset:19440
	ds_write_b16_d16_hi v181, v141 offset:19512
	s_waitcnt vmcnt(13)
	ds_write_b16 v181, v134 offset:19584
	ds_write_b16_d16_hi v181, v134 offset:19656
	ds_write_b16 v181, v135 offset:19728
	ds_write_b16_d16_hi v181, v135 offset:19800
	ds_write_b16 v181, v136 offset:19872
	ds_write_b16_d16_hi v181, v136 offset:19944
	ds_write_b16 v181, v137 offset:20016
	ds_write_b16_d16_hi v181, v137 offset:20088
	s_waitcnt vmcnt(12)
	ds_write_b16 v181, v130 offset:20160
	ds_write_b16_d16_hi v181, v130 offset:20232
	ds_write_b16 v181, v131 offset:20304
	ds_write_b16_d16_hi v181, v131 offset:20376
	ds_write_b16 v181, v132 offset:20448
	ds_write_b16_d16_hi v181, v132 offset:20520
	ds_write_b16 v181, v133 offset:20592
	ds_write_b16_d16_hi v181, v133 offset:20664
	v_add3_u32 v50, v50, v65, s46
	v_lshrrev_b32_e32 v62, 16, v62
	s_mov_b32 s47, 0xffff0000
	s_waitcnt lgkmcnt(0)
	v_cvt_pk_bf16_f32 v69, v57, v58
	v_cvt_pk_bf16_f32 v67, v66, v59
	v_and_or_b32 v66, v50, s47, v62
	v_bfe_u32 v50, v60, 16, 1
	v_bfe_u32 v57, v61, 16, 1
	v_bfe_u32 v58, v51, 16, 1
	v_bfe_u32 v59, v54, 16, 1
	v_add_u32_e32 v130, 0x4800, v201
	v_add3_u32 v74, v54, v59, s46
	v_add3_u32 v75, v51, v58, s46
	v_add3_u32 v76, v61, v57, s46
	v_add3_u32 v77, v60, v50, s46
	ds_read2_b64 v[58:61], v130 offset1:2
	v_bfe_u32 v65, v68, 16, 1
	v_add3_u32 v65, v68, v65, s46
	v_lshrrev_b32_e32 v65, 16, v65
	v_bfe_u32 v50, v52, 16, 1
	v_and_or_b32 v68, v63, s47, v65
	v_bfe_u32 v51, v56, 16, 1
	v_bfe_u32 v54, v55, 16, 1
	v_bfe_u32 v57, v53, 16, 1
	v_add3_u32 v50, v52, v50, s46
	ds_read2_b64 v[70:73], v130 offset0:4 offset1:6
	v_add3_u32 v78, v53, v57, s46
	v_add3_u32 v79, v55, v54, s46
	v_add3_u32 v80, v56, v51, s46
	v_lshrrev_b32_e32 v81, 16, v50
	s_waitcnt lgkmcnt(1)
	v_mfma_f32_32x32x16_bf16 v[50:65], v[58:61], v[66:69], 0
	v_lshrrev_b32_e32 v80, 16, v80
	v_lshrrev_b32_e32 v79, 16, v79
	v_lshrrev_b32_e32 v78, 16, v78
	v_and_or_b32 v135, v77, s47, v78
	v_and_or_b32 v134, v76, s47, v79
	v_and_or_b32 v133, v75, s47, v80
	v_and_or_b32 v132, v74, s47, v81
	v_add_u32_e32 v131, 0x5000, v201
	ds_read2_b64 v[136:139], v131 offset0:36 offset1:38
	s_waitcnt lgkmcnt(1)
	v_mfma_f32_32x32x16_bf16 v[50:65], v[70:73], v[132:135], v[50:65]
	ds_read2_b64 v[70:73], v131 offset0:32 offset1:34
	v_sub_f32_e32 v2, v2, v0
	v_exp_f32_e32 v2, v2
	v_sub_f32_e32 v5, v5, v0
	v_exp_f32_e32 v5, v5
	s_waitcnt lgkmcnt(0)
	s_waitcnt lgkmcnt(0)
	v_mfma_f32_32x32x16_bf16 v[66:81], v[70:73], v[66:69], 0
	v_mfma_f32_32x32x16_bf16 v[66:81], v[136:139], v[132:135], v[66:81]
	v_sub_f32_e32 v132, v3, v0
	v_sub_f32_e32 v3, v4, v0
	v_exp_f32_e32 v3, v3
	v_exp_f32_e32 v4, v132
	v_pk_mul_f32 v[2:3], v[2:3], v[170:171]
	s_nop 0
	v_cndmask_b32_e64 v132, 0, v3, s[40:41]
	v_cndmask_b32_e64 v133, 0, v2, s[38:39]
	v_pk_mul_f32 v[2:3], v[4:5], v[170:171]
	s_nop 0
	v_cndmask_b32_e64 v2, 0, v2, s[44:45]
	v_add_f32_e32 v4, v133, v2
	v_add_f32_e32 v4, v132, v4
	s_nop 1
	v_add_f32_dpp v4, v4, v4 quad_perm:[1,0,3,2] row_mask:0xf bank_mask:0xf bound_ctrl:1
	s_nop 1
	v_mov_b32_dpp v5, v4 quad_perm:[2,3,0,1] row_mask:0xf bank_mask:0xf bound_ctrl:1
	s_mov_b64 s[38:39], exec
	v_readlane_b32 s40, v251, 0
	v_readlane_b32 s41, v251, 1
	s_and_b64 s[40:41], s[38:39], s[40:41]
	s_mov_b64 exec, s[40:41]
	v_add_f32_e32 v4, v4, v5
	ds_write_b32 v179, v4 offset:256
	s_or_b64 exec, exec, s[38:39]
	v_sub_f32_e32 v5, v7, v0
	v_sub_f32_e32 v4, v6, v0
	v_exp_f32_e32 v6, v5
	v_sub_f32_e32 v5, v8, v0
	v_sub_f32_e32 v7, v9, v0
	v_exp_f32_e32 v4, v4
	v_exp_f32_e32 v5, v5
	v_exp_f32_e32 v7, v7
	v_pk_mul_f32 v[8:9], v[4:5], v[170:171]
	v_pk_mul_f32 v[4:5], v[6:7], v[170:171]
	v_cndmask_b32_e64 v135, 0, v8, s[30:31]
	v_cndmask_b32_e64 v136, 0, v4, s[34:35]
	v_cndmask_b32_e64 v134, 0, v9, s[42:43]
	v_add_f32_e32 v4, v135, v136
	v_add_f32_e32 v4, v134, v4
	s_nop 1
	v_add_f32_dpp v4, v4, v4 quad_perm:[1,0,3,2] row_mask:0xf bank_mask:0xf bound_ctrl:1
	s_nop 1
	v_mov_b32_dpp v6, v4 quad_perm:[2,3,0,1] row_mask:0xf bank_mask:0xf bound_ctrl:1
	s_mov_b64 s[30:31], exec
	v_readlane_b32 s34, v251, 0
	v_readlane_b32 s35, v251, 1
	s_and_b64 s[34:35], s[30:31], s[34:35]
	s_mov_b64 exec, s[34:35]
	v_add_f32_e32 v4, v4, v6
	ds_write_b32 v179, v4 offset:264
	s_or_b64 exec, exec, s[30:31]
	v_sub_f32_e32 v4, v10, v0
	v_exp_f32_e32 v6, v4
	v_sub_f32_e32 v4, v11, v0
	v_exp_f32_e32 v8, v4
	v_sub_f32_e32 v4, v12, v0
	v_exp_f32_e32 v7, v4
	v_sub_f32_e32 v4, v13, v0
	v_exp_f32_e32 v9, v4
	v_pk_mul_f32 v[12:13], v[6:7], v[170:171]
	s_nop 0
	v_cndmask_b32_e64 v4, 0, v12, s[24:25]
	v_pk_mul_f32 v[6:7], v[8:9], v[170:171]
	v_cndmask_b32_e64 v10, 0, v13, s[36:37]
	v_cndmask_b32_e64 v6, 0, v6, s[26:27]
	v_add_f32_e32 v8, v4, v6
	v_add_f32_e32 v8, v10, v8
	s_nop 1
	v_add_f32_dpp v8, v8, v8 quad_perm:[1,0,3,2] row_mask:0xf bank_mask:0xf bound_ctrl:1
	s_nop 1
	v_mov_b32_dpp v9, v8 quad_perm:[2,3,0,1] row_mask:0xf bank_mask:0xf bound_ctrl:1
	s_mov_b64 s[24:25], exec
	v_readlane_b32 s26, v251, 0
	v_readlane_b32 s27, v251, 1
	s_and_b64 s[26:27], s[24:25], s[26:27]
	s_mov_b64 exec, s[26:27]
	v_add_f32_e32 v8, v8, v9
	ds_write_b32 v179, v8 offset:272
	s_or_b64 exec, exec, s[24:25]
	v_sub_f32_e32 v9, v15, v0
	v_sub_f32_e32 v8, v14, v0
	v_exp_f32_e32 v12, v9
	v_sub_f32_e32 v9, v16, v0
	v_sub_f32_e32 v11, v17, v0
	v_exp_f32_e32 v8, v8
	v_exp_f32_e32 v9, v9
	v_exp_f32_e32 v13, v11
	v_pk_mul_f32 v[14:15], v[8:9], v[170:171]
	v_pk_mul_f32 v[8:9], v[12:13], v[170:171]
	v_cndmask_b32_e64 v12, 0, v14, s[20:21]
	v_cndmask_b32_e64 v8, 0, v8, s[22:23]
	v_cndmask_b32_e64 v11, 0, v15, s[28:29]
	v_add_f32_e32 v13, v12, v8
	v_add_f32_e32 v13, v11, v13
	s_nop 1
	v_add_f32_dpp v13, v13, v13 quad_perm:[1,0,3,2] row_mask:0xf bank_mask:0xf bound_ctrl:1
	s_nop 1
	v_mov_b32_dpp v14, v13 quad_perm:[2,3,0,1] row_mask:0xf bank_mask:0xf bound_ctrl:1
	s_mov_b64 s[20:21], exec
	v_readlane_b32 s22, v251, 0
	v_readlane_b32 s23, v251, 1
	s_and_b64 s[22:23], s[20:21], s[22:23]
	s_mov_b64 exec, s[22:23]
	v_add_f32_e32 v13, v13, v14
	ds_write_b32 v179, v13 offset:280
	s_or_b64 exec, exec, s[20:21]
	v_cndmask_b32_e64 v3, 0, v3, s[8:9]
	v_cndmask_b32_e64 v5, 0, v5, s[10:11]
	s_movk_i32 s8, 0x7fff
	v_cndmask_b32_e64 v7, 0, v7, s[16:17]
	v_cndmask_b32_e64 v9, 0, v9, s[18:19]
	s_waitcnt vmcnt(11)
; #define LAS __attribute__((address_space(3)))
; __device__ __forceinline__ float ex2(float x) { return __builtin_amdgcn_exp2f(x); }
; #define LDS_WAIT() asm volatile("s_waitcnt lgkmcnt(0)" ::: "memory")
; #define MFMA32(a, b, c) __builtin_amdgcn_mfma_f32_32x32x16_bf16((a), (b), (c), 0, 0, 0)
; __device__ __forceinline__ float quad_sum(float v) { v += __int_as_float(dpp_x1(__float_as_int(v))); v += __int_as_float(dpp_x2(__float_as_int(v))); return v; }
; __device__ __forceinline__ void sample_task(const Prm& P, Ctx& C, int task) {
;     ...
;         for (int tt = 0; tt < 4; ++tt) { const int tile = C.wave + 8 * tt;
; #pragma unroll
;             for (int r = 0; r < 16; ++r) S[tt][r] = (S[tt][r] > -1e29f) ? ex2(S[tt][r] - M) * invl : 0.f;
; #pragma unroll
;             for (int i = 0; i < 4; ++i) { const float v = quad_sum(S[tt][4 * i] + S[tt][4 * i + 1] + S[tt][4 * i + 2]); if (g == 0) sc[slot * 256 + 8 * tile + 2 * i + hi] = v; }
;             {
;                 const int key = lane >> 1, d0 = 32 * (lane & 1);
; #pragma unroll
;                 for (int c = 0; c < 4; ++c) { const unsigned w[4] = {vld[tt][c].x, vld[tt][c].y, vld[tt][c].z, vld[tt][c].w};
; #pragma unroll
;                     for (int e = 0; e < 4; ++e) { vts[(d0 + 8 * c + 2 * e) * 36 + key] = (bf16_t)(w[e] & 0xffffu); vts[(d0 + 8 * c + 2 * e + 1) * 36 + key] = (bf16_t)(w[e] >> 16); } }
;             }
;             LDS_WAIT();
;             bf16x8 pf[2]; pf[0] = pack8(S[tt], 0); pf[1] = pack8(S[tt], 8);
; #pragma unroll
;             for (int dblk = 0; dblk < 2; ++dblk)
; #pragma unroll
;                 for (int ks = 0; ks < 2; ++ks) { const LAS bf16_t* vp = vts + (32 * dblk + q) * 36 + 16 * ks + 4 * hi;
;                     const s16x4 lo = *(const LAS s16x4*)vp, hh = *(const LAS s16x4*)(vp + 8);
;                     o[dblk] = MFMA32(((bf16x8){lo[0], lo[1], lo[2], lo[3], hh[0], hh[1], hh[2], hh[3]}), pf[ks], o[dblk]); }
;             LDS_WAIT();
	ds_write_b16 v181, v126 offset:18432
	ds_write_b16_d16_hi v181, v126 offset:18504
	ds_write_b16 v181, v127 offset:18576
	ds_write_b16_d16_hi v181, v127 offset:18648
	ds_write_b16 v181, v128 offset:18720
	ds_write_b16_d16_hi v181, v128 offset:18792
	ds_write_b16 v181, v129 offset:18864
	ds_write_b16_d16_hi v181, v129 offset:18936
	s_waitcnt vmcnt(10)
	ds_write_b16 v181, v122 offset:19008
	ds_write_b16_d16_hi v181, v122 offset:19080
	ds_write_b16 v181, v123 offset:19152
	ds_write_b16_d16_hi v181, v123 offset:19224
	ds_write_b16 v181, v124 offset:19296
	ds_write_b16_d16_hi v181, v124 offset:19368
	ds_write_b16 v181, v125 offset:19440
	ds_write_b16_d16_hi v181, v125 offset:19512
	s_waitcnt vmcnt(9)
	ds_write_b16 v181, v118 offset:19584
	ds_write_b16_d16_hi v181, v118 offset:19656
	ds_write_b16 v181, v119 offset:19728
	ds_write_b16_d16_hi v181, v119 offset:19800
	ds_write_b16 v181, v120 offset:19872
	ds_write_b16_d16_hi v181, v120 offset:19944
	ds_write_b16 v181, v121 offset:20016
	ds_write_b16_d16_hi v181, v121 offset:20088
	s_waitcnt vmcnt(8)
	ds_write_b16 v181, v114 offset:20160
	ds_write_b16_d16_hi v181, v114 offset:20232
	ds_write_b16 v181, v115 offset:20304
	ds_write_b16_d16_hi v181, v115 offset:20376
	ds_write_b16 v181, v116 offset:20448
	ds_write_b16_d16_hi v181, v116 offset:20520
	ds_write_b16 v181, v117 offset:20592
	ds_write_b16_d16_hi v181, v117 offset:20664
	s_mov_b32 s9, 0xffff0000
	s_waitcnt lgkmcnt(0)
	v_cvt_pk_bf16_f32 v17, v134, v5
	v_cvt_pk_bf16_f32 v16, v135, v136
	v_cvt_pk_bf16_f32 v15, v132, v3
	v_cvt_pk_bf16_f32 v14, v133, v2
	v_bfe_u32 v2, v9, 16, 1
	v_bfe_u32 v3, v8, 16, 1
	v_bfe_u32 v5, v7, 16, 1
	v_bfe_u32 v13, v6, 16, 1
	v_add3_u32 v13, v6, v13, s8
	v_add3_u32 v114, v7, v5, s8
	v_add3_u32 v115, v8, v3, s8
	v_add3_u32 v116, v9, v2, s8
	ds_read2_b64 v[6:9], v130 offset1:2
	v_bfe_u32 v2, v4, 16, 1
	v_bfe_u32 v3, v10, 16, 1
	v_bfe_u32 v5, v12, 16, 1
	v_bfe_u32 v117, v11, 16, 1
	v_add3_u32 v2, v4, v2, s8
	v_add3_u32 v11, v11, v117, s8
	v_add3_u32 v12, v12, v5, s8
	v_add3_u32 v10, v10, v3, s8
	v_lshrrev_b32_e32 v117, 16, v2
	ds_read2_b64 v[2:5], v130 offset0:4 offset1:6
	s_waitcnt lgkmcnt(1)
	v_mfma_f32_32x32x16_bf16 v[50:65], v[6:9], v[14:17], v[50:65]
	v_lshrrev_b32_e32 v6, 16, v10
	v_lshrrev_b32_e32 v7, 16, v12
	v_lshrrev_b32_e32 v8, 16, v11
	v_and_or_b32 v9, v116, s9, v8
	v_and_or_b32 v8, v115, s9, v7
	v_and_or_b32 v7, v114, s9, v6
	v_and_or_b32 v6, v13, s9, v117
	s_waitcnt lgkmcnt(0)
	s_nop 0
	v_mfma_f32_32x32x16_bf16 v[50:65], v[2:5], v[6:9], v[50:65]
	ds_read2_b64 v[2:5], v131 offset0:32 offset1:34
	s_waitcnt lgkmcnt(0)
	v_mfma_f32_32x32x16_bf16 v[66:81], v[2:5], v[14:17], v[66:81]
	ds_read2_b64 v[2:5], v131 offset0:36 offset1:38
	s_waitcnt lgkmcnt(0)
	s_waitcnt lgkmcnt(0)
	v_mfma_f32_32x32x16_bf16 v[66:81], v[2:5], v[6:9], v[66:81]
	v_sub_f32_e32 v2, v18, v0
	v_sub_f32_e32 v3, v20, v0
	v_exp_f32_e32 v2, v2
	v_sub_f32_e32 v4, v19, v0
	v_exp_f32_e32 v3, v3
	v_sub_f32_e32 v5, v21, v0
	v_exp_f32_e32 v4, v4
	v_exp_f32_e32 v5, v5
	v_pk_mul_f32 v[2:3], v[2:3], v[170:171]
	s_nop 0
	v_cndmask_b32_e64 v10, 0, v3, s[6:7]
	v_cndmask_b32_e64 v11, 0, v2, s[0:1]
	v_pk_mul_f32 v[2:3], v[4:5], v[170:171]
	s_nop 0
	v_cndmask_b32_e64 v2, 0, v2, s[2:3]
	v_add_f32_e32 v4, v11, v2
	v_add_f32_e32 v4, v10, v4
	s_nop 1
	v_add_f32_dpp v4, v4, v4 quad_perm:[1,0,3,2] row_mask:0xf bank_mask:0xf bound_ctrl:1
	s_nop 1
	v_mov_b32_dpp v5, v4 quad_perm:[2,3,0,1] row_mask:0xf bank_mask:0xf bound_ctrl:1
	s_mov_b64 s[0:1], exec
	v_readlane_b32 s2, v251, 0
	v_readlane_b32 s3, v251, 1
	s_and_b64 s[2:3], s[0:1], s[2:3]
	s_mov_b64 exec, s[2:3]
	v_add_f32_e32 v4, v4, v5
	ds_write_b32 v179, v4 offset:512
	s_or_b64 exec, exec, s[0:1]
	v_sub_f32_e32 v5, v23, v0
	v_sub_f32_e32 v4, v22, v0
	v_exp_f32_e32 v6, v5
	v_sub_f32_e32 v5, v24, v0
	v_sub_f32_e32 v7, v25, v0
	v_exp_f32_e32 v4, v4
	v_exp_f32_e32 v5, v5
	v_exp_f32_e32 v7, v7
	v_pk_mul_f32 v[8:9], v[4:5], v[170:171]
	v_pk_mul_f32 v[4:5], v[6:7], v[170:171]
	v_cndmask_b32_e64 v14, 0, v8, s[92:93]
	v_cndmask_b32_e64 v15, 0, v4, s[94:95]
	v_cndmask_b32_e64 v13, 0, v9, s[4:5]
	v_add_f32_e32 v4, v14, v15
	v_add_f32_e32 v4, v13, v4
	s_nop 1
	v_add_f32_dpp v4, v4, v4 quad_perm:[1,0,3,2] row_mask:0xf bank_mask:0xf bound_ctrl:1
	s_nop 1
	v_mov_b32_dpp v6, v4 quad_perm:[2,3,0,1] row_mask:0xf bank_mask:0xf bound_ctrl:1
	s_mov_b64 s[0:1], exec
	v_readlane_b32 s2, v251, 0
	v_readlane_b32 s3, v251, 1
	s_and_b64 s[2:3], s[0:1], s[2:3]
	s_mov_b64 exec, s[2:3]
	v_add_f32_e32 v4, v4, v6
	ds_write_b32 v179, v4 offset:520
	s_or_b64 exec, exec, s[0:1]
	v_sub_f32_e32 v4, v26, v0
	v_exp_f32_e32 v6, v4
	v_sub_f32_e32 v4, v27, v0
	v_exp_f32_e32 v8, v4
	v_sub_f32_e32 v4, v28, v0
	v_exp_f32_e32 v7, v4
	v_sub_f32_e32 v4, v29, v0
	v_exp_f32_e32 v9, v4
	v_pk_mul_f32 v[16:17], v[6:7], v[170:171]
	s_nop 0
	v_cndmask_b32_e64 v4, 0, v16, s[88:89]
	v_pk_mul_f32 v[6:7], v[8:9], v[170:171]
	v_cndmask_b32_e64 v12, 0, v17, s[96:97]
	v_cndmask_b32_e64 v6, 0, v6, s[90:91]
	v_add_f32_e32 v8, v4, v6
	v_add_f32_e32 v8, v12, v8
	s_nop 1
	v_add_f32_dpp v8, v8, v8 quad_perm:[1,0,3,2] row_mask:0xf bank_mask:0xf bound_ctrl:1
	s_nop 1
	v_mov_b32_dpp v9, v8 quad_perm:[2,3,0,1] row_mask:0xf bank_mask:0xf bound_ctrl:1
	s_mov_b64 s[0:1], exec
	v_readlane_b32 s2, v251, 0
	v_readlane_b32 s3, v251, 1
	s_and_b64 s[2:3], s[0:1], s[2:3]
	s_mov_b64 exec, s[2:3]
	v_add_f32_e32 v8, v8, v9
	ds_write_b32 v179, v8 offset:528
	s_or_b64 exec, exec, s[0:1]
	v_sub_f32_e32 v9, v31, v0
	v_sub_f32_e32 v8, v30, v0
	v_exp_f32_e32 v16, v9
	v_sub_f32_e32 v9, v32, v0
	v_sub_f32_e32 v17, v33, v0
	v_exp_f32_e32 v8, v8
	v_exp_f32_e32 v9, v9
	v_exp_f32_e32 v17, v17
	v_pk_mul_f32 v[18:19], v[8:9], v[170:171]
	v_pk_mul_f32 v[8:9], v[16:17], v[170:171]
	v_cndmask_b32_e64 v17, 0, v18, s[84:85]
	v_cndmask_b32_e64 v8, 0, v8, s[86:87]
	v_cndmask_b32_e64 v16, 0, v19, s[14:15]
	v_add_f32_e32 v18, v17, v8
	v_add_f32_e32 v18, v16, v18
	s_nop 1
	v_add_f32_dpp v18, v18, v18 quad_perm:[1,0,3,2] row_mask:0xf bank_mask:0xf bound_ctrl:1
	s_nop 1
	v_mov_b32_dpp v19, v18 quad_perm:[2,3,0,1] row_mask:0xf bank_mask:0xf bound_ctrl:1
	s_mov_b64 s[0:1], exec
	v_readlane_b32 s2, v251, 0
	v_readlane_b32 s3, v251, 1
	s_and_b64 s[2:3], s[0:1], s[2:3]
	s_mov_b64 exec, s[2:3]
	v_add_f32_e32 v18, v18, v19
	ds_write_b32 v179, v18 offset:536
	s_or_b64 exec, exec, s[0:1]
	v_readlane_b32 s0, v253, 30
	v_readlane_b32 s1, v253, 31
	s_nop 1
	v_cndmask_b32_e64 v3, 0, v3, s[0:1]
	v_readlane_b32 s0, v253, 32
	v_readlane_b32 s1, v253, 33
	v_cndmask_b32_e64 v9, 0, v9, s[12:13]
	s_nop 0
	v_cndmask_b32_e64 v5, 0, v5, s[0:1]
	v_readlane_b32 s0, v253, 34
	v_readlane_b32 s1, v253, 35
	s_waitcnt vmcnt(7)
; #define LAS __attribute__((address_space(3)))
; __device__ __forceinline__ float ex2(float x) { return __builtin_amdgcn_exp2f(x); }
; #define LDS_WAIT() asm volatile("s_waitcnt lgkmcnt(0)" ::: "memory")
; #define MFMA32(a, b, c) __builtin_amdgcn_mfma_f32_32x32x16_bf16((a), (b), (c), 0, 0, 0)
; __device__ __forceinline__ float quad_sum(float v) { v += __int_as_float(dpp_x1(__float_as_int(v))); v += __int_as_float(dpp_x2(__float_as_int(v))); return v; }
; __device__ __forceinline__ void sample_task(const Prm& P, Ctx& C, int task) {
;     ...
;         for (int tt = 0; tt < 4; ++tt) { const int tile = C.wave + 8 * tt;
; #pragma unroll
;             for (int r = 0; r < 16; ++r) S[tt][r] = (S[tt][r] > -1e29f) ? ex2(S[tt][r] - M) * invl : 0.f;
; #pragma unroll
;             for (int i = 0; i < 4; ++i) { const float v = quad_sum(S[tt][4 * i] + S[tt][4 * i + 1] + S[tt][4 * i + 2]); if (g == 0) sc[slot * 256 + 8 * tile + 2 * i + hi] = v; }
;             {
;                 const int key = lane >> 1, d0 = 32 * (lane & 1);
; #pragma unroll
;                 for (int c = 0; c < 4; ++c) { const unsigned w[4] = {vld[tt][c].x, vld[tt][c].y, vld[tt][c].z, vld[tt][c].w};
; #pragma unroll
;                     for (int e = 0; e < 4; ++e) { vts[(d0 + 8 * c + 2 * e) * 36 + key] = (bf16_t)(w[e] & 0xffffu); vts[(d0 + 8 * c + 2 * e + 1) * 36 + key] = (bf16_t)(w[e] >> 16); } }
;             }
;             LDS_WAIT();
;             bf16x8 pf[2]; pf[0] = pack8(S[tt], 0); pf[1] = pack8(S[tt], 8);
; #pragma unroll
;             for (int dblk = 0; dblk < 2; ++dblk)
; #pragma unroll
;                 for (int ks = 0; ks < 2; ++ks) { const LAS bf16_t* vp = vts + (32 * dblk + q) * 36 + 16 * ks + 4 * hi;
;                     const s16x4 lo = *(const LAS s16x4*)vp, hh = *(const LAS s16x4*)(vp + 8);
;                     o[dblk] = MFMA32(((bf16x8){lo[0], lo[1], lo[2], lo[3], hh[0], hh[1], hh[2], hh[3]}), pf[ks], o[dblk]); }
;             LDS_WAIT();
	ds_write_b16 v181, v110 offset:18432
	ds_write_b16_d16_hi v181, v110 offset:18504
	ds_write_b16 v181, v111 offset:18576
	ds_write_b16_d16_hi v181, v111 offset:18648
	ds_write_b16 v181, v112 offset:18720
	ds_write_b16_d16_hi v181, v112 offset:18792
	ds_write_b16 v181, v113 offset:18864
	ds_write_b16_d16_hi v181, v113 offset:18936
	s_waitcnt vmcnt(6)
	ds_write_b16 v181, v106 offset:19008
	ds_write_b16_d16_hi v181, v106 offset:19080
	ds_write_b16 v181, v107 offset:19152
	ds_write_b16_d16_hi v181, v107 offset:19224
	ds_write_b16 v181, v108 offset:19296
	ds_write_b16_d16_hi v181, v108 offset:19368
	ds_write_b16 v181, v109 offset:19440
	ds_write_b16_d16_hi v181, v109 offset:19512
	s_waitcnt vmcnt(5)
	ds_write_b16 v181, v102 offset:19584
	ds_write_b16_d16_hi v181, v102 offset:19656
	ds_write_b16 v181, v103 offset:19728
	ds_write_b16_d16_hi v181, v103 offset:19800
	ds_write_b16 v181, v104 offset:19872
	ds_write_b16_d16_hi v181, v104 offset:19944
	ds_write_b16 v181, v105 offset:20016
	ds_write_b16_d16_hi v181, v105 offset:20088
	s_waitcnt vmcnt(4)
	ds_write_b16 v181, v98 offset:20160
	ds_write_b16_d16_hi v181, v98 offset:20232
	ds_write_b16 v181, v99 offset:20304
	ds_write_b16_d16_hi v181, v99 offset:20376
	ds_write_b16 v181, v100 offset:20448
	ds_write_b16_d16_hi v181, v100 offset:20520
	ds_write_b16 v181, v101 offset:20592
	ds_write_b16_d16_hi v181, v101 offset:20664
	v_cndmask_b32_e64 v7, 0, v7, s[0:1]
	s_movk_i32 s0, 0x7fff
	s_mov_b32 s1, 0xffff0000
	s_waitcnt lgkmcnt(0)
	v_cvt_pk_bf16_f32 v21, v13, v5
	v_cvt_pk_bf16_f32 v19, v10, v3
	v_cvt_pk_bf16_f32 v18, v11, v2
	v_bfe_u32 v2, v9, 16, 1
	v_bfe_u32 v3, v8, 16, 1
	v_bfe_u32 v5, v7, 16, 1
	v_bfe_u32 v10, v6, 16, 1
	v_cvt_pk_bf16_f32 v20, v14, v15
	v_add3_u32 v10, v6, v10, s0
	v_add3_u32 v11, v7, v5, s0
	v_add3_u32 v13, v8, v3, s0
	v_add3_u32 v14, v9, v2, s0
	ds_read2_b64 v[6:9], v130 offset1:2
	v_bfe_u32 v2, v4, 16, 1
	v_bfe_u32 v3, v12, 16, 1
	v_bfe_u32 v5, v17, 16, 1
	v_bfe_u32 v15, v16, 16, 1
	v_add3_u32 v2, v4, v2, s0
	v_add3_u32 v15, v16, v15, s0
	v_add3_u32 v16, v17, v5, s0
	v_add3_u32 v12, v12, v3, s0
	v_lshrrev_b32_e32 v17, 16, v2
	ds_read2_b64 v[2:5], v130 offset0:4 offset1:6
	s_waitcnt lgkmcnt(1)
	v_mfma_f32_32x32x16_bf16 v[50:65], v[6:9], v[18:21], v[50:65]
	v_lshrrev_b32_e32 v6, 16, v12
	v_lshrrev_b32_e32 v7, 16, v16
	v_lshrrev_b32_e32 v8, 16, v15
	v_and_or_b32 v9, v14, s1, v8
	v_and_or_b32 v8, v13, s1, v7
	v_and_or_b32 v7, v11, s1, v6
	v_and_or_b32 v6, v10, s1, v17
	v_readlane_b32 s0, v253, 40
	v_readlane_b32 s1, v253, 41
	s_waitcnt lgkmcnt(0)
	v_mfma_f32_32x32x16_bf16 v[50:65], v[2:5], v[6:9], v[50:65]
	ds_read2_b64 v[2:5], v131 offset0:32 offset1:34
	s_waitcnt lgkmcnt(0)
	v_mfma_f32_32x32x16_bf16 v[66:81], v[2:5], v[18:21], v[66:81]
	ds_read2_b64 v[2:5], v131 offset0:36 offset1:38
	s_waitcnt lgkmcnt(0)
	s_waitcnt lgkmcnt(0)
	v_mfma_f32_32x32x16_bf16 v[66:81], v[2:5], v[6:9], v[66:81]
	v_sub_f32_e32 v2, v34, v0
	v_sub_f32_e32 v3, v36, v0
	v_exp_f32_e32 v2, v2
	v_exp_f32_e32 v3, v3
	v_sub_f32_e32 v4, v35, v0
	v_sub_f32_e32 v5, v37, v0
	v_exp_f32_e32 v4, v4
	v_exp_f32_e32 v5, v5
	v_pk_mul_f32 v[2:3], v[2:3], v[170:171]
	s_nop 0
	v_cndmask_b32_e64 v10, 0, v3, s[0:1]
	v_readlane_b32 s0, v253, 36
	v_readlane_b32 s1, v253, 37
	s_nop 1
	v_cndmask_b32_e64 v11, 0, v2, s[0:1]
	v_readlane_b32 s0, v253, 38
	v_pk_mul_f32 v[2:3], v[4:5], v[170:171]
	v_readlane_b32 s1, v253, 39
	s_nop 1
	v_cndmask_b32_e64 v2, 0, v2, s[0:1]
	v_add_f32_e32 v4, v11, v2
	v_add_f32_e32 v4, v10, v4
	s_nop 1
	v_add_f32_dpp v4, v4, v4 quad_perm:[1,0,3,2] row_mask:0xf bank_mask:0xf bound_ctrl:1
	s_nop 1
	v_mov_b32_dpp v5, v4 quad_perm:[2,3,0,1] row_mask:0xf bank_mask:0xf bound_ctrl:1
	s_mov_b64 s[0:1], exec
	v_readlane_b32 s2, v251, 0
	v_readlane_b32 s3, v251, 1
	s_and_b64 s[2:3], s[0:1], s[2:3]
	s_mov_b64 exec, s[2:3]
	v_add_f32_e32 v4, v4, v5
	ds_write_b32 v179, v4 offset:768
	s_or_b64 exec, exec, s[0:1]
	v_sub_f32_e32 v5, v39, v0
	v_sub_f32_e32 v4, v38, v0
	v_exp_f32_e32 v6, v5
	v_sub_f32_e32 v5, v40, v0
	v_exp_f32_e32 v4, v4
	v_exp_f32_e32 v5, v5
	v_sub_f32_e32 v7, v41, v0
	v_readlane_b32 s0, v253, 48
	v_exp_f32_e32 v7, v7
	v_pk_mul_f32 v[8:9], v[4:5], v[170:171]
	v_readlane_b32 s1, v253, 49
	v_pk_mul_f32 v[4:5], v[6:7], v[170:171]
	s_nop 0
	v_cndmask_b32_e64 v13, 0, v9, s[0:1]
	v_readlane_b32 s0, v253, 44
	v_readlane_b32 s1, v253, 45
	s_nop 1
	v_cndmask_b32_e64 v14, 0, v8, s[0:1]
	v_readlane_b32 s0, v253, 46
	v_readlane_b32 s1, v253, 47
	s_nop 1
	v_cndmask_b32_e64 v15, 0, v4, s[0:1]
	v_add_f32_e32 v4, v14, v15
	v_add_f32_e32 v4, v13, v4
	s_nop 1
	v_add_f32_dpp v4, v4, v4 quad_perm:[1,0,3,2] row_mask:0xf bank_mask:0xf bound_ctrl:1
	s_nop 1
	v_mov_b32_dpp v6, v4 quad_perm:[2,3,0,1] row_mask:0xf bank_mask:0xf bound_ctrl:1
	s_mov_b64 s[0:1], exec
	v_readlane_b32 s2, v251, 0
	v_readlane_b32 s3, v251, 1
	s_and_b64 s[2:3], s[0:1], s[2:3]
	s_mov_b64 exec, s[2:3]
	v_add_f32_e32 v4, v4, v6
	ds_write_b32 v179, v4 offset:776
	s_or_b64 exec, exec, s[0:1]
	v_sub_f32_e32 v4, v42, v0
	v_exp_f32_e32 v6, v4
	v_sub_f32_e32 v4, v43, v0
	v_exp_f32_e32 v8, v4
	v_sub_f32_e32 v4, v44, v0
	v_exp_f32_e32 v7, v4
	v_sub_f32_e32 v4, v45, v0
	v_readlane_b32 s0, v253, 56
	v_exp_f32_e32 v9, v4
	v_pk_mul_f32 v[16:17], v[6:7], v[170:171]
	v_readlane_b32 s1, v253, 57
	v_pk_mul_f32 v[6:7], v[8:9], v[170:171]
	s_nop 0
	v_cndmask_b32_e64 v4, 0, v17, s[0:1]
	v_readlane_b32 s0, v253, 52
	v_readlane_b32 s1, v253, 53
	s_nop 1
	v_cndmask_b32_e64 v12, 0, v16, s[0:1]
	v_readlane_b32 s0, v253, 54
	v_readlane_b32 s1, v253, 55
	s_nop 1
	v_cndmask_b32_e64 v6, 0, v6, s[0:1]
	v_add_f32_e32 v8, v12, v6
	v_add_f32_e32 v8, v4, v8
	s_nop 1
; #define LAS __attribute__((address_space(3)))
; __device__ __forceinline__ float ex2(float x) { return __builtin_amdgcn_exp2f(x); }
; #define LDS_WAIT() asm volatile("s_waitcnt lgkmcnt(0)" ::: "memory")
; #define MFMA32(a, b, c) __builtin_amdgcn_mfma_f32_32x32x16_bf16((a), (b), (c), 0, 0, 0)
; __device__ __forceinline__ float quad_sum(float v) { v += __int_as_float(dpp_x1(__float_as_int(v))); v += __int_as_float(dpp_x2(__float_as_int(v))); return v; }
; __device__ __forceinline__ void sample_task(const Prm& P, Ctx& C, int task) {
;     ...
;         for (int tt = 0; tt < 4; ++tt) { const int tile = C.wave + 8 * tt;
; #pragma unroll
;             for (int r = 0; r < 16; ++r) S[tt][r] = (S[tt][r] > -1e29f) ? ex2(S[tt][r] - M) * invl : 0.f;
; #pragma unroll
;             for (int i = 0; i < 4; ++i) { const float v = quad_sum(S[tt][4 * i] + S[tt][4 * i + 1] + S[tt][4 * i + 2]); if (g == 0) sc[slot * 256 + 8 * tile + 2 * i + hi] = v; }
;             {
;                 const int key = lane >> 1, d0 = 32 * (lane & 1);
; #pragma unroll
;                 for (int c = 0; c < 4; ++c) { const unsigned w[4] = {vld[tt][c].x, vld[tt][c].y, vld[tt][c].z, vld[tt][c].w};
; #pragma unroll
;                     for (int e = 0; e < 4; ++e) { vts[(d0 + 8 * c + 2 * e) * 36 + key] = (bf16_t)(w[e] & 0xffffu); vts[(d0 + 8 * c + 2 * e + 1) * 36 + key] = (bf16_t)(w[e] >> 16); } }
;             }
;             LDS_WAIT();
;             bf16x8 pf[2]; pf[0] = pack8(S[tt], 0); pf[1] = pack8(S[tt], 8);
; #pragma unroll
;             for (int dblk = 0; dblk < 2; ++dblk)
; #pragma unroll
;                 for (int ks = 0; ks < 2; ++ks) { const LAS bf16_t* vp = vts + (32 * dblk + q) * 36 + 16 * ks + 4 * hi;
;                     const s16x4 lo = *(const LAS s16x4*)vp, hh = *(const LAS s16x4*)(vp + 8);
;                     o[dblk] = MFMA32(((bf16x8){lo[0], lo[1], lo[2], lo[3], hh[0], hh[1], hh[2], hh[3]}), pf[ks], o[dblk]); }
;             LDS_WAIT();
;         }
; #pragma unroll
;         for (int dblk = 0; dblk < 2; ++dblk)
; #pragma unroll
;             for (int r = 0; r < 16; ++r) atomicAdd((float*)(oacc + (dblk * 16 + r) * 64 + lane), o[dblk][r]);
;         __syncthreads();
	v_add_f32_dpp v8, v8, v8 quad_perm:[1,0,3,2] row_mask:0xf bank_mask:0xf bound_ctrl:1
	s_nop 1
	v_mov_b32_dpp v9, v8 quad_perm:[2,3,0,1] row_mask:0xf bank_mask:0xf bound_ctrl:1
	s_mov_b64 s[0:1], exec
	v_readlane_b32 s2, v251, 0
	v_readlane_b32 s3, v251, 1
	s_and_b64 s[2:3], s[0:1], s[2:3]
	s_mov_b64 exec, s[2:3]
	v_add_f32_e32 v8, v8, v9
	ds_write_b32 v179, v8 offset:784
	s_or_b64 exec, exec, s[0:1]
	v_sub_f32_e32 v9, v47, v0
	v_sub_f32_e32 v8, v46, v0
	v_exp_f32_e32 v16, v9
	v_sub_f32_e32 v9, v48, v0
	v_exp_f32_e32 v8, v8
	v_exp_f32_e32 v9, v9
	v_sub_f32_e32 v0, v49, v0
	v_exp_f32_e32 v17, v0
	v_readlane_b32 s0, v252, 0
	v_pk_mul_f32 v[18:19], v[8:9], v[170:171]
	v_readlane_b32 s1, v252, 1
	v_pk_mul_f32 v[8:9], v[16:17], v[170:171]
	s_nop 0
	v_cndmask_b32_e64 v0, 0, v19, s[0:1]
	v_readlane_b32 s0, v253, 60
	v_readlane_b32 s1, v253, 61
	s_nop 1
	v_cndmask_b32_e64 v16, 0, v18, s[0:1]
	v_readlane_b32 s0, v253, 62
	v_readlane_b32 s1, v253, 63
	s_nop 1
	v_cndmask_b32_e64 v8, 0, v8, s[0:1]
	v_add_f32_e32 v17, v16, v8
	v_add_f32_e32 v17, v0, v17
	s_nop 1
	v_add_f32_dpp v17, v17, v17 quad_perm:[1,0,3,2] row_mask:0xf bank_mask:0xf bound_ctrl:1
	s_nop 1
	v_mov_b32_dpp v18, v17 quad_perm:[2,3,0,1] row_mask:0xf bank_mask:0xf bound_ctrl:1
	s_mov_b64 s[0:1], exec
	v_readlane_b32 s2, v251, 0
	v_readlane_b32 s3, v251, 1
	s_and_b64 s[2:3], s[0:1], s[2:3]
	s_mov_b64 exec, s[2:3]
	v_add_f32_e32 v17, v17, v18
	ds_write_b32 v179, v17 offset:792
	s_or_b64 exec, exec, s[0:1]
	v_readlane_b32 s0, v253, 42
	v_readlane_b32 s1, v253, 43
	s_nop 1
	v_cndmask_b32_e64 v3, 0, v3, s[0:1]
	v_readlane_b32 s0, v253, 50
	v_readlane_b32 s1, v253, 51
	s_waitcnt vmcnt(3)
	ds_write_b16 v181, v94 offset:18432
	ds_write_b16_d16_hi v181, v94 offset:18504
	ds_write_b16 v181, v95 offset:18576
	ds_write_b16_d16_hi v181, v95 offset:18648
	ds_write_b16 v181, v96 offset:18720
	ds_write_b16_d16_hi v181, v96 offset:18792
	ds_write_b16 v181, v97 offset:18864
	ds_write_b16_d16_hi v181, v97 offset:18936
	s_waitcnt vmcnt(2)
	ds_write_b16 v181, v90 offset:19008
	ds_write_b16_d16_hi v181, v90 offset:19080
	ds_write_b16 v181, v91 offset:19152
	ds_write_b16_d16_hi v181, v91 offset:19224
	ds_write_b16 v181, v92 offset:19296
	ds_write_b16_d16_hi v181, v92 offset:19368
	ds_write_b16 v181, v93 offset:19440
	ds_write_b16_d16_hi v181, v93 offset:19512
	s_waitcnt vmcnt(1)
	ds_write_b16 v181, v86 offset:19584
	ds_write_b16_d16_hi v181, v86 offset:19656
	ds_write_b16 v181, v87 offset:19728
	ds_write_b16_d16_hi v181, v87 offset:19800
	ds_write_b16 v181, v88 offset:19872
	ds_write_b16_d16_hi v181, v88 offset:19944
	ds_write_b16 v181, v89 offset:20016
	ds_write_b16_d16_hi v181, v89 offset:20088
	s_waitcnt vmcnt(0)
	ds_write_b16 v181, v82 offset:20160
	ds_write_b16_d16_hi v181, v82 offset:20232
	ds_write_b16 v181, v83 offset:20304
	ds_write_b16_d16_hi v181, v83 offset:20376
	ds_write_b16 v181, v84 offset:20448
	ds_write_b16_d16_hi v181, v84 offset:20520
	ds_write_b16 v181, v85 offset:20592
	ds_write_b16_d16_hi v181, v85 offset:20664
	v_cndmask_b32_e64 v5, 0, v5, s[0:1]
	v_readlane_b32 s0, v253, 58
	v_readlane_b32 s1, v253, 59
	s_waitcnt lgkmcnt(0)
	s_movk_i32 s24, 0x7fff
	v_cndmask_b32_e64 v7, 0, v7, s[0:1]
	v_readlane_b32 s0, v252, 2
	v_readlane_b32 s1, v252, 3
	s_nop 1
	v_cndmask_b32_e64 v9, 0, v9, s[0:1]
	s_movk_i32 s0, 0x7fff
	s_mov_b32 s1, 0xffff0000
	v_cvt_pk_bf16_f32 v21, v13, v5
	v_cvt_pk_bf16_f32 v19, v10, v3
	v_cvt_pk_bf16_f32 v18, v11, v2
	v_bfe_u32 v2, v9, 16, 1
	v_bfe_u32 v3, v8, 16, 1
	v_bfe_u32 v5, v7, 16, 1
	v_bfe_u32 v10, v6, 16, 1
	v_cvt_pk_bf16_f32 v20, v14, v15
	v_add3_u32 v10, v6, v10, s0
	v_add3_u32 v11, v7, v5, s0
	v_add3_u32 v13, v8, v3, s0
	v_add3_u32 v14, v9, v2, s0
	ds_read2_b64 v[6:9], v130 offset1:2
	v_bfe_u32 v2, v12, 16, 1
	v_bfe_u32 v3, v4, 16, 1
	v_bfe_u32 v5, v16, 16, 1
	v_bfe_u32 v15, v0, 16, 1
	v_add3_u32 v2, v12, v2, s0
	v_add3_u32 v0, v0, v15, s0
	v_add3_u32 v15, v16, v5, s0
	v_add3_u32 v16, v4, v3, s0
	v_lshrrev_b32_e32 v12, 16, v2
	ds_read2_b64 v[2:5], v130 offset0:4 offset1:6
	s_waitcnt lgkmcnt(1)
	v_mfma_f32_32x32x16_bf16 v[50:65], v[6:9], v[18:21], v[50:65]
	v_lshrrev_b32_e32 v6, 16, v16
	v_lshrrev_b32_e32 v7, 16, v15
	v_lshrrev_b32_e32 v0, 16, v0
	v_and_or_b32 v9, v14, s1, v0
	v_and_or_b32 v8, v13, s1, v7
	v_and_or_b32 v7, v11, s1, v6
	v_and_or_b32 v6, v10, s1, v12
	v_readlane_b32 s0, v250, 62
	v_readlane_b32 s1, v250, 63
	s_waitcnt lgkmcnt(0)
	v_mfma_f32_32x32x16_bf16 v[50:65], v[2:5], v[6:9], v[50:65]
	ds_read2_b64 v[2:5], v131 offset0:32 offset1:34
	s_andn2_b64 vcc, exec, s[0:1]
	s_waitcnt lgkmcnt(0)
	v_mfma_f32_32x32x16_bf16 v[66:81], v[2:5], v[18:21], v[66:81]
	ds_read2_b64 v[2:5], v131 offset0:36 offset1:38
	s_waitcnt lgkmcnt(0)
	s_waitcnt lgkmcnt(0)
	v_mfma_f32_32x32x16_bf16 v[66:81], v[2:5], v[6:9], v[66:81]
	s_nop 4
	ds_add_f32 v183, v50 offset:8192
	ds_add_f32 v183, v51 offset:8448
	ds_add_f32 v183, v52 offset:8704
	ds_add_f32 v183, v53 offset:8960
	ds_add_f32 v183, v54 offset:9216
	ds_add_f32 v183, v55 offset:9472
	ds_add_f32 v183, v56 offset:9728
	ds_add_f32 v183, v57 offset:9984
	ds_add_f32 v183, v58 offset:10240
	ds_add_f32 v183, v59 offset:10496
	ds_add_f32 v183, v60 offset:10752
	ds_add_f32 v183, v61 offset:11008
	ds_add_f32 v183, v62 offset:11264
	ds_add_f32 v183, v63 offset:11520
	ds_add_f32 v183, v64 offset:11776
	ds_add_f32 v183, v65 offset:12032
	ds_add_f32 v183, v66 offset:12288
	ds_add_f32 v183, v67 offset:12544
	ds_add_f32 v183, v68 offset:12800
	ds_add_f32 v183, v69 offset:13056
	ds_add_f32 v183, v70 offset:13312
	ds_add_f32 v183, v71 offset:13568
	ds_add_f32 v183, v72 offset:13824
	ds_add_f32 v183, v73 offset:14080
	ds_add_f32 v183, v74 offset:14336
	ds_add_f32 v183, v75 offset:14592
	ds_add_f32 v183, v76 offset:14848
	ds_add_f32 v183, v77 offset:15104
	ds_add_f32 v183, v78 offset:15360
	ds_add_f32 v183, v79 offset:15616
	ds_add_f32 v183, v80 offset:15872
	ds_add_f32 v183, v81 offset:16128
	s_waitcnt lgkmcnt(0)
	s_barrier
; __device__ __forceinline__ int crow(int r, int hi) { return (r & 3) + 8 * (r >> 2) + 4 * hi; }
; __device__ __forceinline__ void sample_task(const Prm& P, Ctx& C, int task) {
;     ...
;         if (C.wave == 0) {
;             if (slot == ts) { const float gate = ((const float*)(P.ws + WS_G))[row * 24 + head * 3 + 0];
; #pragma unroll
;                 for (int dblk = 0; dblk < 2; ++dblk)
; #pragma unroll
;                     for (int r = 0; r < 16; ++r) ocs[g * 64 + 32 * dblk + crow(r, hi)] = oacc[(dblk * 16 + r) * 64 + lane] * gate; }
	s_cbranch_vccnz .LBB0_1555
	v_readlane_b32 s0, v251, 2
	s_nop 1
	v_cmp_eq_u32_e32 vcc, s0, v173
	s_and_saveexec_b64 s[0:1], vcc
	s_cbranch_execz .LBB0_1529
	s_mul_i32 s2, s81, 0x60
	s_mul_hi_u32 s3, s80, 0x60
	s_add_i32 s3, s3, s2
	s_mul_i32 s2, s80, 0x60
	v_readlane_b32 s4, v251, 21
	v_mul_u32_u24_e32 v0, 3, v172
	s_add_u32 s2, s4, s2
	v_readlane_b32 s4, v251, 22
	s_addc_u32 s3, s4, s3
	v_lshlrev_b32_e32 v0, 2, v0
	global_load_dword v0, v0, s[2:3]
	ds_read_b32 v2, v183 offset:8192
	ds_read_b32 v3, v183 offset:8448
	ds_read_b32 v4, v183 offset:8704
	ds_read_b32 v5, v183 offset:8960
	ds_read_b32 v6, v183 offset:9216
	ds_read_b32 v7, v183 offset:9472
	ds_read_b32 v8, v183 offset:9728
	ds_read_b32 v9, v183 offset:9984
	s_waitcnt vmcnt(0)
	s_waitcnt lgkmcnt(7)
	v_mul_f32_e32 v2, v0, v2
	s_waitcnt lgkmcnt(6)
	v_mul_f32_e32 v3, v0, v3
	s_waitcnt lgkmcnt(5)
	v_mul_f32_e32 v4, v0, v4
	s_waitcnt lgkmcnt(4)
	v_mul_f32_e32 v5, v0, v5
	s_waitcnt lgkmcnt(3)
	v_mul_f32_e32 v6, v0, v6
	s_waitcnt lgkmcnt(2)
	v_mul_f32_e32 v7, v0, v7
	s_waitcnt lgkmcnt(1)
	v_mul_f32_e32 v8, v0, v8
	s_waitcnt lgkmcnt(0)
	v_mul_f32_e32 v9, v0, v9
	ds_write_b32 v199, v2
	ds_write_b32 v199, v3 offset:4
	ds_write_b32 v199, v4 offset:8
	ds_write_b32 v199, v5 offset:12
	ds_write_b32 v199, v6 offset:32
	ds_write_b32 v199, v7 offset:36
	ds_write_b32 v199, v8 offset:40
	ds_write_b32 v199, v9 offset:44
	ds_read_b32 v2, v183 offset:10240
	ds_read_b32 v3, v183 offset:10496
	ds_read_b32 v4, v183 offset:10752
	ds_read_b32 v5, v183 offset:11008
	ds_read_b32 v6, v183 offset:11264
	ds_read_b32 v7, v183 offset:11520
	ds_read_b32 v8, v183 offset:11776
	ds_read_b32 v9, v183 offset:12032
	s_waitcnt lgkmcnt(7)
	v_mul_f32_e32 v2, v0, v2
	s_waitcnt lgkmcnt(6)
	v_mul_f32_e32 v3, v0, v3
	s_waitcnt lgkmcnt(5)
	v_mul_f32_e32 v4, v0, v4
	s_waitcnt lgkmcnt(4)
	v_mul_f32_e32 v5, v0, v5
	s_waitcnt lgkmcnt(3)
	v_mul_f32_e32 v6, v0, v6
	s_waitcnt lgkmcnt(2)
	v_mul_f32_e32 v7, v0, v7
	s_waitcnt lgkmcnt(1)
	v_mul_f32_e32 v8, v0, v8
	s_waitcnt lgkmcnt(0)
	v_mul_f32_e32 v9, v0, v9
	ds_write_b32 v199, v2 offset:64
	ds_write_b32 v199, v3 offset:68
	ds_write_b32 v199, v4 offset:72
	ds_write_b32 v199, v5 offset:76
	ds_write_b32 v199, v6 offset:96
	ds_write_b32 v199, v7 offset:100
	ds_write_b32 v199, v8 offset:104
	ds_write_b32 v199, v9 offset:108
	ds_read_b32 v2, v183 offset:12288
	ds_read_b32 v3, v183 offset:12544
	ds_read_b32 v4, v183 offset:12800
	ds_read_b32 v5, v183 offset:13056
	ds_read_b32 v6, v183 offset:13312
	ds_read_b32 v7, v183 offset:13568
	ds_read_b32 v8, v183 offset:13824
	ds_read_b32 v9, v183 offset:14080
	s_waitcnt lgkmcnt(7)
	v_mul_f32_e32 v2, v0, v2
	s_waitcnt lgkmcnt(6)
	v_mul_f32_e32 v3, v0, v3
	s_waitcnt lgkmcnt(5)
	v_mul_f32_e32 v4, v0, v4
	s_waitcnt lgkmcnt(4)
	v_mul_f32_e32 v5, v0, v5
	s_waitcnt lgkmcnt(3)
	v_mul_f32_e32 v6, v0, v6
	s_waitcnt lgkmcnt(2)
	v_mul_f32_e32 v7, v0, v7
	s_waitcnt lgkmcnt(1)
	v_mul_f32_e32 v8, v0, v8
	s_waitcnt lgkmcnt(0)
	v_mul_f32_e32 v9, v0, v9
	ds_write_b32 v199, v2 offset:128
	ds_write_b32 v199, v3 offset:132
	ds_write_b32 v199, v4 offset:136
	ds_write_b32 v199, v5 offset:140
	ds_write_b32 v199, v6 offset:160
	ds_write_b32 v199, v7 offset:164
	ds_write_b32 v199, v8 offset:168
	ds_write_b32 v199, v9 offset:172
	ds_read_b32 v2, v183 offset:14336
	ds_read_b32 v3, v183 offset:14592
	ds_read_b32 v4, v183 offset:14848
	ds_read_b32 v5, v183 offset:15104
	ds_read_b32 v6, v183 offset:15360
	ds_read_b32 v7, v183 offset:15616
	ds_read_b32 v8, v183 offset:15872
	ds_read_b32 v9, v183 offset:16128
	s_waitcnt lgkmcnt(7)
	v_mul_f32_e32 v2, v0, v2
	s_waitcnt lgkmcnt(6)
	v_mul_f32_e32 v3, v0, v3
	s_waitcnt lgkmcnt(5)
	v_mul_f32_e32 v4, v0, v4
	s_waitcnt lgkmcnt(4)
	v_mul_f32_e32 v5, v0, v5
	s_waitcnt lgkmcnt(3)
	v_mul_f32_e32 v6, v0, v6
	s_waitcnt lgkmcnt(2)
	v_mul_f32_e32 v7, v0, v7
	s_waitcnt lgkmcnt(1)
	v_mul_f32_e32 v8, v0, v8
	s_waitcnt lgkmcnt(0)
	v_mul_f32_e32 v9, v0, v9
	ds_write_b32 v199, v2 offset:192
	ds_write_b32 v199, v3 offset:196
	ds_write_b32 v199, v4 offset:200
	ds_write_b32 v199, v5 offset:204
	ds_write_b32 v199, v6 offset:224
	ds_write_b32 v199, v7 offset:228
	ds_write_b32 v199, v8 offset:232
	ds_write_b32 v199, v9 offset:236

; __device__ __forceinline__ unsigned pk2(float lo, float hi) { return f2bf(lo) | (f2bf(hi) << 16); }
; #define EPI_LOOP_ROWS(body) _Pragma("unroll") for (int ai = 0; ai < 2; ++ai) _Pragma("unroll") for (int m = 0; m < 4; ++m) { const int row = u.pm * 256 + ai * 128 + wr * 64 + m * 16 + fr; body }
; __device__ __forceinline__ void st8bf(bf16_t* p, f32x4 a, f32x4 b) { u32x4 w; w.x = pk2(a[0], a[1]); w.y = pk2(a[2], a[3]); w.z = pk2(b[0], b[1]); w.w = pk2(b[2], b[3]); st16(p, w); }
;     __device__ __forceinline__ void operator()(const f32x4 (&acc)[2][2][4][2], const pg8::Unit& u, int wr, int wc, int fr, int fq) const {
;         const int cw = wc * 32 + 8 * fq;
;         EPI_LOOP_ROWS( _Pragma("unroll") for (int bj = 0; bj < 2; ++bj) st8bf(W3P + (size_t)row * 1024 + u.pn * 256 + bj * 128 + cw, acc[ai][bj][m][0], acc[ai][bj][m][1]); )
.LBB0_1777:
	v_lshl_add_u32 v128, s0, 8, v128
	v_or_b32_e32 v134, s13, v129
	v_ashrrev_i32_e32 v129, 31, v128
	v_lshlrev_b64 v[130:131], 11, v[128:129]
	s_movk_i32 s4, 0x7fff
	s_mov_b32 s5, 0xffff0000
	v_cvt_pk_bf16_f32 v124, v124, v125
	v_cvt_pk_bf16_f32 v125, v126, v127
	v_cvt_pk_bf16_f32 v126, v120, v121
	v_bfe_u32 v120, v122, 16, 1
	v_add3_u32 v120, v122, v120, s4
	v_bfe_u32 v121, v123, 16, 1
	v_lshrrev_b32_e32 v120, 16, v120
	v_add3_u32 v121, v123, v121, s4
	v_and_or_b32 v127, v121, s5, v120
	v_cvt_pk_bf16_f32 v116, v116, v117
	v_cvt_pk_bf16_f32 v117, v118, v119
	v_cvt_pk_bf16_f32 v118, v112, v113
	v_bfe_u32 v112, v114, 16, 1
	v_add3_u32 v112, v114, v112, s4
	v_cvt_pk_bf16_f32 v108, v108, v109
	v_cvt_pk_bf16_f32 v109, v110, v111
	v_cvt_pk_bf16_f32 v110, v104, v105
	v_bfe_u32 v104, v106, 16, 1
	v_add3_u32 v104, v106, v104, s4
	v_bfe_u32 v105, v107, 16, 1
	v_lshrrev_b32_e32 v104, 16, v104
	v_add3_u32 v105, v107, v105, s4
	v_and_or_b32 v111, v105, s5, v104
	v_cvt_pk_bf16_f32 v100, v100, v101
	v_cvt_pk_bf16_f32 v101, v102, v103
	v_cvt_pk_bf16_f32 v102, v96, v97
	v_bfe_u32 v96, v98, 16, 1
	v_add3_u32 v96, v98, v96, s4
	v_cvt_pk_bf16_f32 v92, v92, v93
	v_cvt_pk_bf16_f32 v93, v94, v95
	v_cvt_pk_bf16_f32 v94, v88, v89
	v_bfe_u32 v88, v90, 16, 1
	v_add3_u32 v88, v90, v88, s4
	v_bfe_u32 v89, v91, 16, 1
	v_lshrrev_b32_e32 v88, 16, v88
	v_add3_u32 v89, v91, v89, s4
	v_and_or_b32 v95, v89, s5, v88
	v_cvt_pk_bf16_f32 v84, v84, v85
	v_cvt_pk_bf16_f32 v85, v86, v87
	v_cvt_pk_bf16_f32 v86, v80, v81
	v_bfe_u32 v80, v82, 16, 1
	v_add3_u32 v80, v82, v80, s4
	v_cvt_pk_bf16_f32 v76, v76, v77
	v_cvt_pk_bf16_f32 v77, v78, v79
	v_cvt_pk_bf16_f32 v78, v72, v73
	v_bfe_u32 v72, v74, 16, 1
	v_add3_u32 v72, v74, v72, s4
	v_bfe_u32 v73, v75, 16, 1
	v_lshrrev_b32_e32 v72, 16, v72
	v_add3_u32 v73, v75, v73, s4
	v_and_or_b32 v79, v73, s5, v72
	v_cvt_pk_bf16_f32 v68, v68, v69
	v_cvt_pk_bf16_f32 v69, v70, v71
	v_bfe_u32 v81, v83, 16, 1
	v_cvt_pk_bf16_f32 v70, v60, v61
	v_readlane_b32 s24, v250, 49
	v_lshrrev_b32_e32 v80, 16, v80
	v_add3_u32 v81, v83, v81, s4
	v_readlane_b32 s28, v250, 53
	v_and_or_b32 v87, v81, s5, v80
	v_or_b32_e32 v80, 48, v128
	v_readlane_b32 s29, v250, 54
	s_add_u32 s2, s28, 0x2b00000
	v_ashrrev_i32_e32 v81, 31, v80
	v_cvt_pk_bf16_f32 v71, v62, v63
	v_add_u32_e32 v60, 0x80, v128
	s_addc_u32 s3, s29, 0
	v_lshlrev_b64 v[80:81], 11, v[80:81]
	v_ashrrev_i32_e32 v61, 31, v60
	v_lshl_add_u64 v[130:131], s[2:3], 0, v[130:131]
	s_lshl_b32 s0, s12, 9
	v_lshl_add_u64 v[80:81], s[2:3], 0, v[80:81]
	v_lshlrev_b64 v[60:61], 11, v[60:61]
	v_lshl_add_u64 v[132:133], v[130:131], 0, s[0:1]
	v_lshlrev_b32_e32 v130, 1, v134
	v_mov_b32_e32 v131, 0
	v_lshl_add_u64 v[80:81], v[80:81], 0, s[0:1]
	v_lshl_add_u64 v[60:61], s[2:3], 0, v[60:61]
	v_lshl_add_u64 v[80:81], v[80:81], 0, v[130:131]
	v_lshl_add_u64 v[60:61], v[60:61], 0, s[0:1]
	global_store_dwordx4 v[80:81], v[68:71], off offset:256
	s_nop 1
	v_lshl_add_u64 v[68:69], v[60:61], 0, v[130:131]
	v_cvt_pk_bf16_f32 v60, v64, v65
	v_cvt_pk_bf16_f32 v61, v66, v67
	v_cvt_pk_bf16_f32 v62, v56, v57
	v_bfe_u32 v56, v58, 16, 1
	v_add3_u32 v56, v58, v56, s4
	v_bfe_u32 v57, v59, 16, 1
	v_lshrrev_b32_e32 v56, 16, v56
	v_add3_u32 v57, v59, v57, s4
	v_and_or_b32 v63, v57, s5, v56
	v_cvt_pk_bf16_f32 v52, v52, v53
	v_cvt_pk_bf16_f32 v53, v54, v55
	v_cvt_pk_bf16_f32 v54, v48, v49
	v_bfe_u32 v48, v50, 16, 1
	v_add3_u32 v48, v50, v48, s4
	v_cvt_pk_bf16_f32 v44, v44, v45
	v_cvt_pk_bf16_f32 v45, v46, v47
	v_cvt_pk_bf16_f32 v46, v40, v41
	v_bfe_u32 v40, v42, 16, 1
	v_add3_u32 v40, v42, v40, s4
	v_bfe_u32 v41, v43, 16, 1
	v_lshrrev_b32_e32 v40, 16, v40
	v_add3_u32 v41, v43, v41, s4
	v_and_or_b32 v47, v41, s5, v40
; __device__ __forceinline__ unsigned pk2(float lo, float hi) { return f2bf(lo) | (f2bf(hi) << 16); }
; #define EPI_LOOP_ROWS(body) _Pragma("unroll") for (int ai = 0; ai < 2; ++ai) _Pragma("unroll") for (int m = 0; m < 4; ++m) { const int row = u.pm * 256 + ai * 128 + wr * 64 + m * 16 + fr; body }
; __device__ __forceinline__ void st8bf(bf16_t* p, f32x4 a, f32x4 b) { u32x4 w; w.x = pk2(a[0], a[1]); w.y = pk2(a[2], a[3]); w.z = pk2(b[0], b[1]); w.w = pk2(b[2], b[3]); st16(p, w); }
;     __device__ __forceinline__ void operator()(const f32x4 (&acc)[2][2][4][2], const pg8::Unit& u, int wr, int wc, int fr, int fq) const {
;         const int cw = wc * 32 + 8 * fq;
;         EPI_LOOP_ROWS( _Pragma("unroll") for (int bj = 0; bj < 2; ++bj) st8bf(W3P + (size_t)row * 1024 + u.pn * 256 + bj * 128 + cw, acc[ai][bj][m][0], acc[ai][bj][m][1]); )
	v_cvt_pk_bf16_f32 v36, v36, v37
	v_cvt_pk_bf16_f32 v37, v38, v39
	v_cvt_pk_bf16_f32 v38, v32, v33
	v_bfe_u32 v32, v34, 16, 1
	v_add3_u32 v32, v34, v32, s4
	v_cvt_pk_bf16_f32 v28, v28, v29
	v_cvt_pk_bf16_f32 v29, v30, v31
	v_cvt_pk_bf16_f32 v30, v24, v25
	v_bfe_u32 v24, v26, 16, 1
	v_add3_u32 v24, v26, v24, s4
	v_bfe_u32 v25, v27, 16, 1
	v_lshrrev_b32_e32 v24, 16, v24
	v_add3_u32 v25, v27, v25, s4
	v_and_or_b32 v31, v25, s5, v24
	v_cvt_pk_bf16_f32 v20, v20, v21
	v_cvt_pk_bf16_f32 v21, v22, v23
	v_cvt_pk_bf16_f32 v22, v16, v17
	v_bfe_u32 v16, v18, 16, 1
	v_add3_u32 v16, v18, v16, s4
	v_cvt_pk_bf16_f32 v12, v12, v13
	v_cvt_pk_bf16_f32 v13, v14, v15
	v_cvt_pk_bf16_f32 v14, v8, v9
	v_cvt_pk_bf16_f32 v15, v10, v11
	v_cvt_pk_bf16_f32 v4, v4, v5
	v_bfe_u32 v113, v115, 16, 1
	v_bfe_u32 v97, v99, 16, 1
	v_bfe_u32 v49, v51, 16, 1
	v_bfe_u32 v33, v35, 16, 1
	v_bfe_u32 v17, v19, 16, 1
	v_lshrrev_b32_e32 v112, 16, v112
	v_add3_u32 v113, v115, v113, s4
	v_lshrrev_b32_e32 v96, 16, v96
	v_add3_u32 v97, v99, v97, s4
	v_lshrrev_b32_e32 v48, 16, v48
	v_add3_u32 v49, v51, v49, s4
	v_lshrrev_b32_e32 v32, 16, v32
	v_add3_u32 v33, v35, v33, s4
	v_lshrrev_b32_e32 v16, 16, v16
	v_add3_u32 v17, v19, v17, s4
	v_cvt_pk_bf16_f32 v5, v6, v7
	v_and_or_b32 v119, v113, s5, v112
	v_or_b32_e32 v112, 16, v128
	v_and_or_b32 v103, v97, s5, v96
	v_or_b32_e32 v96, 32, v128
	v_and_or_b32 v55, v49, s5, v48
	v_add_u32_e32 v48, 0x90, v128
	v_and_or_b32 v39, v33, s5, v32
	v_add_u32_e32 v32, 0xa0, v128
	v_and_or_b32 v23, v17, s5, v16
	v_add_u32_e32 v16, 0xb0, v128
	v_ashrrev_i32_e32 v113, 31, v112
	v_ashrrev_i32_e32 v97, 31, v96
	v_ashrrev_i32_e32 v49, 31, v48
	v_ashrrev_i32_e32 v33, 31, v32
	v_ashrrev_i32_e32 v17, 31, v16
	v_lshlrev_b64 v[112:113], 11, v[112:113]
	v_lshlrev_b64 v[96:97], 11, v[96:97]
	v_lshlrev_b64 v[48:49], 11, v[48:49]
	v_lshlrev_b64 v[32:33], 11, v[32:33]
	v_lshlrev_b64 v[16:17], 11, v[16:17]
	v_cvt_pk_bf16_f32 v6, v0, v1
	v_lshl_add_u64 v[112:113], s[2:3], 0, v[112:113]
	v_lshl_add_u64 v[96:97], s[2:3], 0, v[96:97]
	v_lshl_add_u64 v[48:49], s[2:3], 0, v[48:49]
	v_lshl_add_u64 v[32:33], s[2:3], 0, v[32:33]
	v_lshl_add_u64 v[16:17], s[2:3], 0, v[16:17]
	v_lshl_add_u64 v[112:113], v[112:113], 0, s[0:1]
	v_lshl_add_u64 v[96:97], v[96:97], 0, s[0:1]
	v_lshl_add_u64 v[48:49], v[48:49], 0, s[0:1]
	v_lshl_add_u64 v[32:33], v[32:33], 0, s[0:1]
	v_lshl_add_u64 v[16:17], v[16:17], 0, s[0:1]
	v_lshl_add_u64 v[132:133], v[132:133], 0, v[130:131]
	v_lshl_add_u64 v[112:113], v[112:113], 0, v[130:131]
	v_lshl_add_u64 v[96:97], v[96:97], 0, v[130:131]
	v_lshl_add_u64 v[48:49], v[48:49], 0, v[130:131]
	v_lshl_add_u64 v[32:33], v[32:33], 0, v[130:131]
	v_lshl_add_u64 v[16:17], v[16:17], 0, v[130:131]
	v_cvt_pk_bf16_f32 v7, v2, v3
	global_store_dwordx4 v[132:133], v[124:127], off
	global_store_dwordx4 v[132:133], v[116:119], off offset:256
	global_store_dwordx4 v[112:113], v[108:111], off
	global_store_dwordx4 v[112:113], v[100:103], off offset:256
	global_store_dwordx4 v[96:97], v[92:95], off
	global_store_dwordx4 v[96:97], v[84:87], off offset:256
	global_store_dwordx4 v[80:81], v[76:79], off
	global_store_dwordx4 v[68:69], v[60:63], off
	global_store_dwordx4 v[68:69], v[52:55], off offset:256
	global_store_dwordx4 v[48:49], v[44:47], off
	global_store_dwordx4 v[48:49], v[36:39], off offset:256
	global_store_dwordx4 v[32:33], v[28:31], off
	global_store_dwordx4 v[32:33], v[20:23], off offset:256
	global_store_dwordx4 v[16:17], v[12:15], off
	global_store_dwordx4 v[16:17], v[4:7], off offset:256
	s_waitcnt vmcnt(0)
	v_readlane_b32 s31, v250, 56
	v_readlane_b32 s25, v250, 50
	v_readlane_b32 s26, v250, 51
	v_readlane_b32 s27, v250, 52
	v_readlane_b32 s30, v250, 55
	s_barrier

; __device__ __forceinline__ void ln_row(const float* xin, const float* dp, const float* gam, const float* bet, float* of, bf16_t* ob, int lane) {
;     f32x4 v[4]; float s = 0.f;
; #pragma unroll
;     for (int j = 0; j < 4; ++j) { const f32x4 a = *(const f32x4*)(xin + 4 * lane + 256 * j), d = *(const f32x4*)(dp + 4 * lane + 256 * j); v[j] = a * ALPHA + d; s += (v[j][0] + v[j][1]) + (v[j][2] + v[j][3]); }
;     const float mean = wave_sum(s) * (1.f / DM); float q = 0.f;
;     ...
;                     for (int rr = 0; rr < 2; ++rr) { const int rs = 16 * mt2 + 2 * C.wave + rr; const size_t m = (size_t)MP + rs;
;                         if (LNL == 0) ln_row(P.x_sample + (size_t)rs * DM, dps + (size_t)rs * DM, P.ln_g, P.ln_b, (float*)(P.ws + WS_X1) + m * DM, (bf16_t*)(P.ws + WS_X1A) + m * DM, lane);
.LBB0_1847:
	s_or_b32 s8, s4, s22
	s_lshl_b64 s[4:5], s[8:9], 10
	s_add_u32 s4, s4, 0x2000000
	s_addc_u32 s5, s5, 0
	s_lshl_b64 s[38:39], s[8:9], 12
	v_lshl_add_u64 v[68:69], v[16:17], 0, s[38:39]
	v_lshl_add_u64 v[72:73], v[14:15], 0, s[38:39]
	global_load_dwordx4 v[40:43], v[18:19], off
	global_load_dwordx4 v[44:47], v[20:21], off
	global_load_dwordx4 v[4:7], v[72:73], off
	global_load_dwordx4 v[48:51], v[68:69], off
	global_load_dwordx4 v[52:55], v[68:69], off offset:1024
	global_load_dwordx4 v[56:59], v[72:73], off offset:1024
	global_load_dwordx4 v[60:63], v[72:73], off offset:2048
	global_load_dwordx4 v[64:67], v[68:69], off offset:2048
	s_nop 0
	global_load_dwordx4 v[68:71], v[68:69], off offset:3072
	s_nop 0
	global_load_dwordx4 v[72:75], v[72:73], off offset:3072
	v_mov_b32_e32 v39, 0
	v_mov_b32_e32 v76, 0
	v_lshl_add_u64 v[2:3], s[4:5], 2, v[22:23]
	v_lshl_add_u64 v[0:1], s[4:5], 1, v[24:25]
	v_mov_b32_e32 v77, 0
	v_mov_b32_e32 v78, 0
	s_waitcnt vmcnt(6)
	v_pk_fma_f32 v[48:49], v[48:49], s[18:19], v[4:5] op_sel_hi:[1,0,1]
	v_pk_fma_f32 v[50:51], v[50:51], s[18:19], v[6:7] op_sel_hi:[1,0,1]
	s_waitcnt vmcnt(4)
	v_pk_fma_f32 v[52:53], v[52:53], s[18:19], v[56:57] op_sel_hi:[1,0,1]
	v_pk_fma_f32 v[54:55], v[54:55], s[18:19], v[58:59] op_sel_hi:[1,0,1]
	s_waitcnt vmcnt(2)
	v_pk_fma_f32 v[56:57], v[66:67], s[18:19], v[62:63] op_sel_hi:[1,0,1]
	v_pk_fma_f32 v[58:59], v[64:65], s[18:19], v[60:61] op_sel_hi:[1,0,1]
	v_pk_mov_b32 v[60:61], v[48:49], v[50:51] op_sel:[1,0]
	v_mov_b32_e32 v62, v48
	v_mov_b32_e32 v63, v51
	v_pk_mov_b32 v[64:65], v[52:53], v[54:55] op_sel:[1,0]
	v_mov_b32_e32 v66, v52
	v_mov_b32_e32 v67, v55
	v_pk_add_f32 v[60:61], v[60:61], v[62:63]
	v_pk_add_f32 v[62:63], v[64:65], v[66:67]
	s_waitcnt vmcnt(0)
; __device__ __forceinline__ unsigned pk2(float lo, float hi) { return f2bf(lo) | (f2bf(hi) << 16); }
; __device__ __forceinline__ void ln_row(const float* xin, const float* dp, const float* gam, const float* bet, float* of, bf16_t* ob, int lane) {
;     ...
;     for (int j = 0; j < 4; ++j) { const f32x4 a = *(const f32x4*)(xin + 4 * lane + 256 * j), d = *(const f32x4*)(dp + 4 * lane + 256 * j); v[j] = a * ALPHA + d; s += (v[j][0] + v[j][1]) + (v[j][2] + v[j][3]); }
;     const float mean = wave_sum(s) * (1.f / DM); float q = 0.f;
; #pragma unroll
;     for (int j = 0; j < 4; ++j) { v[j] = v[j] - mean; q += (v[j][0] * v[j][0] + v[j][1] * v[j][1]) + (v[j][2] * v[j][2] + v[j][3] * v[j][3]); }
;     const float rstd = 1.f / sqrtf(wave_sum(q) * (1.f / DM) + LN_EPS);
; #pragma unroll
;     for (int j = 0; j < 4; ++j) { const f32x4 gg = *(const f32x4*)(gam + 4 * lane + 256 * j), bb = *(const f32x4*)(bet + 4 * lane + 256 * j); const f32x4 o = v[j] * rstd * gg + bb;
;         *(f32x4*)(of + 4 * lane + 256 * j) = o;
;         if (ob) { u32x2 w; w.x = pk2(o[0], o[1]); w.y = pk2(o[2], o[3]); *(u32x2*)(ob + 4 * lane + 256 * j) = w; } }
	v_pk_fma_f32 v[6:7], v[70:71], s[18:19], v[74:75] op_sel_hi:[1,0,1]
	v_pk_fma_f32 v[4:5], v[68:69], s[18:19], v[72:73] op_sel_hi:[1,0,1]
	v_add_f32_e32 v66, v60, v61
	v_pk_add_f32 v[60:61], v[62:63], v[62:63] op_sel:[0,1] op_sel_hi:[1,0]
	v_add_f32_e32 v68, v58, v59
	v_add_f32_e32 v70, v56, v57
	v_mov_b32_e32 v73, v4
	v_mov_b32_e32 v69, v6
	v_mov_b32_e32 v71, v7
	v_add_f32_e32 v72, 0, v66
	v_mov_b32_e32 v61, v5
	v_pk_add_f32 v[64:65], v[68:69], v[70:71]
	v_pk_add_f32 v[60:61], v[72:73], v[60:61]
	s_nop 0
	v_pk_add_f32 v[60:61], v[60:61], v[64:65]
	s_nop 0
	v_add_f32_e32 v60, v60, v61
	s_nop 1
	v_add_f32_dpp v60, v60, v60 row_shr:1 row_mask:0xf bank_mask:0xf bound_ctrl:1
	s_nop 1
	v_add_f32_dpp v60, v60, v60 row_shr:2 row_mask:0xf bank_mask:0xf bound_ctrl:1
	s_nop 1
	v_add_f32_dpp v60, v60, v60 row_shr:4 row_mask:0xf bank_mask:0xf bound_ctrl:1
	s_nop 1
	v_add_f32_dpp v60, v60, v60 row_shr:8 row_mask:0xf bank_mask:0xf bound_ctrl:1
	s_nop 1
	v_mov_b32_dpp v39, v60 row_bcast:15 row_mask:0xa bank_mask:0xf
	v_add_f32_e32 v39, v60, v39
	s_nop 1
	v_mov_b32_dpp v76, v39 row_bcast:31 row_mask:0xc bank_mask:0xf
	v_add_f32_e32 v39, v39, v76
	s_nop 0
	v_readlane_b32 s4, v39, 63
	s_nop 1
	v_fmac_f32_e32 v51, s4, v37
	v_fmac_f32_e32 v49, s4, v37
	v_fmac_f32_e32 v55, s4, v37
	v_fmac_f32_e32 v53, s4, v37
	v_fma_f32 v50, s4, v37, v50
	v_fma_f32 v48, s4, v37, v48
	v_fma_f32 v54, s4, v37, v54
	v_fma_f32 v52, s4, v37, v52
	v_fmac_f32_e32 v57, s4, v37
	v_fmac_f32_e32 v59, s4, v37
	v_mul_f32_e32 v39, v49, v49
	v_mul_f32_e32 v60, v51, v51
	v_mul_f32_e32 v61, v53, v53
	v_mul_f32_e32 v62, v55, v55
	v_fma_f32 v56, s4, v37, v56
	v_fma_f32 v58, s4, v37, v58
	v_fmac_f32_e32 v7, s4, v37
	v_fmac_f32_e32 v5, s4, v37
	v_mul_f32_e32 v63, v59, v59
	v_mul_f32_e32 v64, v57, v57
	v_fmac_f32_e32 v39, v48, v48
	v_fmac_f32_e32 v60, v50, v50
	v_fmac_f32_e32 v61, v52, v52
	v_fmac_f32_e32 v62, v54, v54
	v_fma_f32 v6, s4, v37, v6
	v_fma_f32 v4, s4, v37, v4
	v_mul_f32_e32 v65, v5, v5
	v_mul_f32_e32 v66, v7, v7
	v_fmac_f32_e32 v63, v58, v58
	v_fmac_f32_e32 v64, v56, v56
	v_add_f32_e32 v39, v39, v60
	v_add_f32_e32 v60, v61, v62
	v_fmac_f32_e32 v65, v4, v4
	v_fmac_f32_e32 v66, v6, v6
	v_add_f32_e32 v61, v63, v64
	v_add_f32_e32 v39, v39, v60
	v_add_f32_e32 v62, v65, v66
	v_add_f32_e32 v39, v61, v39
	v_add_f32_e32 v39, v62, v39
	s_nop 1
	v_add_f32_dpp v39, v39, v39 row_shr:1 row_mask:0xf bank_mask:0xf bound_ctrl:1
	s_nop 1
	v_add_f32_dpp v39, v39, v39 row_shr:2 row_mask:0xf bank_mask:0xf bound_ctrl:1
	s_nop 1
	v_add_f32_dpp v39, v39, v39 row_shr:4 row_mask:0xf bank_mask:0xf bound_ctrl:1
	s_nop 1
	v_add_f32_dpp v39, v39, v39 row_shr:8 row_mask:0xf bank_mask:0xf bound_ctrl:1
	s_nop 1
	v_mov_b32_dpp v77, v39 row_bcast:15 row_mask:0xa bank_mask:0xf
	v_add_f32_e32 v39, v39, v77
	s_nop 1
	v_mov_b32_dpp v78, v39 row_bcast:31 row_mask:0xc bank_mask:0xf
	v_add_f32_e32 v39, v39, v78
	s_nop 0
	v_readlane_b32 s4, v39, 63
	s_nop 1
	v_fma_f32 v39, s4, v38, v34
	v_mul_f32_e32 v60, 0x4f800000, v39
	v_cmp_gt_f32_e32 vcc, s31, v39
	s_nop 1
	v_cndmask_b32_e32 v39, v39, v60, vcc
	v_sqrt_f32_e32 v60, v39
	s_nop 0
	v_add_u32_e32 v61, -1, v60
	v_add_u32_e32 v62, 1, v60
	v_fma_f32 v63, -v61, v60, v39
	v_fma_f32 v64, -v62, v60, v39
	v_cmp_ge_f32_e64 s[4:5], 0, v63
	s_nop 1
	v_cndmask_b32_e64 v60, v60, v61, s[4:5]
	v_cmp_lt_f32_e64 s[4:5], 0, v64
	s_nop 1
	v_cndmask_b32_e64 v60, v60, v62, s[4:5]
	v_mul_f32_e32 v61, 0x37800000, v60
	v_cndmask_b32_e32 v60, v60, v61, vcc
	v_cmp_class_f32_e32 vcc, v39, v35
	s_nop 1
	v_cndmask_b32_e32 v39, v60, v39, vcc
	v_div_scale_f32 v60, s[4:5], v39, v39, 1.0
	v_rcp_f32_e32 v62, v60
	v_div_scale_f32 v61, vcc, 1.0, v39, 1.0
	s_mov_b32 s4, 1
	v_fma_f32 v63, -v60, v62, 1.0
	v_fmac_f32_e32 v62, v63, v62
	v_mul_f32_e32 v63, v61, v62
	v_fma_f32 v64, -v60, v63, v61
	v_fmac_f32_e32 v63, v64, v62
	v_fma_f32 v60, -v60, v63, v61
	v_div_fmas_f32 v60, v60, v62, v63
	v_div_fixup_f32 v60, v60, v39, 1.0
	v_pk_mul_f32 v[48:49], v[48:49], v[60:61] op_sel_hi:[1,0]
	v_pk_mul_f32 v[50:51], v[50:51], v[60:61] op_sel_hi:[1,0]
	v_pk_fma_f32 v[40:41], v[40:41], v[48:49], v[44:45]
	v_pk_fma_f32 v[42:43], v[42:43], v[50:51], v[46:47]
	global_store_dwordx4 v[2:3], v[40:43], off
	s_nop 0
	s_nop 0
	v_cvt_pk_bf16_f32 v40, v40, v41
	v_cvt_pk_bf16_f32 v41, v42, v43
	global_store_dwordx2 v[0:1], v[40:41], off
	global_load_dwordx4 v[40:43], v[18:19], off offset:1024
	s_nop 0
	global_load_dwordx4 v[44:47], v[20:21], off offset:1024
	v_pk_mul_f32 v[48:49], v[54:55], v[60:61] op_sel_hi:[1,0]
	v_pk_mul_f32 v[50:51], v[52:53], v[60:61] op_sel_hi:[1,0]
	v_pk_mul_f32 v[6:7], v[6:7], v[60:61] op_sel_hi:[1,0]
	v_pk_mul_f32 v[4:5], v[4:5], v[60:61] op_sel_hi:[1,0]
	s_and_b64 vcc, exec, s[20:21]
	s_mov_b64 s[20:21], 0
	s_waitcnt vmcnt(0)
	v_pk_fma_f32 v[40:41], v[40:41], v[50:51], v[44:45]
	v_pk_fma_f32 v[42:43], v[42:43], v[48:49], v[46:47]
	global_store_dwordx4 v[2:3], v[40:43], off offset:1024
	s_nop 0
	s_nop 0
	v_cvt_pk_bf16_f32 v40, v40, v41
	v_cvt_pk_bf16_f32 v41, v42, v43
	global_store_dwordx2 v[0:1], v[40:41], off offset:512
	global_load_dwordx4 v[40:43], v[18:19], off offset:2048
	s_nop 0
	global_load_dwordx4 v[44:47], v[20:21], off offset:2048
	v_pk_mul_f32 v[48:49], v[56:57], v[60:61] op_sel_hi:[1,0]
	v_pk_mul_f32 v[50:51], v[58:59], v[60:61] op_sel_hi:[1,0]
	s_waitcnt vmcnt(0)
	v_pk_fma_f32 v[42:43], v[48:49], v[42:43], v[46:47]
	v_pk_fma_f32 v[40:41], v[50:51], v[40:41], v[44:45]
	global_store_dwordx4 v[2:3], v[40:43], off offset:2048
	s_nop 0
	s_nop 0
	v_cvt_pk_bf16_f32 v40, v40, v41
	v_cvt_pk_bf16_f32 v41, v42, v43
	global_store_dwordx2 v[0:1], v[40:41], off offset:1024
	global_load_dwordx4 v[40:43], v[18:19], off offset:3072
	s_nop 0
	global_load_dwordx4 v[44:47], v[20:21], off offset:3072
	s_waitcnt vmcnt(0)
	v_pk_fma_f32 v[4:5], v[4:5], v[40:41], v[44:45]
	v_pk_fma_f32 v[6:7], v[6:7], v[42:43], v[46:47]
	global_store_dwordx4 v[2:3], v[4:7], off offset:3072
	v_cvt_pk_bf16_f32 v2, v4, v5
	v_cvt_pk_bf16_f32 v3, v6, v7
	global_store_dwordx2 v[0:1], v[2:3], off offset:1536
	s_cbranch_vccnz .LBB0_1847

; __device__ __forceinline__ void ln_row(const float* xin, const float* dp, const float* gam, const float* bet, float* of, bf16_t* ob, int lane) {
;     f32x4 v[4]; float s = 0.f;
; #pragma unroll
;     for (int j = 0; j < 4; ++j) { const f32x4 a = *(const f32x4*)(xin + 4 * lane + 256 * j), d = *(const f32x4*)(dp + 4 * lane + 256 * j); v[j] = a * ALPHA + d; s += (v[j][0] + v[j][1]) + (v[j][2] + v[j][3]); }
;     const float mean = wave_sum(s) * (1.f / DM); float q = 0.f;
;     ...
;                     for (int rr = 0; rr < 2; ++rr) { const int rs = 16 * mt2 + 2 * C.wave + rr; const size_t m = (size_t)MP + rs;
;                         if (LNL == 0) ln_row(P.x_sample + (size_t)rs * DM, dps + (size_t)rs * DM, P.ln_g, P.ln_b, (float*)(P.ws + WS_X1) + m * DM, (bf16_t*)(P.ws + WS_X1A) + m * DM, lane);
.LBB0_1856:
	s_or_b32 s8, s4, s22
	s_lshl_b64 s[4:5], s[8:9], 10
	s_add_u32 s4, s4, 0x2000000
	s_addc_u32 s5, s5, 0
	s_lshl_b64 s[38:39], s[8:9], 12
	v_lshl_add_u64 v[68:69], v[16:17], 0, s[38:39]
	v_lshl_add_u64 v[72:73], v[14:15], 0, s[38:39]
	global_load_dwordx4 v[40:43], v[18:19], off
	global_load_dwordx4 v[44:47], v[20:21], off
	global_load_dwordx4 v[4:7], v[72:73], off
	global_load_dwordx4 v[48:51], v[68:69], off
	global_load_dwordx4 v[52:55], v[68:69], off offset:1024
	global_load_dwordx4 v[56:59], v[72:73], off offset:1024
	global_load_dwordx4 v[60:63], v[72:73], off offset:2048
	global_load_dwordx4 v[64:67], v[68:69], off offset:2048
	s_nop 0
	global_load_dwordx4 v[68:71], v[68:69], off offset:3072
	s_nop 0
	global_load_dwordx4 v[72:75], v[72:73], off offset:3072
	v_mov_b32_e32 v39, 0
	v_mov_b32_e32 v76, 0
	v_lshl_add_u64 v[2:3], s[4:5], 2, v[22:23]
	v_lshl_add_u64 v[0:1], s[4:5], 1, v[24:25]
	v_mov_b32_e32 v77, 0
	v_mov_b32_e32 v78, 0
	s_waitcnt vmcnt(6)
	v_pk_fma_f32 v[48:49], v[48:49], s[18:19], v[4:5] op_sel_hi:[1,0,1]
	v_pk_fma_f32 v[50:51], v[50:51], s[18:19], v[6:7] op_sel_hi:[1,0,1]
	s_waitcnt vmcnt(4)
	v_pk_fma_f32 v[52:53], v[52:53], s[18:19], v[56:57] op_sel_hi:[1,0,1]
	v_pk_fma_f32 v[54:55], v[54:55], s[18:19], v[58:59] op_sel_hi:[1,0,1]
	s_waitcnt vmcnt(2)
	v_pk_fma_f32 v[56:57], v[66:67], s[18:19], v[62:63] op_sel_hi:[1,0,1]
	v_pk_fma_f32 v[58:59], v[64:65], s[18:19], v[60:61] op_sel_hi:[1,0,1]
	v_pk_mov_b32 v[60:61], v[48:49], v[50:51] op_sel:[1,0]
	v_mov_b32_e32 v62, v48
	v_mov_b32_e32 v63, v51
	v_pk_mov_b32 v[64:65], v[52:53], v[54:55] op_sel:[1,0]
	v_mov_b32_e32 v66, v52
	v_mov_b32_e32 v67, v55
	v_pk_add_f32 v[60:61], v[60:61], v[62:63]
	v_pk_add_f32 v[62:63], v[64:65], v[66:67]
	s_waitcnt vmcnt(0)
; __device__ __forceinline__ unsigned pk2(float lo, float hi) { return f2bf(lo) | (f2bf(hi) << 16); }
; __device__ __forceinline__ void ln_row(const float* xin, const float* dp, const float* gam, const float* bet, float* of, bf16_t* ob, int lane) {
;     ...
;     for (int j = 0; j < 4; ++j) { const f32x4 a = *(const f32x4*)(xin + 4 * lane + 256 * j), d = *(const f32x4*)(dp + 4 * lane + 256 * j); v[j] = a * ALPHA + d; s += (v[j][0] + v[j][1]) + (v[j][2] + v[j][3]); }
;     const float mean = wave_sum(s) * (1.f / DM); float q = 0.f;
; #pragma unroll
;     for (int j = 0; j < 4; ++j) { v[j] = v[j] - mean; q += (v[j][0] * v[j][0] + v[j][1] * v[j][1]) + (v[j][2] * v[j][2] + v[j][3] * v[j][3]); }
;     const float rstd = 1.f / sqrtf(wave_sum(q) * (1.f / DM) + LN_EPS);
; #pragma unroll
;     for (int j = 0; j < 4; ++j) { const f32x4 gg = *(const f32x4*)(gam + 4 * lane + 256 * j), bb = *(const f32x4*)(bet + 4 * lane + 256 * j); const f32x4 o = v[j] * rstd * gg + bb;
;         *(f32x4*)(of + 4 * lane + 256 * j) = o;
;         if (ob) { u32x2 w; w.x = pk2(o[0], o[1]); w.y = pk2(o[2], o[3]); *(u32x2*)(ob + 4 * lane + 256 * j) = w; } }
	v_pk_fma_f32 v[6:7], v[70:71], s[18:19], v[74:75] op_sel_hi:[1,0,1]
	v_pk_fma_f32 v[4:5], v[68:69], s[18:19], v[72:73] op_sel_hi:[1,0,1]
	v_add_f32_e32 v66, v60, v61
	v_pk_add_f32 v[60:61], v[62:63], v[62:63] op_sel:[0,1] op_sel_hi:[1,0]
	v_add_f32_e32 v68, v58, v59
	v_add_f32_e32 v70, v56, v57
	v_mov_b32_e32 v73, v4
	v_mov_b32_e32 v69, v6
	v_mov_b32_e32 v71, v7
	v_add_f32_e32 v72, 0, v66
	v_mov_b32_e32 v61, v5
	v_pk_add_f32 v[64:65], v[68:69], v[70:71]
	v_pk_add_f32 v[60:61], v[72:73], v[60:61]
	s_nop 0
	v_pk_add_f32 v[60:61], v[60:61], v[64:65]
	s_nop 0
	v_add_f32_e32 v60, v60, v61
	s_nop 1
	v_add_f32_dpp v60, v60, v60 row_shr:1 row_mask:0xf bank_mask:0xf bound_ctrl:1
	s_nop 1
	v_add_f32_dpp v60, v60, v60 row_shr:2 row_mask:0xf bank_mask:0xf bound_ctrl:1
	s_nop 1
	v_add_f32_dpp v60, v60, v60 row_shr:4 row_mask:0xf bank_mask:0xf bound_ctrl:1
	s_nop 1
	v_add_f32_dpp v60, v60, v60 row_shr:8 row_mask:0xf bank_mask:0xf bound_ctrl:1
	s_nop 1
	v_mov_b32_dpp v39, v60 row_bcast:15 row_mask:0xa bank_mask:0xf
	v_add_f32_e32 v39, v60, v39
	s_nop 1
	v_mov_b32_dpp v76, v39 row_bcast:31 row_mask:0xc bank_mask:0xf
	v_add_f32_e32 v39, v39, v76
	s_nop 0
	v_readlane_b32 s4, v39, 63
	s_nop 1
	v_fmac_f32_e32 v51, s4, v37
	v_fmac_f32_e32 v49, s4, v37
	v_fmac_f32_e32 v55, s4, v37
	v_fmac_f32_e32 v53, s4, v37
	v_fma_f32 v50, s4, v37, v50
	v_fma_f32 v48, s4, v37, v48
	v_fma_f32 v54, s4, v37, v54
	v_fma_f32 v52, s4, v37, v52
	v_fmac_f32_e32 v57, s4, v37
	v_fmac_f32_e32 v59, s4, v37
	v_mul_f32_e32 v39, v49, v49
	v_mul_f32_e32 v60, v51, v51
	v_mul_f32_e32 v61, v53, v53
	v_mul_f32_e32 v62, v55, v55
	v_fma_f32 v56, s4, v37, v56
	v_fma_f32 v58, s4, v37, v58
	v_fmac_f32_e32 v7, s4, v37
	v_fmac_f32_e32 v5, s4, v37
	v_mul_f32_e32 v63, v59, v59
	v_mul_f32_e32 v64, v57, v57
	v_fmac_f32_e32 v39, v48, v48
	v_fmac_f32_e32 v60, v50, v50
	v_fmac_f32_e32 v61, v52, v52
	v_fmac_f32_e32 v62, v54, v54
	v_fma_f32 v6, s4, v37, v6
	v_fma_f32 v4, s4, v37, v4
	v_mul_f32_e32 v65, v5, v5
	v_mul_f32_e32 v66, v7, v7
	v_fmac_f32_e32 v63, v58, v58
	v_fmac_f32_e32 v64, v56, v56
	v_add_f32_e32 v39, v39, v60
	v_add_f32_e32 v60, v61, v62
	v_fmac_f32_e32 v65, v4, v4
	v_fmac_f32_e32 v66, v6, v6
	v_add_f32_e32 v61, v63, v64
	v_add_f32_e32 v39, v39, v60
	v_add_f32_e32 v62, v65, v66
	v_add_f32_e32 v39, v61, v39
	v_add_f32_e32 v39, v62, v39
	s_nop 1
	v_add_f32_dpp v39, v39, v39 row_shr:1 row_mask:0xf bank_mask:0xf bound_ctrl:1
	s_nop 1
	v_add_f32_dpp v39, v39, v39 row_shr:2 row_mask:0xf bank_mask:0xf bound_ctrl:1
	s_nop 1
	v_add_f32_dpp v39, v39, v39 row_shr:4 row_mask:0xf bank_mask:0xf bound_ctrl:1
	s_nop 1
	v_add_f32_dpp v39, v39, v39 row_shr:8 row_mask:0xf bank_mask:0xf bound_ctrl:1
	s_nop 1
	v_mov_b32_dpp v77, v39 row_bcast:15 row_mask:0xa bank_mask:0xf
	v_add_f32_e32 v39, v39, v77
	s_nop 1
	v_mov_b32_dpp v78, v39 row_bcast:31 row_mask:0xc bank_mask:0xf
	v_add_f32_e32 v39, v39, v78
	s_nop 0
	v_readlane_b32 s4, v39, 63
	s_nop 1
	v_fma_f32 v39, s4, v38, v34
	v_mul_f32_e32 v60, 0x4f800000, v39
	v_cmp_gt_f32_e32 vcc, s31, v39
	s_nop 1
	v_cndmask_b32_e32 v39, v39, v60, vcc
	v_sqrt_f32_e32 v60, v39
	s_nop 0
	v_add_u32_e32 v61, -1, v60
	v_add_u32_e32 v62, 1, v60
	v_fma_f32 v63, -v61, v60, v39
	v_fma_f32 v64, -v62, v60, v39
	v_cmp_ge_f32_e64 s[4:5], 0, v63
	s_nop 1
	v_cndmask_b32_e64 v60, v60, v61, s[4:5]
	v_cmp_lt_f32_e64 s[4:5], 0, v64
	s_nop 1
	v_cndmask_b32_e64 v60, v60, v62, s[4:5]
	v_mul_f32_e32 v61, 0x37800000, v60
	v_cndmask_b32_e32 v60, v60, v61, vcc
	v_cmp_class_f32_e32 vcc, v39, v35
	s_nop 1
	v_cndmask_b32_e32 v39, v60, v39, vcc
	v_div_scale_f32 v60, s[4:5], v39, v39, 1.0
	v_rcp_f32_e32 v62, v60
	v_div_scale_f32 v61, vcc, 1.0, v39, 1.0
	s_mov_b32 s4, 1
	v_fma_f32 v63, -v60, v62, 1.0
	v_fmac_f32_e32 v62, v63, v62
	v_mul_f32_e32 v63, v61, v62
	v_fma_f32 v64, -v60, v63, v61
	v_fmac_f32_e32 v63, v64, v62
	v_fma_f32 v60, -v60, v63, v61
	v_div_fmas_f32 v60, v60, v62, v63
	v_div_fixup_f32 v60, v60, v39, 1.0
	v_pk_mul_f32 v[48:49], v[48:49], v[60:61] op_sel_hi:[1,0]
	v_pk_mul_f32 v[50:51], v[50:51], v[60:61] op_sel_hi:[1,0]
	v_pk_fma_f32 v[40:41], v[40:41], v[48:49], v[44:45]
	v_pk_fma_f32 v[42:43], v[42:43], v[50:51], v[46:47]
	global_store_dwordx4 v[2:3], v[40:43], off
	s_nop 0
	s_nop 0
	v_cvt_pk_bf16_f32 v40, v40, v41
	v_cvt_pk_bf16_f32 v41, v42, v43
	global_store_dwordx2 v[0:1], v[40:41], off
	global_load_dwordx4 v[40:43], v[18:19], off offset:1024
	s_nop 0
	global_load_dwordx4 v[44:47], v[20:21], off offset:1024
	v_pk_mul_f32 v[48:49], v[54:55], v[60:61] op_sel_hi:[1,0]
	v_pk_mul_f32 v[50:51], v[52:53], v[60:61] op_sel_hi:[1,0]
	v_pk_mul_f32 v[6:7], v[6:7], v[60:61] op_sel_hi:[1,0]
	v_pk_mul_f32 v[4:5], v[4:5], v[60:61] op_sel_hi:[1,0]
	s_and_b64 vcc, exec, s[20:21]
	s_mov_b64 s[20:21], 0
	s_waitcnt vmcnt(0)
	v_pk_fma_f32 v[40:41], v[40:41], v[50:51], v[44:45]
	v_pk_fma_f32 v[42:43], v[42:43], v[48:49], v[46:47]
	global_store_dwordx4 v[2:3], v[40:43], off offset:1024
	s_nop 0
	s_nop 0
	v_cvt_pk_bf16_f32 v40, v40, v41
	v_cvt_pk_bf16_f32 v41, v42, v43
	global_store_dwordx2 v[0:1], v[40:41], off offset:512
	global_load_dwordx4 v[40:43], v[18:19], off offset:2048
	s_nop 0
	global_load_dwordx4 v[44:47], v[20:21], off offset:2048
	v_pk_mul_f32 v[48:49], v[56:57], v[60:61] op_sel_hi:[1,0]
	v_pk_mul_f32 v[50:51], v[58:59], v[60:61] op_sel_hi:[1,0]
	s_waitcnt vmcnt(0)
	v_pk_fma_f32 v[42:43], v[48:49], v[42:43], v[46:47]
	v_pk_fma_f32 v[40:41], v[50:51], v[40:41], v[44:45]
	global_store_dwordx4 v[2:3], v[40:43], off offset:2048
	s_nop 0
	s_nop 0
	v_cvt_pk_bf16_f32 v40, v40, v41
	v_cvt_pk_bf16_f32 v41, v42, v43
	global_store_dwordx2 v[0:1], v[40:41], off offset:1024
	global_load_dwordx4 v[40:43], v[18:19], off offset:3072
	s_nop 0
	global_load_dwordx4 v[44:47], v[20:21], off offset:3072
	s_waitcnt vmcnt(0)
	v_pk_fma_f32 v[4:5], v[4:5], v[40:41], v[44:45]
	v_pk_fma_f32 v[6:7], v[6:7], v[42:43], v[46:47]
	global_store_dwordx4 v[2:3], v[4:7], off offset:3072
	v_bfe_u32 v2, v4, 16, 1
	v_bfe_u32 v3, v5, 16, 1
	v_add3_u32 v2, v4, v2, s34
	v_add3_u32 v3, v5, v3, s34
	v_lshrrev_b32_e32 v2, 16, v2
	v_and_or_b32 v2, v3, s35, v2
	v_cvt_pk_bf16_f32 v3, v6, v7
	global_store_dwordx2 v[0:1], v[2:3], off offset:1536
	s_cbranch_vccnz .LBB0_1856

; __device__ __forceinline__ unsigned pk2(float lo, float hi) { return f2bf(lo) | (f2bf(hi) << 16); }
;     __device__ __forceinline__ void fused(f32x4 (&acc)[2][2][4][2], const pg8::Unit& u, int wr, int wc, int fr, int fq, LAS unsigned char* lds, int wid, int lane) const {
;     ...
;             for (int m = 0; m < 4; ++m) { const int r = ai * 128 + wr * 64 + m * 16 + fr; const f32x2v sr = S[r]; const size_t off = (size_t)(u.pm * 256 + r) * DM + col0;
; #pragma unroll
;                 for (int bj = 0; bj < 2; ++bj)
; #pragma unroll
;                     for (int n = 0; n < 2; ++n) { f32x4 o = (acc[ai][bj][m][n] - sr.x) * sr.y * gg[bj][n] + bb[bj][n];
;                         if (bad) o = (f32x4){qnan, qnan, qnan, qnan};
;                         if (outf) *(f32x4*)(outf + off + bj * 128 + n * 16) = o;
;                         if (outb) { u32x2 w; w.x = pk2(o[0], o[1]); w.y = pk2(o[2], o[3]); *(u32x2*)(outb + off + bj * 128 + n * 16) = w; } } }
.LBB0_1917:
	s_or_b64 exec, exec, s[40:41]
	s_waitcnt lgkmcnt(0)
	s_barrier
	s_waitcnt lgkmcnt(1)
	ds_read_b64 v[180:181], v195
	ds_read_b64 v[182:183], v197
	ds_read_b64 v[184:185], v199
	ds_read_b64 v[186:187], v201
	s_waitcnt lgkmcnt(4)
	v_cmp_eq_u32_e32 vcc, 0, v164
	s_waitcnt lgkmcnt(3)
	v_sub_f32_e32 v145, v145, v180
	v_sub_f32_e32 v144, v144, v180
	v_pk_mul_f32 v[144:145], v[180:181], v[144:145] op_sel:[1,0]
	v_sub_f32_e32 v147, v147, v180
	s_waitcnt vmcnt(5)
	v_pk_fma_f32 v[144:145], v[88:89], v[144:145], v[92:93]
	v_sub_f32_e32 v146, v146, v180
	v_cndmask_b32_e32 v144, v217, v144, vcc
	v_pk_mul_f32 v[146:147], v[180:181], v[146:147] op_sel:[1,0]
	v_cndmask_b32_e32 v145, v217, v145, vcc
	v_pk_fma_f32 v[146:147], v[90:91], v[146:147], v[94:95]
	v_cndmask_b32_e32 v146, v217, v146, vcc
	v_cndmask_b32_e32 v147, v217, v147, vcc
	v_cvt_pk_bf16_f32 v144, v144, v145
	v_sub_f32_e32 v133, v133, v180
	v_sub_f32_e32 v132, v132, v180
	v_pk_mul_f32 v[132:133], v[180:181], v[132:133] op_sel:[1,0]
	v_cvt_pk_bf16_f32 v145, v146, v147
	v_lshl_add_u64 v[146:147], s[14:15], 0, v[178:179]
	s_waitcnt vmcnt(4)
	v_pk_fma_f32 v[132:133], v[76:77], v[132:133], v[80:81]
	v_lshl_add_u64 v[146:147], v[146:147], 0, v[176:177]
	v_sub_f32_e32 v135, v135, v180
	v_sub_f32_e32 v134, v134, v180
	v_cndmask_b32_e32 v132, v217, v132, vcc
	global_store_dwordx2 v[146:147], v[144:145], off
	v_pk_mul_f32 v[134:135], v[180:181], v[134:135] op_sel:[1,0]
	v_cndmask_b32_e32 v133, v217, v133, vcc
	v_pk_fma_f32 v[134:135], v[78:79], v[134:135], v[82:83]
	v_cndmask_b32_e32 v134, v217, v134, vcc
	v_cndmask_b32_e32 v135, v217, v135, vcc
	v_cvt_pk_bf16_f32 v132, v132, v133
	v_bfe_u32 v133, v134, 16, 1
	v_sub_f32_e32 v117, v117, v180
	v_sub_f32_e32 v116, v116, v180
	v_add3_u32 v133, v134, v133, s68
	v_bfe_u32 v134, v135, 16, 1
	v_pk_mul_f32 v[116:117], v[180:181], v[116:117] op_sel:[1,0]
	v_lshrrev_b32_e32 v133, 16, v133
	v_add3_u32 v134, v135, v134, s68
	s_waitcnt vmcnt(2)
	v_pk_fma_f32 v[116:117], v[52:53], v[116:117], v[56:57]
	v_and_or_b32 v133, v134, s65, v133
	v_sub_f32_e32 v119, v119, v180
	v_sub_f32_e32 v118, v118, v180
	v_cndmask_b32_e32 v116, v217, v116, vcc
	global_store_dwordx2 v[146:147], v[132:133], off offset:32
	v_pk_mul_f32 v[118:119], v[180:181], v[118:119] op_sel:[1,0]
	v_cndmask_b32_e32 v117, v217, v117, vcc
	v_pk_fma_f32 v[118:119], v[54:55], v[118:119], v[58:59]
	v_cndmask_b32_e32 v118, v217, v118, vcc
	v_cndmask_b32_e32 v119, v217, v119, vcc
	v_cvt_pk_bf16_f32 v116, v116, v117
	v_sub_f32_e32 v101, v101, v180
	v_sub_f32_e32 v100, v100, v180
	v_pk_mul_f32 v[100:101], v[180:181], v[100:101] op_sel:[1,0]
	s_waitcnt vmcnt(2)
	v_pk_fma_f32 v[100:101], v[20:21], v[100:101], v[32:33]
	v_cvt_pk_bf16_f32 v117, v118, v119
	v_sub_f32_e32 v103, v103, v180
	v_sub_f32_e32 v102, v102, v180
	v_cndmask_b32_e32 v100, v217, v100, vcc
	global_store_dwordx2 v[146:147], v[116:117], off offset:256
	v_pk_mul_f32 v[102:103], v[180:181], v[102:103] op_sel:[1,0]
	v_cndmask_b32_e32 v101, v217, v101, vcc
	v_pk_fma_f32 v[102:103], v[22:23], v[102:103], v[34:35]
	v_cndmask_b32_e32 v102, v217, v102, vcc
	v_cndmask_b32_e32 v103, v217, v103, vcc
	v_cvt_pk_bf16_f32 v100, v100, v101
	v_cvt_pk_bf16_f32 v101, v102, v103
	s_waitcnt lgkmcnt(2)
	v_sub_f32_e32 v103, v149, v182
	v_sub_f32_e32 v102, v148, v182
	v_pk_mul_f32 v[102:103], v[182:183], v[102:103] op_sel:[1,0]
	v_sub_f32_e32 v117, v151, v182
	v_pk_fma_f32 v[102:103], v[88:89], v[102:103], v[92:93]
	v_sub_f32_e32 v116, v150, v182
	v_cndmask_b32_e32 v102, v217, v102, vcc
	v_pk_mul_f32 v[116:117], v[182:183], v[116:117] op_sel:[1,0]
	v_cndmask_b32_e32 v103, v217, v103, vcc
	v_pk_fma_f32 v[116:117], v[90:91], v[116:117], v[94:95]
	global_store_dwordx2 v[146:147], v[100:101], off offset:288
	v_add_u32_e32 v100, s31, v196
	v_cndmask_b32_e32 v116, v217, v116, vcc
	v_ashrrev_i32_e32 v101, 31, v100
	v_cndmask_b32_e32 v117, v217, v117, vcc
	v_cvt_pk_bf16_f32 v102, v102, v103
	v_lshlrev_b64 v[100:101], 11, v[100:101]
	v_lshl_add_u64 v[100:101], s[14:15], 0, v[100:101]
	v_cvt_pk_bf16_f32 v103, v116, v117
	v_lshl_add_u64 v[100:101], v[100:101], 0, v[176:177]
	global_store_dwordx2 v[100:101], v[102:103], off
	v_sub_f32_e32 v103, v137, v182
	v_sub_f32_e32 v102, v136, v182
	v_pk_mul_f32 v[102:103], v[182:183], v[102:103] op_sel:[1,0]
	v_sub_f32_e32 v117, v139, v182
	v_pk_fma_f32 v[102:103], v[76:77], v[102:103], v[80:81]
	v_sub_f32_e32 v116, v138, v182
	v_cndmask_b32_e32 v102, v217, v102, vcc
	v_pk_mul_f32 v[116:117], v[182:183], v[116:117] op_sel:[1,0]
	v_cndmask_b32_e32 v103, v217, v103, vcc
	v_pk_fma_f32 v[116:117], v[78:79], v[116:117], v[82:83]
	v_cndmask_b32_e32 v116, v217, v116, vcc
	v_cndmask_b32_e32 v117, v217, v117, vcc
	v_cvt_pk_bf16_f32 v102, v102, v103
	v_cvt_pk_bf16_f32 v103, v116, v117
	global_store_dwordx2 v[100:101], v[102:103], off offset:32
	v_sub_f32_e32 v103, v121, v182
	v_sub_f32_e32 v102, v120, v182
	v_pk_mul_f32 v[102:103], v[182:183], v[102:103] op_sel:[1,0]
	v_sub_f32_e32 v117, v123, v182
	v_pk_fma_f32 v[102:103], v[52:53], v[102:103], v[56:57]
	v_sub_f32_e32 v116, v122, v182
	v_cndmask_b32_e32 v102, v217, v102, vcc
	v_pk_mul_f32 v[116:117], v[182:183], v[116:117] op_sel:[1,0]
	v_cndmask_b32_e32 v103, v217, v103, vcc
	v_pk_fma_f32 v[116:117], v[54:55], v[116:117], v[58:59]
	v_cndmask_b32_e32 v116, v217, v116, vcc
	v_cndmask_b32_e32 v117, v217, v117, vcc
	v_cvt_pk_bf16_f32 v102, v102, v103
	v_bfe_u32 v103, v116, 16, 1
	v_add3_u32 v103, v116, v103, s68
	v_bfe_u32 v116, v117, 16, 1
	v_lshrrev_b32_e32 v103, 16, v103
	v_add3_u32 v116, v117, v116, s68
	v_and_or_b32 v103, v116, s65, v103
	global_store_dwordx2 v[100:101], v[102:103], off offset:256
	v_sub_f32_e32 v103, v105, v182
	v_sub_f32_e32 v102, v104, v182
	v_pk_mul_f32 v[102:103], v[182:183], v[102:103] op_sel:[1,0]
	v_sub_f32_e32 v105, v107, v182
	v_pk_fma_f32 v[102:103], v[20:21], v[102:103], v[32:33]
	v_sub_f32_e32 v104, v106, v182
	v_cndmask_b32_e32 v102, v217, v102, vcc
	v_pk_mul_f32 v[104:105], v[182:183], v[104:105] op_sel:[1,0]
	v_cndmask_b32_e32 v103, v217, v103, vcc
	v_pk_fma_f32 v[104:105], v[22:23], v[104:105], v[34:35]
	v_cndmask_b32_e32 v104, v217, v104, vcc
	v_cndmask_b32_e32 v105, v217, v105, vcc
	v_cvt_pk_bf16_f32 v102, v102, v103
	v_cvt_pk_bf16_f32 v103, v104, v105
	global_store_dwordx2 v[100:101], v[102:103], off offset:288
	s_waitcnt lgkmcnt(1)
; __device__ __forceinline__ unsigned pk2(float lo, float hi) { return f2bf(lo) | (f2bf(hi) << 16); }
;     __device__ __forceinline__ void fused(f32x4 (&acc)[2][2][4][2], const pg8::Unit& u, int wr, int wc, int fr, int fq, LAS unsigned char* lds, int wid, int lane) const {
;     ...
;             for (int m = 0; m < 4; ++m) { const int r = ai * 128 + wr * 64 + m * 16 + fr; const f32x2v sr = S[r]; const size_t off = (size_t)(u.pm * 256 + r) * DM + col0;
; #pragma unroll
;                 for (int bj = 0; bj < 2; ++bj)
; #pragma unroll
;                     for (int n = 0; n < 2; ++n) { f32x4 o = (acc[ai][bj][m][n] - sr.x) * sr.y * gg[bj][n] + bb[bj][n];
;                         if (bad) o = (f32x4){qnan, qnan, qnan, qnan};
;                         if (outf) *(f32x4*)(outf + off + bj * 128 + n * 16) = o;
;                         if (outb) { u32x2 w; w.x = pk2(o[0], o[1]); w.y = pk2(o[2], o[3]); *(u32x2*)(outb + off + bj * 128 + n * 16) = w; } } }
	v_sub_f32_e32 v103, v157, v184
	v_sub_f32_e32 v102, v156, v184
	v_pk_mul_f32 v[102:103], v[184:185], v[102:103] op_sel:[1,0]
	v_sub_f32_e32 v105, v159, v184
	v_pk_fma_f32 v[102:103], v[88:89], v[102:103], v[92:93]
	v_sub_f32_e32 v104, v158, v184
	v_cndmask_b32_e32 v102, v217, v102, vcc
	v_pk_mul_f32 v[104:105], v[184:185], v[104:105] op_sel:[1,0]
	v_cndmask_b32_e32 v103, v217, v103, vcc
	v_pk_fma_f32 v[104:105], v[90:91], v[104:105], v[94:95]
	v_add_u32_e32 v100, s31, v198
	v_cndmask_b32_e32 v104, v217, v104, vcc
	v_ashrrev_i32_e32 v101, 31, v100
	v_cndmask_b32_e32 v105, v217, v105, vcc
	v_cvt_pk_bf16_f32 v102, v102, v103
	v_lshlrev_b64 v[100:101], 11, v[100:101]
	v_lshl_add_u64 v[100:101], s[14:15], 0, v[100:101]
	v_cvt_pk_bf16_f32 v103, v104, v105
	v_lshl_add_u64 v[100:101], v[100:101], 0, v[176:177]
	global_store_dwordx2 v[100:101], v[102:103], off
	v_sub_f32_e32 v103, v141, v184
	v_sub_f32_e32 v102, v140, v184
	v_pk_mul_f32 v[102:103], v[184:185], v[102:103] op_sel:[1,0]
	v_sub_f32_e32 v105, v143, v184
	v_pk_fma_f32 v[102:103], v[76:77], v[102:103], v[80:81]
	v_sub_f32_e32 v104, v142, v184
	v_cndmask_b32_e32 v102, v217, v102, vcc
	v_pk_mul_f32 v[104:105], v[184:185], v[104:105] op_sel:[1,0]
	v_cndmask_b32_e32 v103, v217, v103, vcc
	v_pk_fma_f32 v[104:105], v[78:79], v[104:105], v[82:83]
	v_cndmask_b32_e32 v104, v217, v104, vcc
	v_cndmask_b32_e32 v105, v217, v105, vcc
	v_cvt_pk_bf16_f32 v102, v102, v103
	v_cvt_pk_bf16_f32 v103, v104, v105
	global_store_dwordx2 v[100:101], v[102:103], off offset:32
	v_sub_f32_e32 v103, v125, v184
	v_sub_f32_e32 v102, v124, v184
	v_pk_mul_f32 v[102:103], v[184:185], v[102:103] op_sel:[1,0]
	v_sub_f32_e32 v105, v127, v184
	v_pk_fma_f32 v[102:103], v[52:53], v[102:103], v[56:57]
	v_sub_f32_e32 v104, v126, v184
	v_cndmask_b32_e32 v102, v217, v102, vcc
	v_pk_mul_f32 v[104:105], v[184:185], v[104:105] op_sel:[1,0]
	v_cndmask_b32_e32 v103, v217, v103, vcc
	v_pk_fma_f32 v[104:105], v[54:55], v[104:105], v[58:59]
	v_cndmask_b32_e32 v104, v217, v104, vcc
	v_cndmask_b32_e32 v105, v217, v105, vcc
	v_cvt_pk_bf16_f32 v102, v102, v103
	v_cvt_pk_bf16_f32 v103, v104, v105
	global_store_dwordx2 v[100:101], v[102:103], off offset:256
	v_sub_f32_e32 v103, v109, v184
	v_sub_f32_e32 v102, v108, v184
	v_pk_mul_f32 v[102:103], v[184:185], v[102:103] op_sel:[1,0]
	v_sub_f32_e32 v105, v111, v184
	v_pk_fma_f32 v[102:103], v[20:21], v[102:103], v[32:33]
	v_sub_f32_e32 v104, v110, v184
	v_cndmask_b32_e32 v102, v217, v102, vcc
	v_pk_mul_f32 v[104:105], v[184:185], v[104:105] op_sel:[1,0]
	v_cndmask_b32_e32 v103, v217, v103, vcc
	v_pk_fma_f32 v[104:105], v[22:23], v[104:105], v[34:35]
	v_cndmask_b32_e32 v104, v217, v104, vcc
	v_cndmask_b32_e32 v105, v217, v105, vcc
	v_cvt_pk_bf16_f32 v102, v102, v103
	v_cvt_pk_bf16_f32 v103, v104, v105
	global_store_dwordx2 v[100:101], v[102:103], off offset:288
	s_waitcnt lgkmcnt(0)
	v_sub_f32_e32 v103, v153, v186
	v_sub_f32_e32 v102, v152, v186
	v_pk_mul_f32 v[102:103], v[186:187], v[102:103] op_sel:[1,0]
	v_sub_f32_e32 v105, v155, v186
	v_pk_fma_f32 v[102:103], v[88:89], v[102:103], v[92:93]
	v_sub_f32_e32 v104, v154, v186
	v_cndmask_b32_e32 v102, v217, v102, vcc
	v_pk_mul_f32 v[104:105], v[186:187], v[104:105] op_sel:[1,0]
	v_cndmask_b32_e32 v103, v217, v103, vcc
	v_pk_fma_f32 v[104:105], v[90:91], v[104:105], v[94:95]
	v_add_u32_e32 v100, s31, v200
	v_cndmask_b32_e32 v104, v217, v104, vcc
	v_ashrrev_i32_e32 v101, 31, v100
	v_cndmask_b32_e32 v105, v217, v105, vcc
	v_cvt_pk_bf16_f32 v102, v102, v103
	v_lshlrev_b64 v[100:101], 11, v[100:101]
	v_lshl_add_u64 v[100:101], s[14:15], 0, v[100:101]
	v_cvt_pk_bf16_f32 v103, v104, v105
	v_lshl_add_u64 v[100:101], v[100:101], 0, v[176:177]
	global_store_dwordx2 v[100:101], v[102:103], off
	v_sub_f32_e32 v103, v129, v186
	v_sub_f32_e32 v102, v128, v186
	v_pk_mul_f32 v[102:103], v[186:187], v[102:103] op_sel:[1,0]
	v_sub_f32_e32 v105, v131, v186
	v_pk_fma_f32 v[102:103], v[76:77], v[102:103], v[80:81]
	v_sub_f32_e32 v104, v130, v186
	v_cndmask_b32_e32 v102, v217, v102, vcc
	v_pk_mul_f32 v[104:105], v[186:187], v[104:105] op_sel:[1,0]
	v_cndmask_b32_e32 v103, v217, v103, vcc
	v_pk_fma_f32 v[104:105], v[78:79], v[104:105], v[82:83]
	v_cndmask_b32_e32 v104, v217, v104, vcc
	v_cndmask_b32_e32 v105, v217, v105, vcc
	v_cvt_pk_bf16_f32 v102, v102, v103
	v_cvt_pk_bf16_f32 v103, v104, v105
	global_store_dwordx2 v[100:101], v[102:103], off offset:32
	v_sub_f32_e32 v103, v113, v186
	v_sub_f32_e32 v102, v112, v186
	v_pk_mul_f32 v[102:103], v[186:187], v[102:103] op_sel:[1,0]
	v_sub_f32_e32 v105, v115, v186
	v_pk_fma_f32 v[102:103], v[52:53], v[102:103], v[56:57]
	v_sub_f32_e32 v104, v114, v186
	v_cndmask_b32_e32 v102, v217, v102, vcc
	v_pk_mul_f32 v[104:105], v[186:187], v[104:105] op_sel:[1,0]
	v_cndmask_b32_e32 v103, v217, v103, vcc
	v_pk_fma_f32 v[104:105], v[54:55], v[104:105], v[58:59]
	v_cndmask_b32_e32 v104, v217, v104, vcc
	v_cndmask_b32_e32 v105, v217, v105, vcc
	v_cvt_pk_bf16_f32 v102, v102, v103
	v_sub_f32_e32 v97, v97, v186
	v_sub_f32_e32 v96, v96, v186
	v_pk_mul_f32 v[96:97], v[186:187], v[96:97] op_sel:[1,0]
	v_pk_fma_f32 v[96:97], v[20:21], v[96:97], v[32:33]
	v_cvt_pk_bf16_f32 v103, v104, v105
	v_sub_f32_e32 v99, v99, v186
	v_sub_f32_e32 v98, v98, v186
	v_cndmask_b32_e32 v96, v217, v96, vcc
	global_store_dwordx2 v[100:101], v[102:103], off offset:256
	v_pk_mul_f32 v[98:99], v[186:187], v[98:99] op_sel:[1,0]
	v_cndmask_b32_e32 v97, v217, v97, vcc
	v_pk_fma_f32 v[98:99], v[22:23], v[98:99], v[34:35]
	v_cndmask_b32_e32 v98, v217, v98, vcc
	v_cndmask_b32_e32 v99, v217, v99, vcc
	v_cvt_pk_bf16_f32 v96, v96, v97
	v_cvt_pk_bf16_f32 v97, v98, v99
	global_store_dwordx2 v[100:101], v[96:97], off offset:288
	ds_read_b64 v[96:97], v203
	v_add_u32_e32 v104, s31, v202
	v_ashrrev_i32_e32 v105, 31, v104
	ds_read_b64 v[98:99], v205
	ds_read_b64 v[100:101], v207
	ds_read_b64 v[102:103], v209
	s_waitcnt lgkmcnt(3)
; __device__ __forceinline__ unsigned pk2(float lo, float hi) { return f2bf(lo) | (f2bf(hi) << 16); }
;     __device__ __forceinline__ void fused(f32x4 (&acc)[2][2][4][2], const pg8::Unit& u, int wr, int wc, int fr, int fq, LAS unsigned char* lds, int wid, int lane) const {
;     ...
;             for (int m = 0; m < 4; ++m) { const int r = ai * 128 + wr * 64 + m * 16 + fr; const f32x2v sr = S[r]; const size_t off = (size_t)(u.pm * 256 + r) * DM + col0;
; #pragma unroll
;                 for (int bj = 0; bj < 2; ++bj)
; #pragma unroll
;                     for (int n = 0; n < 2; ++n) { f32x4 o = (acc[ai][bj][m][n] - sr.x) * sr.y * gg[bj][n] + bb[bj][n];
;                         if (bad) o = (f32x4){qnan, qnan, qnan, qnan};
;                         if (outf) *(f32x4*)(outf + off + bj * 128 + n * 16) = o;
;                         if (outb) { u32x2 w; w.x = pk2(o[0], o[1]); w.y = pk2(o[2], o[3]); *(u32x2*)(outb + off + bj * 128 + n * 16) = w; } } }
	v_sub_f32_e32 v61, v61, v96
	v_sub_f32_e32 v60, v60, v96
	v_pk_mul_f32 v[60:61], v[96:97], v[60:61] op_sel:[1,0]
	v_sub_f32_e32 v63, v63, v96
	v_pk_fma_f32 v[60:61], v[88:89], v[60:61], v[92:93]
	v_sub_f32_e32 v62, v62, v96
	v_cndmask_b32_e32 v60, v217, v60, vcc
	v_pk_mul_f32 v[62:63], v[96:97], v[62:63] op_sel:[1,0]
	v_cndmask_b32_e32 v61, v217, v61, vcc
	v_pk_fma_f32 v[62:63], v[90:91], v[62:63], v[94:95]
	v_cndmask_b32_e32 v62, v217, v62, vcc
	v_cndmask_b32_e32 v63, v217, v63, vcc
	v_cvt_pk_bf16_f32 v60, v60, v61
	v_sub_f32_e32 v37, v37, v96
	v_sub_f32_e32 v36, v36, v96
	v_cvt_pk_bf16_f32 v61, v62, v63
	v_lshlrev_b64 v[62:63], 11, v[104:105]
	v_pk_mul_f32 v[36:37], v[96:97], v[36:37] op_sel:[1,0]
	v_lshl_add_u64 v[62:63], s[14:15], 0, v[62:63]
	v_pk_fma_f32 v[36:37], v[76:77], v[36:37], v[80:81]
	v_lshl_add_u64 v[62:63], v[62:63], 0, v[176:177]
	v_sub_f32_e32 v39, v39, v96
	v_sub_f32_e32 v38, v38, v96
	v_cndmask_b32_e32 v36, v217, v36, vcc
	global_store_dwordx2 v[62:63], v[60:61], off
	v_pk_mul_f32 v[38:39], v[96:97], v[38:39] op_sel:[1,0]
	v_cndmask_b32_e32 v37, v217, v37, vcc
	v_pk_fma_f32 v[38:39], v[78:79], v[38:39], v[82:83]
	v_cndmask_b32_e32 v38, v217, v38, vcc
	v_cndmask_b32_e32 v39, v217, v39, vcc
	v_cvt_pk_bf16_f32 v36, v36, v37
	v_bfe_u32 v37, v38, 16, 1
	v_sub_f32_e32 v13, v13, v96
	v_sub_f32_e32 v12, v12, v96
	v_add3_u32 v37, v38, v37, s68
	v_bfe_u32 v38, v39, 16, 1
	v_pk_mul_f32 v[12:13], v[96:97], v[12:13] op_sel:[1,0]
	v_lshrrev_b32_e32 v37, 16, v37
	v_add3_u32 v38, v39, v38, s68
	v_pk_fma_f32 v[12:13], v[52:53], v[12:13], v[56:57]
	v_and_or_b32 v37, v38, s65, v37
	v_sub_f32_e32 v15, v15, v96
	v_sub_f32_e32 v14, v14, v96
	v_cndmask_b32_e32 v12, v217, v12, vcc
	global_store_dwordx2 v[62:63], v[36:37], off offset:32
	v_pk_mul_f32 v[14:15], v[96:97], v[14:15] op_sel:[1,0]
	v_cndmask_b32_e32 v13, v217, v13, vcc
	v_pk_fma_f32 v[14:15], v[54:55], v[14:15], v[58:59]
	v_cndmask_b32_e32 v14, v217, v14, vcc
	v_cndmask_b32_e32 v15, v217, v15, vcc
	v_cvt_pk_bf16_f32 v12, v12, v13
	v_sub_f32_e32 v1, v1, v96
	v_sub_f32_e32 v0, v0, v96
	v_pk_mul_f32 v[0:1], v[96:97], v[0:1] op_sel:[1,0]
	v_pk_fma_f32 v[0:1], v[20:21], v[0:1], v[32:33]
	v_cvt_pk_bf16_f32 v13, v14, v15
	v_sub_f32_e32 v3, v3, v96
	v_sub_f32_e32 v2, v2, v96
	v_cndmask_b32_e32 v0, v217, v0, vcc
	global_store_dwordx2 v[62:63], v[12:13], off offset:256
	v_pk_mul_f32 v[2:3], v[96:97], v[2:3] op_sel:[1,0]
	v_cndmask_b32_e32 v1, v217, v1, vcc
	v_pk_fma_f32 v[2:3], v[22:23], v[2:3], v[34:35]
	v_cndmask_b32_e32 v2, v217, v2, vcc
	v_cndmask_b32_e32 v3, v217, v3, vcc
	v_cvt_pk_bf16_f32 v0, v0, v1
	v_cvt_pk_bf16_f32 v1, v2, v3
	s_waitcnt lgkmcnt(2)
	v_sub_f32_e32 v3, v65, v98
	v_sub_f32_e32 v2, v64, v98
	v_pk_mul_f32 v[2:3], v[98:99], v[2:3] op_sel:[1,0]
	v_sub_f32_e32 v13, v67, v98
	v_pk_fma_f32 v[2:3], v[88:89], v[2:3], v[92:93]
	v_sub_f32_e32 v12, v66, v98
	v_cndmask_b32_e32 v2, v217, v2, vcc
	v_pk_mul_f32 v[12:13], v[98:99], v[12:13] op_sel:[1,0]
	v_cndmask_b32_e32 v3, v217, v3, vcc
	v_pk_fma_f32 v[12:13], v[90:91], v[12:13], v[94:95]
	global_store_dwordx2 v[62:63], v[0:1], off offset:288
	v_add_u32_e32 v0, s31, v204
	v_cndmask_b32_e32 v12, v217, v12, vcc
	v_ashrrev_i32_e32 v1, 31, v0
	v_cndmask_b32_e32 v13, v217, v13, vcc
	v_cvt_pk_bf16_f32 v2, v2, v3
	v_lshlrev_b64 v[0:1], 11, v[0:1]
	v_lshl_add_u64 v[0:1], s[14:15], 0, v[0:1]
	v_cvt_pk_bf16_f32 v3, v12, v13
	v_lshl_add_u64 v[0:1], v[0:1], 0, v[176:177]
	global_store_dwordx2 v[0:1], v[2:3], off
	v_sub_f32_e32 v3, v41, v98
	v_sub_f32_e32 v2, v40, v98
	v_pk_mul_f32 v[2:3], v[98:99], v[2:3] op_sel:[1,0]
	v_sub_f32_e32 v13, v43, v98
	v_pk_fma_f32 v[2:3], v[76:77], v[2:3], v[80:81]
	v_sub_f32_e32 v12, v42, v98
	v_cndmask_b32_e32 v2, v217, v2, vcc
	v_pk_mul_f32 v[12:13], v[98:99], v[12:13] op_sel:[1,0]
	v_cndmask_b32_e32 v3, v217, v3, vcc
	v_pk_fma_f32 v[12:13], v[78:79], v[12:13], v[82:83]
	v_cndmask_b32_e32 v12, v217, v12, vcc
	v_cndmask_b32_e32 v13, v217, v13, vcc
	v_cvt_pk_bf16_f32 v2, v2, v3
	v_cvt_pk_bf16_f32 v3, v12, v13
	global_store_dwordx2 v[0:1], v[2:3], off offset:32
	v_sub_f32_e32 v3, v25, v98
	v_sub_f32_e32 v2, v24, v98
	v_pk_mul_f32 v[2:3], v[98:99], v[2:3] op_sel:[1,0]
	v_sub_f32_e32 v13, v27, v98
	v_pk_fma_f32 v[2:3], v[52:53], v[2:3], v[56:57]
	v_sub_f32_e32 v12, v26, v98
	v_cndmask_b32_e32 v2, v217, v2, vcc
	v_pk_mul_f32 v[12:13], v[98:99], v[12:13] op_sel:[1,0]
	v_cndmask_b32_e32 v3, v217, v3, vcc
	v_pk_fma_f32 v[12:13], v[54:55], v[12:13], v[58:59]
	v_cndmask_b32_e32 v12, v217, v12, vcc
	v_cndmask_b32_e32 v13, v217, v13, vcc
	v_cvt_pk_bf16_f32 v2, v2, v3
	v_cvt_pk_bf16_f32 v3, v12, v13
	global_store_dwordx2 v[0:1], v[2:3], off offset:256
	v_sub_f32_e32 v3, v5, v98
	v_sub_f32_e32 v2, v4, v98
	v_pk_mul_f32 v[2:3], v[98:99], v[2:3] op_sel:[1,0]
	v_sub_f32_e32 v5, v7, v98
	v_pk_fma_f32 v[2:3], v[20:21], v[2:3], v[32:33]
	v_sub_f32_e32 v4, v6, v98
	v_cndmask_b32_e32 v2, v217, v2, vcc
	v_pk_mul_f32 v[4:5], v[98:99], v[4:5] op_sel:[1,0]
	v_cndmask_b32_e32 v3, v217, v3, vcc
	v_pk_fma_f32 v[4:5], v[22:23], v[4:5], v[34:35]
	v_cndmask_b32_e32 v4, v217, v4, vcc
	v_cndmask_b32_e32 v5, v217, v5, vcc
	v_cvt_pk_bf16_f32 v2, v2, v3
	v_cvt_pk_bf16_f32 v3, v4, v5
	global_store_dwordx2 v[0:1], v[2:3], off offset:288
	s_waitcnt lgkmcnt(1)
; __device__ __forceinline__ unsigned pk2(float lo, float hi) { return f2bf(lo) | (f2bf(hi) << 16); }
;     __device__ __forceinline__ void fused(f32x4 (&acc)[2][2][4][2], const pg8::Unit& u, int wr, int wc, int fr, int fq, LAS unsigned char* lds, int wid, int lane) const {
;     ...
;             for (int m = 0; m < 4; ++m) { const int r = ai * 128 + wr * 64 + m * 16 + fr; const f32x2v sr = S[r]; const size_t off = (size_t)(u.pm * 256 + r) * DM + col0;
; #pragma unroll
;                 for (int bj = 0; bj < 2; ++bj)
; #pragma unroll
;                     for (int n = 0; n < 2; ++n) { f32x4 o = (acc[ai][bj][m][n] - sr.x) * sr.y * gg[bj][n] + bb[bj][n];
;                         if (bad) o = (f32x4){qnan, qnan, qnan, qnan};
;                         if (outf) *(f32x4*)(outf + off + bj * 128 + n * 16) = o;
;                         if (outb) { u32x2 w; w.x = pk2(o[0], o[1]); w.y = pk2(o[2], o[3]); *(u32x2*)(outb + off + bj * 128 + n * 16) = w; } } }
	v_sub_f32_e32 v3, v69, v100
	v_sub_f32_e32 v2, v68, v100
	v_pk_mul_f32 v[2:3], v[100:101], v[2:3] op_sel:[1,0]
	v_sub_f32_e32 v5, v71, v100
	v_pk_fma_f32 v[2:3], v[88:89], v[2:3], v[92:93]
	v_sub_f32_e32 v4, v70, v100
	v_cndmask_b32_e32 v2, v217, v2, vcc
	v_pk_mul_f32 v[4:5], v[100:101], v[4:5] op_sel:[1,0]
	v_cndmask_b32_e32 v3, v217, v3, vcc
	v_pk_fma_f32 v[4:5], v[90:91], v[4:5], v[94:95]
	v_add_u32_e32 v0, s31, v206
	v_cndmask_b32_e32 v4, v217, v4, vcc
	v_ashrrev_i32_e32 v1, 31, v0
	v_cndmask_b32_e32 v5, v217, v5, vcc
	v_cvt_pk_bf16_f32 v2, v2, v3
	v_lshlrev_b64 v[0:1], 11, v[0:1]
	v_lshl_add_u64 v[0:1], s[14:15], 0, v[0:1]
	v_cvt_pk_bf16_f32 v3, v4, v5
	v_lshl_add_u64 v[0:1], v[0:1], 0, v[176:177]
	global_store_dwordx2 v[0:1], v[2:3], off
	v_sub_f32_e32 v3, v45, v100
	v_sub_f32_e32 v2, v44, v100
	v_pk_mul_f32 v[2:3], v[100:101], v[2:3] op_sel:[1,0]
	v_sub_f32_e32 v5, v47, v100
	v_pk_fma_f32 v[2:3], v[76:77], v[2:3], v[80:81]
	v_sub_f32_e32 v4, v46, v100
	v_cndmask_b32_e32 v2, v217, v2, vcc
	v_pk_mul_f32 v[4:5], v[100:101], v[4:5] op_sel:[1,0]
	v_cndmask_b32_e32 v3, v217, v3, vcc
	v_pk_fma_f32 v[4:5], v[78:79], v[4:5], v[82:83]
	v_cndmask_b32_e32 v4, v217, v4, vcc
	v_cndmask_b32_e32 v5, v217, v5, vcc
	v_cvt_pk_bf16_f32 v2, v2, v3
	v_cvt_pk_bf16_f32 v3, v4, v5
	global_store_dwordx2 v[0:1], v[2:3], off offset:32
	v_sub_f32_e32 v3, v29, v100
	v_sub_f32_e32 v2, v28, v100
	v_pk_mul_f32 v[2:3], v[100:101], v[2:3] op_sel:[1,0]
	v_sub_f32_e32 v5, v31, v100
	v_pk_fma_f32 v[2:3], v[52:53], v[2:3], v[56:57]
	v_sub_f32_e32 v4, v30, v100
	v_cndmask_b32_e32 v2, v217, v2, vcc
	v_pk_mul_f32 v[4:5], v[100:101], v[4:5] op_sel:[1,0]
	v_cndmask_b32_e32 v3, v217, v3, vcc
	v_pk_fma_f32 v[4:5], v[54:55], v[4:5], v[58:59]
	v_cndmask_b32_e32 v4, v217, v4, vcc
	v_cndmask_b32_e32 v5, v217, v5, vcc
	v_cvt_pk_bf16_f32 v2, v2, v3
	v_cvt_pk_bf16_f32 v3, v4, v5
	global_store_dwordx2 v[0:1], v[2:3], off offset:256
	v_sub_f32_e32 v3, v9, v100
	v_sub_f32_e32 v2, v8, v100
	v_pk_mul_f32 v[2:3], v[100:101], v[2:3] op_sel:[1,0]
	v_sub_f32_e32 v5, v11, v100
	v_pk_fma_f32 v[2:3], v[20:21], v[2:3], v[32:33]
	v_sub_f32_e32 v4, v10, v100
	v_cndmask_b32_e32 v2, v217, v2, vcc
	v_pk_mul_f32 v[4:5], v[100:101], v[4:5] op_sel:[1,0]
	v_cndmask_b32_e32 v3, v217, v3, vcc
	v_pk_fma_f32 v[4:5], v[22:23], v[4:5], v[34:35]
	v_cndmask_b32_e32 v4, v217, v4, vcc
	v_cndmask_b32_e32 v5, v217, v5, vcc
	v_cvt_pk_bf16_f32 v2, v2, v3
	v_cvt_pk_bf16_f32 v3, v4, v5
	global_store_dwordx2 v[0:1], v[2:3], off offset:288
	s_waitcnt lgkmcnt(0)
	v_sub_f32_e32 v3, v85, v102
	v_sub_f32_e32 v2, v84, v102
	v_pk_mul_f32 v[2:3], v[102:103], v[2:3] op_sel:[1,0]
	v_sub_f32_e32 v5, v87, v102
	v_pk_fma_f32 v[2:3], v[88:89], v[2:3], v[92:93]
	v_sub_f32_e32 v4, v86, v102
	v_cndmask_b32_e32 v2, v217, v2, vcc
	v_pk_mul_f32 v[4:5], v[102:103], v[4:5] op_sel:[1,0]
	v_cndmask_b32_e32 v3, v217, v3, vcc
	v_pk_fma_f32 v[4:5], v[90:91], v[4:5], v[94:95]
	v_add_u32_e32 v0, s31, v208
	v_cndmask_b32_e32 v4, v217, v4, vcc
	v_ashrrev_i32_e32 v1, 31, v0
	v_cndmask_b32_e32 v5, v217, v5, vcc
	v_cvt_pk_bf16_f32 v2, v2, v3
	v_lshlrev_b64 v[0:1], 11, v[0:1]
	v_lshl_add_u64 v[0:1], s[14:15], 0, v[0:1]
	v_cvt_pk_bf16_f32 v3, v4, v5
	v_lshl_add_u64 v[0:1], v[0:1], 0, v[176:177]
	global_store_dwordx2 v[0:1], v[2:3], off
	v_sub_f32_e32 v3, v73, v102
	v_sub_f32_e32 v2, v72, v102
	v_pk_mul_f32 v[2:3], v[102:103], v[2:3] op_sel:[1,0]
	v_sub_f32_e32 v5, v75, v102
	v_pk_fma_f32 v[2:3], v[76:77], v[2:3], v[80:81]
	v_sub_f32_e32 v4, v74, v102
	v_cndmask_b32_e32 v2, v217, v2, vcc
	v_pk_mul_f32 v[4:5], v[102:103], v[4:5] op_sel:[1,0]
	v_cndmask_b32_e32 v3, v217, v3, vcc
	v_pk_fma_f32 v[4:5], v[78:79], v[4:5], v[82:83]
	v_cndmask_b32_e32 v4, v217, v4, vcc
	v_cndmask_b32_e32 v5, v217, v5, vcc
	v_cvt_pk_bf16_f32 v2, v2, v3
	v_cvt_pk_bf16_f32 v3, v4, v5
	global_store_dwordx2 v[0:1], v[2:3], off offset:32
	v_sub_f32_e32 v3, v49, v102
	v_sub_f32_e32 v2, v48, v102
	v_pk_mul_f32 v[2:3], v[102:103], v[2:3] op_sel:[1,0]
	v_sub_f32_e32 v5, v51, v102
	v_pk_fma_f32 v[2:3], v[52:53], v[2:3], v[56:57]
	v_sub_f32_e32 v4, v50, v102
	v_cndmask_b32_e32 v2, v217, v2, vcc
	v_pk_mul_f32 v[4:5], v[102:103], v[4:5] op_sel:[1,0]
	v_cndmask_b32_e32 v3, v217, v3, vcc
	v_pk_fma_f32 v[4:5], v[54:55], v[4:5], v[58:59]
	v_cndmask_b32_e32 v4, v217, v4, vcc
	v_cndmask_b32_e32 v5, v217, v5, vcc
	v_cvt_pk_bf16_f32 v2, v2, v3
	v_cvt_pk_bf16_f32 v3, v4, v5
	global_store_dwordx2 v[0:1], v[2:3], off offset:256
	v_sub_f32_e32 v3, v17, v102
	v_sub_f32_e32 v2, v16, v102
	v_pk_mul_f32 v[2:3], v[102:103], v[2:3] op_sel:[1,0]
	v_sub_f32_e32 v5, v19, v102
	v_pk_fma_f32 v[2:3], v[20:21], v[2:3], v[32:33]
	v_sub_f32_e32 v4, v18, v102
	v_cndmask_b32_e32 v2, v217, v2, vcc
	v_pk_mul_f32 v[4:5], v[102:103], v[4:5] op_sel:[1,0]
	v_cndmask_b32_e32 v3, v217, v3, vcc
	v_pk_fma_f32 v[4:5], v[22:23], v[4:5], v[34:35]
	v_cndmask_b32_e32 v4, v217, v4, vcc
	v_cndmask_b32_e32 v5, v217, v5, vcc
	v_cvt_pk_bf16_f32 v2, v2, v3
	v_cvt_pk_bf16_f32 v3, v4, v5
	s_andn2_b64 vcc, exec, s[8:9]
	s_mov_b64 s[8:9], -1
	global_store_dwordx2 v[0:1], v[2:3], off offset:288
	s_cbranch_vccnz .LBB0_1866
	s_andn2_b64 vcc, exec, s[16:17]
	s_cbranch_vccnz .LBB0_1865
	s_barrier
	s_branch .LBB0_1865

; __device__ __forceinline__ unsigned pk2(float lo, float hi) { return f2bf(lo) | (f2bf(hi) << 16); }
; __device__ __forceinline__ float sigmoidf_(float x) { return __builtin_amdgcn_rcpf(1.0f + __expf(-x)); }
; __device__ __forceinline__ void st8bf(bf16_t* p, f32x4 a, f32x4 b) { u32x4 w; w.x = pk2(a[0], a[1]); w.y = pk2(a[2], a[3]); w.z = pk2(b[0], b[1]); w.w = pk2(b[2], b[3]); st16(p, w); }
; __device__ __forceinline__ void stnt8(float* o, f32x4 a, f32x4 b) { __builtin_nontemporal_store(a, (f32x4*)o); __builtin_nontemporal_store(b, (f32x4*)(o + 4)); }
; __device__ __forceinline__ f32x4 sig4(f32x4 v) { f32x4 r; r[0] = sigmoidf_(v[0]); r[1] = sigmoidf_(v[1]); r[2] = sigmoidf_(v[2]); r[3] = sigmoidf_(v[3]); return r; }
;     __device__ __forceinline__ void st(int pn, int row, int c, f32x4 v0, f32x4 v1) const {
;     ...
;         else st8bf(GT + (size_t)row * 1024 + (pn - 4) * 256 + c, v0 * sig4(v0), v1 * sig4(v1));
.LBB0_2117:
	v_lshl_add_u64 v[104:105], s[54:55], 0, v[118:119]
	v_mul_f32_e32 v106, 0xbfb8aa3b, v100
	v_exp_f32_e32 v106, v106
	v_lshl_add_u64 v[104:105], s[60:61], 1, v[104:105]
	v_lshlrev_b32_e32 v138, 1, v140
	v_lshl_add_u64 v[108:109], v[104:105], 0, v[138:139]
	v_mul_f32_e32 v105, 0xbfb8aa3b, v101
	v_exp_f32_e32 v105, v105
	v_add_f32_e32 v104, 1.0, v106
	v_mul_f32_e32 v106, 0xbfb8aa3b, v102
	v_mul_f32_e32 v107, 0xbfb8aa3b, v103
	v_exp_f32_e32 v106, v106
	v_exp_f32_e32 v107, v107
	v_add_f32_e32 v105, 1.0, v105
	v_rcp_f32_e32 v104, v104
	v_rcp_f32_e32 v105, v105
	v_mul_f32_e32 v110, 0xbfb8aa3b, v96
	v_mul_f32_e32 v111, 0xbfb8aa3b, v97
	v_exp_f32_e32 v110, v110
	v_exp_f32_e32 v111, v111
	v_add_f32_e32 v106, 1.0, v106
	v_add_f32_e32 v107, 1.0, v107
	v_rcp_f32_e32 v106, v106
	v_rcp_f32_e32 v107, v107
	v_mul_f32_e32 v118, 0xbfb8aa3b, v98
	v_mul_f32_e32 v119, 0xbfb8aa3b, v99
	v_exp_f32_e32 v118, v118
	v_exp_f32_e32 v119, v119
	v_pk_mul_f32 v[104:105], v[100:101], v[104:105]
	v_add_f32_e32 v110, 1.0, v110
	v_add_f32_e32 v111, 1.0, v111
	v_rcp_f32_e32 v110, v110
	v_rcp_f32_e32 v111, v111
	v_pk_mul_f32 v[106:107], v[102:103], v[106:107]
	v_add_f32_e32 v118, 1.0, v118
	v_add_f32_e32 v119, 1.0, v119
	v_cvt_pk_bf16_f32 v104, v104, v105
	v_rcp_f32_e32 v118, v118
	v_rcp_f32_e32 v119, v119
	v_pk_mul_f32 v[110:111], v[96:97], v[110:111]
	v_cvt_pk_bf16_f32 v105, v106, v107
	v_pk_mul_f32 v[118:119], v[98:99], v[118:119]
	v_cvt_pk_bf16_f32 v106, v110, v111
	v_cvt_pk_bf16_f32 v107, v118, v119
	global_store_dwordx4 v[108:109], v[104:107], off offset:256
	s_cbranch_execnz .LBB0_2137

; __device__ __forceinline__ unsigned pk2(float lo, float hi) { return f2bf(lo) | (f2bf(hi) << 16); }
; __device__ __forceinline__ float sigmoidf_(float x) { return __builtin_amdgcn_rcpf(1.0f + __expf(-x)); }
; __device__ __forceinline__ void st8bf(bf16_t* p, f32x4 a, f32x4 b) { u32x4 w; w.x = pk2(a[0], a[1]); w.y = pk2(a[2], a[3]); w.z = pk2(b[0], b[1]); w.w = pk2(b[2], b[3]); st16(p, w); }
; __device__ __forceinline__ void stnt8(float* o, f32x4 a, f32x4 b) { __builtin_nontemporal_store(a, (f32x4*)o); __builtin_nontemporal_store(b, (f32x4*)(o + 4)); }
; __device__ __forceinline__ f32x4 sig4(f32x4 v) { f32x4 r; r[0] = sigmoidf_(v[0]); r[1] = sigmoidf_(v[1]); r[2] = sigmoidf_(v[2]); r[3] = sigmoidf_(v[3]); return r; }
;     __device__ __forceinline__ void st(int pn, int row, int c, f32x4 v0, f32x4 v1) const {
;     ...
;         else st8bf(GT + (size_t)row * 1024 + (pn - 4) * 256 + c, v0 * sig4(v0), v1 * sig4(v1));
.LBB0_2161:
	v_lshl_add_u64 v[88:89], s[54:55], 0, v[102:103]
	v_mul_f32_e32 v90, 0xbfb8aa3b, v84
	v_exp_f32_e32 v90, v90
	v_lshl_add_u64 v[88:89], s[60:61], 1, v[88:89]
	v_lshlrev_b32_e32 v138, 1, v140
	v_lshl_add_u64 v[92:93], v[88:89], 0, v[138:139]
	v_mul_f32_e32 v89, 0xbfb8aa3b, v85
	v_exp_f32_e32 v89, v89
	v_add_f32_e32 v88, 1.0, v90
	v_mul_f32_e32 v90, 0xbfb8aa3b, v86
	v_mul_f32_e32 v91, 0xbfb8aa3b, v87
	v_exp_f32_e32 v90, v90
	v_exp_f32_e32 v91, v91
	v_add_f32_e32 v89, 1.0, v89
	v_rcp_f32_e32 v88, v88
	v_rcp_f32_e32 v89, v89
	v_mul_f32_e32 v94, 0xbfb8aa3b, v80
	v_mul_f32_e32 v95, 0xbfb8aa3b, v81
	v_exp_f32_e32 v94, v94
	v_exp_f32_e32 v95, v95
	v_add_f32_e32 v90, 1.0, v90
	v_add_f32_e32 v91, 1.0, v91
	v_rcp_f32_e32 v90, v90
	v_rcp_f32_e32 v91, v91
	v_mul_f32_e32 v102, 0xbfb8aa3b, v82
	v_mul_f32_e32 v103, 0xbfb8aa3b, v83
	v_exp_f32_e32 v102, v102
	v_exp_f32_e32 v103, v103
	v_pk_mul_f32 v[88:89], v[84:85], v[88:89]
	v_add_f32_e32 v94, 1.0, v94
	v_add_f32_e32 v95, 1.0, v95
	v_rcp_f32_e32 v94, v94
	v_rcp_f32_e32 v95, v95
	v_pk_mul_f32 v[90:91], v[86:87], v[90:91]
	v_add_f32_e32 v102, 1.0, v102
	v_add_f32_e32 v103, 1.0, v103
	v_cvt_pk_bf16_f32 v88, v88, v89
	v_rcp_f32_e32 v102, v102
	v_rcp_f32_e32 v103, v103
	v_pk_mul_f32 v[94:95], v[80:81], v[94:95]
	v_cvt_pk_bf16_f32 v89, v90, v91
	v_pk_mul_f32 v[102:103], v[82:83], v[102:103]
	v_cvt_pk_bf16_f32 v90, v94, v95
	v_cvt_pk_bf16_f32 v91, v102, v103
	global_store_dwordx4 v[92:93], v[88:91], off offset:256
	s_cbranch_execnz .LBB0_2181

; __device__ __forceinline__ unsigned pk2(float lo, float hi) { return f2bf(lo) | (f2bf(hi) << 16); }
; __device__ __forceinline__ float sigmoidf_(float x) { return __builtin_amdgcn_rcpf(1.0f + __expf(-x)); }
; __device__ __forceinline__ void st8bf(bf16_t* p, f32x4 a, f32x4 b) { u32x4 w; w.x = pk2(a[0], a[1]); w.y = pk2(a[2], a[3]); w.z = pk2(b[0], b[1]); w.w = pk2(b[2], b[3]); st16(p, w); }
; __device__ __forceinline__ void stnt8(float* o, f32x4 a, f32x4 b) { __builtin_nontemporal_store(a, (f32x4*)o); __builtin_nontemporal_store(b, (f32x4*)(o + 4)); }
; __device__ __forceinline__ f32x4 sig4(f32x4 v) { f32x4 r; r[0] = sigmoidf_(v[0]); r[1] = sigmoidf_(v[1]); r[2] = sigmoidf_(v[2]); r[3] = sigmoidf_(v[3]); return r; }
;     __device__ __forceinline__ void st(int pn, int row, int c, f32x4 v0, f32x4 v1) const {
;     ...
;         else st8bf(GT + (size_t)row * 1024 + (pn - 4) * 256 + c, v0 * sig4(v0), v1 * sig4(v1));
.LBB0_2205:
	v_lshl_add_u64 v[72:73], s[54:55], 0, v[86:87]
	v_mul_f32_e32 v74, 0xbfb8aa3b, v68
	v_exp_f32_e32 v74, v74
	v_lshl_add_u64 v[72:73], s[60:61], 1, v[72:73]
	v_lshlrev_b32_e32 v138, 1, v140
	v_lshl_add_u64 v[76:77], v[72:73], 0, v[138:139]
	v_mul_f32_e32 v73, 0xbfb8aa3b, v69
	v_exp_f32_e32 v73, v73
	v_add_f32_e32 v72, 1.0, v74
	v_mul_f32_e32 v74, 0xbfb8aa3b, v70
	v_mul_f32_e32 v75, 0xbfb8aa3b, v71
	v_exp_f32_e32 v74, v74
	v_exp_f32_e32 v75, v75
	v_add_f32_e32 v73, 1.0, v73
	v_rcp_f32_e32 v72, v72
	v_rcp_f32_e32 v73, v73
	v_mul_f32_e32 v78, 0xbfb8aa3b, v64
	v_mul_f32_e32 v79, 0xbfb8aa3b, v65
	v_exp_f32_e32 v78, v78
	v_exp_f32_e32 v79, v79
	v_add_f32_e32 v74, 1.0, v74
	v_add_f32_e32 v75, 1.0, v75
	v_rcp_f32_e32 v74, v74
	v_rcp_f32_e32 v75, v75
	v_mul_f32_e32 v86, 0xbfb8aa3b, v66
	v_mul_f32_e32 v87, 0xbfb8aa3b, v67
	v_exp_f32_e32 v86, v86
	v_exp_f32_e32 v87, v87
	v_pk_mul_f32 v[72:73], v[68:69], v[72:73]
	v_add_f32_e32 v78, 1.0, v78
	v_add_f32_e32 v79, 1.0, v79
	v_rcp_f32_e32 v78, v78
	v_rcp_f32_e32 v79, v79
	v_pk_mul_f32 v[74:75], v[70:71], v[74:75]
	v_add_f32_e32 v86, 1.0, v86
	v_add_f32_e32 v87, 1.0, v87
	v_cvt_pk_bf16_f32 v72, v72, v73
	v_rcp_f32_e32 v86, v86
	v_rcp_f32_e32 v87, v87
	v_pk_mul_f32 v[78:79], v[64:65], v[78:79]
	v_cvt_pk_bf16_f32 v73, v74, v75
	v_pk_mul_f32 v[86:87], v[66:67], v[86:87]
	v_cvt_pk_bf16_f32 v74, v78, v79
	v_cvt_pk_bf16_f32 v75, v86, v87
	global_store_dwordx4 v[76:77], v[72:75], off offset:256
	s_cbranch_execnz .LBB0_2225

; __device__ __forceinline__ unsigned pk2(float lo, float hi) { return f2bf(lo) | (f2bf(hi) << 16); }
; __device__ __forceinline__ float sigmoidf_(float x) { return __builtin_amdgcn_rcpf(1.0f + __expf(-x)); }
; __device__ __forceinline__ void st8bf(bf16_t* p, f32x4 a, f32x4 b) { u32x4 w; w.x = pk2(a[0], a[1]); w.y = pk2(a[2], a[3]); w.z = pk2(b[0], b[1]); w.w = pk2(b[2], b[3]); st16(p, w); }
; __device__ __forceinline__ void stnt8(float* o, f32x4 a, f32x4 b) { __builtin_nontemporal_store(a, (f32x4*)o); __builtin_nontemporal_store(b, (f32x4*)(o + 4)); }
; __device__ __forceinline__ f32x4 sig4(f32x4 v) { f32x4 r; r[0] = sigmoidf_(v[0]); r[1] = sigmoidf_(v[1]); r[2] = sigmoidf_(v[2]); r[3] = sigmoidf_(v[3]); return r; }
;     __device__ __forceinline__ void st(int pn, int row, int c, f32x4 v0, f32x4 v1) const {
;     ...
;         else st8bf(GT + (size_t)row * 1024 + (pn - 4) * 256 + c, v0 * sig4(v0), v1 * sig4(v1));
.LBB0_2249:
	v_lshl_add_u64 v[56:57], s[54:55], 0, v[70:71]
	v_mul_f32_e32 v58, 0xbfb8aa3b, v52
	v_exp_f32_e32 v58, v58
	v_lshl_add_u64 v[56:57], s[60:61], 1, v[56:57]
	v_lshlrev_b32_e32 v138, 1, v140
	v_lshl_add_u64 v[60:61], v[56:57], 0, v[138:139]
	v_mul_f32_e32 v57, 0xbfb8aa3b, v53
	v_exp_f32_e32 v57, v57
	v_add_f32_e32 v56, 1.0, v58
	v_mul_f32_e32 v58, 0xbfb8aa3b, v54
	v_mul_f32_e32 v59, 0xbfb8aa3b, v55
	v_exp_f32_e32 v58, v58
	v_exp_f32_e32 v59, v59
	v_add_f32_e32 v57, 1.0, v57
	v_rcp_f32_e32 v56, v56
	v_rcp_f32_e32 v57, v57
	v_mul_f32_e32 v62, 0xbfb8aa3b, v48
	v_mul_f32_e32 v63, 0xbfb8aa3b, v49
	v_exp_f32_e32 v62, v62
	v_exp_f32_e32 v63, v63
	v_add_f32_e32 v58, 1.0, v58
	v_add_f32_e32 v59, 1.0, v59
	v_rcp_f32_e32 v58, v58
	v_rcp_f32_e32 v59, v59
	v_mul_f32_e32 v70, 0xbfb8aa3b, v50
	v_mul_f32_e32 v71, 0xbfb8aa3b, v51
	v_exp_f32_e32 v70, v70
	v_exp_f32_e32 v71, v71
	v_pk_mul_f32 v[56:57], v[52:53], v[56:57]
	v_add_f32_e32 v62, 1.0, v62
	v_add_f32_e32 v63, 1.0, v63
	v_rcp_f32_e32 v62, v62
	v_rcp_f32_e32 v63, v63
	v_pk_mul_f32 v[58:59], v[54:55], v[58:59]
	v_add_f32_e32 v70, 1.0, v70
	v_add_f32_e32 v71, 1.0, v71
	v_cvt_pk_bf16_f32 v56, v56, v57
	v_rcp_f32_e32 v70, v70
	v_rcp_f32_e32 v71, v71
	v_pk_mul_f32 v[62:63], v[48:49], v[62:63]
	v_cvt_pk_bf16_f32 v57, v58, v59
	v_pk_mul_f32 v[70:71], v[50:51], v[70:71]
	v_cvt_pk_bf16_f32 v58, v62, v63
	v_cvt_pk_bf16_f32 v59, v70, v71
	global_store_dwordx4 v[60:61], v[56:59], off offset:256
	s_cbranch_execnz .LBB0_2269

; __device__ __forceinline__ unsigned pk2(float lo, float hi) { return f2bf(lo) | (f2bf(hi) << 16); }
; __device__ __forceinline__ float sigmoidf_(float x) { return __builtin_amdgcn_rcpf(1.0f + __expf(-x)); }
; __device__ __forceinline__ void st8bf(bf16_t* p, f32x4 a, f32x4 b) { u32x4 w; w.x = pk2(a[0], a[1]); w.y = pk2(a[2], a[3]); w.z = pk2(b[0], b[1]); w.w = pk2(b[2], b[3]); st16(p, w); }
; __device__ __forceinline__ void stnt8(float* o, f32x4 a, f32x4 b) { __builtin_nontemporal_store(a, (f32x4*)o); __builtin_nontemporal_store(b, (f32x4*)(o + 4)); }
; __device__ __forceinline__ f32x4 sig4(f32x4 v) { f32x4 r; r[0] = sigmoidf_(v[0]); r[1] = sigmoidf_(v[1]); r[2] = sigmoidf_(v[2]); r[3] = sigmoidf_(v[3]); return r; }
;     __device__ __forceinline__ void st(int pn, int row, int c, f32x4 v0, f32x4 v1) const {
;     ...
;         else st8bf(GT + (size_t)row * 1024 + (pn - 4) * 256 + c, v0 * sig4(v0), v1 * sig4(v1));
.LBB0_2293:
	v_lshl_add_u64 v[40:41], s[54:55], 0, v[54:55]
	v_mul_f32_e32 v42, 0xbfb8aa3b, v36
	v_exp_f32_e32 v42, v42
	v_lshl_add_u64 v[40:41], s[60:61], 1, v[40:41]
	v_lshlrev_b32_e32 v138, 1, v140
	v_lshl_add_u64 v[44:45], v[40:41], 0, v[138:139]
	v_mul_f32_e32 v41, 0xbfb8aa3b, v37
	v_exp_f32_e32 v41, v41
	v_add_f32_e32 v40, 1.0, v42
	v_mul_f32_e32 v42, 0xbfb8aa3b, v38
	v_mul_f32_e32 v43, 0xbfb8aa3b, v39
	v_exp_f32_e32 v42, v42
	v_exp_f32_e32 v43, v43
	v_add_f32_e32 v41, 1.0, v41
	v_rcp_f32_e32 v40, v40
	v_rcp_f32_e32 v41, v41
	v_mul_f32_e32 v46, 0xbfb8aa3b, v32
	v_mul_f32_e32 v47, 0xbfb8aa3b, v33
	v_exp_f32_e32 v46, v46
	v_exp_f32_e32 v47, v47
	v_add_f32_e32 v42, 1.0, v42
	v_add_f32_e32 v43, 1.0, v43
	v_rcp_f32_e32 v42, v42
	v_rcp_f32_e32 v43, v43
	v_mul_f32_e32 v54, 0xbfb8aa3b, v34
	v_mul_f32_e32 v55, 0xbfb8aa3b, v35
	v_exp_f32_e32 v54, v54
	v_exp_f32_e32 v55, v55
	v_pk_mul_f32 v[40:41], v[36:37], v[40:41]
	v_add_f32_e32 v46, 1.0, v46
	v_add_f32_e32 v47, 1.0, v47
	v_rcp_f32_e32 v46, v46
	v_rcp_f32_e32 v47, v47
	v_pk_mul_f32 v[42:43], v[38:39], v[42:43]
	v_add_f32_e32 v54, 1.0, v54
	v_add_f32_e32 v55, 1.0, v55
	v_cvt_pk_bf16_f32 v40, v40, v41
	v_rcp_f32_e32 v54, v54
	v_rcp_f32_e32 v55, v55
	v_pk_mul_f32 v[46:47], v[32:33], v[46:47]
	v_cvt_pk_bf16_f32 v41, v42, v43
	v_pk_mul_f32 v[54:55], v[34:35], v[54:55]
	v_cvt_pk_bf16_f32 v42, v46, v47
	v_cvt_pk_bf16_f32 v43, v54, v55
	global_store_dwordx4 v[44:45], v[40:43], off offset:256
	s_cbranch_execnz .LBB0_2313

; __device__ __forceinline__ void st8bf(bf16_t* p, f32x4 a, f32x4 b) { u32x4 w; w.x = pk2(a[0], a[1]); w.y = pk2(a[2], a[3]); w.z = pk2(b[0], b[1]); w.w = pk2(b[2], b[3]); st16(p, w); }
;     __device__ __forceinline__ void st(int pn, int row, int c, f32x4 v0, f32x4 v1) const {
;     ...
;                 const float inv = 1.f / (float)w;
;                 st8bf(DMs + (size_t)row * 1024 + col, (f32x4){s[0] * inv - x[0], s[1] * inv - x[1], s[2] * inv - x[2], s[3] * inv - x[3]}, (f32x4){s[4] * inv - x[4], s[5] * inv - x[5], s[6] * inv - x[6], s[7] * inv - x[7]});
.LBB0_2333:
	s_or_b64 exec, exec, s[74:75]
	v_readlane_b32 s4, v251, 0
	v_readlane_b32 s5, v251, 1
	v_mov_b32_e32 v53, v30
	v_mov_b32_e32 v30, v29
	v_lshl_add_u64 v[50:51], v[32:33], 1, s[4:5]
	v_lshl_add_u64 v[40:41], v[40:41], 1, v[50:51]
	v_mov_b32_e32 v51, v44
	v_mov_b32_e32 v44, v43
	v_mov_b32_e32 v52, v28
	v_pk_fma_f32 v[28:29], s[68:69], v[44:45], v[30:31] op_sel_hi:[0,1,1] neg_lo:[0,0,1] neg_hi:[0,0,1]
	v_mov_b32_e32 v31, v48
	v_mov_b32_e32 v43, v26
	v_mov_b32_e32 v48, v47
	v_mov_b32_e32 v26, v25
	v_mov_b32_e32 v50, v42
	v_mov_b32_e32 v30, v46
	v_mov_b32_e32 v42, v24
	v_pk_fma_f32 v[24:25], s[68:69], v[48:49], v[26:27] op_sel_hi:[0,1,1] neg_lo:[0,0,1] neg_hi:[0,0,1]
	v_pk_fma_f32 v[50:51], s[68:69], v[50:51], v[52:53] op_sel_hi:[0,1,1] neg_lo:[0,0,1] neg_hi:[0,0,1]
	v_pk_fma_f32 v[30:31], s[68:69], v[30:31], v[42:43] op_sel_hi:[0,1,1] neg_lo:[0,0,1] neg_hi:[0,0,1]
	v_cvt_pk_bf16_f32 v27, v31, v25
	v_cvt_pk_bf16_f32 v26, v30, v24
	v_cvt_pk_bf16_f32 v25, v51, v29
	v_cvt_pk_bf16_f32 v24, v50, v28
	global_store_dwordx4 v[40:41], v[24:27], off

; __device__ __forceinline__ unsigned pk2(float lo, float hi) { return f2bf(lo) | (f2bf(hi) << 16); }
; __device__ __forceinline__ float sigmoidf_(float x) { return __builtin_amdgcn_rcpf(1.0f + __expf(-x)); }
; __device__ __forceinline__ void st8bf(bf16_t* p, f32x4 a, f32x4 b) { u32x4 w; w.x = pk2(a[0], a[1]); w.y = pk2(a[2], a[3]); w.z = pk2(b[0], b[1]); w.w = pk2(b[2], b[3]); st16(p, w); }
; __device__ __forceinline__ void stnt8(float* o, f32x4 a, f32x4 b) { __builtin_nontemporal_store(a, (f32x4*)o); __builtin_nontemporal_store(b, (f32x4*)(o + 4)); }
; __device__ __forceinline__ f32x4 sig4(f32x4 v) { f32x4 r; r[0] = sigmoidf_(v[0]); r[1] = sigmoidf_(v[1]); r[2] = sigmoidf_(v[2]); r[3] = sigmoidf_(v[3]); return r; }
;     __device__ __forceinline__ void st(int pn, int row, int c, f32x4 v0, f32x4 v1) const {
;     ...
;         else st8bf(GT + (size_t)row * 1024 + (pn - 4) * 256 + c, v0 * sig4(v0), v1 * sig4(v1));
.LBB0_2337:
	v_lshl_add_u64 v[24:25], s[54:55], 0, v[38:39]
	v_mul_f32_e32 v26, 0xbfb8aa3b, v20
	v_exp_f32_e32 v26, v26
	v_lshl_add_u64 v[24:25], s[60:61], 1, v[24:25]
	v_lshlrev_b32_e32 v138, 1, v140
	v_lshl_add_u64 v[28:29], v[24:25], 0, v[138:139]
	v_mul_f32_e32 v25, 0xbfb8aa3b, v21
	v_exp_f32_e32 v25, v25
	v_add_f32_e32 v24, 1.0, v26
	v_mul_f32_e32 v26, 0xbfb8aa3b, v22
	v_mul_f32_e32 v27, 0xbfb8aa3b, v23
	v_exp_f32_e32 v26, v26
	v_exp_f32_e32 v27, v27
	v_add_f32_e32 v25, 1.0, v25
	v_rcp_f32_e32 v24, v24
	v_rcp_f32_e32 v25, v25
	v_mul_f32_e32 v30, 0xbfb8aa3b, v16
	v_mul_f32_e32 v31, 0xbfb8aa3b, v17
	v_exp_f32_e32 v30, v30
	v_exp_f32_e32 v31, v31
	v_add_f32_e32 v26, 1.0, v26
	v_add_f32_e32 v27, 1.0, v27
	v_rcp_f32_e32 v26, v26
	v_rcp_f32_e32 v27, v27
	v_mul_f32_e32 v38, 0xbfb8aa3b, v18
	v_mul_f32_e32 v39, 0xbfb8aa3b, v19
	v_exp_f32_e32 v38, v38
	v_exp_f32_e32 v39, v39
	v_pk_mul_f32 v[24:25], v[20:21], v[24:25]
	v_add_f32_e32 v30, 1.0, v30
	v_add_f32_e32 v31, 1.0, v31
	v_rcp_f32_e32 v30, v30
	v_rcp_f32_e32 v31, v31
	v_pk_mul_f32 v[26:27], v[22:23], v[26:27]
	v_add_f32_e32 v38, 1.0, v38
	v_add_f32_e32 v39, 1.0, v39
	v_cvt_pk_bf16_f32 v24, v24, v25
	v_rcp_f32_e32 v38, v38
	v_rcp_f32_e32 v39, v39
	v_pk_mul_f32 v[30:31], v[16:17], v[30:31]
	v_cvt_pk_bf16_f32 v25, v26, v27
	v_pk_mul_f32 v[38:39], v[18:19], v[38:39]
	v_cvt_pk_bf16_f32 v26, v30, v31
	v_cvt_pk_bf16_f32 v27, v38, v39
	global_store_dwordx4 v[28:29], v[24:27], off offset:256
	s_cbranch_execnz .LBB0_2357
; __device__ __forceinline__ void st16f(float* p, f32x4 v) { st16(p, __builtin_bit_cast(u32x4, v)); }
; __device__ __forceinline__ void st8bf(bf16_t* p, f32x4 a, f32x4 b) { u32x4 w; w.x = pk2(a[0], a[1]); w.y = pk2(a[2], a[3]); w.z = pk2(b[0], b[1]); w.w = pk2(b[2], b[3]); st16(p, w); }
;     __device__ __forceinline__ void st(int pn, int row, int c, f32x4 v0, f32x4 v1) const {
;     ...
;         if (pn < 4) { const int col = pn * 256 + c; float* o = nullptr;
;             if (smp) o = out + O_POOLS + ((size_t)b * 15 + 11 + t) * 1024 + col;
;             st8bf(V + (size_t)row * 1024 + col, v0, v1); if (o) { st16f(o, v0); st16f(o + 4, v1); }
;             if (smp) {
;                 const int w = 2 << pn;
;                 float x[8] = {v0[0], v0[1], v0[2], v0[3], v1[0], v1[1], v1[2], v1[3]}, s[8];
; #pragma unroll
;                 for (int e = 0; e < 8; ++e) { s[e] = 0.f;
; #pragma unroll
;                     for (int tp = 0; tp < 4; ++tp) { const float xo = quad_bcast(x[e], tp); if (tp <= t && t - tp < w) s[e] += xo; } }
;                 const int e_lo = 15 + t - w + 1;
; #pragma unroll
;                 for (int e2 = 0; e2 < 15; ++e2) if (e2 >= e_lo) { const float* sp = state_pool + ((size_t)b * 15 + e2) * 1024 + col; const f32x4 a = *(const f32x4*)sp, d = *(const f32x4*)(sp + 4);
;                     s[0] += a[0]; s[1] += a[1]; s[2] += a[2]; s[3] += a[3]; s[4] += d[0]; s[5] += d[1]; s[6] += d[2]; s[7] += d[3]; }
.LBB0_2338:
	s_ashr_i32 s71, s70, 31
	v_lshl_add_u64 v[26:27], v[32:33], 1, s[52:53]
	v_lshl_add_u64 v[24:25], s[70:71], 0, v[140:141]
	v_lshl_add_u64 v[30:31], v[24:25], 1, v[26:27]
	v_cvt_pk_bf16_f32 v26, v20, v21
	v_cvt_pk_bf16_f32 v27, v22, v23
	v_cvt_pk_bf16_f32 v28, v16, v17
	v_cvt_pk_bf16_f32 v29, v18, v19
	global_store_dwordx4 v[30:31], v[26:29], off offset:256
	s_and_saveexec_b64 s[72:73], s[48:49]
	s_cbranch_execz .LBB0_2356
	v_readlane_b32 s4, v250, 58
	v_readlane_b32 s5, v250, 59
	v_lshlrev_b64 v[38:39], 2, v[24:25]
	s_nop 0
	v_lshl_add_u64 v[26:27], s[4:5], 0, v[36:37]
	v_lshl_add_u64 v[26:27], v[26:27], 0, v[38:39]
	global_store_dwordx4 v[26:27], v[20:23], off offset:512
	global_store_dwordx4 v[26:27], v[16:19], off offset:528
	v_mov_b32_dpp v26, v20 quad_perm:[0,0,0,0] row_mask:0xf bank_mask:0xf bound_ctrl:1
	v_add_f32_e32 v26, 0, v26
	v_cndmask_b32_e64 v26, 0, v26, s[40:41]
	v_readlane_b32 s4, v250, 12
	v_readlane_b32 s16, v250, 24
	v_add_f32_dpp v27, v20, v26 quad_perm:[1,1,1,1] row_mask:0xf bank_mask:0xf bound_ctrl:1
	v_cndmask_b32_e64 v26, v26, v27, s[44:45]
	v_readlane_b32 s17, v250, 25
	v_readlane_b32 s5, v250, 13
	v_add_f32_dpp v27, v20, v26 quad_perm:[2,2,2,2] row_mask:0xf bank_mask:0xf bound_ctrl:1
	v_cndmask_b32_e64 v26, v26, v27, s[42:43]
	v_lshl_add_u64 v[38:39], s[16:17], 0, v[38:39]
	v_lshl_add_u64 v[34:35], v[38:39], 0, v[34:35]
	v_add_f32_dpp v27, v20, v26 quad_perm:[3,3,3,3] row_mask:0xf bank_mask:0xf bound_ctrl:1
	v_cndmask_b32_e64 v26, v26, v27, s[0:1]
	v_readlane_b32 s6, v250, 14
	v_mov_b32_dpp v27, v21 quad_perm:[0,0,0,0] row_mask:0xf bank_mask:0xf bound_ctrl:1
	v_add_f32_e32 v27, 0, v27
	v_cndmask_b32_e64 v27, 0, v27, s[40:41]
	v_readlane_b32 s7, v250, 15
	v_readlane_b32 s8, v250, 16
	v_add_f32_dpp v28, v21, v27 quad_perm:[1,1,1,1] row_mask:0xf bank_mask:0xf bound_ctrl:1
	v_cndmask_b32_e64 v27, v27, v28, s[44:45]
	v_readlane_b32 s9, v250, 17
	v_readlane_b32 s10, v250, 18
	v_add_f32_dpp v28, v21, v27 quad_perm:[2,2,2,2] row_mask:0xf bank_mask:0xf bound_ctrl:1
	v_cndmask_b32_e64 v27, v27, v28, s[42:43]
	v_readlane_b32 s11, v250, 19
	v_readlane_b32 s12, v250, 20
	v_add_f32_dpp v28, v21, v27 quad_perm:[3,3,3,3] row_mask:0xf bank_mask:0xf bound_ctrl:1
	v_cndmask_b32_e64 v27, v27, v28, s[0:1]
	v_readlane_b32 s13, v250, 21
	v_mov_b32_dpp v28, v22 quad_perm:[0,0,0,0] row_mask:0xf bank_mask:0xf bound_ctrl:1
	v_add_f32_e32 v28, 0, v28
	v_cndmask_b32_e64 v28, 0, v28, s[40:41]
	v_readlane_b32 s14, v250, 22
	v_readlane_b32 s15, v250, 23
	v_add_f32_dpp v29, v22, v28 quad_perm:[1,1,1,1] row_mask:0xf bank_mask:0xf bound_ctrl:1
	v_cndmask_b32_e64 v28, v28, v29, s[44:45]
	v_readlane_b32 s18, v250, 26
	v_readlane_b32 s19, v250, 27
	v_add_f32_dpp v29, v22, v28 quad_perm:[2,2,2,2] row_mask:0xf bank_mask:0xf bound_ctrl:1
	v_cndmask_b32_e64 v28, v28, v29, s[42:43]
	s_nop 1
	v_add_f32_dpp v29, v22, v28 quad_perm:[3,3,3,3] row_mask:0xf bank_mask:0xf bound_ctrl:1
	v_cndmask_b32_e64 v28, v28, v29, s[0:1]
	s_nop 0
	v_mov_b32_dpp v29, v23 quad_perm:[0,0,0,0] row_mask:0xf bank_mask:0xf bound_ctrl:1
	v_add_f32_e32 v29, 0, v29
	v_cndmask_b32_e64 v29, 0, v29, s[40:41]
	s_nop 1
	v_add_f32_dpp v30, v23, v29 quad_perm:[1,1,1,1] row_mask:0xf bank_mask:0xf bound_ctrl:1
	v_cndmask_b32_e64 v29, v29, v30, s[44:45]
	s_nop 1
	v_add_f32_dpp v30, v23, v29 quad_perm:[2,2,2,2] row_mask:0xf bank_mask:0xf bound_ctrl:1
	v_cndmask_b32_e64 v29, v29, v30, s[42:43]
	s_nop 1
	v_add_f32_dpp v30, v23, v29 quad_perm:[3,3,3,3] row_mask:0xf bank_mask:0xf bound_ctrl:1
	v_cndmask_b32_e64 v29, v29, v30, s[0:1]
	s_nop 0
	v_mov_b32_dpp v30, v16 quad_perm:[0,0,0,0] row_mask:0xf bank_mask:0xf bound_ctrl:1
	v_add_f32_e32 v30, 0, v30
	v_cndmask_b32_e64 v30, 0, v30, s[40:41]
	s_nop 1
	v_add_f32_dpp v31, v16, v30 quad_perm:[1,1,1,1] row_mask:0xf bank_mask:0xf bound_ctrl:1
	v_cndmask_b32_e64 v30, v30, v31, s[44:45]
	s_nop 1
	v_add_f32_dpp v31, v16, v30 quad_perm:[2,2,2,2] row_mask:0xf bank_mask:0xf bound_ctrl:1
	v_cndmask_b32_e64 v30, v30, v31, s[42:43]
	s_nop 1
	v_add_f32_dpp v31, v16, v30 quad_perm:[3,3,3,3] row_mask:0xf bank_mask:0xf bound_ctrl:1
	v_cndmask_b32_e64 v30, v30, v31, s[0:1]
	s_nop 0
	v_mov_b32_dpp v31, v17 quad_perm:[0,0,0,0] row_mask:0xf bank_mask:0xf bound_ctrl:1
	v_add_f32_e32 v31, 0, v31
	v_cndmask_b32_e64 v31, 0, v31, s[40:41]
	s_nop 1
	v_add_f32_dpp v36, v17, v31 quad_perm:[1,1,1,1] row_mask:0xf bank_mask:0xf bound_ctrl:1
	v_cndmask_b32_e64 v31, v31, v36, s[44:45]
	s_nop 1
	v_add_f32_dpp v36, v17, v31 quad_perm:[2,2,2,2] row_mask:0xf bank_mask:0xf bound_ctrl:1
	v_cndmask_b32_e64 v31, v31, v36, s[42:43]
	s_nop 1
	v_add_f32_dpp v36, v17, v31 quad_perm:[3,3,3,3] row_mask:0xf bank_mask:0xf bound_ctrl:1
	v_cndmask_b32_e64 v31, v31, v36, s[0:1]
	s_nop 0
	v_mov_b32_dpp v36, v18 quad_perm:[0,0,0,0] row_mask:0xf bank_mask:0xf bound_ctrl:1
	v_add_f32_e32 v36, 0, v36
	v_cndmask_b32_e64 v36, 0, v36, s[40:41]
	s_nop 1
	v_add_f32_dpp v37, v18, v36 quad_perm:[1,1,1,1] row_mask:0xf bank_mask:0xf bound_ctrl:1
	v_cndmask_b32_e64 v36, v36, v37, s[44:45]
	s_nop 1
	v_add_f32_dpp v37, v18, v36 quad_perm:[2,2,2,2] row_mask:0xf bank_mask:0xf bound_ctrl:1
	v_cndmask_b32_e64 v36, v36, v37, s[42:43]
	s_nop 1
	v_add_f32_dpp v37, v18, v36 quad_perm:[3,3,3,3] row_mask:0xf bank_mask:0xf bound_ctrl:1
	v_cndmask_b32_e64 v36, v36, v37, s[0:1]
	s_nop 0
	v_mov_b32_dpp v37, v19 quad_perm:[0,0,0,0] row_mask:0xf bank_mask:0xf bound_ctrl:1
	v_add_f32_e32 v37, 0, v37
	v_cndmask_b32_e64 v37, 0, v37, s[40:41]
	s_nop 1
	v_add_f32_dpp v40, v19, v37 quad_perm:[1,1,1,1] row_mask:0xf bank_mask:0xf bound_ctrl:1
	v_cndmask_b32_e64 v37, v37, v40, s[44:45]
	s_nop 1
	v_add_f32_dpp v40, v19, v37 quad_perm:[2,2,2,2] row_mask:0xf bank_mask:0xf bound_ctrl:1
	v_cndmask_b32_e64 v37, v37, v40, s[42:43]
	s_nop 1
	v_add_f32_dpp v40, v19, v37 quad_perm:[3,3,3,3] row_mask:0xf bank_mask:0xf bound_ctrl:1
	v_cndmask_b32_e64 v37, v37, v40, s[0:1]
	s_and_saveexec_b64 s[48:49], s[38:39]
	s_cbranch_execz .LBB0_2586
	global_load_dwordx4 v[38:41], v[34:35], off offset:528
	global_load_dwordx4 v[42:45], v[34:35], off offset:512
	s_waitcnt vmcnt(0)
	v_pk_add_f32 v[30:31], v[30:31], v[38:39]
	v_pk_add_f32 v[36:37], v[36:37], v[40:41]
	v_pk_add_f32 v[28:29], v[28:29], v[44:45]
	v_pk_add_f32 v[26:27], v[26:27], v[42:43]
	s_or_b64 exec, exec, s[48:49]
	s_and_saveexec_b64 s[48:49], s[36:37]
	s_cbranch_execnz .LBB0_2587

; __device__ __forceinline__ void st8bf(bf16_t* p, f32x4 a, f32x4 b) { u32x4 w; w.x = pk2(a[0], a[1]); w.y = pk2(a[2], a[3]); w.z = pk2(b[0], b[1]); w.w = pk2(b[2], b[3]); st16(p, w); }
;     __device__ __forceinline__ void st(int pn, int row, int c, f32x4 v0, f32x4 v1) const {
;     ...
;                 const float inv = 1.f / (float)w;
;                 st8bf(DMs + (size_t)row * 1024 + col, (f32x4){s[0] * inv - x[0], s[1] * inv - x[1], s[2] * inv - x[2], s[3] * inv - x[3]}, (f32x4){s[4] * inv - x[4], s[5] * inv - x[5], s[6] * inv - x[6], s[7] * inv - x[7]});
.LBB0_2355:
	s_or_b64 exec, exec, s[48:49]
	v_readlane_b32 s4, v251, 0
	v_readlane_b32 s5, v251, 1
	v_mov_b32_e32 v35, v22
	v_mov_b32_e32 v22, v21
	v_lshl_add_u64 v[32:33], v[32:33], 1, s[4:5]
	v_lshl_add_u64 v[24:25], v[24:25], 1, v[32:33]
	v_mov_b32_e32 v33, v28
	v_mov_b32_e32 v28, v27
	v_mov_b32_e32 v34, v20
	v_pk_fma_f32 v[20:21], s[68:69], v[28:29], v[22:23] op_sel_hi:[0,1,1] neg_lo:[0,0,1] neg_hi:[0,0,1]
	v_mov_b32_e32 v23, v36
	v_mov_b32_e32 v27, v18
	v_mov_b32_e32 v36, v31
	v_mov_b32_e32 v18, v17
	v_mov_b32_e32 v32, v26
	v_mov_b32_e32 v22, v30
	v_mov_b32_e32 v26, v16
	v_pk_fma_f32 v[16:17], s[68:69], v[36:37], v[18:19] op_sel_hi:[0,1,1] neg_lo:[0,0,1] neg_hi:[0,0,1]
	v_pk_fma_f32 v[32:33], s[68:69], v[32:33], v[34:35] op_sel_hi:[0,1,1] neg_lo:[0,0,1] neg_hi:[0,0,1]
	v_pk_fma_f32 v[22:23], s[68:69], v[22:23], v[26:27] op_sel_hi:[0,1,1] neg_lo:[0,0,1] neg_hi:[0,0,1]
	v_cvt_pk_bf16_f32 v19, v23, v17
	v_cvt_pk_bf16_f32 v18, v22, v16
	v_cvt_pk_bf16_f32 v17, v33, v21
	v_cvt_pk_bf16_f32 v16, v32, v20
	global_store_dwordx4 v[24:25], v[16:19], off offset:256

; __device__ __forceinline__ void acc8(float (&s)[8], const u32x4 x, float sg) {
;     s[0] += sg * bflo(x.x); s[1] += sg * bfhi(x.x); s[2] += sg * bflo(x.y); s[3] += sg * bfhi(x.y); s[4] += sg * bflo(x.z); s[5] += sg * bfhi(x.z); s[6] += sg * bflo(x.w); s[7] += sg * bfhi(x.w);
; }
; __device__ __forceinline__ void fir_tile(const Prm& P, Ctx& C, int pm, int gi) {
;     const bf16_t* Z = (const bf16_t*)(P.ws + WS_V); const bf16_t* GT = (const bf16_t*)(P.ws + WS_GT); bf16_t* MX = (bf16_t*)(P.ws + WS_MX);
;     constexpr int RUN = 16;
;     const int c0 = 256 * gi + (C.tid & 31) * 8, row0 = 256 * pm + (C.tid >> 5) * RUN, w = 2 << gi, t0 = row0 & (SEQ - 1);
;     const bf16_t* zp = Z + (size_t)row0 * 1024 + c0;
;     u32x4 x[RUN + 15];
; #pragma unroll
;     for (int j = 0; j < RUN + 15; ++j) { const int k = j - 15; x[j] = (k >= 1 - w && t0 + k >= 0) ? *(const u32x4*)(zp + (ptrdiff_t)k * 1024) : (u32x4){0u, 0u, 0u, 0u}; }
;     const f32x4 sc0 = *(const f32x4*)(P.pool_scale + c0), sc1 = *(const f32x4*)(P.pool_scale + c0 + 4);
;     float s[8];
; #pragma unroll
;     for (int e = 0; e < 8; ++e) s[e] = 0.f;
; #pragma unroll
;     for (int j = 0; j < 15; ++j) acc8(s, x[j], 1.f);
.LBB0_2760:
	v_readlane_b32 s20, v250, 0
	v_readlane_b32 s22, v250, 2
	v_readlane_b32 s23, v250, 3
	s_waitcnt vmcnt(0)
	v_lshlrev_b32_e32 v199, 16, v93
	v_lshlrev_b32_e32 v198, 16, v92
	v_and_b32_e32 v201, 0xffff0000, v93
	v_and_b32_e32 v200, 0xffff0000, v92
	v_lshlrev_b64 v[92:93], 1, v[168:169]
	v_lshl_add_u64 v[4:5], v[168:169], 2, s[22:23]
	v_lshlrev_b32_e32 v190, 16, v98
	v_and_b32_e32 v192, 0xffff0000, v98
	v_lshlrev_b32_e32 v191, 16, v99
	v_and_b32_e32 v193, 0xffff0000, v99
	v_lshl_add_u64 v[98:99], s[4:5], 0, v[92:93]
	global_load_dwordx4 v[0:3], v[4:5], off offset:16
	s_nop 0
	global_load_dwordx4 v[4:7], v[4:5], off
	v_lshlrev_b32_e32 v186, 16, v96
	v_and_b32_e32 v188, 0xffff0000, v96
	v_lshlrev_b32_e32 v187, 16, v97
	v_and_b32_e32 v189, 0xffff0000, v97
	v_lshl_add_u64 v[96:97], s[6:7], 0, v[92:93]
	v_lshl_add_u64 v[92:93], v[98:99], 0, v[196:197]
	v_lshlrev_b32_e32 v203, 16, v95
	v_lshlrev_b32_e32 v202, 16, v94
	v_and_b32_e32 v205, 0xffff0000, v95
	v_and_b32_e32 v204, 0xffff0000, v94
	global_load_dwordx4 v[92:95], v[92:93], off
	v_and_b32_e32 v217, 0xffff0000, v69
	v_and_b32_e32 v216, 0xffff0000, v68
	v_lshlrev_b32_e32 v207, 16, v65
	v_lshlrev_b32_e32 v206, 16, v64
	v_and_b32_e32 v209, 0xffff0000, v65
	v_and_b32_e32 v208, 0xffff0000, v64
	v_pk_add_f32 v[64:65], v[216:217], 0 op_sel_hi:[1,0]
	v_lshlrev_b32_e32 v175, 16, v85
	v_lshlrev_b32_e32 v174, 16, v84
	v_and_b32_e32 v177, 0xffff0000, v85
	v_and_b32_e32 v176, 0xffff0000, v84
	v_and_b32_e32 v85, 0xffff0000, v73
	v_and_b32_e32 v84, 0xffff0000, v72
	v_pk_add_f32 v[64:65], v[64:65], v[208:209]
	v_and_b32_e32 v183, 0xffff0000, v77
	v_pk_add_f32 v[64:65], v[64:65], v[84:85]
	v_and_b32_e32 v182, 0xffff0000, v76
	v_pk_add_f32 v[64:65], v[64:65], v[200:201]
	v_lshlrev_b32_e32 v137, 16, v105
	v_pk_add_f32 v[64:65], v[64:65], v[188:189]
	v_lshlrev_b32_e32 v136, 16, v104
	v_pk_add_f32 v[64:65], v[64:65], v[182:183]
	v_and_b32_e32 v139, 0xffff0000, v105
	v_and_b32_e32 v138, 0xffff0000, v104
	v_lshlrev_b32_e32 v141, 16, v107
	v_lshlrev_b32_e32 v140, 16, v106
	v_and_b32_e32 v143, 0xffff0000, v107
	v_and_b32_e32 v142, 0xffff0000, v106
	v_lshlrev_b32_e32 v105, 16, v129
	v_lshlrev_b32_e32 v104, 16, v128
	v_and_b32_e32 v107, 0xffff0000, v129
	v_and_b32_e32 v106, 0xffff0000, v128
	v_lshlrev_b32_e32 v129, 16, v81
	v_lshlrev_b32_e32 v128, 16, v80
	v_and_b32_e32 v81, 0xffff0000, v81
	v_and_b32_e32 v80, 0xffff0000, v80
	v_pk_add_f32 v[64:65], v[64:65], v[176:177]
	v_and_b32_e32 v163, 0xffff0000, v117
	v_and_b32_e32 v162, 0xffff0000, v116
	v_pk_add_f32 v[64:65], v[64:65], v[80:81]
	v_and_b32_e32 v155, 0xffff0000, v109
	v_and_b32_e32 v154, 0xffff0000, v108
	v_pk_add_f32 v[64:65], v[64:65], v[162:163]
	v_and_b32_e32 v147, 0xffff0000, v113
	v_and_b32_e32 v146, 0xffff0000, v112
	v_pk_add_f32 v[64:65], v[64:65], v[154:155]
	v_lshlrev_b32_e32 v135, 16, v125
	v_pk_add_f32 v[64:65], v[64:65], v[146:147]
	v_lshlrev_b32_e32 v134, 16, v124
	v_and_b32_e32 v125, 0xffff0000, v125
	v_and_b32_e32 v124, 0xffff0000, v124
	v_pk_add_f32 v[64:65], v[64:65], v[138:139]
	v_lshlrev_b32_e32 v145, 16, v113
	v_lshlrev_b32_e32 v144, 16, v112
	v_and_b32_e32 v113, 0xffff0000, v121
	v_and_b32_e32 v112, 0xffff0000, v120
	v_pk_add_f32 v[64:65], v[64:65], v[124:125]
	v_lshlrev_b32_e32 v169, 16, v77
	v_pk_add_f32 v[64:65], v[64:65], v[112:113]
	v_lshlrev_b32_e32 v168, 16, v76
	v_and_b32_e32 v77, 0xffff0000, v101
	v_and_b32_e32 v76, 0xffff0000, v100
	v_pk_add_f32 v[64:65], v[64:65], v[106:107]
	v_lshlrev_b32_e32 v221, 16, v71
	v_lshlrev_b32_e32 v220, 16, v70
	v_pk_add_f32 v[218:219], v[64:65], v[76:77]
	v_lshlrev_b32_e32 v211, 16, v67
	v_lshlrev_b32_e32 v210, 16, v66
	v_pk_add_f32 v[64:65], v[220:221], 0 op_sel_hi:[1,0]
	v_lshlrev_b32_e32 v165, 16, v119
	v_lshlrev_b32_e32 v164, 16, v118
	v_and_b32_e32 v167, 0xffff0000, v119
	v_and_b32_e32 v166, 0xffff0000, v118
	v_lshlrev_b32_e32 v149, 16, v115
	v_lshlrev_b32_e32 v148, 16, v114
	v_lshlrev_b32_e32 v119, 16, v123
	v_lshlrev_b32_e32 v118, 16, v122
	v_and_b32_e32 v151, 0xffff0000, v115
	v_and_b32_e32 v150, 0xffff0000, v114
	v_and_b32_e32 v115, 0xffff0000, v123
	v_and_b32_e32 v114, 0xffff0000, v122
	v_lshlrev_b32_e32 v123, 16, v101
	v_lshlrev_b32_e32 v122, 16, v100
	v_lshlrev_b32_e32 v101, 16, v75
	v_lshlrev_b32_e32 v100, 16, v74
	v_pk_add_f32 v[64:65], v[64:65], v[210:211]
	v_lshlrev_b32_e32 v185, 16, v79
	v_pk_add_f32 v[64:65], v[64:65], v[100:101]
	v_lshlrev_b32_e32 v184, 16, v78
	v_pk_add_f32 v[64:65], v[64:65], v[202:203]
	v_lshlrev_b32_e32 v179, 16, v87
	v_pk_add_f32 v[64:65], v[64:65], v[190:191]
	v_lshlrev_b32_e32 v178, 16, v86
	v_pk_add_f32 v[64:65], v[64:65], v[184:185]
	v_lshlrev_b32_e32 v153, 16, v109
	v_lshlrev_b32_e32 v152, 16, v108
	v_lshlrev_b32_e32 v157, 16, v111
	v_lshlrev_b32_e32 v156, 16, v110
	v_and_b32_e32 v159, 0xffff0000, v111
	v_and_b32_e32 v158, 0xffff0000, v110
	v_lshlrev_b32_e32 v109, 16, v131
	v_lshlrev_b32_e32 v108, 16, v130
	v_and_b32_e32 v111, 0xffff0000, v131
	v_and_b32_e32 v110, 0xffff0000, v130
	v_lshlrev_b32_e32 v131, 16, v73
	v_lshlrev_b32_e32 v130, 16, v72
	v_lshlrev_b32_e32 v73, 16, v83
	v_lshlrev_b32_e32 v72, 16, v82
; __device__ __forceinline__ unsigned f2bf(float f) { unsigned u = __builtin_bit_cast(unsigned, f); return (u + 0x7fffu + ((u >> 16) & 1u)) >> 16; }
; __device__ __forceinline__ unsigned pk2(float lo, float hi) { return f2bf(lo) | (f2bf(hi) << 16); }
; __device__ __forceinline__ void fir_tile(const Prm& P, Ctx& C, int pm, int gi) {
;     ...
;     for (int j = 0; j < 15; ++j) acc8(s, x[j], 1.f);
; #pragma unroll
;     for (int j = 0; j < RUN; ++j) {
;         const int t = t0 + j;
;         const u32x4 g = *(const u32x4*)(GT + (size_t)(row0 + j) * 1024 + c0);
;         acc8(s, x[15 + j], 1.f);
;         const float inv = 1.f / (float)(t + 1 < w ? t + 1 : w);
;         const u32x4 xc = x[15 + j];
;         u32x4 o;
;         o.x = pk2((s[0] * inv - bflo(xc.x)) * sc0[0] * bflo(g.x), (s[1] * inv - bfhi(xc.x)) * sc0[1] * bfhi(g.x));
;         o.y = pk2((s[2] * inv - bflo(xc.y)) * sc0[2] * bflo(g.y), (s[3] * inv - bfhi(xc.y)) * sc0[3] * bfhi(g.y));
;         o.z = pk2((s[4] * inv - bflo(xc.z)) * sc1[0] * bflo(g.z), (s[5] * inv - bfhi(xc.z)) * sc1[1] * bfhi(g.z));
;         o.w = pk2((s[6] * inv - bflo(xc.w)) * sc1[2] * bflo(g.w), (s[7] * inv - bfhi(xc.w)) * sc1[3] * bfhi(g.w));
;         *(u32x4*)(MX + (size_t)(row0 + j) * 1024 + c0) = o;
;         if (w == 2) acc8(s, x[15 + j - 1], -1.f); else if (w == 4) acc8(s, x[15 + j - 3], -1.f); else if (w == 8) acc8(s, x[15 + j - 7], -1.f); else acc8(s, x[j], -1.f);
	v_pk_add_f32 v[64:65], v[64:65], v[178:179]
	v_lshlrev_b32_e32 v161, 16, v117
	v_pk_add_f32 v[64:65], v[64:65], v[72:73]
	v_lshlrev_b32_e32 v160, 16, v116
	v_pk_add_f32 v[64:65], v[64:65], v[164:165]
	v_lshlrev_b32_e32 v117, 16, v121
	v_pk_add_f32 v[64:65], v[64:65], v[156:157]
	v_lshlrev_b32_e32 v116, 16, v120
	v_pk_add_f32 v[64:65], v[64:65], v[148:149]
	v_lshlrev_b32_e32 v121, 16, v127
	v_lshlrev_b32_e32 v120, 16, v126
	v_pk_add_f32 v[64:65], v[64:65], v[140:141]
	v_lshlrev_b32_e32 v213, 16, v69
	v_pk_add_f32 v[64:65], v[64:65], v[120:121]
	v_lshlrev_b32_e32 v212, 16, v68
	v_pk_add_f32 v[64:65], v[64:65], v[118:119]
	v_pk_add_f32 v[170:171], v[212:213], 0 op_sel_hi:[1,0]
	v_lshlrev_b32_e32 v69, 16, v103
	v_lshlrev_b32_e32 v68, 16, v102
	v_pk_add_f32 v[64:65], v[64:65], v[108:109]
	v_and_b32_e32 v195, 0xffff0000, v79
	v_and_b32_e32 v194, 0xffff0000, v78
	v_and_b32_e32 v79, 0xffff0000, v71
	v_and_b32_e32 v78, 0xffff0000, v70
	v_pk_add_f32 v[170:171], v[170:171], v[206:207]
	v_pk_add_f32 v[222:223], v[64:65], v[68:69]
	v_and_b32_e32 v71, 0xffff0000, v67
	v_and_b32_e32 v70, 0xffff0000, v66
	v_pk_add_f32 v[64:65], v[78:79], 0 op_sel_hi:[1,0]
	v_pk_add_f32 v[170:171], v[170:171], v[130:131]
	v_and_b32_e32 v181, 0xffff0000, v87
	v_and_b32_e32 v180, 0xffff0000, v86
	v_and_b32_e32 v87, 0xffff0000, v75
	v_and_b32_e32 v86, 0xffff0000, v74
	v_pk_add_f32 v[64:65], v[64:65], v[70:71]
	v_pk_add_f32 v[170:171], v[170:171], v[198:199]
	v_pk_add_f32 v[64:65], v[64:65], v[86:87]
	v_pk_add_f32 v[170:171], v[170:171], v[186:187]
	v_pk_add_f32 v[64:65], v[64:65], v[204:205]
	v_or_b32_e32 v133, 1, v226
	v_pk_add_f32 v[170:171], v[170:171], v[168:169]
	v_pk_add_f32 v[64:65], v[64:65], v[192:193]
	v_pk_add_f32 v[170:171], v[170:171], v[174:175]
	v_pk_add_f32 v[64:65], v[64:65], v[194:195]
	v_min_i32_e32 v66, s16, v133
	v_pk_add_f32 v[170:171], v[170:171], v[128:129]
	v_and_b32_e32 v173, 0xffff0000, v83
	v_and_b32_e32 v172, 0xffff0000, v82
	v_pk_add_f32 v[64:65], v[64:65], v[180:181]
	v_cvt_f32_i32_e32 v74, v66
	v_pk_add_f32 v[170:171], v[170:171], v[160:161]
	v_pk_add_f32 v[64:65], v[64:65], v[172:173]
	v_pk_add_f32 v[170:171], v[170:171], v[152:153]
	v_pk_add_f32 v[64:65], v[64:65], v[166:167]
	v_pk_add_f32 v[170:171], v[170:171], v[144:145]
	v_pk_add_f32 v[64:65], v[64:65], v[158:159]
	v_pk_add_f32 v[170:171], v[170:171], v[136:137]
	v_pk_add_f32 v[64:65], v[64:65], v[150:151]
	v_div_scale_f32 v75, s[10:11], v74, v74, 1.0
	v_and_b32_e32 v127, 0xffff0000, v127
	v_and_b32_e32 v126, 0xffff0000, v126
	v_pk_add_f32 v[170:171], v[170:171], v[134:135]
	v_pk_add_f32 v[64:65], v[64:65], v[142:143]
	v_rcp_f32_e32 v82, v75
	v_pk_add_f32 v[170:171], v[170:171], v[116:117]
	v_pk_add_f32 v[64:65], v[64:65], v[126:127]
	v_pk_add_f32 v[170:171], v[170:171], v[104:105]
	v_pk_add_f32 v[64:65], v[64:65], v[114:115]
	v_pk_add_f32 v[214:215], v[170:171], v[122:123]
	v_and_b32_e32 v171, 0xffff0000, v103
	v_and_b32_e32 v170, 0xffff0000, v102
	v_pk_add_f32 v[64:65], v[64:65], v[110:111]
	s_waitcnt vmcnt(0)
	v_lshlrev_b32_e32 v103, 16, v93
	v_pk_add_f32 v[66:67], v[64:65], v[170:171]
	v_fma_f32 v64, -v75, v82, 1.0
	v_fmac_f32_e32 v82, v64, v82
	v_div_scale_f32 v64, vcc, 1.0, v74, 1.0
	v_mul_f32_e32 v65, v64, v82
	v_fma_f32 v83, -v75, v65, v64
	v_fmac_f32_e32 v65, v83, v82
	v_fma_f32 v64, -v75, v65, v64
	v_div_fmas_f32 v64, v64, v82, v65
	v_div_fixup_f32 v74, v64, v74, 1.0
	v_pk_fma_f32 v[82:83], v[74:75], v[214:215], v[122:123] op_sel_hi:[0,1,1] neg_lo:[0,0,1] neg_hi:[0,0,1]
	v_mov_b32_e32 v64, v4
	v_mov_b32_e32 v65, v6
	v_pk_mul_f32 v[82:83], v[82:83], v[64:65]
	v_lshlrev_b32_e32 v102, 16, v92
	v_pk_mul_f32 v[82:83], v[82:83], v[102:103]
	v_pk_fma_f32 v[102:103], v[74:75], v[218:219], v[76:77] op_sel_hi:[0,1,1] neg_lo:[0,0,1] neg_hi:[0,0,1]
	v_mov_b32_e32 v6, v5
	v_pk_mul_f32 v[4:5], v[102:103], v[6:7]
	v_and_b32_e32 v93, 0xffff0000, v93
	v_and_b32_e32 v92, 0xffff0000, v92
	v_pk_mul_f32 v[92:93], v[4:5], v[92:93]
	v_pk_fma_f32 v[102:103], v[74:75], v[222:223], v[68:69] op_sel_hi:[0,1,1] neg_lo:[0,0,1] neg_hi:[0,0,1]
	v_mov_b32_e32 v5, v2
	v_pk_fma_f32 v[74:75], v[74:75], v[66:67], v[170:171] op_sel_hi:[0,1,1] neg_lo:[0,0,1] neg_hi:[0,0,1]
	v_mov_b32_e32 v2, v1
	v_mov_b32_e32 v4, v0
	v_pk_mul_f32 v[0:1], v[74:75], v[2:3]
	v_and_b32_e32 v75, 0xffff0000, v95
	v_and_b32_e32 v74, 0xffff0000, v94
	v_pk_mul_f32 v[102:103], v[102:103], v[4:5]
	v_lshlrev_b32_e32 v229, 16, v95
	v_lshlrev_b32_e32 v228, 16, v94
	v_pk_mul_f32 v[0:1], v[0:1], v[74:75]
	v_pk_mul_f32 v[102:103], v[102:103], v[228:229]
	s_movk_i32 s1, 0x7fff
	s_mov_b32 s0, 0xffff0000
	v_cvt_pk_bf16_f32 v95, v103, v1
	v_cvt_pk_bf16_f32 v94, v102, v0
	v_cvt_pk_bf16_f32 v93, v83, v93
	v_cvt_pk_bf16_f32 v92, v82, v92
	v_lshl_add_u64 v[0:1], v[96:97], 0, v[196:197]
	s_cmp_lt_i32 s14, 1
	v_readlane_b32 s21, v250, 1
	v_readlane_b32 s24, v250, 4
	v_readlane_b32 s25, v250, 5
	v_readlane_b32 s26, v250, 6
	v_readlane_b32 s27, v250, 7
	global_store_dwordx4 v[0:1], v[92:95], off
	s_cbranch_scc1 .LBB0_2765
	s_cmp_gt_i32 s14, 1
	s_cbranch_scc0 .LBB0_2766
	s_cmp_eq_u32 s14, 2
	s_mov_b64 s[0:1], -1
	s_cbranch_scc0 .LBB0_2764
	s_mov_b64 s[0:1], 0

; __device__ __forceinline__ unsigned f2bf(float f) { unsigned u = __builtin_bit_cast(unsigned, f); return (u + 0x7fffu + ((u >> 16) & 1u)) >> 16; }
; __device__ __forceinline__ unsigned pk2(float lo, float hi) { return f2bf(lo) | (f2bf(hi) << 16); }
; __device__ __forceinline__ void fir_tile(const Prm& P, Ctx& C, int pm, int gi) {
;     ...
;     for (int j = 0; j < RUN; ++j) {
;         const int t = t0 + j;
;         const u32x4 g = *(const u32x4*)(GT + (size_t)(row0 + j) * 1024 + c0);
;         acc8(s, x[15 + j], 1.f);
;         const float inv = 1.f / (float)(t + 1 < w ? t + 1 : w);
;         const u32x4 xc = x[15 + j];
;         u32x4 o;
;         o.x = pk2((s[0] * inv - bflo(xc.x)) * sc0[0] * bflo(g.x), (s[1] * inv - bfhi(xc.x)) * sc0[1] * bfhi(g.x));
;         o.y = pk2((s[2] * inv - bflo(xc.y)) * sc0[2] * bflo(g.y), (s[3] * inv - bfhi(xc.y)) * sc0[3] * bfhi(g.y));
;         o.z = pk2((s[4] * inv - bflo(xc.z)) * sc1[0] * bflo(g.z), (s[5] * inv - bfhi(xc.z)) * sc1[1] * bfhi(g.z));
;         o.w = pk2((s[6] * inv - bflo(xc.w)) * sc1[2] * bflo(g.w), (s[7] * inv - bfhi(xc.w)) * sc1[3] * bfhi(g.w));
;         *(u32x4*)(MX + (size_t)(row0 + j) * 1024 + c0) = o;
;         if (w == 2) acc8(s, x[15 + j - 1], -1.f); else if (w == 4) acc8(s, x[15 + j - 3], -1.f); else if (w == 8) acc8(s, x[15 + j - 7], -1.f); else acc8(s, x[j], -1.f);
.LBB0_2773:
	v_or_b32_e32 v78, 1, v132
	v_ashrrev_i32_e32 v79, 31, v78
	v_lshlrev_b64 v[94:95], 11, v[78:79]
	v_lshl_add_u64 v[78:79], v[98:99], 0, v[94:95]
	global_load_dwordx4 v[228:231], v[78:79], off
	v_pk_add_f32 v[196:197], v[222:223], v[82:83] neg_lo:[0,1] neg_hi:[0,1]
	v_or_b32_e32 v82, 2, v226
	v_min_i32_e32 v82, s16, v82
	v_cvt_f32_i32_e32 v133, v82
	v_pk_add_f32 v[102:103], v[218:219], v[74:75] neg_lo:[0,1] neg_hi:[0,1]
	v_and_b32_e32 v75, 0xffff0000, v89
	v_and_b32_e32 v74, 0xffff0000, v88
	v_pk_add_f32 v[82:83], v[102:103], v[74:75]
	v_div_scale_f32 v102, s[0:1], v133, v133, 1.0
	v_rcp_f32_e32 v103, v102
	v_lshlrev_b32_e32 v79, 16, v91
	v_lshlrev_b32_e32 v78, 16, v90
	v_pk_add_f32 v[212:213], v[66:67], v[92:93] neg_lo:[0,1] neg_hi:[0,1]
	v_lshlrev_b32_e32 v67, 16, v89
	v_lshlrev_b32_e32 v66, 16, v88
	v_pk_add_f32 v[88:89], v[196:197], v[78:79]
	v_fma_f32 v197, -v102, v103, 1.0
	v_div_scale_f32 v196, vcc, 1.0, v133, 1.0
	v_fmac_f32_e32 v103, v197, v103
	v_and_b32_e32 v93, 0xffff0000, v91
	v_and_b32_e32 v92, 0xffff0000, v90
	v_mul_f32_e32 v197, v196, v103
	v_pk_add_f32 v[90:91], v[212:213], v[92:93]
	v_fma_f32 v212, -v102, v197, v196
	v_fmac_f32_e32 v197, v212, v103
	v_fma_f32 v102, -v102, v197, v196
	v_pk_add_f32 v[0:1], v[214:215], v[0:1] neg_lo:[0,1] neg_hi:[0,1]
	v_div_fmas_f32 v102, v102, v103, v197
	v_pk_add_f32 v[0:1], v[0:1], v[66:67]
	v_div_fixup_f32 v102, v102, v133, 1.0
	v_pk_fma_f32 v[196:197], v[102:103], v[0:1], v[66:67] op_sel_hi:[0,1,1] neg_lo:[0,0,1] neg_hi:[0,0,1]
	v_pk_fma_f32 v[212:213], v[102:103], v[82:83], v[74:75] op_sel_hi:[0,1,1] neg_lo:[0,0,1] neg_hi:[0,0,1]
	v_pk_fma_f32 v[214:215], v[102:103], v[88:89], v[78:79] op_sel_hi:[0,1,1] neg_lo:[0,0,1] neg_hi:[0,0,1]
	v_pk_fma_f32 v[102:103], v[102:103], v[90:91], v[92:93] op_sel_hi:[0,1,1] neg_lo:[0,0,1] neg_hi:[0,0,1]
	v_pk_mul_f32 v[196:197], v[64:65], v[196:197]
	v_pk_mul_f32 v[214:215], v[4:5], v[214:215]
	v_pk_mul_f32 v[102:103], v[2:3], v[102:103]
	v_pk_mul_f32 v[212:213], v[6:7], v[212:213]
	s_movk_i32 s11, 0x7fff
	s_mov_b32 s10, 0xffff0000
	v_lshl_add_u64 v[94:95], v[96:97], 0, v[94:95]
	s_cmp_lt_i32 s14, 1
	s_mov_b64 s[0:1], 0
	s_waitcnt vmcnt(0)
	v_lshlrev_b32_e32 v217, 16, v229
	v_lshlrev_b32_e32 v216, 16, v228
	v_lshlrev_b32_e32 v221, 16, v231
	v_lshlrev_b32_e32 v220, 16, v230
	v_and_b32_e32 v223, 0xffff0000, v231
	v_and_b32_e32 v222, 0xffff0000, v230
	v_and_b32_e32 v219, 0xffff0000, v229
	v_and_b32_e32 v218, 0xffff0000, v228
	v_pk_mul_f32 v[196:197], v[196:197], v[216:217]
	v_pk_mul_f32 v[214:215], v[214:215], v[220:221]
	v_pk_mul_f32 v[102:103], v[102:103], v[222:223]
	v_pk_mul_f32 v[212:213], v[212:213], v[218:219]
	v_cvt_pk_bf16_f32 v215, v215, v103
	v_cvt_pk_bf16_f32 v214, v214, v102
	v_cvt_pk_bf16_f32 v213, v197, v213
	v_cvt_pk_bf16_f32 v212, v196, v212
	global_store_dwordx4 v[94:95], v[212:215], off
	s_cbranch_scc1 .LBB0_2776
	s_cmp_gt_i32 s14, 1
	s_cbranch_scc0 .LBB0_2777
	s_cmp_lg_u32 s14, 2
	s_mov_b64 s[12:13], 0
	s_cselect_b64 s[10:11], -1, 0
	s_branch .LBB0_2778

; __device__ __forceinline__ unsigned f2bf(float f) { unsigned u = __builtin_bit_cast(unsigned, f); return (u + 0x7fffu + ((u >> 16) & 1u)) >> 16; }
; __device__ __forceinline__ unsigned pk2(float lo, float hi) { return f2bf(lo) | (f2bf(hi) << 16); }
; __device__ __forceinline__ void fir_tile(const Prm& P, Ctx& C, int pm, int gi) {
;     ...
;     for (int j = 0; j < RUN; ++j) {
;         const int t = t0 + j;
;         const u32x4 g = *(const u32x4*)(GT + (size_t)(row0 + j) * 1024 + c0);
;         acc8(s, x[15 + j], 1.f);
;         const float inv = 1.f / (float)(t + 1 < w ? t + 1 : w);
;         const u32x4 xc = x[15 + j];
;         u32x4 o;
;         o.x = pk2((s[0] * inv - bflo(xc.x)) * sc0[0] * bflo(g.x), (s[1] * inv - bfhi(xc.x)) * sc0[1] * bfhi(g.x));
;         o.y = pk2((s[2] * inv - bflo(xc.y)) * sc0[2] * bflo(g.y), (s[3] * inv - bfhi(xc.y)) * sc0[3] * bfhi(g.y));
;         o.z = pk2((s[4] * inv - bflo(xc.z)) * sc1[0] * bflo(g.z), (s[5] * inv - bfhi(xc.z)) * sc1[1] * bfhi(g.z));
;         o.w = pk2((s[6] * inv - bflo(xc.w)) * sc1[2] * bflo(g.w), (s[7] * inv - bfhi(xc.w)) * sc1[3] * bfhi(g.w));
;         *(u32x4*)(MX + (size_t)(row0 + j) * 1024 + c0) = o;
;         if (w == 2) acc8(s, x[15 + j - 1], -1.f); else if (w == 4) acc8(s, x[15 + j - 3], -1.f); else if (w == 8) acc8(s, x[15 + j - 7], -1.f); else acc8(s, x[j], -1.f);
.LBB0_2786:
	v_or_b32_e32 v70, 2, v132
	v_ashrrev_i32_e32 v71, 31, v70
	v_lshlrev_b64 v[210:211], 11, v[70:71]
	v_lshl_add_u64 v[70:71], v[98:99], 0, v[210:211]
	global_load_dwordx4 v[206:209], v[70:71], off
	v_pk_add_f32 v[214:215], v[0:1], v[94:95] neg_lo:[0,1] neg_hi:[0,1]
	v_pk_add_f32 v[102:103], v[82:83], v[102:103] neg_lo:[0,1] neg_hi:[0,1]
	v_lshlrev_b32_e32 v82, 16, v62
	v_and_b32_e32 v94, 0xffff0000, v62
	v_or_b32_e32 v62, 3, v226
	v_min_i32_e32 v62, s16, v62
	v_cvt_f32_i32_e32 v133, v62
	v_and_b32_e32 v71, 0xffff0000, v61
	v_and_b32_e32 v70, 0xffff0000, v60
	v_lshlrev_b32_e32 v83, 16, v63
	v_and_b32_e32 v95, 0xffff0000, v63
	v_pk_add_f32 v[62:63], v[102:103], v[70:71]
	v_div_scale_f32 v102, s[0:1], v133, v133, 1.0
	v_rcp_f32_e32 v103, v102
	v_pk_add_f32 v[88:89], v[88:89], v[196:197] neg_lo:[0,1] neg_hi:[0,1]
	v_div_scale_f32 v196, vcc, 1.0, v133, 1.0
	v_fma_f32 v197, -v102, v103, 1.0
	v_fmac_f32_e32 v103, v197, v103
	v_mul_f32_e32 v197, v196, v103
	v_pk_add_f32 v[90:91], v[90:91], v[212:213] neg_lo:[0,1] neg_hi:[0,1]
	v_fma_f32 v212, -v102, v197, v196
	v_fmac_f32_e32 v197, v212, v103
	v_fma_f32 v102, -v102, v197, v196
	v_lshlrev_b32_e32 v1, 16, v61
	v_lshlrev_b32_e32 v0, 16, v60
	v_div_fmas_f32 v102, v102, v103, v197
	v_pk_add_f32 v[60:61], v[214:215], v[0:1]
	v_pk_add_f32 v[88:89], v[88:89], v[82:83]
	v_pk_add_f32 v[90:91], v[90:91], v[94:95]
	v_div_fixup_f32 v102, v102, v133, 1.0
	v_pk_fma_f32 v[196:197], v[102:103], v[60:61], v[0:1] op_sel_hi:[0,1,1] neg_lo:[0,0,1] neg_hi:[0,0,1]
	v_pk_fma_f32 v[212:213], v[102:103], v[62:63], v[70:71] op_sel_hi:[0,1,1] neg_lo:[0,0,1] neg_hi:[0,0,1]
	v_pk_fma_f32 v[214:215], v[102:103], v[88:89], v[82:83] op_sel_hi:[0,1,1] neg_lo:[0,0,1] neg_hi:[0,0,1]
	v_pk_fma_f32 v[102:103], v[102:103], v[90:91], v[94:95] op_sel_hi:[0,1,1] neg_lo:[0,0,1] neg_hi:[0,0,1]
	v_pk_mul_f32 v[196:197], v[64:65], v[196:197]
	v_pk_mul_f32 v[212:213], v[6:7], v[212:213]
	v_pk_mul_f32 v[214:215], v[4:5], v[214:215]
	v_pk_mul_f32 v[102:103], v[2:3], v[102:103]
	s_movk_i32 s11, 0x7fff
	s_mov_b32 s10, 0xffff0000
	s_cmp_lt_i32 s14, 1
	s_mov_b64 s[0:1], 0
	s_waitcnt vmcnt(0)
	v_lshlrev_b32_e32 v217, 16, v207
	v_lshlrev_b32_e32 v216, 16, v206
	v_and_b32_e32 v207, 0xffff0000, v207
	v_and_b32_e32 v206, 0xffff0000, v206
	v_lshlrev_b32_e32 v219, 16, v209
	v_lshlrev_b32_e32 v218, 16, v208
	v_and_b32_e32 v209, 0xffff0000, v209
	v_and_b32_e32 v208, 0xffff0000, v208
	v_pk_mul_f32 v[196:197], v[196:197], v[216:217]
	v_pk_mul_f32 v[206:207], v[212:213], v[206:207]
	v_pk_mul_f32 v[212:213], v[214:215], v[218:219]
	v_pk_mul_f32 v[102:103], v[102:103], v[208:209]
	v_cvt_pk_bf16_f32 v209, v213, v103
	v_cvt_pk_bf16_f32 v208, v212, v102
	v_cvt_pk_bf16_f32 v207, v197, v207
	v_cvt_pk_bf16_f32 v206, v196, v206
	v_lshl_add_u64 v[102:103], v[96:97], 0, v[210:211]
	global_store_dwordx4 v[102:103], v[206:209], off
	s_cbranch_scc1 .LBB0_2789
	s_cmp_gt_i32 s14, 1
	s_cbranch_scc0 .LBB0_2790
	s_cmp_lg_u32 s14, 2
	s_mov_b64 s[12:13], 0
	s_cselect_b64 s[10:11], -1, 0
	s_branch .LBB0_2791

; __device__ __forceinline__ unsigned f2bf(float f) { unsigned u = __builtin_bit_cast(unsigned, f); return (u + 0x7fffu + ((u >> 16) & 1u)) >> 16; }
; __device__ __forceinline__ unsigned pk2(float lo, float hi) { return f2bf(lo) | (f2bf(hi) << 16); }
; __device__ __forceinline__ void fir_tile(const Prm& P, Ctx& C, int pm, int gi) {
;     ...
;     for (int j = 0; j < RUN; ++j) {
;         const int t = t0 + j;
;         const u32x4 g = *(const u32x4*)(GT + (size_t)(row0 + j) * 1024 + c0);
;         acc8(s, x[15 + j], 1.f);
;         const float inv = 1.f / (float)(t + 1 < w ? t + 1 : w);
;         const u32x4 xc = x[15 + j];
;         u32x4 o;
;         o.x = pk2((s[0] * inv - bflo(xc.x)) * sc0[0] * bflo(g.x), (s[1] * inv - bfhi(xc.x)) * sc0[1] * bfhi(g.x));
;         o.y = pk2((s[2] * inv - bflo(xc.y)) * sc0[2] * bflo(g.y), (s[3] * inv - bfhi(xc.y)) * sc0[3] * bfhi(g.y));
;         o.z = pk2((s[4] * inv - bflo(xc.z)) * sc1[0] * bflo(g.z), (s[5] * inv - bfhi(xc.z)) * sc1[1] * bfhi(g.z));
;         o.w = pk2((s[6] * inv - bflo(xc.w)) * sc1[2] * bflo(g.w), (s[7] * inv - bfhi(xc.w)) * sc1[3] * bfhi(g.w));
;         *(u32x4*)(MX + (size_t)(row0 + j) * 1024 + c0) = o;
;         if (w == 2) acc8(s, x[15 + j - 1], -1.f); else if (w == 4) acc8(s, x[15 + j - 3], -1.f); else if (w == 8) acc8(s, x[15 + j - 7], -1.f); else acc8(s, x[j], -1.f);
.LBB0_2799:
	v_or_b32_e32 v84, 3, v132
	v_ashrrev_i32_e32 v85, 31, v84
	v_lshlrev_b64 v[130:131], 11, v[84:85]
	v_lshl_add_u64 v[84:85], v[98:99], 0, v[130:131]
	global_load_dwordx4 v[210:213], v[84:85], off
	v_lshlrev_b32_e32 v84, 16, v58
	v_and_b32_e32 v100, 0xffff0000, v58
	v_or_b32_e32 v58, 4, v226
	v_min_i32_e32 v58, s16, v58
	v_cvt_f32_i32_e32 v133, v58
	v_pk_add_f32 v[86:87], v[60:61], v[102:103] neg_lo:[0,1] neg_hi:[0,1]
	v_pk_add_f32 v[102:103], v[62:63], v[196:197] neg_lo:[0,1] neg_hi:[0,1]
	v_and_b32_e32 v63, 0xffff0000, v57
	v_and_b32_e32 v62, 0xffff0000, v56
	v_lshlrev_b32_e32 v85, 16, v59
	v_and_b32_e32 v101, 0xffff0000, v59
	v_pk_add_f32 v[58:59], v[102:103], v[62:63]
	v_div_scale_f32 v102, s[0:1], v133, v133, 1.0
	v_rcp_f32_e32 v103, v102
	v_pk_add_f32 v[88:89], v[88:89], v[206:207] neg_lo:[0,1] neg_hi:[0,1]
	v_pk_add_f32 v[90:91], v[90:91], v[208:209] neg_lo:[0,1] neg_hi:[0,1]
	v_lshlrev_b32_e32 v61, 16, v57
	v_lshlrev_b32_e32 v60, 16, v56
	v_pk_add_f32 v[56:57], v[86:87], v[60:61]
	v_pk_add_f32 v[86:87], v[88:89], v[84:85]
	v_pk_add_f32 v[88:89], v[90:91], v[100:101]
	v_fma_f32 v91, -v102, v103, 1.0
	v_div_scale_f32 v90, vcc, 1.0, v133, 1.0
	v_fmac_f32_e32 v103, v91, v103
	v_mul_f32_e32 v91, v90, v103
	v_fma_f32 v196, -v102, v91, v90
	v_fmac_f32_e32 v91, v196, v103
	v_fma_f32 v90, -v102, v91, v90
	v_div_fmas_f32 v90, v90, v103, v91
	v_div_fixup_f32 v90, v90, v133, 1.0
	v_pk_fma_f32 v[102:103], v[90:91], v[56:57], v[60:61] op_sel_hi:[0,1,1] neg_lo:[0,0,1] neg_hi:[0,0,1]
	v_pk_fma_f32 v[196:197], v[90:91], v[58:59], v[62:63] op_sel_hi:[0,1,1] neg_lo:[0,0,1] neg_hi:[0,0,1]
	v_pk_fma_f32 v[206:207], v[90:91], v[86:87], v[84:85] op_sel_hi:[0,1,1] neg_lo:[0,0,1] neg_hi:[0,0,1]
	v_pk_fma_f32 v[90:91], v[90:91], v[88:89], v[100:101] op_sel_hi:[0,1,1] neg_lo:[0,0,1] neg_hi:[0,0,1]
	v_pk_mul_f32 v[102:103], v[64:65], v[102:103]
	v_pk_mul_f32 v[206:207], v[4:5], v[206:207]
	v_pk_mul_f32 v[90:91], v[2:3], v[90:91]
	v_pk_mul_f32 v[196:197], v[6:7], v[196:197]
	s_movk_i32 s11, 0x7fff
	s_mov_b32 s10, 0xffff0000
	s_cmp_lt_i32 s14, 1
	s_mov_b64 s[0:1], 0
	s_waitcnt vmcnt(0)
	v_lshlrev_b32_e32 v209, 16, v211
	v_lshlrev_b32_e32 v208, 16, v210
	v_lshlrev_b32_e32 v215, 16, v213
	v_lshlrev_b32_e32 v214, 16, v212
	v_and_b32_e32 v213, 0xffff0000, v213
	v_and_b32_e32 v212, 0xffff0000, v212
	v_and_b32_e32 v211, 0xffff0000, v211
	v_and_b32_e32 v210, 0xffff0000, v210
	v_pk_mul_f32 v[102:103], v[102:103], v[208:209]
	v_pk_mul_f32 v[206:207], v[206:207], v[214:215]
	v_pk_mul_f32 v[90:91], v[90:91], v[212:213]
	v_pk_mul_f32 v[196:197], v[196:197], v[210:211]
	v_cvt_pk_bf16_f32 v209, v207, v91
	v_cvt_pk_bf16_f32 v208, v206, v90
	v_cvt_pk_bf16_f32 v207, v103, v197
	v_cvt_pk_bf16_f32 v206, v102, v196
	v_lshl_add_u64 v[90:91], v[96:97], 0, v[130:131]
	global_store_dwordx4 v[90:91], v[206:209], off
	s_cbranch_scc1 .LBB0_2802
	s_cmp_gt_i32 s14, 1
	s_cbranch_scc0 .LBB0_2803
	s_cmp_lg_u32 s14, 2
	s_mov_b64 s[12:13], 0
	s_cselect_b64 s[10:11], -1, 0
	s_branch .LBB0_2804

; __device__ __forceinline__ unsigned f2bf(float f) { unsigned u = __builtin_bit_cast(unsigned, f); return (u + 0x7fffu + ((u >> 16) & 1u)) >> 16; }
; __device__ __forceinline__ unsigned pk2(float lo, float hi) { return f2bf(lo) | (f2bf(hi) << 16); }
; __device__ __forceinline__ void fir_tile(const Prm& P, Ctx& C, int pm, int gi) {
;     ...
;     for (int j = 0; j < RUN; ++j) {
;         const int t = t0 + j;
;         const u32x4 g = *(const u32x4*)(GT + (size_t)(row0 + j) * 1024 + c0);
;         acc8(s, x[15 + j], 1.f);
;         const float inv = 1.f / (float)(t + 1 < w ? t + 1 : w);
;         const u32x4 xc = x[15 + j];
;         u32x4 o;
;         o.x = pk2((s[0] * inv - bflo(xc.x)) * sc0[0] * bflo(g.x), (s[1] * inv - bfhi(xc.x)) * sc0[1] * bfhi(g.x));
;         o.y = pk2((s[2] * inv - bflo(xc.y)) * sc0[2] * bflo(g.y), (s[3] * inv - bfhi(xc.y)) * sc0[3] * bfhi(g.y));
;         o.z = pk2((s[4] * inv - bflo(xc.z)) * sc1[0] * bflo(g.z), (s[5] * inv - bfhi(xc.z)) * sc1[1] * bfhi(g.z));
;         o.w = pk2((s[6] * inv - bflo(xc.w)) * sc1[2] * bflo(g.w), (s[7] * inv - bfhi(xc.w)) * sc1[3] * bfhi(g.w));
;         *(u32x4*)(MX + (size_t)(row0 + j) * 1024 + c0) = o;
;         if (w == 2) acc8(s, x[15 + j - 1], -1.f); else if (w == 4) acc8(s, x[15 + j - 3], -1.f); else if (w == 8) acc8(s, x[15 + j - 7], -1.f); else acc8(s, x[j], -1.f);
.LBB0_2812:
	v_or_b32_e32 v198, 4, v132
	v_ashrrev_i32_e32 v199, 31, v198
	v_lshlrev_b64 v[202:203], 11, v[198:199]
	v_lshl_add_u64 v[198:199], v[98:99], 0, v[202:203]
	global_load_dwordx4 v[198:201], v[198:199], off
	v_pk_add_f32 v[204:205], v[86:87], v[102:103] neg_lo:[0,1] neg_hi:[0,1]
	v_lshlrev_b32_e32 v86, 16, v54
	v_and_b32_e32 v102, 0xffff0000, v54
	v_or_b32_e32 v54, 5, v226
	v_min_i32_e32 v54, s16, v54
	v_cvt_f32_i32_e32 v133, v54
	v_pk_add_f32 v[130:131], v[58:59], v[130:131] neg_lo:[0,1] neg_hi:[0,1]
	v_and_b32_e32 v59, 0xffff0000, v53
	v_and_b32_e32 v58, 0xffff0000, v52
	v_lshlrev_b32_e32 v87, 16, v55
	v_and_b32_e32 v103, 0xffff0000, v55
	v_pk_add_f32 v[54:55], v[130:131], v[58:59]
	v_div_scale_f32 v130, s[0:1], v133, v133, 1.0
	v_rcp_f32_e32 v131, v130
	v_pk_add_f32 v[196:197], v[56:57], v[196:197] neg_lo:[0,1] neg_hi:[0,1]
	v_lshlrev_b32_e32 v57, 16, v53
	v_lshlrev_b32_e32 v56, 16, v52
	v_pk_add_f32 v[52:53], v[196:197], v[56:57]
	v_fma_f32 v197, -v130, v131, 1.0
	v_div_scale_f32 v196, vcc, 1.0, v133, 1.0
	v_fmac_f32_e32 v131, v197, v131
	v_mul_f32_e32 v197, v196, v131
	v_pk_add_f32 v[90:91], v[88:89], v[90:91] neg_lo:[0,1] neg_hi:[0,1]
	v_pk_add_f32 v[88:89], v[204:205], v[86:87]
	v_fma_f32 v204, -v130, v197, v196
	v_fmac_f32_e32 v197, v204, v131
	v_fma_f32 v130, -v130, v197, v196
	v_div_fmas_f32 v130, v130, v131, v197
	v_pk_add_f32 v[90:91], v[90:91], v[102:103]
	v_div_fixup_f32 v130, v130, v133, 1.0
	v_pk_fma_f32 v[196:197], v[130:131], v[52:53], v[56:57] op_sel_hi:[0,1,1] neg_lo:[0,0,1] neg_hi:[0,0,1]
	v_pk_fma_f32 v[204:205], v[130:131], v[54:55], v[58:59] op_sel_hi:[0,1,1] neg_lo:[0,0,1] neg_hi:[0,0,1]
	v_pk_fma_f32 v[206:207], v[130:131], v[88:89], v[86:87] op_sel_hi:[0,1,1] neg_lo:[0,0,1] neg_hi:[0,0,1]
	v_pk_fma_f32 v[130:131], v[130:131], v[90:91], v[102:103] op_sel_hi:[0,1,1] neg_lo:[0,0,1] neg_hi:[0,0,1]
	v_pk_mul_f32 v[196:197], v[64:65], v[196:197]
	v_pk_mul_f32 v[204:205], v[6:7], v[204:205]
	v_pk_mul_f32 v[206:207], v[4:5], v[206:207]
	v_pk_mul_f32 v[130:131], v[2:3], v[130:131]
	s_movk_i32 s11, 0x7fff
	s_mov_b32 s10, 0xffff0000
	s_cmp_lt_i32 s14, 1
	s_mov_b64 s[0:1], 0
	s_waitcnt vmcnt(0)
	v_lshlrev_b32_e32 v209, 16, v199
	v_lshlrev_b32_e32 v208, 16, v198
	v_and_b32_e32 v199, 0xffff0000, v199
	v_and_b32_e32 v198, 0xffff0000, v198
	v_lshlrev_b32_e32 v211, 16, v201
	v_lshlrev_b32_e32 v210, 16, v200
	v_and_b32_e32 v201, 0xffff0000, v201
	v_and_b32_e32 v200, 0xffff0000, v200
	v_pk_mul_f32 v[196:197], v[196:197], v[208:209]
	v_pk_mul_f32 v[198:199], v[204:205], v[198:199]
	v_pk_mul_f32 v[204:205], v[206:207], v[210:211]
	v_pk_mul_f32 v[130:131], v[130:131], v[200:201]
	v_bfe_u32 v206, v198, 16, 1
	v_bfe_u32 v207, v196, 16, 1
	v_bfe_u32 v208, v197, 16, 1
	v_bfe_u32 v201, v199, 16, 1
	v_add3_u32 v206, v198, v206, s11
	v_add3_u32 v197, v197, v208, s11
	v_add3_u32 v196, v196, v207, s11
	v_add3_u32 v201, v199, v201, s11
	v_lshrrev_b32_e32 v196, 16, v196
	v_lshrrev_b32_e32 v197, 16, v197
	v_cvt_pk_bf16_f32 v199, v205, v131
	v_cvt_pk_bf16_f32 v198, v204, v130
	v_and_or_b32 v197, v201, s10, v197
	v_and_or_b32 v196, v206, s10, v196
	v_lshl_add_u64 v[130:131], v[96:97], 0, v[202:203]
	global_store_dwordx4 v[130:131], v[196:199], off
	s_cbranch_scc1 .LBB0_2815
	s_cmp_gt_i32 s14, 1
	s_cbranch_scc0 .LBB0_2816
	s_cmp_lg_u32 s14, 2
	s_mov_b64 s[12:13], 0
	s_cselect_b64 s[10:11], -1, 0
	s_branch .LBB0_2817

; __device__ __forceinline__ unsigned f2bf(float f) { unsigned u = __builtin_bit_cast(unsigned, f); return (u + 0x7fffu + ((u >> 16) & 1u)) >> 16; }
; __device__ __forceinline__ unsigned pk2(float lo, float hi) { return f2bf(lo) | (f2bf(hi) << 16); }
; __device__ __forceinline__ void fir_tile(const Prm& P, Ctx& C, int pm, int gi) {
;     ...
;     for (int j = 0; j < RUN; ++j) {
;         const int t = t0 + j;
;         const u32x4 g = *(const u32x4*)(GT + (size_t)(row0 + j) * 1024 + c0);
;         acc8(s, x[15 + j], 1.f);
;         const float inv = 1.f / (float)(t + 1 < w ? t + 1 : w);
;         const u32x4 xc = x[15 + j];
;         u32x4 o;
;         o.x = pk2((s[0] * inv - bflo(xc.x)) * sc0[0] * bflo(g.x), (s[1] * inv - bfhi(xc.x)) * sc0[1] * bfhi(g.x));
;         o.y = pk2((s[2] * inv - bflo(xc.y)) * sc0[2] * bflo(g.y), (s[3] * inv - bfhi(xc.y)) * sc0[3] * bfhi(g.y));
;         o.z = pk2((s[4] * inv - bflo(xc.z)) * sc1[0] * bflo(g.z), (s[5] * inv - bfhi(xc.z)) * sc1[1] * bfhi(g.z));
;         o.w = pk2((s[6] * inv - bflo(xc.w)) * sc1[2] * bflo(g.w), (s[7] * inv - bfhi(xc.w)) * sc1[3] * bfhi(g.w));
;         *(u32x4*)(MX + (size_t)(row0 + j) * 1024 + c0) = o;
;         if (w == 2) acc8(s, x[15 + j - 1], -1.f); else if (w == 4) acc8(s, x[15 + j - 3], -1.f); else if (w == 8) acc8(s, x[15 + j - 7], -1.f); else acc8(s, x[j], -1.f);
.LBB0_2825:
	v_or_b32_e32 v186, 5, v132
	v_ashrrev_i32_e32 v187, 31, v186
	v_lshlrev_b64 v[192:193], 11, v[186:187]
	v_lshl_add_u64 v[186:187], v[98:99], 0, v[192:193]
	global_load_dwordx4 v[188:191], v[186:187], off
	v_pk_add_f32 v[186:187], v[52:53], v[130:131] neg_lo:[0,1] neg_hi:[0,1]
	v_pk_add_f32 v[198:199], v[88:89], v[198:199] neg_lo:[0,1] neg_hi:[0,1]
	v_lshlrev_b32_e32 v88, 16, v50
	v_and_b32_e32 v130, 0xffff0000, v50
	v_or_b32_e32 v50, 6, v226
	v_min_i32_e32 v50, s16, v50
	v_cvt_f32_i32_e32 v133, v50
	v_pk_add_f32 v[196:197], v[54:55], v[196:197] neg_lo:[0,1] neg_hi:[0,1]
	v_and_b32_e32 v55, 0xffff0000, v49
	v_and_b32_e32 v54, 0xffff0000, v48
	v_lshlrev_b32_e32 v89, 16, v51
	v_and_b32_e32 v131, 0xffff0000, v51
	v_pk_add_f32 v[50:51], v[196:197], v[54:55]
	v_div_scale_f32 v196, s[0:1], v133, v133, 1.0
	v_rcp_f32_e32 v197, v196
	v_pk_add_f32 v[200:201], v[90:91], v[200:201] neg_lo:[0,1] neg_hi:[0,1]
	v_pk_add_f32 v[90:91], v[198:199], v[88:89]
	v_div_scale_f32 v198, vcc, 1.0, v133, 1.0
	v_fma_f32 v199, -v196, v197, 1.0
	v_fmac_f32_e32 v197, v199, v197
	v_lshlrev_b32_e32 v53, 16, v49
	v_lshlrev_b32_e32 v52, 16, v48
	v_mul_f32_e32 v199, v198, v197
	v_pk_add_f32 v[48:49], v[186:187], v[52:53]
	v_pk_add_f32 v[186:187], v[200:201], v[130:131]
	v_fma_f32 v200, -v196, v199, v198
	v_fmac_f32_e32 v199, v200, v197
	v_fma_f32 v196, -v196, v199, v198
	v_div_fmas_f32 v196, v196, v197, v199
	v_div_fixup_f32 v196, v196, v133, 1.0
	v_pk_fma_f32 v[198:199], v[196:197], v[48:49], v[52:53] op_sel_hi:[0,1,1] neg_lo:[0,0,1] neg_hi:[0,0,1]
	v_pk_fma_f32 v[200:201], v[196:197], v[50:51], v[54:55] op_sel_hi:[0,1,1] neg_lo:[0,0,1] neg_hi:[0,0,1]
	v_pk_fma_f32 v[202:203], v[196:197], v[90:91], v[88:89] op_sel_hi:[0,1,1] neg_lo:[0,0,1] neg_hi:[0,0,1]
	v_pk_fma_f32 v[196:197], v[196:197], v[186:187], v[130:131] op_sel_hi:[0,1,1] neg_lo:[0,0,1] neg_hi:[0,0,1]
	v_pk_mul_f32 v[198:199], v[64:65], v[198:199]
	v_pk_mul_f32 v[200:201], v[6:7], v[200:201]
	v_pk_mul_f32 v[202:203], v[4:5], v[202:203]
	v_pk_mul_f32 v[196:197], v[2:3], v[196:197]
	s_movk_i32 s11, 0x7fff
	s_mov_b32 s10, 0xffff0000
	v_lshl_add_u64 v[192:193], v[96:97], 0, v[192:193]
	s_cmp_lt_i32 s14, 1
	s_mov_b64 s[0:1], 0
	s_waitcnt vmcnt(0)
	v_lshlrev_b32_e32 v205, 16, v189
	v_lshlrev_b32_e32 v204, 16, v188
	v_and_b32_e32 v189, 0xffff0000, v189
	v_and_b32_e32 v188, 0xffff0000, v188
	v_lshlrev_b32_e32 v207, 16, v191
	v_lshlrev_b32_e32 v206, 16, v190
	v_and_b32_e32 v191, 0xffff0000, v191
	v_and_b32_e32 v190, 0xffff0000, v190
	v_pk_mul_f32 v[198:199], v[198:199], v[204:205]
	v_pk_mul_f32 v[188:189], v[200:201], v[188:189]
	v_pk_mul_f32 v[200:201], v[202:203], v[206:207]
	v_pk_mul_f32 v[190:191], v[196:197], v[190:191]
	v_cvt_pk_bf16_f32 v191, v201, v191
	v_cvt_pk_bf16_f32 v190, v200, v190
	v_cvt_pk_bf16_f32 v189, v199, v189
	v_cvt_pk_bf16_f32 v188, v198, v188
	global_store_dwordx4 v[192:193], v[188:191], off
	s_cbranch_scc1 .LBB0_2828
	s_cmp_gt_i32 s14, 1
	s_cbranch_scc0 .LBB0_2829
	s_cmp_lg_u32 s14, 2
	s_mov_b64 s[12:13], 0
	s_cselect_b64 s[10:11], -1, 0
	s_branch .LBB0_2830

; __device__ __forceinline__ unsigned f2bf(float f) { unsigned u = __builtin_bit_cast(unsigned, f); return (u + 0x7fffu + ((u >> 16) & 1u)) >> 16; }
; __device__ __forceinline__ unsigned pk2(float lo, float hi) { return f2bf(lo) | (f2bf(hi) << 16); }
; __device__ __forceinline__ void fir_tile(const Prm& P, Ctx& C, int pm, int gi) {
;     ...
;     for (int j = 0; j < RUN; ++j) {
;         const int t = t0 + j;
;         const u32x4 g = *(const u32x4*)(GT + (size_t)(row0 + j) * 1024 + c0);
;         acc8(s, x[15 + j], 1.f);
;         const float inv = 1.f / (float)(t + 1 < w ? t + 1 : w);
;         const u32x4 xc = x[15 + j];
;         u32x4 o;
;         o.x = pk2((s[0] * inv - bflo(xc.x)) * sc0[0] * bflo(g.x), (s[1] * inv - bfhi(xc.x)) * sc0[1] * bfhi(g.x));
;         o.y = pk2((s[2] * inv - bflo(xc.y)) * sc0[2] * bflo(g.y), (s[3] * inv - bfhi(xc.y)) * sc0[3] * bfhi(g.y));
;         o.z = pk2((s[4] * inv - bflo(xc.z)) * sc1[0] * bflo(g.z), (s[5] * inv - bfhi(xc.z)) * sc1[1] * bfhi(g.z));
;         o.w = pk2((s[6] * inv - bflo(xc.w)) * sc1[2] * bflo(g.w), (s[7] * inv - bfhi(xc.w)) * sc1[3] * bfhi(g.w));
;         *(u32x4*)(MX + (size_t)(row0 + j) * 1024 + c0) = o;
;         if (w == 2) acc8(s, x[15 + j - 1], -1.f); else if (w == 4) acc8(s, x[15 + j - 3], -1.f); else if (w == 8) acc8(s, x[15 + j - 7], -1.f); else acc8(s, x[j], -1.f);
.LBB0_2838:
	v_or_b32_e32 v168, 6, v132
	v_ashrrev_i32_e32 v169, 31, v168
	v_lshlrev_b64 v[194:195], 11, v[168:169]
	v_lshl_add_u64 v[168:169], v[98:99], 0, v[194:195]
	global_load_dwordx4 v[198:201], v[168:169], off
	v_pk_add_f32 v[182:183], v[48:49], v[188:189] neg_lo:[0,1] neg_hi:[0,1]
	v_pk_add_f32 v[188:189], v[90:91], v[192:193] neg_lo:[0,1] neg_hi:[0,1]
	v_lshlrev_b32_e32 v90, 16, v46
	v_and_b32_e32 v168, 0xffff0000, v46
	v_or_b32_e32 v46, 7, v226
	v_min_i32_e32 v46, s16, v46
	v_cvt_f32_i32_e32 v133, v46
	v_lshlrev_b32_e32 v49, 16, v45
	v_lshlrev_b32_e32 v48, 16, v44
	v_lshlrev_b32_e32 v91, 16, v47
	v_pk_add_f32 v[184:185], v[50:51], v[190:191] neg_lo:[0,1] neg_hi:[0,1]
	v_and_b32_e32 v51, 0xffff0000, v45
	v_and_b32_e32 v50, 0xffff0000, v44
	v_pk_add_f32 v[44:45], v[182:183], v[48:49]
	v_pk_add_f32 v[182:183], v[188:189], v[90:91]
	v_div_scale_f32 v188, s[0:1], v133, v133, 1.0
	v_rcp_f32_e32 v189, v188
	v_pk_add_f32 v[186:187], v[186:187], v[196:197] neg_lo:[0,1] neg_hi:[0,1]
	v_and_b32_e32 v169, 0xffff0000, v47
	v_pk_add_f32 v[46:47], v[184:185], v[50:51]
	v_pk_add_f32 v[184:185], v[186:187], v[168:169]
	v_fma_f32 v187, -v188, v189, 1.0
	v_div_scale_f32 v186, vcc, 1.0, v133, 1.0
	v_fmac_f32_e32 v189, v187, v189
	v_mul_f32_e32 v187, v186, v189
	v_fma_f32 v190, -v188, v187, v186
	v_fmac_f32_e32 v187, v190, v189
	v_fma_f32 v186, -v188, v187, v186
	v_div_fmas_f32 v186, v186, v189, v187
	v_div_fixup_f32 v186, v186, v133, 1.0
	v_pk_fma_f32 v[188:189], v[186:187], v[44:45], v[48:49] op_sel_hi:[0,1,1] neg_lo:[0,0,1] neg_hi:[0,0,1]
	v_pk_fma_f32 v[190:191], v[186:187], v[46:47], v[50:51] op_sel_hi:[0,1,1] neg_lo:[0,0,1] neg_hi:[0,0,1]
	v_pk_fma_f32 v[192:193], v[186:187], v[182:183], v[90:91] op_sel_hi:[0,1,1] neg_lo:[0,0,1] neg_hi:[0,0,1]
	v_pk_fma_f32 v[186:187], v[186:187], v[184:185], v[168:169] op_sel_hi:[0,1,1] neg_lo:[0,0,1] neg_hi:[0,0,1]
	v_pk_mul_f32 v[188:189], v[64:65], v[188:189]
	v_pk_mul_f32 v[192:193], v[4:5], v[192:193]
	v_pk_mul_f32 v[186:187], v[2:3], v[186:187]
	v_pk_mul_f32 v[190:191], v[6:7], v[190:191]
	s_movk_i32 s11, 0x7fff
	s_mov_b32 s10, 0xffff0000
	s_cmp_lt_i32 s14, 1
	s_mov_b64 s[0:1], 0
	s_waitcnt vmcnt(0)
	v_lshlrev_b32_e32 v197, 16, v199
	v_lshlrev_b32_e32 v196, 16, v198
	v_lshlrev_b32_e32 v203, 16, v201
	v_lshlrev_b32_e32 v202, 16, v200
	v_and_b32_e32 v201, 0xffff0000, v201
	v_and_b32_e32 v200, 0xffff0000, v200
	v_and_b32_e32 v199, 0xffff0000, v199
	v_and_b32_e32 v198, 0xffff0000, v198
	v_pk_mul_f32 v[188:189], v[188:189], v[196:197]
	v_pk_mul_f32 v[192:193], v[192:193], v[202:203]
	v_pk_mul_f32 v[186:187], v[186:187], v[200:201]
	v_pk_mul_f32 v[190:191], v[190:191], v[198:199]
	v_bfe_u32 v133, v187, 16, 1
	v_bfe_u32 v199, v188, 16, 1
	v_bfe_u32 v200, v189, 16, 1
	v_bfe_u32 v202, v193, 16, 1
	v_bfe_u32 v197, v191, 16, 1
	v_bfe_u32 v198, v190, 16, 1
	v_add3_u32 v133, v187, v133, s11
	v_add3_u32 v187, v193, v202, s11
	v_add3_u32 v189, v189, v200, s11
	v_add3_u32 v188, v188, v199, s11
	v_add3_u32 v190, v190, v198, s11
	v_add3_u32 v191, v191, v197, s11
	v_lshrrev_b32_e32 v193, 16, v188
	v_lshrrev_b32_e32 v196, 16, v189
	v_lshrrev_b32_e32 v187, 16, v187
	v_and_or_b32 v189, v133, s10, v187
	v_cvt_pk_bf16_f32 v188, v192, v186
	v_and_or_b32 v187, v191, s10, v196
	v_and_or_b32 v186, v190, s10, v193
	v_lshl_add_u64 v[190:191], v[96:97], 0, v[194:195]
	global_store_dwordx4 v[190:191], v[186:189], off
	s_cbranch_scc1 .LBB0_2841
	s_cmp_gt_i32 s14, 1
	s_cbranch_scc0 .LBB0_2842
	s_cmp_lg_u32 s14, 2
	s_mov_b64 s[12:13], 0
	s_cselect_b64 s[10:11], -1, 0
	s_branch .LBB0_2843

; __device__ __forceinline__ unsigned f2bf(float f) { unsigned u = __builtin_bit_cast(unsigned, f); return (u + 0x7fffu + ((u >> 16) & 1u)) >> 16; }
; __device__ __forceinline__ unsigned pk2(float lo, float hi) { return f2bf(lo) | (f2bf(hi) << 16); }
; __device__ __forceinline__ void fir_tile(const Prm& P, Ctx& C, int pm, int gi) {
;     ...
;     for (int j = 0; j < RUN; ++j) {
;         const int t = t0 + j;
;         const u32x4 g = *(const u32x4*)(GT + (size_t)(row0 + j) * 1024 + c0);
;         acc8(s, x[15 + j], 1.f);
;         const float inv = 1.f / (float)(t + 1 < w ? t + 1 : w);
;         const u32x4 xc = x[15 + j];
;         u32x4 o;
;         o.x = pk2((s[0] * inv - bflo(xc.x)) * sc0[0] * bflo(g.x), (s[1] * inv - bfhi(xc.x)) * sc0[1] * bfhi(g.x));
;         o.y = pk2((s[2] * inv - bflo(xc.y)) * sc0[2] * bflo(g.y), (s[3] * inv - bfhi(xc.y)) * sc0[3] * bfhi(g.y));
;         o.z = pk2((s[4] * inv - bflo(xc.z)) * sc1[0] * bflo(g.z), (s[5] * inv - bfhi(xc.z)) * sc1[1] * bfhi(g.z));
;         o.w = pk2((s[6] * inv - bflo(xc.w)) * sc1[2] * bflo(g.w), (s[7] * inv - bfhi(xc.w)) * sc1[3] * bfhi(g.w));
;         *(u32x4*)(MX + (size_t)(row0 + j) * 1024 + c0) = o;
;         if (w == 2) acc8(s, x[15 + j - 1], -1.f); else if (w == 4) acc8(s, x[15 + j - 3], -1.f); else if (w == 8) acc8(s, x[15 + j - 7], -1.f); else acc8(s, x[j], -1.f);
.LBB0_2875:
	v_or_b32_e32 v160, 9, v132
	v_ashrrev_i32_e32 v161, 31, v160
	v_lshlrev_b64 v[164:165], 11, v[160:161]
	v_lshl_add_u64 v[160:161], v[98:99], 0, v[164:165]
	global_load_dwordx4 v[160:163], v[160:161], off
	v_pk_add_f32 v[66:67], v[36:37], v[66:67] neg_lo:[0,1] neg_hi:[0,1]
	v_pk_add_f32 v[78:79], v[122:123], v[78:79] neg_lo:[0,1] neg_hi:[0,1]
	v_lshlrev_b32_e32 v37, 16, v33
	v_lshlrev_b32_e32 v36, 16, v32
	v_or_b32_e32 v122, 10, v226
	v_pk_add_f32 v[166:167], v[38:39], v[74:75] neg_lo:[0,1] neg_hi:[0,1]
	v_lshlrev_b32_e32 v39, 16, v35
	v_lshlrev_b32_e32 v38, 16, v34
	v_and_b32_e32 v75, 0xffff0000, v35
	v_and_b32_e32 v74, 0xffff0000, v34
	v_pk_add_f32 v[34:35], v[66:67], v[36:37]
	v_min_i32_e32 v66, s16, v122
	v_cvt_f32_i32_e32 v122, v66
	v_pk_add_f32 v[92:93], v[128:129], v[92:93] neg_lo:[0,1] neg_hi:[0,1]
	v_and_b32_e32 v33, 0xffff0000, v33
	v_and_b32_e32 v32, 0xffff0000, v32
	v_div_scale_f32 v123, s[0:1], v122, v122, 1.0
	v_rcp_f32_e32 v128, v123
	v_div_scale_f32 v129, vcc, 1.0, v122, 1.0
	v_pk_add_f32 v[66:67], v[166:167], v[32:33]
	v_fma_f32 v133, -v123, v128, 1.0
	v_fmac_f32_e32 v128, v133, v128
	v_mul_f32_e32 v133, v129, v128
	v_fma_f32 v166, -v123, v133, v129
	v_fmac_f32_e32 v133, v166, v128
	v_fma_f32 v123, -v123, v133, v129
	v_div_fmas_f32 v123, v123, v128, v133
	v_pk_add_f32 v[78:79], v[78:79], v[38:39]
	v_pk_add_f32 v[92:93], v[92:93], v[74:75]
	v_div_fixup_f32 v122, v123, v122, 1.0
	v_pk_fma_f32 v[128:129], v[122:123], v[34:35], v[36:37] op_sel_hi:[0,1,1] neg_lo:[0,0,1] neg_hi:[0,0,1]
	v_pk_fma_f32 v[166:167], v[122:123], v[66:67], v[32:33] op_sel_hi:[0,1,1] neg_lo:[0,0,1] neg_hi:[0,0,1]
	v_pk_fma_f32 v[170:171], v[122:123], v[78:79], v[38:39] op_sel_hi:[0,1,1] neg_lo:[0,0,1] neg_hi:[0,0,1]
	v_pk_fma_f32 v[122:123], v[122:123], v[92:93], v[74:75] op_sel_hi:[0,1,1] neg_lo:[0,0,1] neg_hi:[0,0,1]
	v_pk_mul_f32 v[128:129], v[64:65], v[128:129]
	v_pk_mul_f32 v[166:167], v[6:7], v[166:167]
	v_pk_mul_f32 v[170:171], v[4:5], v[170:171]
	v_pk_mul_f32 v[122:123], v[2:3], v[122:123]
	s_movk_i32 s11, 0x7fff
	s_mov_b32 s10, 0xffff0000
	s_cmp_lt_i32 s14, 1
	s_mov_b64 s[0:1], 0
	s_waitcnt vmcnt(0)
	v_lshlrev_b32_e32 v173, 16, v161
	v_lshlrev_b32_e32 v172, 16, v160
	v_and_b32_e32 v161, 0xffff0000, v161
	v_and_b32_e32 v160, 0xffff0000, v160
	v_lshlrev_b32_e32 v175, 16, v163
	v_lshlrev_b32_e32 v174, 16, v162
	v_and_b32_e32 v163, 0xffff0000, v163
	v_and_b32_e32 v162, 0xffff0000, v162
	v_pk_mul_f32 v[128:129], v[128:129], v[172:173]
	v_pk_mul_f32 v[160:161], v[166:167], v[160:161]
	v_pk_mul_f32 v[166:167], v[170:171], v[174:175]
	v_pk_mul_f32 v[122:123], v[122:123], v[162:163]
	v_cvt_pk_bf16_f32 v163, v167, v123
	v_cvt_pk_bf16_f32 v162, v166, v122
	v_cvt_pk_bf16_f32 v161, v129, v161
	v_cvt_pk_bf16_f32 v160, v128, v160
	v_lshl_add_u64 v[122:123], v[96:97], 0, v[164:165]
	global_store_dwordx4 v[122:123], v[160:163], off
	s_cbranch_scc1 .LBB0_2878
	s_cmp_gt_i32 s14, 1
	s_cbranch_scc0 .LBB0_2879
	s_cmp_lg_u32 s14, 2
	s_cselect_b64 s[10:11], -1, 0
	s_cbranch_execz .LBB0_2880
	s_branch .LBB0_2881

; __device__ __forceinline__ unsigned f2bf(float f) { unsigned u = __builtin_bit_cast(unsigned, f); return (u + 0x7fffu + ((u >> 16) & 1u)) >> 16; }
; __device__ __forceinline__ unsigned pk2(float lo, float hi) { return f2bf(lo) | (f2bf(hi) << 16); }
; __device__ __forceinline__ void fir_tile(const Prm& P, Ctx& C, int pm, int gi) {
;     ...
;     for (int j = 0; j < RUN; ++j) {
;         const int t = t0 + j;
;         const u32x4 g = *(const u32x4*)(GT + (size_t)(row0 + j) * 1024 + c0);
;         acc8(s, x[15 + j], 1.f);
;         const float inv = 1.f / (float)(t + 1 < w ? t + 1 : w);
;         const u32x4 xc = x[15 + j];
;         u32x4 o;
;         o.x = pk2((s[0] * inv - bflo(xc.x)) * sc0[0] * bflo(g.x), (s[1] * inv - bfhi(xc.x)) * sc0[1] * bfhi(g.x));
;         o.y = pk2((s[2] * inv - bflo(xc.y)) * sc0[2] * bflo(g.y), (s[3] * inv - bfhi(xc.y)) * sc0[3] * bfhi(g.y));
;         o.z = pk2((s[4] * inv - bflo(xc.z)) * sc1[0] * bflo(g.z), (s[5] * inv - bfhi(xc.z)) * sc1[1] * bfhi(g.z));
;         o.w = pk2((s[6] * inv - bflo(xc.w)) * sc1[2] * bflo(g.w), (s[7] * inv - bfhi(xc.w)) * sc1[3] * bfhi(g.w));
;         *(u32x4*)(MX + (size_t)(row0 + j) * 1024 + c0) = o;
;         if (w == 2) acc8(s, x[15 + j - 1], -1.f); else if (w == 4) acc8(s, x[15 + j - 3], -1.f); else if (w == 8) acc8(s, x[15 + j - 7], -1.f); else acc8(s, x[j], -1.f);
.LBB0_2899:
	v_or_b32_e32 v92, 11, v132
	v_ashrrev_i32_e32 v93, 31, v92
	v_lshlrev_b64 v[122:123], 11, v[92:93]
	v_lshl_add_u64 v[92:93], v[98:99], 0, v[122:123]
	global_load_dwordx4 v[92:95], v[92:93], off
	v_pk_add_f32 v[78:79], v[78:79], v[84:85] neg_lo:[0,1] neg_hi:[0,1]
	v_or_b32_e32 v84, 12, v226
	v_min_i32_e32 v84, s16, v84
	v_cvt_f32_i32_e32 v84, v84
	v_pk_add_f32 v[82:83], v[82:83], v[100:101] neg_lo:[0,1] neg_hi:[0,1]
	v_pk_add_f32 v[60:61], v[28:29], v[60:61] neg_lo:[0,1] neg_hi:[0,1]
	v_pk_add_f32 v[62:63], v[30:31], v[62:63] neg_lo:[0,1] neg_hi:[0,1]
	v_div_scale_f32 v85, s[0:1], v84, v84, 1.0
	v_rcp_f32_e32 v100, v85
	v_div_scale_f32 v101, vcc, 1.0, v84, 1.0
	v_lshlrev_b32_e32 v29, 16, v25
	v_fma_f32 v128, -v85, v100, 1.0
	v_fmac_f32_e32 v100, v128, v100
	v_mul_f32_e32 v128, v101, v100
	v_fma_f32 v129, -v85, v128, v101
	v_fmac_f32_e32 v128, v129, v100
	v_fma_f32 v85, -v85, v128, v101
	v_lshlrev_b32_e32 v28, 16, v24
	v_and_b32_e32 v25, 0xffff0000, v25
	v_and_b32_e32 v24, 0xffff0000, v24
	v_lshlrev_b32_e32 v31, 16, v27
	v_lshlrev_b32_e32 v30, 16, v26
	v_and_b32_e32 v27, 0xffff0000, v27
	v_and_b32_e32 v26, 0xffff0000, v26
	v_div_fmas_f32 v85, v85, v100, v128
	v_pk_add_f32 v[60:61], v[60:61], v[28:29]
	v_pk_add_f32 v[62:63], v[62:63], v[24:25]
	v_pk_add_f32 v[78:79], v[78:79], v[30:31]
	v_pk_add_f32 v[82:83], v[82:83], v[26:27]
	v_div_fixup_f32 v84, v85, v84, 1.0
	v_pk_fma_f32 v[100:101], v[84:85], v[60:61], v[28:29] op_sel_hi:[0,1,1] neg_lo:[0,0,1] neg_hi:[0,0,1]
	v_pk_fma_f32 v[128:129], v[84:85], v[62:63], v[24:25] op_sel_hi:[0,1,1] neg_lo:[0,0,1] neg_hi:[0,0,1]
	v_pk_fma_f32 v[144:145], v[84:85], v[78:79], v[30:31] op_sel_hi:[0,1,1] neg_lo:[0,0,1] neg_hi:[0,0,1]
	v_pk_fma_f32 v[84:85], v[84:85], v[82:83], v[26:27] op_sel_hi:[0,1,1] neg_lo:[0,0,1] neg_hi:[0,0,1]
	v_pk_mul_f32 v[100:101], v[64:65], v[100:101]
	v_pk_mul_f32 v[128:129], v[6:7], v[128:129]
	v_pk_mul_f32 v[144:145], v[4:5], v[144:145]
	v_pk_mul_f32 v[84:85], v[2:3], v[84:85]
	s_movk_i32 s11, 0x7fff
	s_mov_b32 s10, 0xffff0000
	s_cmp_lt_i32 s14, 1
	s_mov_b64 s[0:1], 0
	s_waitcnt vmcnt(0)
	v_lshlrev_b32_e32 v147, 16, v93
	v_lshlrev_b32_e32 v146, 16, v92
	v_and_b32_e32 v93, 0xffff0000, v93
	v_and_b32_e32 v92, 0xffff0000, v92
	v_lshlrev_b32_e32 v149, 16, v95
	v_lshlrev_b32_e32 v148, 16, v94
	v_and_b32_e32 v95, 0xffff0000, v95
	v_and_b32_e32 v94, 0xffff0000, v94
	v_pk_mul_f32 v[100:101], v[100:101], v[146:147]
	v_pk_mul_f32 v[92:93], v[128:129], v[92:93]
	v_pk_mul_f32 v[128:129], v[144:145], v[148:149]
	v_pk_mul_f32 v[84:85], v[84:85], v[94:95]
	v_bfe_u32 v95, v84, 16, 1
	v_bfe_u32 v147, v128, 16, 1
	v_add3_u32 v84, v84, v95, s11
	v_add3_u32 v95, v128, v147, s11
	v_lshrrev_b32_e32 v128, 16, v95
	v_cvt_pk_bf16_f32 v95, v129, v85
	v_and_or_b32 v94, v84, s10, v128
	v_cvt_pk_bf16_f32 v93, v101, v93
	v_cvt_pk_bf16_f32 v92, v100, v92
	v_lshl_add_u64 v[84:85], v[96:97], 0, v[122:123]
	global_store_dwordx4 v[84:85], v[92:95], off
	s_cbranch_scc1 .LBB0_2902
	s_cmp_gt_i32 s14, 1
	s_cbranch_scc0 .LBB0_2903
	s_cmp_lg_u32 s14, 2
	s_cselect_b64 s[10:11], -1, 0
	s_cbranch_execz .LBB0_2904
	s_branch .LBB0_2905

; __device__ __forceinline__ unsigned f2bf(float f) { unsigned u = __builtin_bit_cast(unsigned, f); return (u + 0x7fffu + ((u >> 16) & 1u)) >> 16; }
; __device__ __forceinline__ unsigned pk2(float lo, float hi) { return f2bf(lo) | (f2bf(hi) << 16); }
; __device__ __forceinline__ void fir_tile(const Prm& P, Ctx& C, int pm, int gi) {
;     ...
;     for (int j = 0; j < RUN; ++j) {
;         const int t = t0 + j;
;         const u32x4 g = *(const u32x4*)(GT + (size_t)(row0 + j) * 1024 + c0);
;         acc8(s, x[15 + j], 1.f);
;         const float inv = 1.f / (float)(t + 1 < w ? t + 1 : w);
;         const u32x4 xc = x[15 + j];
;         u32x4 o;
;         o.x = pk2((s[0] * inv - bflo(xc.x)) * sc0[0] * bflo(g.x), (s[1] * inv - bfhi(xc.x)) * sc0[1] * bfhi(g.x));
;         o.y = pk2((s[2] * inv - bflo(xc.y)) * sc0[2] * bflo(g.y), (s[3] * inv - bfhi(xc.y)) * sc0[3] * bfhi(g.y));
;         o.z = pk2((s[4] * inv - bflo(xc.z)) * sc1[0] * bflo(g.z), (s[5] * inv - bfhi(xc.z)) * sc1[1] * bfhi(g.z));
;         o.w = pk2((s[6] * inv - bflo(xc.w)) * sc1[2] * bflo(g.w), (s[7] * inv - bfhi(xc.w)) * sc1[3] * bfhi(g.w));
;         *(u32x4*)(MX + (size_t)(row0 + j) * 1024 + c0) = o;
;         if (w == 2) acc8(s, x[15 + j - 1], -1.f); else if (w == 4) acc8(s, x[15 + j - 3], -1.f); else if (w == 8) acc8(s, x[15 + j - 7], -1.f); else acc8(s, x[j], -1.f);
.LBB0_2911:
	v_or_b32_e32 v68, 12, v132
	v_ashrrev_i32_e32 v69, 31, v68
	v_lshlrev_b64 v[80:81], 11, v[68:69]
	v_lshl_add_u64 v[68:69], v[98:99], 0, v[80:81]
	global_load_dwordx4 v[92:95], v[68:69], off
	v_pk_add_f32 v[68:69], v[60:61], v[56:57] neg_lo:[0,1] neg_hi:[0,1]
	v_pk_add_f32 v[72:73], v[62:63], v[58:59] neg_lo:[0,1] neg_hi:[0,1]
	v_lshlrev_b32_e32 v60, 16, v22
	v_and_b32_e32 v62, 0xffff0000, v22
	v_or_b32_e32 v22, 13, v226
	v_min_i32_e32 v22, s16, v22
	v_pk_add_f32 v[76:77], v[78:79], v[86:87] neg_lo:[0,1] neg_hi:[0,1]
	v_pk_add_f32 v[78:79], v[82:83], v[102:103] neg_lo:[0,1] neg_hi:[0,1]
	v_cvt_f32_i32_e32 v82, v22
	v_lshlrev_b32_e32 v57, 16, v21
	v_lshlrev_b32_e32 v56, 16, v20
	v_lshlrev_b32_e32 v61, 16, v23
	v_and_b32_e32 v59, 0xffff0000, v21
	v_and_b32_e32 v58, 0xffff0000, v20
	v_pk_add_f32 v[20:21], v[68:69], v[56:57]
	v_pk_add_f32 v[68:69], v[76:77], v[60:61]
	v_div_scale_f32 v76, s[0:1], v82, v82, 1.0
	v_rcp_f32_e32 v77, v76
	v_and_b32_e32 v63, 0xffff0000, v23
	v_pk_add_f32 v[22:23], v[72:73], v[58:59]
	v_pk_add_f32 v[72:73], v[78:79], v[62:63]
	v_fma_f32 v79, -v76, v77, 1.0
	v_div_scale_f32 v78, vcc, 1.0, v82, 1.0
	v_fmac_f32_e32 v77, v79, v77
	v_mul_f32_e32 v79, v78, v77
	v_fma_f32 v83, -v76, v79, v78
	v_fmac_f32_e32 v79, v83, v77
	v_fma_f32 v76, -v76, v79, v78
	v_div_fmas_f32 v76, v76, v77, v79
	v_div_fixup_f32 v76, v76, v82, 1.0
	v_pk_fma_f32 v[78:79], v[76:77], v[20:21], v[56:57] op_sel_hi:[0,1,1] neg_lo:[0,0,1] neg_hi:[0,0,1]
	v_pk_fma_f32 v[84:85], v[76:77], v[68:69], v[60:61] op_sel_hi:[0,1,1] neg_lo:[0,0,1] neg_hi:[0,0,1]
	v_pk_fma_f32 v[82:83], v[76:77], v[22:23], v[58:59] op_sel_hi:[0,1,1] neg_lo:[0,0,1] neg_hi:[0,0,1]
	v_pk_fma_f32 v[76:77], v[76:77], v[72:73], v[62:63] op_sel_hi:[0,1,1] neg_lo:[0,0,1] neg_hi:[0,0,1]
	v_pk_mul_f32 v[78:79], v[64:65], v[78:79]
	v_pk_mul_f32 v[84:85], v[4:5], v[84:85]
	v_pk_mul_f32 v[82:83], v[6:7], v[82:83]
	v_pk_mul_f32 v[76:77], v[2:3], v[76:77]
	s_movk_i32 s11, 0x7fff
	s_mov_b32 s10, 0xffff0000
	v_lshl_add_u64 v[80:81], v[96:97], 0, v[80:81]
	s_cmp_lt_i32 s14, 1
	s_mov_b64 s[0:1], 0
	s_waitcnt vmcnt(0)
	v_lshlrev_b32_e32 v87, 16, v93
	v_lshlrev_b32_e32 v86, 16, v92
	v_lshlrev_b32_e32 v101, 16, v95
	v_lshlrev_b32_e32 v100, 16, v94
	v_and_b32_e32 v93, 0xffff0000, v93
	v_and_b32_e32 v92, 0xffff0000, v92
	v_and_b32_e32 v95, 0xffff0000, v95
	v_and_b32_e32 v94, 0xffff0000, v94
	v_pk_mul_f32 v[78:79], v[78:79], v[86:87]
	v_pk_mul_f32 v[84:85], v[84:85], v[100:101]
	v_pk_mul_f32 v[82:83], v[82:83], v[92:93]
	v_pk_mul_f32 v[76:77], v[76:77], v[94:95]
	v_bfe_u32 v94, v78, 16, 1
	v_bfe_u32 v95, v79, 16, 1
	v_bfe_u32 v92, v83, 16, 1
	v_bfe_u32 v93, v82, 16, 1
	v_add3_u32 v79, v79, v95, s11
	v_add3_u32 v78, v78, v94, s11
	v_add3_u32 v82, v82, v93, s11
	v_add3_u32 v83, v83, v92, s11
	v_lshrrev_b32_e32 v86, 16, v78
	v_lshrrev_b32_e32 v87, 16, v79
	v_cvt_pk_bf16_f32 v79, v85, v77
	v_cvt_pk_bf16_f32 v78, v84, v76
	v_and_or_b32 v77, v83, s10, v87
	v_and_or_b32 v76, v82, s10, v86
	global_store_dwordx4 v[80:81], v[76:79], off
	s_cbranch_scc1 .LBB0_2914
	s_cmp_gt_i32 s14, 1
	s_cbranch_scc0 .LBB0_2915
	s_cmp_lg_u32 s14, 2
	s_cselect_b64 s[10:11], -1, 0
	s_cbranch_execz .LBB0_2916
	s_branch .LBB0_2917

; __device__ __forceinline__ unsigned f2bf(float f) { unsigned u = __builtin_bit_cast(unsigned, f); return (u + 0x7fffu + ((u >> 16) & 1u)) >> 16; }
; __device__ __forceinline__ unsigned pk2(float lo, float hi) { return f2bf(lo) | (f2bf(hi) << 16); }
; __device__ __forceinline__ void fir_tile(const Prm& P, Ctx& C, int pm, int gi) {
;     ...
;     for (int j = 0; j < RUN; ++j) {
;         const int t = t0 + j;
;         const u32x4 g = *(const u32x4*)(GT + (size_t)(row0 + j) * 1024 + c0);
;         acc8(s, x[15 + j], 1.f);
;         const float inv = 1.f / (float)(t + 1 < w ? t + 1 : w);
;         const u32x4 xc = x[15 + j];
;         u32x4 o;
;         o.x = pk2((s[0] * inv - bflo(xc.x)) * sc0[0] * bflo(g.x), (s[1] * inv - bfhi(xc.x)) * sc0[1] * bfhi(g.x));
;         o.y = pk2((s[2] * inv - bflo(xc.y)) * sc0[2] * bflo(g.y), (s[3] * inv - bfhi(xc.y)) * sc0[3] * bfhi(g.y));
;         o.z = pk2((s[4] * inv - bflo(xc.z)) * sc1[0] * bflo(g.z), (s[5] * inv - bfhi(xc.z)) * sc1[1] * bfhi(g.z));
;         o.w = pk2((s[6] * inv - bflo(xc.w)) * sc1[2] * bflo(g.w), (s[7] * inv - bfhi(xc.w)) * sc1[3] * bfhi(g.w));
;         *(u32x4*)(MX + (size_t)(row0 + j) * 1024 + c0) = o;
;         if (w == 2) acc8(s, x[15 + j - 1], -1.f); else if (w == 4) acc8(s, x[15 + j - 3], -1.f); else if (w == 8) acc8(s, x[15 + j - 7], -1.f); else acc8(s, x[j], -1.f);
.LBB0_2923:
	v_or_b32_e32 v32, 13, v132
	v_ashrrev_i32_e32 v33, 31, v32
	v_lshlrev_b64 v[78:79], 11, v[32:33]
	v_lshl_add_u64 v[32:33], v[98:99], 0, v[78:79]
	global_load_dwordx4 v[74:77], v[32:33], off
	v_pk_add_f32 v[36:37], v[22:23], v[54:55] neg_lo:[0,1] neg_hi:[0,1]
	v_or_b32_e32 v54, 14, v226
	v_min_i32_e32 v54, s16, v54
	v_cvt_f32_i32_e32 v54, v54
	v_pk_add_f32 v[38:39], v[68:69], v[88:89] neg_lo:[0,1] neg_hi:[0,1]
	v_pk_add_f32 v[32:33], v[20:21], v[52:53] neg_lo:[0,1] neg_hi:[0,1]
	v_pk_add_f32 v[52:53], v[72:73], v[130:131] neg_lo:[0,1] neg_hi:[0,1]
	v_div_scale_f32 v55, s[0:1], v54, v54, 1.0
	v_rcp_f32_e32 v68, v55
	v_div_scale_f32 v69, vcc, 1.0, v54, 1.0
	v_lshlrev_b32_e32 v21, 16, v17
	v_fma_f32 v72, -v55, v68, 1.0
	v_fmac_f32_e32 v68, v72, v68
	v_mul_f32_e32 v72, v69, v68
	v_fma_f32 v73, -v55, v72, v69
	v_fmac_f32_e32 v72, v73, v68
	v_fma_f32 v55, -v55, v72, v69
	v_lshlrev_b32_e32 v20, 16, v16
	v_and_b32_e32 v17, 0xffff0000, v17
	v_and_b32_e32 v16, 0xffff0000, v16
	v_lshlrev_b32_e32 v23, 16, v19
	v_lshlrev_b32_e32 v22, 16, v18
	v_div_fmas_f32 v55, v55, v68, v72
	v_and_b32_e32 v19, 0xffff0000, v19
	v_and_b32_e32 v18, 0xffff0000, v18
	v_pk_add_f32 v[32:33], v[32:33], v[20:21]
	v_pk_add_f32 v[36:37], v[36:37], v[16:17]
	v_pk_add_f32 v[38:39], v[38:39], v[22:23]
	v_div_fixup_f32 v54, v55, v54, 1.0
	v_pk_add_f32 v[52:53], v[52:53], v[18:19]
	v_pk_fma_f32 v[68:69], v[54:55], v[32:33], v[20:21] op_sel_hi:[0,1,1] neg_lo:[0,0,1] neg_hi:[0,0,1]
	v_pk_fma_f32 v[72:73], v[54:55], v[36:37], v[16:17] op_sel_hi:[0,1,1] neg_lo:[0,0,1] neg_hi:[0,0,1]
	v_pk_fma_f32 v[80:81], v[54:55], v[38:39], v[22:23] op_sel_hi:[0,1,1] neg_lo:[0,0,1] neg_hi:[0,0,1]
	v_pk_fma_f32 v[54:55], v[54:55], v[52:53], v[18:19] op_sel_hi:[0,1,1] neg_lo:[0,0,1] neg_hi:[0,0,1]
	v_pk_mul_f32 v[68:69], v[64:65], v[68:69]
	v_pk_mul_f32 v[72:73], v[6:7], v[72:73]
	v_pk_mul_f32 v[80:81], v[4:5], v[80:81]
	v_pk_mul_f32 v[54:55], v[2:3], v[54:55]
	s_movk_i32 s11, 0x7fff
	s_mov_b32 s10, 0xffff0000
	s_cmp_lt_i32 s14, 1
	s_mov_b64 s[0:1], 0
	s_waitcnt vmcnt(0)
	v_lshlrev_b32_e32 v83, 16, v75
	v_lshlrev_b32_e32 v82, 16, v74
	v_and_b32_e32 v75, 0xffff0000, v75
	v_and_b32_e32 v74, 0xffff0000, v74
	v_lshlrev_b32_e32 v85, 16, v77
	v_lshlrev_b32_e32 v84, 16, v76
	v_and_b32_e32 v77, 0xffff0000, v77
	v_and_b32_e32 v76, 0xffff0000, v76
	v_pk_mul_f32 v[68:69], v[68:69], v[82:83]
	v_pk_mul_f32 v[72:73], v[72:73], v[74:75]
	v_pk_mul_f32 v[74:75], v[80:81], v[84:85]
	v_pk_mul_f32 v[54:55], v[54:55], v[76:77]
	v_cvt_pk_bf16_f32 v75, v75, v55
	v_cvt_pk_bf16_f32 v74, v74, v54
	v_cvt_pk_bf16_f32 v73, v69, v73
	v_cvt_pk_bf16_f32 v72, v68, v72
	v_lshl_add_u64 v[54:55], v[96:97], 0, v[78:79]
	global_store_dwordx4 v[54:55], v[72:75], off
	s_cbranch_scc1 .LBB0_2926
	s_cmp_gt_i32 s14, 1
	s_cbranch_scc0 .LBB0_2927
	s_cmp_lg_u32 s14, 2
	s_cselect_b64 s[10:11], -1, 0
	s_cbranch_execz .LBB0_2928
	s_branch .LBB0_2929

; __device__ __forceinline__ unsigned f2bf(float f) { unsigned u = __builtin_bit_cast(unsigned, f); return (u + 0x7fffu + ((u >> 16) & 1u)) >> 16; }
; __device__ __forceinline__ unsigned pk2(float lo, float hi) { return f2bf(lo) | (f2bf(hi) << 16); }
; __device__ __forceinline__ void fir_tile(const Prm& P, Ctx& C, int pm, int gi) {
;     ...
;     for (int j = 0; j < RUN; ++j) {
;         const int t = t0 + j;
;         const u32x4 g = *(const u32x4*)(GT + (size_t)(row0 + j) * 1024 + c0);
;         acc8(s, x[15 + j], 1.f);
;         const float inv = 1.f / (float)(t + 1 < w ? t + 1 : w);
;         const u32x4 xc = x[15 + j];
;         u32x4 o;
;         o.x = pk2((s[0] * inv - bflo(xc.x)) * sc0[0] * bflo(g.x), (s[1] * inv - bfhi(xc.x)) * sc0[1] * bfhi(g.x));
;         o.y = pk2((s[2] * inv - bflo(xc.y)) * sc0[2] * bflo(g.y), (s[3] * inv - bfhi(xc.y)) * sc0[3] * bfhi(g.y));
;         o.z = pk2((s[4] * inv - bflo(xc.z)) * sc1[0] * bflo(g.z), (s[5] * inv - bfhi(xc.z)) * sc1[1] * bfhi(g.z));
;         o.w = pk2((s[6] * inv - bflo(xc.w)) * sc1[2] * bflo(g.w), (s[7] * inv - bfhi(xc.w)) * sc1[3] * bfhi(g.w));
;         *(u32x4*)(MX + (size_t)(row0 + j) * 1024 + c0) = o;
;         if (w == 2) acc8(s, x[15 + j - 1], -1.f); else if (w == 4) acc8(s, x[15 + j - 3], -1.f); else if (w == 8) acc8(s, x[15 + j - 7], -1.f); else acc8(s, x[j], -1.f);
.LBB0_2947:
	v_or_b32_e32 v16, 15, v132
	v_ashrrev_i32_e32 v17, 31, v16
	v_lshlrev_b64 v[20:21], 11, v[16:17]
	v_lshl_add_u64 v[16:17], v[98:99], 0, v[20:21]
	global_load_dwordx4 v[16:19], v[16:17], off
	v_add_u32_e32 v28, 16, v226
	v_min_i32_e32 v28, s16, v28
	v_cvt_f32_i32_e32 v28, v28
	v_pk_add_f32 v[22:23], v[32:33], v[42:43] neg_lo:[0,1] neg_hi:[0,1]
	v_pk_add_f32 v[0:1], v[0:1], v[44:45] neg_lo:[0,1] neg_hi:[0,1]
	v_pk_add_f32 v[12:13], v[12:13], v[40:41] neg_lo:[0,1] neg_hi:[0,1]
	v_div_scale_f32 v29, s[0:1], v28, v28, 1.0
	v_rcp_f32_e32 v30, v29
	v_div_scale_f32 v31, vcc, 1.0, v28, 1.0
	v_pk_add_f32 v[14:15], v[14:15], v[46:47] neg_lo:[0,1] neg_hi:[0,1]
	v_fma_f32 v32, -v29, v30, 1.0
	v_fmac_f32_e32 v30, v32, v30
	v_mul_f32_e32 v32, v31, v30
	v_fma_f32 v33, -v29, v32, v31
	v_fmac_f32_e32 v32, v33, v30
	v_fma_f32 v29, -v29, v32, v31
	v_lshlrev_b32_e32 v24, 16, v8
	v_and_b32_e32 v8, 0xffff0000, v8
	v_lshlrev_b32_e32 v25, 16, v9
	v_and_b32_e32 v9, 0xffff0000, v9
	v_lshlrev_b32_e32 v26, 16, v10
	v_lshlrev_b32_e32 v27, 16, v11
	v_div_fmas_f32 v29, v29, v30, v32
	v_and_b32_e32 v10, 0xffff0000, v10
	v_and_b32_e32 v11, 0xffff0000, v11
	v_pk_add_f32 v[0:1], v[0:1], v[24:25]
	v_pk_add_f32 v[12:13], v[12:13], v[8:9]
	v_pk_add_f32 v[14:15], v[14:15], v[26:27]
	v_div_fixup_f32 v28, v29, v28, 1.0
	v_pk_add_f32 v[22:23], v[22:23], v[10:11]
	v_pk_fma_f32 v[0:1], v[28:29], v[0:1], v[24:25] op_sel_hi:[0,1,1] neg_lo:[0,0,1] neg_hi:[0,0,1]
	v_pk_fma_f32 v[8:9], v[28:29], v[12:13], v[8:9] op_sel_hi:[0,1,1] neg_lo:[0,0,1] neg_hi:[0,0,1]
	v_pk_fma_f32 v[12:13], v[28:29], v[14:15], v[26:27] op_sel_hi:[0,1,1] neg_lo:[0,0,1] neg_hi:[0,0,1]
	v_pk_fma_f32 v[10:11], v[28:29], v[22:23], v[10:11] op_sel_hi:[0,1,1] neg_lo:[0,0,1] neg_hi:[0,0,1]
	v_pk_mul_f32 v[0:1], v[64:65], v[0:1]
	v_pk_mul_f32 v[6:7], v[6:7], v[8:9]
	v_pk_mul_f32 v[4:5], v[4:5], v[12:13]
	v_pk_mul_f32 v[2:3], v[2:3], v[10:11]
	s_movk_i32 s11, 0x7fff
	s_mov_b32 s10, 0xffff0000
	s_waitcnt vmcnt(0)
	v_lshlrev_b32_e32 v9, 16, v17
	v_lshlrev_b32_e32 v8, 16, v16
	v_lshlrev_b32_e32 v13, 16, v19
	v_lshlrev_b32_e32 v12, 16, v18
	v_and_b32_e32 v11, 0xffff0000, v17
	v_and_b32_e32 v10, 0xffff0000, v16
	v_and_b32_e32 v15, 0xffff0000, v19
	v_and_b32_e32 v14, 0xffff0000, v18
	v_pk_mul_f32 v[0:1], v[0:1], v[8:9]
	v_pk_mul_f32 v[4:5], v[4:5], v[12:13]
	v_pk_mul_f32 v[6:7], v[6:7], v[10:11]
	v_pk_mul_f32 v[2:3], v[2:3], v[14:15]
	v_bfe_u32 v12, v0, 16, 1
	v_bfe_u32 v13, v1, 16, 1
	v_bfe_u32 v10, v7, 16, 1
	v_bfe_u32 v11, v6, 16, 1
	v_add3_u32 v1, v1, v13, s11
	v_add3_u32 v0, v0, v12, s11
	v_add3_u32 v6, v6, v11, s11
	v_add3_u32 v7, v7, v10, s11
	v_lshrrev_b32_e32 v0, 16, v0
	v_lshrrev_b32_e32 v1, 16, v1
	v_cvt_pk_bf16_f32 v3, v5, v3
	v_cvt_pk_bf16_f32 v2, v4, v2
	v_and_or_b32 v1, v7, s10, v1
	v_and_or_b32 v0, v6, s10, v0
	v_lshl_add_u64 v[4:5], v[96:97], 0, v[20:21]
	global_store_dwordx4 v[4:5], v[0:3], off

; __device__ __forceinline__ void acc8(float (&s)[8], const u32x4 x, float sg) {
;     s[0] += sg * bflo(x.x); s[1] += sg * bfhi(x.x); s[2] += sg * bflo(x.y); s[3] += sg * bfhi(x.y); s[4] += sg * bflo(x.z); s[5] += sg * bfhi(x.z); s[6] += sg * bflo(x.w); s[7] += sg * bfhi(x.w);
; }
; __device__ __forceinline__ void fir_tile(const Prm& P, Ctx& C, int pm, int gi) {
;     const bf16_t* Z = (const bf16_t*)(P.ws + WS_V); const bf16_t* GT = (const bf16_t*)(P.ws + WS_GT); bf16_t* MX = (bf16_t*)(P.ws + WS_MX);
;     constexpr int RUN = 16;
;     const int c0 = 256 * gi + (C.tid & 31) * 8, row0 = 256 * pm + (C.tid >> 5) * RUN, w = 2 << gi, t0 = row0 & (SEQ - 1);
;     const bf16_t* zp = Z + (size_t)row0 * 1024 + c0;
;     u32x4 x[RUN + 15];
; #pragma unroll
;     for (int j = 0; j < RUN + 15; ++j) { const int k = j - 15; x[j] = (k >= 1 - w && t0 + k >= 0) ? *(const u32x4*)(zp + (ptrdiff_t)k * 1024) : (u32x4){0u, 0u, 0u, 0u}; }
;     const f32x4 sc0 = *(const f32x4*)(P.pool_scale + c0), sc1 = *(const f32x4*)(P.pool_scale + c0 + 4);
;     float s[8];
; #pragma unroll
;     for (int e = 0; e < 8; ++e) s[e] = 0.f;
; #pragma unroll
;     for (int j = 0; j < 15; ++j) acc8(s, x[j], 1.f);
.LBB0_3018:
	v_readlane_b32 s16, v250, 0
	v_readlane_b32 s18, v250, 2
	v_readlane_b32 s19, v250, 3
	s_waitcnt vmcnt(0)
	v_lshlrev_b32_e32 v199, 16, v93
	v_lshlrev_b32_e32 v198, 16, v92
	v_and_b32_e32 v201, 0xffff0000, v93
	v_and_b32_e32 v200, 0xffff0000, v92
	v_lshlrev_b64 v[92:93], 1, v[168:169]
	v_lshl_add_u64 v[4:5], v[168:169], 2, s[18:19]
	v_lshlrev_b32_e32 v190, 16, v98
	v_and_b32_e32 v192, 0xffff0000, v98
	v_lshlrev_b32_e32 v191, 16, v99
	v_and_b32_e32 v193, 0xffff0000, v99
	v_lshl_add_u64 v[98:99], s[4:5], 0, v[92:93]
	global_load_dwordx4 v[0:3], v[4:5], off offset:16
	s_nop 0
	global_load_dwordx4 v[4:7], v[4:5], off
	v_lshlrev_b32_e32 v186, 16, v96
	v_and_b32_e32 v188, 0xffff0000, v96
	v_lshlrev_b32_e32 v187, 16, v97
	v_and_b32_e32 v189, 0xffff0000, v97
	v_lshl_add_u64 v[96:97], s[6:7], 0, v[92:93]
	v_lshl_add_u64 v[92:93], v[98:99], 0, v[196:197]
	v_lshlrev_b32_e32 v203, 16, v95
	v_lshlrev_b32_e32 v202, 16, v94
	v_and_b32_e32 v205, 0xffff0000, v95
	v_and_b32_e32 v204, 0xffff0000, v94
	global_load_dwordx4 v[92:95], v[92:93], off
	v_and_b32_e32 v217, 0xffff0000, v69
	v_and_b32_e32 v216, 0xffff0000, v68
	v_lshlrev_b32_e32 v207, 16, v65
	v_lshlrev_b32_e32 v206, 16, v64
	v_and_b32_e32 v209, 0xffff0000, v65
	v_and_b32_e32 v208, 0xffff0000, v64
	v_pk_add_f32 v[64:65], v[216:217], 0 op_sel_hi:[1,0]
	v_lshlrev_b32_e32 v175, 16, v85
	v_lshlrev_b32_e32 v174, 16, v84
	v_and_b32_e32 v177, 0xffff0000, v85
	v_and_b32_e32 v176, 0xffff0000, v84
	v_and_b32_e32 v85, 0xffff0000, v73
	v_and_b32_e32 v84, 0xffff0000, v72
	v_pk_add_f32 v[64:65], v[64:65], v[208:209]
	v_and_b32_e32 v183, 0xffff0000, v77
	v_pk_add_f32 v[64:65], v[64:65], v[84:85]
	v_and_b32_e32 v182, 0xffff0000, v76
	v_pk_add_f32 v[64:65], v[64:65], v[200:201]
	v_lshlrev_b32_e32 v137, 16, v105
	v_pk_add_f32 v[64:65], v[64:65], v[188:189]
	v_lshlrev_b32_e32 v136, 16, v104
	v_pk_add_f32 v[64:65], v[64:65], v[182:183]
	v_and_b32_e32 v139, 0xffff0000, v105
	v_and_b32_e32 v138, 0xffff0000, v104
	v_lshlrev_b32_e32 v141, 16, v107
	v_lshlrev_b32_e32 v140, 16, v106
	v_and_b32_e32 v143, 0xffff0000, v107
	v_and_b32_e32 v142, 0xffff0000, v106
	v_lshlrev_b32_e32 v105, 16, v129
	v_lshlrev_b32_e32 v104, 16, v128
	v_and_b32_e32 v107, 0xffff0000, v129
	v_and_b32_e32 v106, 0xffff0000, v128
	v_lshlrev_b32_e32 v129, 16, v81
	v_lshlrev_b32_e32 v128, 16, v80
	v_and_b32_e32 v81, 0xffff0000, v81
	v_and_b32_e32 v80, 0xffff0000, v80
	v_pk_add_f32 v[64:65], v[64:65], v[176:177]
	v_and_b32_e32 v163, 0xffff0000, v117
	v_and_b32_e32 v162, 0xffff0000, v116
	v_pk_add_f32 v[64:65], v[64:65], v[80:81]
	v_and_b32_e32 v155, 0xffff0000, v109
	v_and_b32_e32 v154, 0xffff0000, v108
	v_pk_add_f32 v[64:65], v[64:65], v[162:163]
	v_and_b32_e32 v147, 0xffff0000, v113
	v_and_b32_e32 v146, 0xffff0000, v112
	v_pk_add_f32 v[64:65], v[64:65], v[154:155]
	v_lshlrev_b32_e32 v135, 16, v125
	v_pk_add_f32 v[64:65], v[64:65], v[146:147]
	v_lshlrev_b32_e32 v134, 16, v124
	v_and_b32_e32 v125, 0xffff0000, v125
	v_and_b32_e32 v124, 0xffff0000, v124
	v_pk_add_f32 v[64:65], v[64:65], v[138:139]
	v_lshlrev_b32_e32 v145, 16, v113
	v_lshlrev_b32_e32 v144, 16, v112
	v_and_b32_e32 v113, 0xffff0000, v121
	v_and_b32_e32 v112, 0xffff0000, v120
	v_pk_add_f32 v[64:65], v[64:65], v[124:125]
	v_lshlrev_b32_e32 v169, 16, v77
	v_pk_add_f32 v[64:65], v[64:65], v[112:113]
	v_lshlrev_b32_e32 v168, 16, v76
	v_and_b32_e32 v77, 0xffff0000, v101
	v_and_b32_e32 v76, 0xffff0000, v100
	v_pk_add_f32 v[64:65], v[64:65], v[106:107]
	v_lshlrev_b32_e32 v221, 16, v71
	v_lshlrev_b32_e32 v220, 16, v70
	v_pk_add_f32 v[218:219], v[64:65], v[76:77]
	v_lshlrev_b32_e32 v211, 16, v67
	v_lshlrev_b32_e32 v210, 16, v66
	v_pk_add_f32 v[64:65], v[220:221], 0 op_sel_hi:[1,0]
	v_lshlrev_b32_e32 v165, 16, v119
	v_lshlrev_b32_e32 v164, 16, v118
	v_and_b32_e32 v167, 0xffff0000, v119
	v_and_b32_e32 v166, 0xffff0000, v118
	v_lshlrev_b32_e32 v149, 16, v115
	v_lshlrev_b32_e32 v148, 16, v114
	v_lshlrev_b32_e32 v119, 16, v123
	v_lshlrev_b32_e32 v118, 16, v122
	v_and_b32_e32 v151, 0xffff0000, v115
	v_and_b32_e32 v150, 0xffff0000, v114
	v_and_b32_e32 v115, 0xffff0000, v123
	v_and_b32_e32 v114, 0xffff0000, v122
	v_lshlrev_b32_e32 v123, 16, v101
	v_lshlrev_b32_e32 v122, 16, v100
	v_lshlrev_b32_e32 v101, 16, v75
	v_lshlrev_b32_e32 v100, 16, v74
	v_pk_add_f32 v[64:65], v[64:65], v[210:211]
	v_lshlrev_b32_e32 v185, 16, v79
	v_pk_add_f32 v[64:65], v[64:65], v[100:101]
	v_lshlrev_b32_e32 v184, 16, v78
	v_pk_add_f32 v[64:65], v[64:65], v[202:203]
	v_lshlrev_b32_e32 v179, 16, v87
	v_pk_add_f32 v[64:65], v[64:65], v[190:191]
	v_lshlrev_b32_e32 v178, 16, v86
	v_pk_add_f32 v[64:65], v[64:65], v[184:185]
	v_lshlrev_b32_e32 v153, 16, v109
	v_lshlrev_b32_e32 v152, 16, v108
	v_lshlrev_b32_e32 v157, 16, v111
	v_lshlrev_b32_e32 v156, 16, v110
	v_and_b32_e32 v159, 0xffff0000, v111
	v_and_b32_e32 v158, 0xffff0000, v110
	v_lshlrev_b32_e32 v109, 16, v131
	v_lshlrev_b32_e32 v108, 16, v130
	v_and_b32_e32 v111, 0xffff0000, v131
	v_and_b32_e32 v110, 0xffff0000, v130
	v_lshlrev_b32_e32 v131, 16, v73
	v_lshlrev_b32_e32 v130, 16, v72
	v_lshlrev_b32_e32 v73, 16, v83
	v_lshlrev_b32_e32 v72, 16, v82
; __device__ __forceinline__ unsigned f2bf(float f) { unsigned u = __builtin_bit_cast(unsigned, f); return (u + 0x7fffu + ((u >> 16) & 1u)) >> 16; }
; __device__ __forceinline__ unsigned pk2(float lo, float hi) { return f2bf(lo) | (f2bf(hi) << 16); }
; __device__ __forceinline__ void fir_tile(const Prm& P, Ctx& C, int pm, int gi) {
;     ...
;     for (int j = 0; j < 15; ++j) acc8(s, x[j], 1.f);
; #pragma unroll
;     for (int j = 0; j < RUN; ++j) {
;         const int t = t0 + j;
;         const u32x4 g = *(const u32x4*)(GT + (size_t)(row0 + j) * 1024 + c0);
;         acc8(s, x[15 + j], 1.f);
;         const float inv = 1.f / (float)(t + 1 < w ? t + 1 : w);
;         const u32x4 xc = x[15 + j];
;         u32x4 o;
;         o.x = pk2((s[0] * inv - bflo(xc.x)) * sc0[0] * bflo(g.x), (s[1] * inv - bfhi(xc.x)) * sc0[1] * bfhi(g.x));
;         o.y = pk2((s[2] * inv - bflo(xc.y)) * sc0[2] * bflo(g.y), (s[3] * inv - bfhi(xc.y)) * sc0[3] * bfhi(g.y));
;         o.z = pk2((s[4] * inv - bflo(xc.z)) * sc1[0] * bflo(g.z), (s[5] * inv - bfhi(xc.z)) * sc1[1] * bfhi(g.z));
;         o.w = pk2((s[6] * inv - bflo(xc.w)) * sc1[2] * bflo(g.w), (s[7] * inv - bfhi(xc.w)) * sc1[3] * bfhi(g.w));
;         *(u32x4*)(MX + (size_t)(row0 + j) * 1024 + c0) = o;
;         if (w == 2) acc8(s, x[15 + j - 1], -1.f); else if (w == 4) acc8(s, x[15 + j - 3], -1.f); else if (w == 8) acc8(s, x[15 + j - 7], -1.f); else acc8(s, x[j], -1.f);
	v_pk_add_f32 v[64:65], v[64:65], v[178:179]
	v_lshlrev_b32_e32 v161, 16, v117
	v_pk_add_f32 v[64:65], v[64:65], v[72:73]
	v_lshlrev_b32_e32 v160, 16, v116
	v_pk_add_f32 v[64:65], v[64:65], v[164:165]
	v_lshlrev_b32_e32 v117, 16, v121
	v_pk_add_f32 v[64:65], v[64:65], v[156:157]
	v_lshlrev_b32_e32 v116, 16, v120
	v_pk_add_f32 v[64:65], v[64:65], v[148:149]
	v_lshlrev_b32_e32 v121, 16, v127
	v_lshlrev_b32_e32 v120, 16, v126
	v_pk_add_f32 v[64:65], v[64:65], v[140:141]
	v_lshlrev_b32_e32 v213, 16, v69
	v_pk_add_f32 v[64:65], v[64:65], v[120:121]
	v_lshlrev_b32_e32 v212, 16, v68
	v_pk_add_f32 v[64:65], v[64:65], v[118:119]
	v_pk_add_f32 v[170:171], v[212:213], 0 op_sel_hi:[1,0]
	v_lshlrev_b32_e32 v69, 16, v103
	v_lshlrev_b32_e32 v68, 16, v102
	v_pk_add_f32 v[64:65], v[64:65], v[108:109]
	v_and_b32_e32 v195, 0xffff0000, v79
	v_and_b32_e32 v194, 0xffff0000, v78
	v_and_b32_e32 v79, 0xffff0000, v71
	v_and_b32_e32 v78, 0xffff0000, v70
	v_pk_add_f32 v[170:171], v[170:171], v[206:207]
	v_pk_add_f32 v[222:223], v[64:65], v[68:69]
	v_and_b32_e32 v71, 0xffff0000, v67
	v_and_b32_e32 v70, 0xffff0000, v66
	v_pk_add_f32 v[64:65], v[78:79], 0 op_sel_hi:[1,0]
	v_pk_add_f32 v[170:171], v[170:171], v[130:131]
	v_and_b32_e32 v181, 0xffff0000, v87
	v_and_b32_e32 v180, 0xffff0000, v86
	v_and_b32_e32 v87, 0xffff0000, v75
	v_and_b32_e32 v86, 0xffff0000, v74
	v_pk_add_f32 v[64:65], v[64:65], v[70:71]
	v_pk_add_f32 v[170:171], v[170:171], v[198:199]
	v_pk_add_f32 v[64:65], v[64:65], v[86:87]
	v_pk_add_f32 v[170:171], v[170:171], v[186:187]
	v_pk_add_f32 v[64:65], v[64:65], v[204:205]
	v_or_b32_e32 v133, 1, v224
	v_pk_add_f32 v[170:171], v[170:171], v[168:169]
	v_pk_add_f32 v[64:65], v[64:65], v[192:193]
	v_pk_add_f32 v[170:171], v[170:171], v[174:175]
	v_pk_add_f32 v[64:65], v[64:65], v[194:195]
	v_min_i32_e32 v66, s10, v133
	v_pk_add_f32 v[170:171], v[170:171], v[128:129]
	v_and_b32_e32 v173, 0xffff0000, v83
	v_and_b32_e32 v172, 0xffff0000, v82
	v_pk_add_f32 v[64:65], v[64:65], v[180:181]
	v_cvt_f32_i32_e32 v74, v66
	v_pk_add_f32 v[170:171], v[170:171], v[160:161]
	v_pk_add_f32 v[64:65], v[64:65], v[172:173]
	v_pk_add_f32 v[170:171], v[170:171], v[152:153]
	v_pk_add_f32 v[64:65], v[64:65], v[166:167]
	v_pk_add_f32 v[170:171], v[170:171], v[144:145]
	v_pk_add_f32 v[64:65], v[64:65], v[158:159]
	v_pk_add_f32 v[170:171], v[170:171], v[136:137]
	v_pk_add_f32 v[64:65], v[64:65], v[150:151]
	v_div_scale_f32 v75, s[4:5], v74, v74, 1.0
	v_and_b32_e32 v127, 0xffff0000, v127
	v_and_b32_e32 v126, 0xffff0000, v126
	v_pk_add_f32 v[170:171], v[170:171], v[134:135]
	v_pk_add_f32 v[64:65], v[64:65], v[142:143]
	v_rcp_f32_e32 v82, v75
	v_pk_add_f32 v[170:171], v[170:171], v[116:117]
	v_pk_add_f32 v[64:65], v[64:65], v[126:127]
	v_pk_add_f32 v[170:171], v[170:171], v[104:105]
	v_pk_add_f32 v[64:65], v[64:65], v[114:115]
	v_pk_add_f32 v[214:215], v[170:171], v[122:123]
	v_and_b32_e32 v171, 0xffff0000, v103
	v_and_b32_e32 v170, 0xffff0000, v102
	v_pk_add_f32 v[64:65], v[64:65], v[110:111]
	s_waitcnt vmcnt(0)
	v_lshlrev_b32_e32 v103, 16, v93
	v_pk_add_f32 v[66:67], v[64:65], v[170:171]
	v_fma_f32 v64, -v75, v82, 1.0
	v_fmac_f32_e32 v82, v64, v82
	v_div_scale_f32 v64, vcc, 1.0, v74, 1.0
	v_mul_f32_e32 v65, v64, v82
	v_fma_f32 v83, -v75, v65, v64
	v_fmac_f32_e32 v65, v83, v82
	v_fma_f32 v64, -v75, v65, v64
	v_div_fmas_f32 v64, v64, v82, v65
	v_div_fixup_f32 v74, v64, v74, 1.0
	v_pk_fma_f32 v[82:83], v[74:75], v[214:215], v[122:123] op_sel_hi:[0,1,1] neg_lo:[0,0,1] neg_hi:[0,0,1]
	v_mov_b32_e32 v64, v4
	v_mov_b32_e32 v65, v6
	v_pk_mul_f32 v[82:83], v[82:83], v[64:65]
	v_lshlrev_b32_e32 v102, 16, v92
	v_pk_mul_f32 v[82:83], v[82:83], v[102:103]
	v_pk_fma_f32 v[102:103], v[74:75], v[218:219], v[76:77] op_sel_hi:[0,1,1] neg_lo:[0,0,1] neg_hi:[0,0,1]
	v_mov_b32_e32 v6, v5
	v_pk_mul_f32 v[4:5], v[102:103], v[6:7]
	v_and_b32_e32 v93, 0xffff0000, v93
	v_and_b32_e32 v92, 0xffff0000, v92
	v_pk_mul_f32 v[92:93], v[4:5], v[92:93]
	v_pk_fma_f32 v[102:103], v[74:75], v[222:223], v[68:69] op_sel_hi:[0,1,1] neg_lo:[0,0,1] neg_hi:[0,0,1]
	v_mov_b32_e32 v5, v2
	v_pk_fma_f32 v[74:75], v[74:75], v[66:67], v[170:171] op_sel_hi:[0,1,1] neg_lo:[0,0,1] neg_hi:[0,0,1]
	v_mov_b32_e32 v2, v1
	v_mov_b32_e32 v4, v0
	v_pk_mul_f32 v[0:1], v[74:75], v[2:3]
	v_and_b32_e32 v75, 0xffff0000, v95
	v_and_b32_e32 v74, 0xffff0000, v94
	v_pk_mul_f32 v[102:103], v[102:103], v[4:5]
	v_lshlrev_b32_e32 v227, 16, v95
	v_lshlrev_b32_e32 v226, 16, v94
	v_pk_mul_f32 v[0:1], v[0:1], v[74:75]
	v_pk_mul_f32 v[102:103], v[102:103], v[226:227]
	s_movk_i32 s1, 0x7fff
	s_mov_b32 s0, 0xffff0000
	v_cvt_pk_bf16_f32 v95, v103, v1
	v_cvt_pk_bf16_f32 v94, v102, v0
	v_cvt_pk_bf16_f32 v93, v83, v93
	v_cvt_pk_bf16_f32 v92, v82, v92
	v_lshl_add_u64 v[0:1], v[96:97], 0, v[196:197]
	s_cmp_lt_i32 s14, 1
	v_readlane_b32 s17, v250, 1
	v_readlane_b32 s20, v250, 4
	v_readlane_b32 s21, v250, 5
	v_readlane_b32 s22, v250, 6
	v_readlane_b32 s23, v250, 7
	global_store_dwordx4 v[0:1], v[92:95], off
	s_cbranch_scc1 .LBB0_3023
	s_cmp_gt_i32 s14, 1
	s_cbranch_scc0 .LBB0_3024
	s_cmp_eq_u32 s14, 2
	s_mov_b64 s[0:1], -1
	s_cbranch_scc0 .LBB0_3022
	s_mov_b64 s[0:1], 0

; __device__ __forceinline__ unsigned f2bf(float f) { unsigned u = __builtin_bit_cast(unsigned, f); return (u + 0x7fffu + ((u >> 16) & 1u)) >> 16; }
; __device__ __forceinline__ unsigned pk2(float lo, float hi) { return f2bf(lo) | (f2bf(hi) << 16); }
; __device__ __forceinline__ void fir_tile(const Prm& P, Ctx& C, int pm, int gi) {
;     ...
;     for (int j = 0; j < RUN; ++j) {
;         const int t = t0 + j;
;         const u32x4 g = *(const u32x4*)(GT + (size_t)(row0 + j) * 1024 + c0);
;         acc8(s, x[15 + j], 1.f);
;         const float inv = 1.f / (float)(t + 1 < w ? t + 1 : w);
;         const u32x4 xc = x[15 + j];
;         u32x4 o;
;         o.x = pk2((s[0] * inv - bflo(xc.x)) * sc0[0] * bflo(g.x), (s[1] * inv - bfhi(xc.x)) * sc0[1] * bfhi(g.x));
;         o.y = pk2((s[2] * inv - bflo(xc.y)) * sc0[2] * bflo(g.y), (s[3] * inv - bfhi(xc.y)) * sc0[3] * bfhi(g.y));
;         o.z = pk2((s[4] * inv - bflo(xc.z)) * sc1[0] * bflo(g.z), (s[5] * inv - bfhi(xc.z)) * sc1[1] * bfhi(g.z));
;         o.w = pk2((s[6] * inv - bflo(xc.w)) * sc1[2] * bflo(g.w), (s[7] * inv - bfhi(xc.w)) * sc1[3] * bfhi(g.w));
;         *(u32x4*)(MX + (size_t)(row0 + j) * 1024 + c0) = o;
;         if (w == 2) acc8(s, x[15 + j - 1], -1.f); else if (w == 4) acc8(s, x[15 + j - 3], -1.f); else if (w == 8) acc8(s, x[15 + j - 7], -1.f); else acc8(s, x[j], -1.f);
.LBB0_3031:
	v_or_b32_e32 v78, 1, v132
	v_ashrrev_i32_e32 v79, 31, v78
	v_lshlrev_b64 v[94:95], 11, v[78:79]
	v_lshl_add_u64 v[78:79], v[98:99], 0, v[94:95]
	global_load_dwordx4 v[226:229], v[78:79], off
	v_pk_add_f32 v[196:197], v[222:223], v[82:83] neg_lo:[0,1] neg_hi:[0,1]
	v_or_b32_e32 v82, 2, v224
	v_min_i32_e32 v82, s10, v82
	v_cvt_f32_i32_e32 v133, v82
	v_pk_add_f32 v[102:103], v[218:219], v[74:75] neg_lo:[0,1] neg_hi:[0,1]
	v_and_b32_e32 v75, 0xffff0000, v89
	v_and_b32_e32 v74, 0xffff0000, v88
	v_pk_add_f32 v[82:83], v[102:103], v[74:75]
	v_div_scale_f32 v102, s[0:1], v133, v133, 1.0
	v_rcp_f32_e32 v103, v102
	v_lshlrev_b32_e32 v79, 16, v91
	v_lshlrev_b32_e32 v78, 16, v90
	v_pk_add_f32 v[212:213], v[66:67], v[92:93] neg_lo:[0,1] neg_hi:[0,1]
	v_lshlrev_b32_e32 v67, 16, v89
	v_lshlrev_b32_e32 v66, 16, v88
	v_pk_add_f32 v[88:89], v[196:197], v[78:79]
	v_fma_f32 v197, -v102, v103, 1.0
	v_div_scale_f32 v196, vcc, 1.0, v133, 1.0
	v_fmac_f32_e32 v103, v197, v103
	v_and_b32_e32 v93, 0xffff0000, v91
	v_and_b32_e32 v92, 0xffff0000, v90
	v_mul_f32_e32 v197, v196, v103
	v_pk_add_f32 v[90:91], v[212:213], v[92:93]
	v_fma_f32 v212, -v102, v197, v196
	v_fmac_f32_e32 v197, v212, v103
	v_fma_f32 v102, -v102, v197, v196
	v_pk_add_f32 v[0:1], v[214:215], v[0:1] neg_lo:[0,1] neg_hi:[0,1]
	v_div_fmas_f32 v102, v102, v103, v197
	v_pk_add_f32 v[0:1], v[0:1], v[66:67]
	v_div_fixup_f32 v102, v102, v133, 1.0
	v_pk_fma_f32 v[196:197], v[102:103], v[0:1], v[66:67] op_sel_hi:[0,1,1] neg_lo:[0,0,1] neg_hi:[0,0,1]
	v_pk_fma_f32 v[212:213], v[102:103], v[82:83], v[74:75] op_sel_hi:[0,1,1] neg_lo:[0,0,1] neg_hi:[0,0,1]
	v_pk_fma_f32 v[214:215], v[102:103], v[88:89], v[78:79] op_sel_hi:[0,1,1] neg_lo:[0,0,1] neg_hi:[0,0,1]
	v_pk_fma_f32 v[102:103], v[102:103], v[90:91], v[92:93] op_sel_hi:[0,1,1] neg_lo:[0,0,1] neg_hi:[0,0,1]
	v_pk_mul_f32 v[196:197], v[64:65], v[196:197]
	v_pk_mul_f32 v[214:215], v[4:5], v[214:215]
	v_pk_mul_f32 v[102:103], v[2:3], v[102:103]
	v_pk_mul_f32 v[212:213], v[6:7], v[212:213]
	s_movk_i32 s5, 0x7fff
	s_mov_b32 s4, 0xffff0000
	v_lshl_add_u64 v[94:95], v[96:97], 0, v[94:95]
	s_cmp_lt_i32 s14, 1
	s_mov_b64 s[0:1], 0
	s_waitcnt vmcnt(0)
	v_lshlrev_b32_e32 v217, 16, v227
	v_lshlrev_b32_e32 v216, 16, v226
	v_lshlrev_b32_e32 v221, 16, v229
	v_lshlrev_b32_e32 v220, 16, v228
	v_and_b32_e32 v223, 0xffff0000, v229
	v_and_b32_e32 v222, 0xffff0000, v228
	v_and_b32_e32 v219, 0xffff0000, v227
	v_and_b32_e32 v218, 0xffff0000, v226
	v_pk_mul_f32 v[196:197], v[196:197], v[216:217]
	v_pk_mul_f32 v[214:215], v[214:215], v[220:221]
	v_pk_mul_f32 v[102:103], v[102:103], v[222:223]
	v_pk_mul_f32 v[212:213], v[212:213], v[218:219]
	v_cvt_pk_bf16_f32 v215, v215, v103
	v_cvt_pk_bf16_f32 v214, v214, v102
	v_cvt_pk_bf16_f32 v213, v197, v213
	v_cvt_pk_bf16_f32 v212, v196, v212
	global_store_dwordx4 v[94:95], v[212:215], off
	s_cbranch_scc1 .LBB0_3034
	s_cmp_gt_i32 s14, 1
	s_cbranch_scc0 .LBB0_3035
	s_cmp_lg_u32 s14, 2
	s_mov_b64 s[6:7], 0
	s_cselect_b64 s[4:5], -1, 0
	s_branch .LBB0_3036

; __device__ __forceinline__ unsigned f2bf(float f) { unsigned u = __builtin_bit_cast(unsigned, f); return (u + 0x7fffu + ((u >> 16) & 1u)) >> 16; }
; __device__ __forceinline__ unsigned pk2(float lo, float hi) { return f2bf(lo) | (f2bf(hi) << 16); }
; __device__ __forceinline__ void fir_tile(const Prm& P, Ctx& C, int pm, int gi) {
;     ...
;     for (int j = 0; j < RUN; ++j) {
;         const int t = t0 + j;
;         const u32x4 g = *(const u32x4*)(GT + (size_t)(row0 + j) * 1024 + c0);
;         acc8(s, x[15 + j], 1.f);
;         const float inv = 1.f / (float)(t + 1 < w ? t + 1 : w);
;         const u32x4 xc = x[15 + j];
;         u32x4 o;
;         o.x = pk2((s[0] * inv - bflo(xc.x)) * sc0[0] * bflo(g.x), (s[1] * inv - bfhi(xc.x)) * sc0[1] * bfhi(g.x));
;         o.y = pk2((s[2] * inv - bflo(xc.y)) * sc0[2] * bflo(g.y), (s[3] * inv - bfhi(xc.y)) * sc0[3] * bfhi(g.y));
;         o.z = pk2((s[4] * inv - bflo(xc.z)) * sc1[0] * bflo(g.z), (s[5] * inv - bfhi(xc.z)) * sc1[1] * bfhi(g.z));
;         o.w = pk2((s[6] * inv - bflo(xc.w)) * sc1[2] * bflo(g.w), (s[7] * inv - bfhi(xc.w)) * sc1[3] * bfhi(g.w));
;         *(u32x4*)(MX + (size_t)(row0 + j) * 1024 + c0) = o;
;         if (w == 2) acc8(s, x[15 + j - 1], -1.f); else if (w == 4) acc8(s, x[15 + j - 3], -1.f); else if (w == 8) acc8(s, x[15 + j - 7], -1.f); else acc8(s, x[j], -1.f);
.LBB0_3044:
	v_or_b32_e32 v70, 2, v132
	v_ashrrev_i32_e32 v71, 31, v70
	v_lshlrev_b64 v[210:211], 11, v[70:71]
	v_lshl_add_u64 v[70:71], v[98:99], 0, v[210:211]
	global_load_dwordx4 v[206:209], v[70:71], off
	v_pk_add_f32 v[214:215], v[0:1], v[94:95] neg_lo:[0,1] neg_hi:[0,1]
	v_pk_add_f32 v[102:103], v[82:83], v[102:103] neg_lo:[0,1] neg_hi:[0,1]
	v_lshlrev_b32_e32 v82, 16, v62
	v_and_b32_e32 v94, 0xffff0000, v62
	v_or_b32_e32 v62, 3, v224
	v_min_i32_e32 v62, s10, v62
	v_cvt_f32_i32_e32 v133, v62
	v_and_b32_e32 v71, 0xffff0000, v61
	v_and_b32_e32 v70, 0xffff0000, v60
	v_lshlrev_b32_e32 v83, 16, v63
	v_and_b32_e32 v95, 0xffff0000, v63
	v_pk_add_f32 v[62:63], v[102:103], v[70:71]
	v_div_scale_f32 v102, s[0:1], v133, v133, 1.0
	v_rcp_f32_e32 v103, v102
	v_pk_add_f32 v[88:89], v[88:89], v[196:197] neg_lo:[0,1] neg_hi:[0,1]
	v_div_scale_f32 v196, vcc, 1.0, v133, 1.0
	v_fma_f32 v197, -v102, v103, 1.0
	v_fmac_f32_e32 v103, v197, v103
	v_mul_f32_e32 v197, v196, v103
	v_pk_add_f32 v[90:91], v[90:91], v[212:213] neg_lo:[0,1] neg_hi:[0,1]
	v_fma_f32 v212, -v102, v197, v196
	v_fmac_f32_e32 v197, v212, v103
	v_fma_f32 v102, -v102, v197, v196
	v_lshlrev_b32_e32 v1, 16, v61
	v_lshlrev_b32_e32 v0, 16, v60
	v_div_fmas_f32 v102, v102, v103, v197
	v_pk_add_f32 v[60:61], v[214:215], v[0:1]
	v_pk_add_f32 v[88:89], v[88:89], v[82:83]
	v_pk_add_f32 v[90:91], v[90:91], v[94:95]
	v_div_fixup_f32 v102, v102, v133, 1.0
	v_pk_fma_f32 v[196:197], v[102:103], v[60:61], v[0:1] op_sel_hi:[0,1,1] neg_lo:[0,0,1] neg_hi:[0,0,1]
	v_pk_fma_f32 v[212:213], v[102:103], v[62:63], v[70:71] op_sel_hi:[0,1,1] neg_lo:[0,0,1] neg_hi:[0,0,1]
	v_pk_fma_f32 v[214:215], v[102:103], v[88:89], v[82:83] op_sel_hi:[0,1,1] neg_lo:[0,0,1] neg_hi:[0,0,1]
	v_pk_fma_f32 v[102:103], v[102:103], v[90:91], v[94:95] op_sel_hi:[0,1,1] neg_lo:[0,0,1] neg_hi:[0,0,1]
	v_pk_mul_f32 v[196:197], v[64:65], v[196:197]
	v_pk_mul_f32 v[212:213], v[6:7], v[212:213]
	v_pk_mul_f32 v[214:215], v[4:5], v[214:215]
	v_pk_mul_f32 v[102:103], v[2:3], v[102:103]
	s_movk_i32 s5, 0x7fff
	s_mov_b32 s4, 0xffff0000
	s_cmp_lt_i32 s14, 1
	s_mov_b64 s[0:1], 0
	s_waitcnt vmcnt(0)
	v_lshlrev_b32_e32 v217, 16, v207
	v_lshlrev_b32_e32 v216, 16, v206
	v_and_b32_e32 v207, 0xffff0000, v207
	v_and_b32_e32 v206, 0xffff0000, v206
	v_lshlrev_b32_e32 v219, 16, v209
	v_lshlrev_b32_e32 v218, 16, v208
	v_and_b32_e32 v209, 0xffff0000, v209
	v_and_b32_e32 v208, 0xffff0000, v208
	v_pk_mul_f32 v[196:197], v[196:197], v[216:217]
	v_pk_mul_f32 v[206:207], v[212:213], v[206:207]
	v_pk_mul_f32 v[212:213], v[214:215], v[218:219]
	v_pk_mul_f32 v[102:103], v[102:103], v[208:209]
	v_cvt_pk_bf16_f32 v209, v213, v103
	v_cvt_pk_bf16_f32 v208, v212, v102
	v_cvt_pk_bf16_f32 v207, v197, v207
	v_cvt_pk_bf16_f32 v206, v196, v206
	v_lshl_add_u64 v[102:103], v[96:97], 0, v[210:211]
	global_store_dwordx4 v[102:103], v[206:209], off
	s_cbranch_scc1 .LBB0_3047
	s_cmp_gt_i32 s14, 1
	s_cbranch_scc0 .LBB0_3048
	s_cmp_lg_u32 s14, 2
	s_mov_b64 s[6:7], 0
	s_cselect_b64 s[4:5], -1, 0
	s_branch .LBB0_3049

; __device__ __forceinline__ unsigned f2bf(float f) { unsigned u = __builtin_bit_cast(unsigned, f); return (u + 0x7fffu + ((u >> 16) & 1u)) >> 16; }
; __device__ __forceinline__ unsigned pk2(float lo, float hi) { return f2bf(lo) | (f2bf(hi) << 16); }
; __device__ __forceinline__ void fir_tile(const Prm& P, Ctx& C, int pm, int gi) {
;     ...
;     for (int j = 0; j < RUN; ++j) {
;         const int t = t0 + j;
;         const u32x4 g = *(const u32x4*)(GT + (size_t)(row0 + j) * 1024 + c0);
;         acc8(s, x[15 + j], 1.f);
;         const float inv = 1.f / (float)(t + 1 < w ? t + 1 : w);
;         const u32x4 xc = x[15 + j];
;         u32x4 o;
;         o.x = pk2((s[0] * inv - bflo(xc.x)) * sc0[0] * bflo(g.x), (s[1] * inv - bfhi(xc.x)) * sc0[1] * bfhi(g.x));
;         o.y = pk2((s[2] * inv - bflo(xc.y)) * sc0[2] * bflo(g.y), (s[3] * inv - bfhi(xc.y)) * sc0[3] * bfhi(g.y));
;         o.z = pk2((s[4] * inv - bflo(xc.z)) * sc1[0] * bflo(g.z), (s[5] * inv - bfhi(xc.z)) * sc1[1] * bfhi(g.z));
;         o.w = pk2((s[6] * inv - bflo(xc.w)) * sc1[2] * bflo(g.w), (s[7] * inv - bfhi(xc.w)) * sc1[3] * bfhi(g.w));
;         *(u32x4*)(MX + (size_t)(row0 + j) * 1024 + c0) = o;
;         if (w == 2) acc8(s, x[15 + j - 1], -1.f); else if (w == 4) acc8(s, x[15 + j - 3], -1.f); else if (w == 8) acc8(s, x[15 + j - 7], -1.f); else acc8(s, x[j], -1.f);
.LBB0_3057:
	v_or_b32_e32 v84, 3, v132
	v_ashrrev_i32_e32 v85, 31, v84
	v_lshlrev_b64 v[130:131], 11, v[84:85]
	v_lshl_add_u64 v[84:85], v[98:99], 0, v[130:131]
	global_load_dwordx4 v[210:213], v[84:85], off
	v_lshlrev_b32_e32 v84, 16, v58
	v_and_b32_e32 v100, 0xffff0000, v58
	v_or_b32_e32 v58, 4, v224
	v_min_i32_e32 v58, s10, v58
	v_cvt_f32_i32_e32 v133, v58
	v_pk_add_f32 v[86:87], v[60:61], v[102:103] neg_lo:[0,1] neg_hi:[0,1]
	v_pk_add_f32 v[102:103], v[62:63], v[196:197] neg_lo:[0,1] neg_hi:[0,1]
	v_and_b32_e32 v63, 0xffff0000, v57
	v_and_b32_e32 v62, 0xffff0000, v56
	v_lshlrev_b32_e32 v85, 16, v59
	v_and_b32_e32 v101, 0xffff0000, v59
	v_pk_add_f32 v[58:59], v[102:103], v[62:63]
	v_div_scale_f32 v102, s[0:1], v133, v133, 1.0
	v_rcp_f32_e32 v103, v102
	v_pk_add_f32 v[88:89], v[88:89], v[206:207] neg_lo:[0,1] neg_hi:[0,1]
	v_pk_add_f32 v[90:91], v[90:91], v[208:209] neg_lo:[0,1] neg_hi:[0,1]
	v_lshlrev_b32_e32 v61, 16, v57
	v_lshlrev_b32_e32 v60, 16, v56
	v_pk_add_f32 v[56:57], v[86:87], v[60:61]
	v_pk_add_f32 v[86:87], v[88:89], v[84:85]
	v_pk_add_f32 v[88:89], v[90:91], v[100:101]
	v_fma_f32 v91, -v102, v103, 1.0
	v_div_scale_f32 v90, vcc, 1.0, v133, 1.0
	v_fmac_f32_e32 v103, v91, v103
	v_mul_f32_e32 v91, v90, v103
	v_fma_f32 v196, -v102, v91, v90
	v_fmac_f32_e32 v91, v196, v103
	v_fma_f32 v90, -v102, v91, v90
	v_div_fmas_f32 v90, v90, v103, v91
	v_div_fixup_f32 v90, v90, v133, 1.0
	v_pk_fma_f32 v[102:103], v[90:91], v[56:57], v[60:61] op_sel_hi:[0,1,1] neg_lo:[0,0,1] neg_hi:[0,0,1]
	v_pk_fma_f32 v[196:197], v[90:91], v[58:59], v[62:63] op_sel_hi:[0,1,1] neg_lo:[0,0,1] neg_hi:[0,0,1]
	v_pk_fma_f32 v[206:207], v[90:91], v[86:87], v[84:85] op_sel_hi:[0,1,1] neg_lo:[0,0,1] neg_hi:[0,0,1]
	v_pk_fma_f32 v[90:91], v[90:91], v[88:89], v[100:101] op_sel_hi:[0,1,1] neg_lo:[0,0,1] neg_hi:[0,0,1]
	v_pk_mul_f32 v[102:103], v[64:65], v[102:103]
	v_pk_mul_f32 v[206:207], v[4:5], v[206:207]
	v_pk_mul_f32 v[90:91], v[2:3], v[90:91]
	v_pk_mul_f32 v[196:197], v[6:7], v[196:197]
	s_movk_i32 s5, 0x7fff
	s_mov_b32 s4, 0xffff0000
	s_cmp_lt_i32 s14, 1
	s_mov_b64 s[0:1], 0
	s_waitcnt vmcnt(0)
	v_lshlrev_b32_e32 v209, 16, v211
	v_lshlrev_b32_e32 v208, 16, v210
	v_lshlrev_b32_e32 v215, 16, v213
	v_lshlrev_b32_e32 v214, 16, v212
	v_and_b32_e32 v213, 0xffff0000, v213
	v_and_b32_e32 v212, 0xffff0000, v212
	v_and_b32_e32 v211, 0xffff0000, v211
	v_and_b32_e32 v210, 0xffff0000, v210
	v_pk_mul_f32 v[102:103], v[102:103], v[208:209]
	v_pk_mul_f32 v[206:207], v[206:207], v[214:215]
	v_pk_mul_f32 v[90:91], v[90:91], v[212:213]
	v_pk_mul_f32 v[196:197], v[196:197], v[210:211]
	v_cvt_pk_bf16_f32 v209, v207, v91
	v_cvt_pk_bf16_f32 v208, v206, v90
	v_cvt_pk_bf16_f32 v207, v103, v197
	v_cvt_pk_bf16_f32 v206, v102, v196
	v_lshl_add_u64 v[90:91], v[96:97], 0, v[130:131]
	global_store_dwordx4 v[90:91], v[206:209], off
	s_cbranch_scc1 .LBB0_3060
	s_cmp_gt_i32 s14, 1
	s_cbranch_scc0 .LBB0_3061
	s_cmp_lg_u32 s14, 2
	s_mov_b64 s[6:7], 0
	s_cselect_b64 s[4:5], -1, 0
	s_branch .LBB0_3062

; __device__ __forceinline__ unsigned f2bf(float f) { unsigned u = __builtin_bit_cast(unsigned, f); return (u + 0x7fffu + ((u >> 16) & 1u)) >> 16; }
; __device__ __forceinline__ unsigned pk2(float lo, float hi) { return f2bf(lo) | (f2bf(hi) << 16); }
; __device__ __forceinline__ void fir_tile(const Prm& P, Ctx& C, int pm, int gi) {
;     ...
;     for (int j = 0; j < RUN; ++j) {
;         const int t = t0 + j;
;         const u32x4 g = *(const u32x4*)(GT + (size_t)(row0 + j) * 1024 + c0);
;         acc8(s, x[15 + j], 1.f);
;         const float inv = 1.f / (float)(t + 1 < w ? t + 1 : w);
;         const u32x4 xc = x[15 + j];
;         u32x4 o;
;         o.x = pk2((s[0] * inv - bflo(xc.x)) * sc0[0] * bflo(g.x), (s[1] * inv - bfhi(xc.x)) * sc0[1] * bfhi(g.x));
;         o.y = pk2((s[2] * inv - bflo(xc.y)) * sc0[2] * bflo(g.y), (s[3] * inv - bfhi(xc.y)) * sc0[3] * bfhi(g.y));
;         o.z = pk2((s[4] * inv - bflo(xc.z)) * sc1[0] * bflo(g.z), (s[5] * inv - bfhi(xc.z)) * sc1[1] * bfhi(g.z));
;         o.w = pk2((s[6] * inv - bflo(xc.w)) * sc1[2] * bflo(g.w), (s[7] * inv - bfhi(xc.w)) * sc1[3] * bfhi(g.w));
;         *(u32x4*)(MX + (size_t)(row0 + j) * 1024 + c0) = o;
;         if (w == 2) acc8(s, x[15 + j - 1], -1.f); else if (w == 4) acc8(s, x[15 + j - 3], -1.f); else if (w == 8) acc8(s, x[15 + j - 7], -1.f); else acc8(s, x[j], -1.f);
.LBB0_3070:
	v_or_b32_e32 v198, 4, v132
	v_ashrrev_i32_e32 v199, 31, v198
	v_lshlrev_b64 v[202:203], 11, v[198:199]
	v_lshl_add_u64 v[198:199], v[98:99], 0, v[202:203]
	global_load_dwordx4 v[198:201], v[198:199], off
	v_pk_add_f32 v[204:205], v[86:87], v[102:103] neg_lo:[0,1] neg_hi:[0,1]
	v_lshlrev_b32_e32 v86, 16, v54
	v_and_b32_e32 v102, 0xffff0000, v54
	v_or_b32_e32 v54, 5, v224
	v_min_i32_e32 v54, s10, v54
	v_cvt_f32_i32_e32 v133, v54
	v_pk_add_f32 v[130:131], v[58:59], v[130:131] neg_lo:[0,1] neg_hi:[0,1]
	v_and_b32_e32 v59, 0xffff0000, v53
	v_and_b32_e32 v58, 0xffff0000, v52
	v_lshlrev_b32_e32 v87, 16, v55
	v_and_b32_e32 v103, 0xffff0000, v55
	v_pk_add_f32 v[54:55], v[130:131], v[58:59]
	v_div_scale_f32 v130, s[0:1], v133, v133, 1.0
	v_rcp_f32_e32 v131, v130
	v_pk_add_f32 v[196:197], v[56:57], v[196:197] neg_lo:[0,1] neg_hi:[0,1]
	v_lshlrev_b32_e32 v57, 16, v53
	v_lshlrev_b32_e32 v56, 16, v52
	v_pk_add_f32 v[52:53], v[196:197], v[56:57]
	v_fma_f32 v197, -v130, v131, 1.0
	v_div_scale_f32 v196, vcc, 1.0, v133, 1.0
	v_fmac_f32_e32 v131, v197, v131
	v_mul_f32_e32 v197, v196, v131
	v_pk_add_f32 v[90:91], v[88:89], v[90:91] neg_lo:[0,1] neg_hi:[0,1]
	v_pk_add_f32 v[88:89], v[204:205], v[86:87]
	v_fma_f32 v204, -v130, v197, v196
	v_fmac_f32_e32 v197, v204, v131
	v_fma_f32 v130, -v130, v197, v196
	v_div_fmas_f32 v130, v130, v131, v197
	v_pk_add_f32 v[90:91], v[90:91], v[102:103]
	v_div_fixup_f32 v130, v130, v133, 1.0
	v_pk_fma_f32 v[196:197], v[130:131], v[52:53], v[56:57] op_sel_hi:[0,1,1] neg_lo:[0,0,1] neg_hi:[0,0,1]
	v_pk_fma_f32 v[204:205], v[130:131], v[54:55], v[58:59] op_sel_hi:[0,1,1] neg_lo:[0,0,1] neg_hi:[0,0,1]
	v_pk_fma_f32 v[206:207], v[130:131], v[88:89], v[86:87] op_sel_hi:[0,1,1] neg_lo:[0,0,1] neg_hi:[0,0,1]
	v_pk_fma_f32 v[130:131], v[130:131], v[90:91], v[102:103] op_sel_hi:[0,1,1] neg_lo:[0,0,1] neg_hi:[0,0,1]
	v_pk_mul_f32 v[196:197], v[64:65], v[196:197]
	v_pk_mul_f32 v[204:205], v[6:7], v[204:205]
	v_pk_mul_f32 v[206:207], v[4:5], v[206:207]
	v_pk_mul_f32 v[130:131], v[2:3], v[130:131]
	s_movk_i32 s5, 0x7fff
	s_mov_b32 s4, 0xffff0000
	s_cmp_lt_i32 s14, 1
	s_mov_b64 s[0:1], 0
	s_waitcnt vmcnt(0)
	v_lshlrev_b32_e32 v209, 16, v199
	v_lshlrev_b32_e32 v208, 16, v198
	v_and_b32_e32 v199, 0xffff0000, v199
	v_and_b32_e32 v198, 0xffff0000, v198
	v_lshlrev_b32_e32 v211, 16, v201
	v_lshlrev_b32_e32 v210, 16, v200
	v_and_b32_e32 v201, 0xffff0000, v201
	v_and_b32_e32 v200, 0xffff0000, v200
	v_pk_mul_f32 v[196:197], v[196:197], v[208:209]
	v_pk_mul_f32 v[198:199], v[204:205], v[198:199]
	v_pk_mul_f32 v[204:205], v[206:207], v[210:211]
	v_pk_mul_f32 v[130:131], v[130:131], v[200:201]
	v_bfe_u32 v206, v198, 16, 1
	v_bfe_u32 v207, v196, 16, 1
	v_bfe_u32 v208, v197, 16, 1
	v_bfe_u32 v201, v199, 16, 1
	v_add3_u32 v206, v198, v206, s5
	v_add3_u32 v197, v197, v208, s5
	v_add3_u32 v196, v196, v207, s5
	v_add3_u32 v201, v199, v201, s5
	v_lshrrev_b32_e32 v196, 16, v196
	v_lshrrev_b32_e32 v197, 16, v197
	v_cvt_pk_bf16_f32 v199, v205, v131
	v_cvt_pk_bf16_f32 v198, v204, v130
	v_and_or_b32 v197, v201, s4, v197
	v_and_or_b32 v196, v206, s4, v196
	v_lshl_add_u64 v[130:131], v[96:97], 0, v[202:203]
	global_store_dwordx4 v[130:131], v[196:199], off
	s_cbranch_scc1 .LBB0_3073
	s_cmp_gt_i32 s14, 1
	s_cbranch_scc0 .LBB0_3074
	s_cmp_lg_u32 s14, 2
	s_mov_b64 s[6:7], 0
	s_cselect_b64 s[4:5], -1, 0
	s_branch .LBB0_3075

; __device__ __forceinline__ unsigned f2bf(float f) { unsigned u = __builtin_bit_cast(unsigned, f); return (u + 0x7fffu + ((u >> 16) & 1u)) >> 16; }
; __device__ __forceinline__ unsigned pk2(float lo, float hi) { return f2bf(lo) | (f2bf(hi) << 16); }
; __device__ __forceinline__ void fir_tile(const Prm& P, Ctx& C, int pm, int gi) {
;     ...
;     for (int j = 0; j < RUN; ++j) {
;         const int t = t0 + j;
;         const u32x4 g = *(const u32x4*)(GT + (size_t)(row0 + j) * 1024 + c0);
;         acc8(s, x[15 + j], 1.f);
;         const float inv = 1.f / (float)(t + 1 < w ? t + 1 : w);
;         const u32x4 xc = x[15 + j];
;         u32x4 o;
;         o.x = pk2((s[0] * inv - bflo(xc.x)) * sc0[0] * bflo(g.x), (s[1] * inv - bfhi(xc.x)) * sc0[1] * bfhi(g.x));
;         o.y = pk2((s[2] * inv - bflo(xc.y)) * sc0[2] * bflo(g.y), (s[3] * inv - bfhi(xc.y)) * sc0[3] * bfhi(g.y));
;         o.z = pk2((s[4] * inv - bflo(xc.z)) * sc1[0] * bflo(g.z), (s[5] * inv - bfhi(xc.z)) * sc1[1] * bfhi(g.z));
;         o.w = pk2((s[6] * inv - bflo(xc.w)) * sc1[2] * bflo(g.w), (s[7] * inv - bfhi(xc.w)) * sc1[3] * bfhi(g.w));
;         *(u32x4*)(MX + (size_t)(row0 + j) * 1024 + c0) = o;
;         if (w == 2) acc8(s, x[15 + j - 1], -1.f); else if (w == 4) acc8(s, x[15 + j - 3], -1.f); else if (w == 8) acc8(s, x[15 + j - 7], -1.f); else acc8(s, x[j], -1.f);
.LBB0_3083:
	v_or_b32_e32 v186, 5, v132
	v_ashrrev_i32_e32 v187, 31, v186
	v_lshlrev_b64 v[192:193], 11, v[186:187]
	v_lshl_add_u64 v[186:187], v[98:99], 0, v[192:193]
	global_load_dwordx4 v[188:191], v[186:187], off
	v_pk_add_f32 v[186:187], v[52:53], v[130:131] neg_lo:[0,1] neg_hi:[0,1]
	v_pk_add_f32 v[198:199], v[88:89], v[198:199] neg_lo:[0,1] neg_hi:[0,1]
	v_lshlrev_b32_e32 v88, 16, v50
	v_and_b32_e32 v130, 0xffff0000, v50
	v_or_b32_e32 v50, 6, v224
	v_min_i32_e32 v50, s10, v50
	v_cvt_f32_i32_e32 v133, v50
	v_pk_add_f32 v[196:197], v[54:55], v[196:197] neg_lo:[0,1] neg_hi:[0,1]
	v_and_b32_e32 v55, 0xffff0000, v49
	v_and_b32_e32 v54, 0xffff0000, v48
	v_lshlrev_b32_e32 v89, 16, v51
	v_and_b32_e32 v131, 0xffff0000, v51
	v_pk_add_f32 v[50:51], v[196:197], v[54:55]
	v_div_scale_f32 v196, s[0:1], v133, v133, 1.0
	v_rcp_f32_e32 v197, v196
	v_pk_add_f32 v[200:201], v[90:91], v[200:201] neg_lo:[0,1] neg_hi:[0,1]
	v_pk_add_f32 v[90:91], v[198:199], v[88:89]
	v_div_scale_f32 v198, vcc, 1.0, v133, 1.0
	v_fma_f32 v199, -v196, v197, 1.0
	v_fmac_f32_e32 v197, v199, v197
	v_lshlrev_b32_e32 v53, 16, v49
	v_lshlrev_b32_e32 v52, 16, v48
	v_mul_f32_e32 v199, v198, v197
	v_pk_add_f32 v[48:49], v[186:187], v[52:53]
	v_pk_add_f32 v[186:187], v[200:201], v[130:131]
	v_fma_f32 v200, -v196, v199, v198
	v_fmac_f32_e32 v199, v200, v197
	v_fma_f32 v196, -v196, v199, v198
	v_div_fmas_f32 v196, v196, v197, v199
	v_div_fixup_f32 v196, v196, v133, 1.0
	v_pk_fma_f32 v[198:199], v[196:197], v[48:49], v[52:53] op_sel_hi:[0,1,1] neg_lo:[0,0,1] neg_hi:[0,0,1]
	v_pk_fma_f32 v[200:201], v[196:197], v[50:51], v[54:55] op_sel_hi:[0,1,1] neg_lo:[0,0,1] neg_hi:[0,0,1]
	v_pk_fma_f32 v[202:203], v[196:197], v[90:91], v[88:89] op_sel_hi:[0,1,1] neg_lo:[0,0,1] neg_hi:[0,0,1]
	v_pk_fma_f32 v[196:197], v[196:197], v[186:187], v[130:131] op_sel_hi:[0,1,1] neg_lo:[0,0,1] neg_hi:[0,0,1]
	v_pk_mul_f32 v[198:199], v[64:65], v[198:199]
	v_pk_mul_f32 v[200:201], v[6:7], v[200:201]
	v_pk_mul_f32 v[202:203], v[4:5], v[202:203]
	v_pk_mul_f32 v[196:197], v[2:3], v[196:197]
	s_movk_i32 s5, 0x7fff
	s_mov_b32 s4, 0xffff0000
	v_lshl_add_u64 v[192:193], v[96:97], 0, v[192:193]
	s_cmp_lt_i32 s14, 1
	s_mov_b64 s[0:1], 0
	s_waitcnt vmcnt(0)
	v_lshlrev_b32_e32 v205, 16, v189
	v_lshlrev_b32_e32 v204, 16, v188
	v_and_b32_e32 v189, 0xffff0000, v189
	v_and_b32_e32 v188, 0xffff0000, v188
	v_lshlrev_b32_e32 v207, 16, v191
	v_lshlrev_b32_e32 v206, 16, v190
	v_and_b32_e32 v191, 0xffff0000, v191
	v_and_b32_e32 v190, 0xffff0000, v190
	v_pk_mul_f32 v[198:199], v[198:199], v[204:205]
	v_pk_mul_f32 v[188:189], v[200:201], v[188:189]
	v_pk_mul_f32 v[200:201], v[202:203], v[206:207]
	v_pk_mul_f32 v[190:191], v[196:197], v[190:191]
	v_cvt_pk_bf16_f32 v191, v201, v191
	v_cvt_pk_bf16_f32 v190, v200, v190
	v_cvt_pk_bf16_f32 v189, v199, v189
	v_cvt_pk_bf16_f32 v188, v198, v188
	global_store_dwordx4 v[192:193], v[188:191], off
	s_cbranch_scc1 .LBB0_3086
	s_cmp_gt_i32 s14, 1
	s_cbranch_scc0 .LBB0_3087
	s_cmp_lg_u32 s14, 2
	s_mov_b64 s[6:7], 0
	s_cselect_b64 s[4:5], -1, 0
	s_branch .LBB0_3088

; __device__ __forceinline__ unsigned f2bf(float f) { unsigned u = __builtin_bit_cast(unsigned, f); return (u + 0x7fffu + ((u >> 16) & 1u)) >> 16; }
; __device__ __forceinline__ unsigned pk2(float lo, float hi) { return f2bf(lo) | (f2bf(hi) << 16); }
; __device__ __forceinline__ void fir_tile(const Prm& P, Ctx& C, int pm, int gi) {
;     ...
;     for (int j = 0; j < RUN; ++j) {
;         const int t = t0 + j;
;         const u32x4 g = *(const u32x4*)(GT + (size_t)(row0 + j) * 1024 + c0);
;         acc8(s, x[15 + j], 1.f);
;         const float inv = 1.f / (float)(t + 1 < w ? t + 1 : w);
;         const u32x4 xc = x[15 + j];
;         u32x4 o;
;         o.x = pk2((s[0] * inv - bflo(xc.x)) * sc0[0] * bflo(g.x), (s[1] * inv - bfhi(xc.x)) * sc0[1] * bfhi(g.x));
;         o.y = pk2((s[2] * inv - bflo(xc.y)) * sc0[2] * bflo(g.y), (s[3] * inv - bfhi(xc.y)) * sc0[3] * bfhi(g.y));
;         o.z = pk2((s[4] * inv - bflo(xc.z)) * sc1[0] * bflo(g.z), (s[5] * inv - bfhi(xc.z)) * sc1[1] * bfhi(g.z));
;         o.w = pk2((s[6] * inv - bflo(xc.w)) * sc1[2] * bflo(g.w), (s[7] * inv - bfhi(xc.w)) * sc1[3] * bfhi(g.w));
;         *(u32x4*)(MX + (size_t)(row0 + j) * 1024 + c0) = o;
;         if (w == 2) acc8(s, x[15 + j - 1], -1.f); else if (w == 4) acc8(s, x[15 + j - 3], -1.f); else if (w == 8) acc8(s, x[15 + j - 7], -1.f); else acc8(s, x[j], -1.f);
.LBB0_3096:
	v_or_b32_e32 v168, 6, v132
	v_ashrrev_i32_e32 v169, 31, v168
	v_lshlrev_b64 v[194:195], 11, v[168:169]
	v_lshl_add_u64 v[168:169], v[98:99], 0, v[194:195]
	global_load_dwordx4 v[198:201], v[168:169], off
	v_pk_add_f32 v[182:183], v[48:49], v[188:189] neg_lo:[0,1] neg_hi:[0,1]
	v_pk_add_f32 v[188:189], v[90:91], v[192:193] neg_lo:[0,1] neg_hi:[0,1]
	v_lshlrev_b32_e32 v90, 16, v46
	v_and_b32_e32 v168, 0xffff0000, v46
	v_or_b32_e32 v46, 7, v224
	v_min_i32_e32 v46, s10, v46
	v_cvt_f32_i32_e32 v133, v46
	v_lshlrev_b32_e32 v49, 16, v45
	v_lshlrev_b32_e32 v48, 16, v44
	v_lshlrev_b32_e32 v91, 16, v47
	v_pk_add_f32 v[184:185], v[50:51], v[190:191] neg_lo:[0,1] neg_hi:[0,1]
	v_and_b32_e32 v51, 0xffff0000, v45
	v_and_b32_e32 v50, 0xffff0000, v44
	v_pk_add_f32 v[44:45], v[182:183], v[48:49]
	v_pk_add_f32 v[182:183], v[188:189], v[90:91]
	v_div_scale_f32 v188, s[0:1], v133, v133, 1.0
	v_rcp_f32_e32 v189, v188
	v_pk_add_f32 v[186:187], v[186:187], v[196:197] neg_lo:[0,1] neg_hi:[0,1]
	v_and_b32_e32 v169, 0xffff0000, v47
	v_pk_add_f32 v[46:47], v[184:185], v[50:51]
	v_pk_add_f32 v[184:185], v[186:187], v[168:169]
	v_fma_f32 v187, -v188, v189, 1.0
	v_div_scale_f32 v186, vcc, 1.0, v133, 1.0
	v_fmac_f32_e32 v189, v187, v189
	v_mul_f32_e32 v187, v186, v189
	v_fma_f32 v190, -v188, v187, v186
	v_fmac_f32_e32 v187, v190, v189
	v_fma_f32 v186, -v188, v187, v186
	v_div_fmas_f32 v186, v186, v189, v187
	v_div_fixup_f32 v186, v186, v133, 1.0
	v_pk_fma_f32 v[188:189], v[186:187], v[44:45], v[48:49] op_sel_hi:[0,1,1] neg_lo:[0,0,1] neg_hi:[0,0,1]
	v_pk_fma_f32 v[190:191], v[186:187], v[46:47], v[50:51] op_sel_hi:[0,1,1] neg_lo:[0,0,1] neg_hi:[0,0,1]
	v_pk_fma_f32 v[192:193], v[186:187], v[182:183], v[90:91] op_sel_hi:[0,1,1] neg_lo:[0,0,1] neg_hi:[0,0,1]
	v_pk_fma_f32 v[186:187], v[186:187], v[184:185], v[168:169] op_sel_hi:[0,1,1] neg_lo:[0,0,1] neg_hi:[0,0,1]
	v_pk_mul_f32 v[188:189], v[64:65], v[188:189]
	v_pk_mul_f32 v[192:193], v[4:5], v[192:193]
	v_pk_mul_f32 v[186:187], v[2:3], v[186:187]
	v_pk_mul_f32 v[190:191], v[6:7], v[190:191]
	s_movk_i32 s5, 0x7fff
	s_mov_b32 s4, 0xffff0000
	s_cmp_lt_i32 s14, 1
	s_mov_b64 s[0:1], 0
	s_waitcnt vmcnt(0)
	v_lshlrev_b32_e32 v197, 16, v199
	v_lshlrev_b32_e32 v196, 16, v198
	v_lshlrev_b32_e32 v203, 16, v201
	v_lshlrev_b32_e32 v202, 16, v200
	v_and_b32_e32 v201, 0xffff0000, v201
	v_and_b32_e32 v200, 0xffff0000, v200
	v_and_b32_e32 v199, 0xffff0000, v199
	v_and_b32_e32 v198, 0xffff0000, v198
	v_pk_mul_f32 v[188:189], v[188:189], v[196:197]
	v_pk_mul_f32 v[192:193], v[192:193], v[202:203]
	v_pk_mul_f32 v[186:187], v[186:187], v[200:201]
	v_pk_mul_f32 v[190:191], v[190:191], v[198:199]
	v_bfe_u32 v133, v187, 16, 1
	v_bfe_u32 v199, v188, 16, 1
	v_bfe_u32 v200, v189, 16, 1
	v_bfe_u32 v202, v193, 16, 1
	v_bfe_u32 v197, v191, 16, 1
	v_bfe_u32 v198, v190, 16, 1
	v_add3_u32 v133, v187, v133, s5
	v_add3_u32 v187, v193, v202, s5
	v_add3_u32 v189, v189, v200, s5
	v_add3_u32 v188, v188, v199, s5
	v_add3_u32 v190, v190, v198, s5
	v_add3_u32 v191, v191, v197, s5
	v_lshrrev_b32_e32 v193, 16, v188
	v_lshrrev_b32_e32 v196, 16, v189
	v_lshrrev_b32_e32 v187, 16, v187
	v_and_or_b32 v189, v133, s4, v187
	v_cvt_pk_bf16_f32 v188, v192, v186
	v_and_or_b32 v187, v191, s4, v196
	v_and_or_b32 v186, v190, s4, v193
	v_lshl_add_u64 v[190:191], v[96:97], 0, v[194:195]
	global_store_dwordx4 v[190:191], v[186:189], off
	s_cbranch_scc1 .LBB0_3099
	s_cmp_gt_i32 s14, 1
	s_cbranch_scc0 .LBB0_3100
	s_cmp_lg_u32 s14, 2
	s_mov_b64 s[6:7], 0
	s_cselect_b64 s[4:5], -1, 0
	s_branch .LBB0_3101

; __device__ __forceinline__ unsigned f2bf(float f) { unsigned u = __builtin_bit_cast(unsigned, f); return (u + 0x7fffu + ((u >> 16) & 1u)) >> 16; }
; __device__ __forceinline__ unsigned pk2(float lo, float hi) { return f2bf(lo) | (f2bf(hi) << 16); }
; __device__ __forceinline__ void fir_tile(const Prm& P, Ctx& C, int pm, int gi) {
;     ...
;     for (int j = 0; j < RUN; ++j) {
;         const int t = t0 + j;
;         const u32x4 g = *(const u32x4*)(GT + (size_t)(row0 + j) * 1024 + c0);
;         acc8(s, x[15 + j], 1.f);
;         const float inv = 1.f / (float)(t + 1 < w ? t + 1 : w);
;         const u32x4 xc = x[15 + j];
;         u32x4 o;
;         o.x = pk2((s[0] * inv - bflo(xc.x)) * sc0[0] * bflo(g.x), (s[1] * inv - bfhi(xc.x)) * sc0[1] * bfhi(g.x));
;         o.y = pk2((s[2] * inv - bflo(xc.y)) * sc0[2] * bflo(g.y), (s[3] * inv - bfhi(xc.y)) * sc0[3] * bfhi(g.y));
;         o.z = pk2((s[4] * inv - bflo(xc.z)) * sc1[0] * bflo(g.z), (s[5] * inv - bfhi(xc.z)) * sc1[1] * bfhi(g.z));
;         o.w = pk2((s[6] * inv - bflo(xc.w)) * sc1[2] * bflo(g.w), (s[7] * inv - bfhi(xc.w)) * sc1[3] * bfhi(g.w));
;         *(u32x4*)(MX + (size_t)(row0 + j) * 1024 + c0) = o;
;         if (w == 2) acc8(s, x[15 + j - 1], -1.f); else if (w == 4) acc8(s, x[15 + j - 3], -1.f); else if (w == 8) acc8(s, x[15 + j - 7], -1.f); else acc8(s, x[j], -1.f);
.LBB0_3133:
	v_or_b32_e32 v160, 9, v132
	v_ashrrev_i32_e32 v161, 31, v160
	v_lshlrev_b64 v[164:165], 11, v[160:161]
	v_lshl_add_u64 v[160:161], v[98:99], 0, v[164:165]
	global_load_dwordx4 v[160:163], v[160:161], off
	v_pk_add_f32 v[66:67], v[36:37], v[66:67] neg_lo:[0,1] neg_hi:[0,1]
	v_pk_add_f32 v[78:79], v[122:123], v[78:79] neg_lo:[0,1] neg_hi:[0,1]
	v_lshlrev_b32_e32 v37, 16, v33
	v_lshlrev_b32_e32 v36, 16, v32
	v_or_b32_e32 v122, 10, v224
	v_pk_add_f32 v[166:167], v[38:39], v[74:75] neg_lo:[0,1] neg_hi:[0,1]
	v_lshlrev_b32_e32 v39, 16, v35
	v_lshlrev_b32_e32 v38, 16, v34
	v_and_b32_e32 v75, 0xffff0000, v35
	v_and_b32_e32 v74, 0xffff0000, v34
	v_pk_add_f32 v[34:35], v[66:67], v[36:37]
	v_min_i32_e32 v66, s10, v122
	v_cvt_f32_i32_e32 v122, v66
	v_pk_add_f32 v[92:93], v[128:129], v[92:93] neg_lo:[0,1] neg_hi:[0,1]
	v_and_b32_e32 v33, 0xffff0000, v33
	v_and_b32_e32 v32, 0xffff0000, v32
	v_div_scale_f32 v123, s[0:1], v122, v122, 1.0
	v_rcp_f32_e32 v128, v123
	v_div_scale_f32 v129, vcc, 1.0, v122, 1.0
	v_pk_add_f32 v[66:67], v[166:167], v[32:33]
	v_fma_f32 v133, -v123, v128, 1.0
	v_fmac_f32_e32 v128, v133, v128
	v_mul_f32_e32 v133, v129, v128
	v_fma_f32 v166, -v123, v133, v129
	v_fmac_f32_e32 v133, v166, v128
	v_fma_f32 v123, -v123, v133, v129
	v_div_fmas_f32 v123, v123, v128, v133
	v_pk_add_f32 v[78:79], v[78:79], v[38:39]
	v_pk_add_f32 v[92:93], v[92:93], v[74:75]
	v_div_fixup_f32 v122, v123, v122, 1.0
	v_pk_fma_f32 v[128:129], v[122:123], v[34:35], v[36:37] op_sel_hi:[0,1,1] neg_lo:[0,0,1] neg_hi:[0,0,1]
	v_pk_fma_f32 v[166:167], v[122:123], v[66:67], v[32:33] op_sel_hi:[0,1,1] neg_lo:[0,0,1] neg_hi:[0,0,1]
	v_pk_fma_f32 v[170:171], v[122:123], v[78:79], v[38:39] op_sel_hi:[0,1,1] neg_lo:[0,0,1] neg_hi:[0,0,1]
	v_pk_fma_f32 v[122:123], v[122:123], v[92:93], v[74:75] op_sel_hi:[0,1,1] neg_lo:[0,0,1] neg_hi:[0,0,1]
	v_pk_mul_f32 v[128:129], v[64:65], v[128:129]
	v_pk_mul_f32 v[166:167], v[6:7], v[166:167]
	v_pk_mul_f32 v[170:171], v[4:5], v[170:171]
	v_pk_mul_f32 v[122:123], v[2:3], v[122:123]
	s_movk_i32 s5, 0x7fff
	s_mov_b32 s4, 0xffff0000
	s_cmp_lt_i32 s14, 1
	s_mov_b64 s[0:1], 0
	s_waitcnt vmcnt(0)
	v_lshlrev_b32_e32 v173, 16, v161
	v_lshlrev_b32_e32 v172, 16, v160
	v_and_b32_e32 v161, 0xffff0000, v161
	v_and_b32_e32 v160, 0xffff0000, v160
	v_lshlrev_b32_e32 v175, 16, v163
	v_lshlrev_b32_e32 v174, 16, v162
	v_and_b32_e32 v163, 0xffff0000, v163
	v_and_b32_e32 v162, 0xffff0000, v162
	v_pk_mul_f32 v[128:129], v[128:129], v[172:173]
	v_pk_mul_f32 v[160:161], v[166:167], v[160:161]
	v_pk_mul_f32 v[166:167], v[170:171], v[174:175]
	v_pk_mul_f32 v[122:123], v[122:123], v[162:163]
	v_cvt_pk_bf16_f32 v163, v167, v123
	v_cvt_pk_bf16_f32 v162, v166, v122
	v_cvt_pk_bf16_f32 v161, v129, v161
	v_cvt_pk_bf16_f32 v160, v128, v160
	v_lshl_add_u64 v[122:123], v[96:97], 0, v[164:165]
	global_store_dwordx4 v[122:123], v[160:163], off
	s_cbranch_scc1 .LBB0_3136
	s_cmp_gt_i32 s14, 1
	s_cbranch_scc0 .LBB0_3137
	s_cmp_lg_u32 s14, 2
	s_cselect_b64 s[4:5], -1, 0
	s_cbranch_execz .LBB0_3138
	s_branch .LBB0_3139

; __device__ __forceinline__ unsigned f2bf(float f) { unsigned u = __builtin_bit_cast(unsigned, f); return (u + 0x7fffu + ((u >> 16) & 1u)) >> 16; }
; __device__ __forceinline__ unsigned pk2(float lo, float hi) { return f2bf(lo) | (f2bf(hi) << 16); }
; __device__ __forceinline__ void fir_tile(const Prm& P, Ctx& C, int pm, int gi) {
;     ...
;     for (int j = 0; j < RUN; ++j) {
;         const int t = t0 + j;
;         const u32x4 g = *(const u32x4*)(GT + (size_t)(row0 + j) * 1024 + c0);
;         acc8(s, x[15 + j], 1.f);
;         const float inv = 1.f / (float)(t + 1 < w ? t + 1 : w);
;         const u32x4 xc = x[15 + j];
;         u32x4 o;
;         o.x = pk2((s[0] * inv - bflo(xc.x)) * sc0[0] * bflo(g.x), (s[1] * inv - bfhi(xc.x)) * sc0[1] * bfhi(g.x));
;         o.y = pk2((s[2] * inv - bflo(xc.y)) * sc0[2] * bflo(g.y), (s[3] * inv - bfhi(xc.y)) * sc0[3] * bfhi(g.y));
;         o.z = pk2((s[4] * inv - bflo(xc.z)) * sc1[0] * bflo(g.z), (s[5] * inv - bfhi(xc.z)) * sc1[1] * bfhi(g.z));
;         o.w = pk2((s[6] * inv - bflo(xc.w)) * sc1[2] * bflo(g.w), (s[7] * inv - bfhi(xc.w)) * sc1[3] * bfhi(g.w));
;         *(u32x4*)(MX + (size_t)(row0 + j) * 1024 + c0) = o;
;         if (w == 2) acc8(s, x[15 + j - 1], -1.f); else if (w == 4) acc8(s, x[15 + j - 3], -1.f); else if (w == 8) acc8(s, x[15 + j - 7], -1.f); else acc8(s, x[j], -1.f);
.LBB0_3157:
	v_or_b32_e32 v92, 11, v132
	v_ashrrev_i32_e32 v93, 31, v92
	v_lshlrev_b64 v[122:123], 11, v[92:93]
	v_lshl_add_u64 v[92:93], v[98:99], 0, v[122:123]
	global_load_dwordx4 v[92:95], v[92:93], off
	v_pk_add_f32 v[78:79], v[78:79], v[84:85] neg_lo:[0,1] neg_hi:[0,1]
	v_or_b32_e32 v84, 12, v224
	v_min_i32_e32 v84, s10, v84
	v_cvt_f32_i32_e32 v84, v84
	v_pk_add_f32 v[82:83], v[82:83], v[100:101] neg_lo:[0,1] neg_hi:[0,1]
	v_pk_add_f32 v[60:61], v[28:29], v[60:61] neg_lo:[0,1] neg_hi:[0,1]
	v_pk_add_f32 v[62:63], v[30:31], v[62:63] neg_lo:[0,1] neg_hi:[0,1]
	v_div_scale_f32 v85, s[0:1], v84, v84, 1.0
	v_rcp_f32_e32 v100, v85
	v_div_scale_f32 v101, vcc, 1.0, v84, 1.0
	v_lshlrev_b32_e32 v29, 16, v25
	v_fma_f32 v128, -v85, v100, 1.0
	v_fmac_f32_e32 v100, v128, v100
	v_mul_f32_e32 v128, v101, v100
	v_fma_f32 v129, -v85, v128, v101
	v_fmac_f32_e32 v128, v129, v100
	v_fma_f32 v85, -v85, v128, v101
	v_lshlrev_b32_e32 v28, 16, v24
	v_and_b32_e32 v25, 0xffff0000, v25
	v_and_b32_e32 v24, 0xffff0000, v24
	v_lshlrev_b32_e32 v31, 16, v27
	v_lshlrev_b32_e32 v30, 16, v26
	v_and_b32_e32 v27, 0xffff0000, v27
	v_and_b32_e32 v26, 0xffff0000, v26
	v_div_fmas_f32 v85, v85, v100, v128
	v_pk_add_f32 v[60:61], v[60:61], v[28:29]
	v_pk_add_f32 v[62:63], v[62:63], v[24:25]
	v_pk_add_f32 v[78:79], v[78:79], v[30:31]
	v_pk_add_f32 v[82:83], v[82:83], v[26:27]
	v_div_fixup_f32 v84, v85, v84, 1.0
	v_pk_fma_f32 v[100:101], v[84:85], v[60:61], v[28:29] op_sel_hi:[0,1,1] neg_lo:[0,0,1] neg_hi:[0,0,1]
	v_pk_fma_f32 v[128:129], v[84:85], v[62:63], v[24:25] op_sel_hi:[0,1,1] neg_lo:[0,0,1] neg_hi:[0,0,1]
	v_pk_fma_f32 v[144:145], v[84:85], v[78:79], v[30:31] op_sel_hi:[0,1,1] neg_lo:[0,0,1] neg_hi:[0,0,1]
	v_pk_fma_f32 v[84:85], v[84:85], v[82:83], v[26:27] op_sel_hi:[0,1,1] neg_lo:[0,0,1] neg_hi:[0,0,1]
	v_pk_mul_f32 v[100:101], v[64:65], v[100:101]
	v_pk_mul_f32 v[128:129], v[6:7], v[128:129]
	v_pk_mul_f32 v[144:145], v[4:5], v[144:145]
	v_pk_mul_f32 v[84:85], v[2:3], v[84:85]
	s_movk_i32 s5, 0x7fff
	s_mov_b32 s4, 0xffff0000
	s_cmp_lt_i32 s14, 1
	s_mov_b64 s[0:1], 0
	s_waitcnt vmcnt(0)
	v_lshlrev_b32_e32 v147, 16, v93
	v_lshlrev_b32_e32 v146, 16, v92
	v_and_b32_e32 v93, 0xffff0000, v93
	v_and_b32_e32 v92, 0xffff0000, v92
	v_lshlrev_b32_e32 v149, 16, v95
	v_lshlrev_b32_e32 v148, 16, v94
	v_and_b32_e32 v95, 0xffff0000, v95
	v_and_b32_e32 v94, 0xffff0000, v94
	v_pk_mul_f32 v[100:101], v[100:101], v[146:147]
	v_pk_mul_f32 v[92:93], v[128:129], v[92:93]
	v_pk_mul_f32 v[128:129], v[144:145], v[148:149]
	v_pk_mul_f32 v[84:85], v[84:85], v[94:95]
	v_bfe_u32 v95, v84, 16, 1
	v_bfe_u32 v147, v128, 16, 1
	v_add3_u32 v84, v84, v95, s5
	v_add3_u32 v95, v128, v147, s5
	v_lshrrev_b32_e32 v128, 16, v95
	v_cvt_pk_bf16_f32 v95, v129, v85
	v_and_or_b32 v94, v84, s4, v128
	v_cvt_pk_bf16_f32 v93, v101, v93
	v_cvt_pk_bf16_f32 v92, v100, v92
	v_lshl_add_u64 v[84:85], v[96:97], 0, v[122:123]
	global_store_dwordx4 v[84:85], v[92:95], off
	s_cbranch_scc1 .LBB0_3160
	s_cmp_gt_i32 s14, 1
	s_cbranch_scc0 .LBB0_3161
	s_cmp_lg_u32 s14, 2
	s_cselect_b64 s[4:5], -1, 0
	s_cbranch_execz .LBB0_3162
	s_branch .LBB0_3163

; __device__ __forceinline__ unsigned f2bf(float f) { unsigned u = __builtin_bit_cast(unsigned, f); return (u + 0x7fffu + ((u >> 16) & 1u)) >> 16; }
; __device__ __forceinline__ unsigned pk2(float lo, float hi) { return f2bf(lo) | (f2bf(hi) << 16); }
; __device__ __forceinline__ void fir_tile(const Prm& P, Ctx& C, int pm, int gi) {
;     ...
;     for (int j = 0; j < RUN; ++j) {
;         const int t = t0 + j;
;         const u32x4 g = *(const u32x4*)(GT + (size_t)(row0 + j) * 1024 + c0);
;         acc8(s, x[15 + j], 1.f);
;         const float inv = 1.f / (float)(t + 1 < w ? t + 1 : w);
;         const u32x4 xc = x[15 + j];
;         u32x4 o;
;         o.x = pk2((s[0] * inv - bflo(xc.x)) * sc0[0] * bflo(g.x), (s[1] * inv - bfhi(xc.x)) * sc0[1] * bfhi(g.x));
;         o.y = pk2((s[2] * inv - bflo(xc.y)) * sc0[2] * bflo(g.y), (s[3] * inv - bfhi(xc.y)) * sc0[3] * bfhi(g.y));
;         o.z = pk2((s[4] * inv - bflo(xc.z)) * sc1[0] * bflo(g.z), (s[5] * inv - bfhi(xc.z)) * sc1[1] * bfhi(g.z));
;         o.w = pk2((s[6] * inv - bflo(xc.w)) * sc1[2] * bflo(g.w), (s[7] * inv - bfhi(xc.w)) * sc1[3] * bfhi(g.w));
;         *(u32x4*)(MX + (size_t)(row0 + j) * 1024 + c0) = o;
;         if (w == 2) acc8(s, x[15 + j - 1], -1.f); else if (w == 4) acc8(s, x[15 + j - 3], -1.f); else if (w == 8) acc8(s, x[15 + j - 7], -1.f); else acc8(s, x[j], -1.f);
.LBB0_3169:
	v_or_b32_e32 v68, 12, v132
	v_ashrrev_i32_e32 v69, 31, v68
	v_lshlrev_b64 v[80:81], 11, v[68:69]
	v_lshl_add_u64 v[68:69], v[98:99], 0, v[80:81]
	global_load_dwordx4 v[92:95], v[68:69], off
	v_pk_add_f32 v[68:69], v[60:61], v[56:57] neg_lo:[0,1] neg_hi:[0,1]
	v_pk_add_f32 v[72:73], v[62:63], v[58:59] neg_lo:[0,1] neg_hi:[0,1]
	v_lshlrev_b32_e32 v60, 16, v22
	v_and_b32_e32 v62, 0xffff0000, v22
	v_or_b32_e32 v22, 13, v224
	v_min_i32_e32 v22, s10, v22
	v_pk_add_f32 v[76:77], v[78:79], v[86:87] neg_lo:[0,1] neg_hi:[0,1]
	v_pk_add_f32 v[78:79], v[82:83], v[102:103] neg_lo:[0,1] neg_hi:[0,1]
	v_cvt_f32_i32_e32 v82, v22
	v_lshlrev_b32_e32 v57, 16, v21
	v_lshlrev_b32_e32 v56, 16, v20
	v_lshlrev_b32_e32 v61, 16, v23
	v_and_b32_e32 v59, 0xffff0000, v21
	v_and_b32_e32 v58, 0xffff0000, v20
	v_pk_add_f32 v[20:21], v[68:69], v[56:57]
	v_pk_add_f32 v[68:69], v[76:77], v[60:61]
	v_div_scale_f32 v76, s[0:1], v82, v82, 1.0
	v_rcp_f32_e32 v77, v76
	v_and_b32_e32 v63, 0xffff0000, v23
	v_pk_add_f32 v[22:23], v[72:73], v[58:59]
	v_pk_add_f32 v[72:73], v[78:79], v[62:63]
	v_fma_f32 v79, -v76, v77, 1.0
	v_div_scale_f32 v78, vcc, 1.0, v82, 1.0
	v_fmac_f32_e32 v77, v79, v77
	v_mul_f32_e32 v79, v78, v77
	v_fma_f32 v83, -v76, v79, v78
	v_fmac_f32_e32 v79, v83, v77
	v_fma_f32 v76, -v76, v79, v78
	v_div_fmas_f32 v76, v76, v77, v79
	v_div_fixup_f32 v76, v76, v82, 1.0
	v_pk_fma_f32 v[78:79], v[76:77], v[20:21], v[56:57] op_sel_hi:[0,1,1] neg_lo:[0,0,1] neg_hi:[0,0,1]
	v_pk_fma_f32 v[84:85], v[76:77], v[68:69], v[60:61] op_sel_hi:[0,1,1] neg_lo:[0,0,1] neg_hi:[0,0,1]
	v_pk_fma_f32 v[82:83], v[76:77], v[22:23], v[58:59] op_sel_hi:[0,1,1] neg_lo:[0,0,1] neg_hi:[0,0,1]
	v_pk_fma_f32 v[76:77], v[76:77], v[72:73], v[62:63] op_sel_hi:[0,1,1] neg_lo:[0,0,1] neg_hi:[0,0,1]
	v_pk_mul_f32 v[78:79], v[64:65], v[78:79]
	v_pk_mul_f32 v[84:85], v[4:5], v[84:85]
	v_pk_mul_f32 v[82:83], v[6:7], v[82:83]
	v_pk_mul_f32 v[76:77], v[2:3], v[76:77]
	s_movk_i32 s5, 0x7fff
	s_mov_b32 s4, 0xffff0000
	v_lshl_add_u64 v[80:81], v[96:97], 0, v[80:81]
	s_cmp_lt_i32 s14, 1
	s_mov_b64 s[0:1], 0
	s_waitcnt vmcnt(0)
	v_lshlrev_b32_e32 v87, 16, v93
	v_lshlrev_b32_e32 v86, 16, v92
	v_lshlrev_b32_e32 v101, 16, v95
	v_lshlrev_b32_e32 v100, 16, v94
	v_and_b32_e32 v93, 0xffff0000, v93
	v_and_b32_e32 v92, 0xffff0000, v92
	v_and_b32_e32 v95, 0xffff0000, v95
	v_and_b32_e32 v94, 0xffff0000, v94
	v_pk_mul_f32 v[78:79], v[78:79], v[86:87]
	v_pk_mul_f32 v[84:85], v[84:85], v[100:101]
	v_pk_mul_f32 v[82:83], v[82:83], v[92:93]
	v_pk_mul_f32 v[76:77], v[76:77], v[94:95]
	v_bfe_u32 v94, v78, 16, 1
	v_bfe_u32 v95, v79, 16, 1
	v_bfe_u32 v92, v83, 16, 1
	v_bfe_u32 v93, v82, 16, 1
	v_add3_u32 v79, v79, v95, s5
	v_add3_u32 v78, v78, v94, s5
	v_add3_u32 v82, v82, v93, s5
	v_add3_u32 v83, v83, v92, s5
	v_lshrrev_b32_e32 v86, 16, v78
	v_lshrrev_b32_e32 v87, 16, v79
	v_cvt_pk_bf16_f32 v79, v85, v77
	v_cvt_pk_bf16_f32 v78, v84, v76
	v_and_or_b32 v77, v83, s4, v87
	v_and_or_b32 v76, v82, s4, v86
	global_store_dwordx4 v[80:81], v[76:79], off
	s_cbranch_scc1 .LBB0_3172
	s_cmp_gt_i32 s14, 1
	s_cbranch_scc0 .LBB0_3173
	s_cmp_lg_u32 s14, 2
	s_cselect_b64 s[4:5], -1, 0
	s_cbranch_execz .LBB0_3174
	s_branch .LBB0_3175

; __device__ __forceinline__ unsigned f2bf(float f) { unsigned u = __builtin_bit_cast(unsigned, f); return (u + 0x7fffu + ((u >> 16) & 1u)) >> 16; }
; __device__ __forceinline__ unsigned pk2(float lo, float hi) { return f2bf(lo) | (f2bf(hi) << 16); }
; __device__ __forceinline__ void fir_tile(const Prm& P, Ctx& C, int pm, int gi) {
;     ...
;     for (int j = 0; j < RUN; ++j) {
;         const int t = t0 + j;
;         const u32x4 g = *(const u32x4*)(GT + (size_t)(row0 + j) * 1024 + c0);
;         acc8(s, x[15 + j], 1.f);
;         const float inv = 1.f / (float)(t + 1 < w ? t + 1 : w);
;         const u32x4 xc = x[15 + j];
;         u32x4 o;
;         o.x = pk2((s[0] * inv - bflo(xc.x)) * sc0[0] * bflo(g.x), (s[1] * inv - bfhi(xc.x)) * sc0[1] * bfhi(g.x));
;         o.y = pk2((s[2] * inv - bflo(xc.y)) * sc0[2] * bflo(g.y), (s[3] * inv - bfhi(xc.y)) * sc0[3] * bfhi(g.y));
;         o.z = pk2((s[4] * inv - bflo(xc.z)) * sc1[0] * bflo(g.z), (s[5] * inv - bfhi(xc.z)) * sc1[1] * bfhi(g.z));
;         o.w = pk2((s[6] * inv - bflo(xc.w)) * sc1[2] * bflo(g.w), (s[7] * inv - bfhi(xc.w)) * sc1[3] * bfhi(g.w));
;         *(u32x4*)(MX + (size_t)(row0 + j) * 1024 + c0) = o;
;         if (w == 2) acc8(s, x[15 + j - 1], -1.f); else if (w == 4) acc8(s, x[15 + j - 3], -1.f); else if (w == 8) acc8(s, x[15 + j - 7], -1.f); else acc8(s, x[j], -1.f);
.LBB0_3181:
	v_or_b32_e32 v32, 13, v132
	v_ashrrev_i32_e32 v33, 31, v32
	v_lshlrev_b64 v[78:79], 11, v[32:33]
	v_lshl_add_u64 v[32:33], v[98:99], 0, v[78:79]
	global_load_dwordx4 v[74:77], v[32:33], off
	v_pk_add_f32 v[36:37], v[22:23], v[54:55] neg_lo:[0,1] neg_hi:[0,1]
	v_or_b32_e32 v54, 14, v224
	v_min_i32_e32 v54, s10, v54
	v_cvt_f32_i32_e32 v54, v54
	v_pk_add_f32 v[38:39], v[68:69], v[88:89] neg_lo:[0,1] neg_hi:[0,1]
	v_pk_add_f32 v[32:33], v[20:21], v[52:53] neg_lo:[0,1] neg_hi:[0,1]
	v_pk_add_f32 v[52:53], v[72:73], v[130:131] neg_lo:[0,1] neg_hi:[0,1]
	v_div_scale_f32 v55, s[0:1], v54, v54, 1.0
	v_rcp_f32_e32 v68, v55
	v_div_scale_f32 v69, vcc, 1.0, v54, 1.0
	v_lshlrev_b32_e32 v21, 16, v17
	v_fma_f32 v72, -v55, v68, 1.0
	v_fmac_f32_e32 v68, v72, v68
	v_mul_f32_e32 v72, v69, v68
	v_fma_f32 v73, -v55, v72, v69
	v_fmac_f32_e32 v72, v73, v68
	v_fma_f32 v55, -v55, v72, v69
	v_lshlrev_b32_e32 v20, 16, v16
	v_and_b32_e32 v17, 0xffff0000, v17
	v_and_b32_e32 v16, 0xffff0000, v16
	v_lshlrev_b32_e32 v23, 16, v19
	v_lshlrev_b32_e32 v22, 16, v18
	v_div_fmas_f32 v55, v55, v68, v72
	v_and_b32_e32 v19, 0xffff0000, v19
	v_and_b32_e32 v18, 0xffff0000, v18
	v_pk_add_f32 v[32:33], v[32:33], v[20:21]
	v_pk_add_f32 v[36:37], v[36:37], v[16:17]
	v_pk_add_f32 v[38:39], v[38:39], v[22:23]
	v_div_fixup_f32 v54, v55, v54, 1.0
	v_pk_add_f32 v[52:53], v[52:53], v[18:19]
	v_pk_fma_f32 v[68:69], v[54:55], v[32:33], v[20:21] op_sel_hi:[0,1,1] neg_lo:[0,0,1] neg_hi:[0,0,1]
	v_pk_fma_f32 v[72:73], v[54:55], v[36:37], v[16:17] op_sel_hi:[0,1,1] neg_lo:[0,0,1] neg_hi:[0,0,1]
	v_pk_fma_f32 v[80:81], v[54:55], v[38:39], v[22:23] op_sel_hi:[0,1,1] neg_lo:[0,0,1] neg_hi:[0,0,1]
	v_pk_fma_f32 v[54:55], v[54:55], v[52:53], v[18:19] op_sel_hi:[0,1,1] neg_lo:[0,0,1] neg_hi:[0,0,1]
	v_pk_mul_f32 v[68:69], v[64:65], v[68:69]
	v_pk_mul_f32 v[72:73], v[6:7], v[72:73]
	v_pk_mul_f32 v[80:81], v[4:5], v[80:81]
	v_pk_mul_f32 v[54:55], v[2:3], v[54:55]
	s_movk_i32 s5, 0x7fff
	s_mov_b32 s4, 0xffff0000
	s_cmp_lt_i32 s14, 1
	s_mov_b64 s[0:1], 0
	s_waitcnt vmcnt(0)
	v_lshlrev_b32_e32 v83, 16, v75
	v_lshlrev_b32_e32 v82, 16, v74
	v_and_b32_e32 v75, 0xffff0000, v75
	v_and_b32_e32 v74, 0xffff0000, v74
	v_lshlrev_b32_e32 v85, 16, v77
	v_lshlrev_b32_e32 v84, 16, v76
	v_and_b32_e32 v77, 0xffff0000, v77
	v_and_b32_e32 v76, 0xffff0000, v76
	v_pk_mul_f32 v[68:69], v[68:69], v[82:83]
	v_pk_mul_f32 v[72:73], v[72:73], v[74:75]
	v_pk_mul_f32 v[74:75], v[80:81], v[84:85]
	v_pk_mul_f32 v[54:55], v[54:55], v[76:77]
	v_bfe_u32 v82, v68, 16, 1
	v_bfe_u32 v83, v69, 16, 1
	v_bfe_u32 v80, v73, 16, 1
	v_bfe_u32 v81, v72, 16, 1
	v_add3_u32 v69, v69, v83, s5
	v_add3_u32 v68, v68, v82, s5
	v_add3_u32 v72, v72, v81, s5
	v_add3_u32 v73, v73, v80, s5
	v_lshrrev_b32_e32 v68, 16, v68
	v_lshrrev_b32_e32 v69, 16, v69
	v_cvt_pk_bf16_f32 v75, v75, v55
	v_cvt_pk_bf16_f32 v74, v74, v54
	v_and_or_b32 v73, v73, s4, v69
	v_and_or_b32 v72, v72, s4, v68
	v_lshl_add_u64 v[54:55], v[96:97], 0, v[78:79]
	global_store_dwordx4 v[54:55], v[72:75], off
	s_cbranch_scc1 .LBB0_3184
	s_cmp_gt_i32 s14, 1
	s_cbranch_scc0 .LBB0_3185
	s_cmp_lg_u32 s14, 2
	s_cselect_b64 s[4:5], -1, 0
	s_cbranch_execz .LBB0_3186
	s_branch .LBB0_3187
